# plus hand-written P2 w_in conversion tail (dwordx4 loads, prefetch) and snake ordering of MFMAs (consecutive MFMAs share one operand) in all GEMM K-loops
# speedup vs baseline: 1.0062x; 1.0048x over previous
; #define PG8_STAGE(bufoff, gbase, voff) do { _Pragma("unroll") for (int _i = 0; _i < 2; ++_i) \
;         __builtin_amdgcn_global_load_lds((const unsigned*)((const char*)(gbase) + (voff)[_i]), (PG8_LAS unsigned*)(lds + (bufoff) + ldsw + _i * 8192), 16, 0, 0); } while (0)
; #define PG8_LDA(dst, b, h) do { _Pragma("unroll") for (int m = 0; m < 4; ++m) _Pragma("unroll") for (int k = 0; k < 2; ++k) dst[m][k] = *(const PG8_LAS bf16x8*)(lds + PG8_SA(b, h) + aoff + m * 2048 + k * 1024); } while (0)
; #define PG8_LDB(dst, b, h) do { _Pragma("unroll") for (int n = 0; n < 2; ++n) _Pragma("unroll") for (int k = 0; k < 2; ++k) dst[n][k] = *(const PG8_LAS bf16x8*)(lds + PG8_SB(b, h) + boff + n * 2048 + k * 1024); } while (0)
; #define PG8_MMA(ai, bj, At, Bt) do { __builtin_amdgcn_s_setprio(1); _Pragma("unroll") for (int m = 0; m < 4; ++m) _Pragma("unroll") for (int n = 0; n < 2; ++n) _Pragma("unroll") for (int k = 0; k < 2; ++k) \
;         acc[ai][bj][m][n] = __builtin_amdgcn_mfma_f32_16x16x32_bf16(Bt[n][k], At[m][k], acc[ai][bj][m][n], 0, 0, 0); __builtin_amdgcn_s_setprio(0); } while (0)
; #define PG8_WAIT_V(n) asm volatile("s_waitcnt vmcnt(" #n ")" ::: "memory")
; #define PG8_WAIT_L(n) asm volatile("s_waitcnt lgkmcnt(" #n ")" ::: "memory")
; #define PG8_BAR __builtin_amdgcn_s_barrier()
; #define PG8_SCHED __builtin_amdgcn_sched_barrier(0)
; template <class Epi, class Sched, bool ALIGN_EPI = false, bool SP2 = false>
; __device__ __forceinline__ void gemm_phase(PG8_LAS unsigned char* lds, const Gemm g, const Sched& S, const Epi& E) {
;     ...
;             PG8_LDB(B0, 0, 0); PG8_LDB(B1, 0, 1); PG8_SCHED; PG8_LDA(At, 0, 0); PG8_STAGE(PG8_SA(1, 1), a1 + hstep, voffA);
;             PG8_WAIT_V(8); PG8_WAIT_L(0); PG8_BAR; PG8_MMA(0, 0, At, B0); PG8_MMA(0, 1, At, B1); PG8_BAR; PG8_SCHED;
;             PG8_LDA(At, 0, 1); PG8_STAGE(PG8_SB(0, 0), b2, voffB); PG8_STAGE(PG8_SB(0, 1), b2 + hstep, voffB); PG8_STAGE(PG8_SA(0, 0), a2, voffA);
;             PG8_WAIT_V(8); PG8_WAIT_L(0); PG8_BAR; PG8_MMA(1, 0, At, B0); PG8_MMA(1, 1, At, B1); PG8_BAR; PG8_SCHED;
.LBB0_88:
	ds_read_b128 v[146:149], v153
	ds_read_b128 v[156:159], v153 offset:1024
	ds_read_b128 v[160:163], v153 offset:2048
	ds_read_b128 v[164:167], v153 offset:3072
	ds_read_b128 v[168:171], v154
	ds_read_b128 v[172:175], v154 offset:1024
	ds_read_b128 v[176:179], v154 offset:2048
	ds_read_b128 v[180:183], v154 offset:3072
	s_add_u32 s42, s40, 0xfff80080
	s_addc_u32 s43, s41, -1
	s_cmp_eq_u32 s52, 28
	s_cselect_b32 s45, s21, s43
	s_cselect_b32 s44, s48, s42
	s_cselect_b32 s43, s15, s51
	s_cselect_b32 s42, s49, s50
	v_lshl_add_u64 v[216:217], s[40:41], 0, v[138:139]
	s_add_i32 m0, s19, 0xc000
	ds_read_b128 v[184:187], v155
	ds_read_b128 v[188:191], v155 offset:1024
	ds_read_b128 v[192:195], v155 offset:2048
	ds_read_b128 v[196:199], v155 offset:3072
	ds_read_b128 v[200:203], v155 offset:4096
	ds_read_b128 v[204:207], v155 offset:5120
	ds_read_b128 v[208:211], v155 offset:6144
	ds_read_b128 v[212:215], v155 offset:7168
	global_load_lds_dwordx4 v[216:217], off
	v_lshl_add_u64 v[216:217], s[40:41], 0, v[140:141]
	s_add_i32 m0, s19, 0xe000
	s_nop 0
	global_load_lds_dwordx4 v[216:217], off
	s_waitcnt vmcnt(8)
	s_waitcnt lgkmcnt(0)
	s_barrier
	s_setprio 1
	s_waitcnt lgkmcnt(0)
	v_mfma_f32_16x16x32_bf16 v[126:129], v[146:149], v[184:187], v[126:129]
	v_mfma_f32_16x16x32_bf16 v[122:125], v[160:163], v[184:187], v[122:125]
	v_mfma_f32_16x16x32_bf16 v[106:109], v[160:163], v[192:195], v[106:109]
	v_mfma_f32_16x16x32_bf16 v[110:113], v[146:149], v[192:195], v[110:113]
	v_mfma_f32_16x16x32_bf16 v[94:97], v[146:149], v[200:203], v[94:97]
	v_mfma_f32_16x16x32_bf16 v[90:93], v[160:163], v[200:203], v[90:93]
	v_mfma_f32_16x16x32_bf16 v[74:77], v[160:163], v[208:211], v[74:77]
	v_mfma_f32_16x16x32_bf16 v[78:81], v[146:149], v[208:211], v[78:81]
	v_mfma_f32_16x16x32_bf16 v[126:129], v[156:159], v[188:191], v[126:129]
	v_mfma_f32_16x16x32_bf16 v[122:125], v[164:167], v[188:191], v[122:125]
	v_mfma_f32_16x16x32_bf16 v[106:109], v[164:167], v[196:199], v[106:109]
	v_mfma_f32_16x16x32_bf16 v[110:113], v[156:159], v[196:199], v[110:113]
	v_mfma_f32_16x16x32_bf16 v[94:97], v[156:159], v[204:207], v[94:97]
	v_mfma_f32_16x16x32_bf16 v[90:93], v[164:167], v[204:207], v[90:93]
	v_mfma_f32_16x16x32_bf16 v[74:77], v[164:167], v[212:215], v[74:77]
	v_mfma_f32_16x16x32_bf16 v[78:81], v[156:159], v[212:215], v[78:81]
	s_setprio 0
	s_setprio 1
	v_mfma_f32_16x16x32_bf16 v[118:121], v[168:171], v[184:187], v[118:121]
	v_mfma_f32_16x16x32_bf16 v[114:117], v[176:179], v[184:187], v[114:117]
	v_mfma_f32_16x16x32_bf16 v[98:101], v[176:179], v[192:195], v[98:101]
	v_mfma_f32_16x16x32_bf16 v[102:105], v[168:171], v[192:195], v[102:105]
	v_mfma_f32_16x16x32_bf16 v[86:89], v[168:171], v[200:203], v[86:89]
	v_mfma_f32_16x16x32_bf16 v[82:85], v[176:179], v[200:203], v[82:85]
	v_mfma_f32_16x16x32_bf16 v[66:69], v[176:179], v[208:211], v[66:69]
	v_mfma_f32_16x16x32_bf16 v[70:73], v[168:171], v[208:211], v[70:73]
	v_mfma_f32_16x16x32_bf16 v[118:121], v[172:175], v[188:191], v[118:121]
	v_mfma_f32_16x16x32_bf16 v[114:117], v[180:183], v[188:191], v[114:117]
	v_mfma_f32_16x16x32_bf16 v[98:101], v[180:183], v[196:199], v[98:101]
	v_mfma_f32_16x16x32_bf16 v[102:105], v[172:175], v[196:199], v[102:105]
	v_mfma_f32_16x16x32_bf16 v[86:89], v[172:175], v[204:207], v[86:89]
	v_mfma_f32_16x16x32_bf16 v[82:85], v[180:183], v[204:207], v[82:85]
	v_mfma_f32_16x16x32_bf16 v[66:69], v[180:183], v[212:215], v[66:69]
	v_mfma_f32_16x16x32_bf16 v[70:73], v[172:175], v[212:215], v[70:73]
	s_setprio 0
	s_barrier
	s_add_i32 s53, s31, s16
	v_lshl_add_u64 v[216:217], s[42:43], 0, v[134:135]
	s_mov_b32 m0, s53
	ds_read_b128 v[184:187], v155 offset:16384
	ds_read_b128 v[188:191], v155 offset:17408
	ds_read_b128 v[192:195], v155 offset:18432
	ds_read_b128 v[196:199], v155 offset:19456
	ds_read_b128 v[200:203], v155 offset:20480
	ds_read_b128 v[204:207], v155 offset:21504
	ds_read_b128 v[208:211], v155 offset:22528
	ds_read_b128 v[212:215], v155 offset:23552
	global_load_lds_dwordx4 v[216:217], off
	s_add_i32 m0, s53, 0x2000
	s_add_u32 s54, s42, 0x80000
	v_lshl_add_u64 v[218:219], s[42:43], 0, v[130:131]
	s_addc_u32 s55, s43, 0
	s_add_i32 s53, s39, s16
	global_load_lds_dwordx4 v[218:219], off
	v_lshl_add_u64 v[220:221], s[54:55], 0, v[134:135]
	s_mov_b32 m0, s53
	v_lshl_add_u64 v[222:223], s[44:45], 0, v[132:133]
	global_load_lds_dwordx4 v[220:221], off
	v_lshl_add_u64 v[220:221], s[54:55], 0, v[130:131]
	s_add_i32 m0, s53, 0x2000
	s_nop 0
	global_load_lds_dwordx4 v[220:221], off
	v_lshl_add_u64 v[220:221], s[44:45], 0, v[136:137]
	s_mov_b32 m0, s19
	s_nop 0
	global_load_lds_dwordx4 v[220:221], off
	s_mov_b32 m0, s24
	s_nop 0
	global_load_lds_dwordx4 v[222:223], off
	s_waitcnt vmcnt(8)
	s_waitcnt lgkmcnt(0)
	s_barrier
; #define PG8_STAGE(bufoff, gbase, voff) do { _Pragma("unroll") for (int _i = 0; _i < 2; ++_i) \
;         __builtin_amdgcn_global_load_lds((const unsigned*)((const char*)(gbase) + (voff)[_i]), (PG8_LAS unsigned*)(lds + (bufoff) + ldsw + _i * 8192), 16, 0, 0); } while (0)
; #define PG8_LDA(dst, b, h) do { _Pragma("unroll") for (int m = 0; m < 4; ++m) _Pragma("unroll") for (int k = 0; k < 2; ++k) dst[m][k] = *(const PG8_LAS bf16x8*)(lds + PG8_SA(b, h) + aoff + m * 2048 + k * 1024); } while (0)
; #define PG8_LDB(dst, b, h) do { _Pragma("unroll") for (int n = 0; n < 2; ++n) _Pragma("unroll") for (int k = 0; k < 2; ++k) dst[n][k] = *(const PG8_LAS bf16x8*)(lds + PG8_SB(b, h) + boff + n * 2048 + k * 1024); } while (0)
; #define PG8_MMA(ai, bj, At, Bt) do { __builtin_amdgcn_s_setprio(1); _Pragma("unroll") for (int m = 0; m < 4; ++m) _Pragma("unroll") for (int n = 0; n < 2; ++n) _Pragma("unroll") for (int k = 0; k < 2; ++k) \
;         acc[ai][bj][m][n] = __builtin_amdgcn_mfma_f32_16x16x32_bf16(Bt[n][k], At[m][k], acc[ai][bj][m][n], 0, 0, 0); __builtin_amdgcn_s_setprio(0); } while (0)
; #define PG8_WAIT_V(n) asm volatile("s_waitcnt vmcnt(" #n ")" ::: "memory")
; #define PG8_WAIT_L(n) asm volatile("s_waitcnt lgkmcnt(" #n ")" ::: "memory")
; #define PG8_BAR __builtin_amdgcn_s_barrier()
; #define PG8_SCHED __builtin_amdgcn_sched_barrier(0)
; template <class Epi, class Sched, bool ALIGN_EPI = false, bool SP2 = false>
; __device__ __forceinline__ void gemm_phase(PG8_LAS unsigned char* lds, const Gemm g, const Sched& S, const Epi& E) {
;     ...
;             PG8_WAIT_V(8); PG8_WAIT_L(0); PG8_BAR; PG8_MMA(1, 0, At, B0); PG8_MMA(1, 1, At, B1); PG8_BAR; PG8_SCHED;
;             PG8_LDB(B0, 1, 0); PG8_LDB(B1, 1, 1); PG8_SCHED; PG8_LDA(At, 1, 0); PG8_STAGE(PG8_SA(0, 1), a2 + hstep, voffA);
;             PG8_WAIT_V(8); PG8_WAIT_L(0); PG8_BAR; PG8_MMA(0, 0, At, B0); PG8_MMA(0, 1, At, B1); PG8_BAR; PG8_SCHED;
	s_setprio 1
	s_waitcnt lgkmcnt(0)
	v_mfma_f32_16x16x32_bf16 v[62:65], v[146:149], v[184:187], v[62:65]
	v_mfma_f32_16x16x32_bf16 v[58:61], v[160:163], v[184:187], v[58:61]
	v_mfma_f32_16x16x32_bf16 v[42:45], v[160:163], v[192:195], v[42:45]
	v_mfma_f32_16x16x32_bf16 v[46:49], v[146:149], v[192:195], v[46:49]
	v_mfma_f32_16x16x32_bf16 v[30:33], v[146:149], v[200:203], v[30:33]
	v_mfma_f32_16x16x32_bf16 v[26:29], v[160:163], v[200:203], v[26:29]
	v_mfma_f32_16x16x32_bf16 v[10:13], v[160:163], v[208:211], v[10:13]
	v_mfma_f32_16x16x32_bf16 v[14:17], v[146:149], v[208:211], v[14:17]
	v_mfma_f32_16x16x32_bf16 v[62:65], v[156:159], v[188:191], v[62:65]
	v_mfma_f32_16x16x32_bf16 v[58:61], v[164:167], v[188:191], v[58:61]
	v_mfma_f32_16x16x32_bf16 v[42:45], v[164:167], v[196:199], v[42:45]
	v_mfma_f32_16x16x32_bf16 v[46:49], v[156:159], v[196:199], v[46:49]
	v_mfma_f32_16x16x32_bf16 v[30:33], v[156:159], v[204:207], v[30:33]
	v_mfma_f32_16x16x32_bf16 v[26:29], v[164:167], v[204:207], v[26:29]
	v_mfma_f32_16x16x32_bf16 v[10:13], v[164:167], v[212:215], v[10:13]
	v_mfma_f32_16x16x32_bf16 v[14:17], v[156:159], v[212:215], v[14:17]
	s_setprio 0
	s_setprio 1
	v_mfma_f32_16x16x32_bf16 v[54:57], v[168:171], v[184:187], v[54:57]
	v_mfma_f32_16x16x32_bf16 v[50:53], v[176:179], v[184:187], v[50:53]
	v_mfma_f32_16x16x32_bf16 v[34:37], v[176:179], v[192:195], v[34:37]
	v_mfma_f32_16x16x32_bf16 v[38:41], v[168:171], v[192:195], v[38:41]
	v_mfma_f32_16x16x32_bf16 v[22:25], v[168:171], v[200:203], v[22:25]
	v_mfma_f32_16x16x32_bf16 v[18:21], v[176:179], v[200:203], v[18:21]
	v_mfma_f32_16x16x32_bf16 v[2:5], v[176:179], v[208:211], v[2:5]
	v_mfma_f32_16x16x32_bf16 v[6:9], v[168:171], v[208:211], v[6:9]
	v_mfma_f32_16x16x32_bf16 v[54:57], v[172:175], v[188:191], v[54:57]
	v_mfma_f32_16x16x32_bf16 v[50:53], v[180:183], v[188:191], v[50:53]
	v_mfma_f32_16x16x32_bf16 v[34:37], v[180:183], v[196:199], v[34:37]
	v_mfma_f32_16x16x32_bf16 v[38:41], v[172:175], v[196:199], v[38:41]
	v_mfma_f32_16x16x32_bf16 v[22:25], v[172:175], v[204:207], v[22:25]
	v_mfma_f32_16x16x32_bf16 v[18:21], v[180:183], v[204:207], v[18:21]
	v_mfma_f32_16x16x32_bf16 v[2:5], v[180:183], v[212:215], v[2:5]
	v_mfma_f32_16x16x32_bf16 v[6:9], v[172:175], v[212:215], v[6:9]
	s_setprio 0
	s_barrier
	s_add_i32 s53, 0, 0x18000
	s_add_i32 s54, 0, 0x1c000
	v_add_u32_e32 v164, s53, v151
	v_add_u32_e32 v180, s54, v151
	ds_read_b128 v[146:149], v164
	ds_read_b128 v[156:159], v164 offset:1024
	ds_read_b128 v[160:163], v164 offset:2048
	ds_read_b128 v[164:167], v164 offset:3072
	ds_read_b128 v[168:171], v180
	ds_read_b128 v[172:175], v180 offset:1024
	ds_read_b128 v[176:179], v180 offset:2048
	ds_read_b128 v[180:183], v180 offset:3072
	s_add_u32 s44, s44, 0x80000
	s_addc_u32 s45, s45, 0
	s_mov_b32 m0, s25
	v_lshl_add_u64 v[224:225], s[44:45], 0, v[136:137]
	ds_read_b128 v[184:187], v155 offset:32768
	ds_read_b128 v[188:191], v155 offset:33792
	ds_read_b128 v[192:195], v155 offset:34816
	ds_read_b128 v[196:199], v155 offset:35840
	ds_read_b128 v[200:203], v155 offset:36864
	ds_read_b128 v[204:207], v155 offset:37888
	ds_read_b128 v[208:211], v155 offset:38912
	ds_read_b128 v[212:215], v155 offset:39936
	global_load_lds_dwordx4 v[224:225], off
	v_lshl_add_u64 v[224:225], s[44:45], 0, v[132:133]
	s_mov_b32 m0, s26
	s_nop 0
	global_load_lds_dwordx4 v[224:225], off
	s_waitcnt vmcnt(8)
	s_waitcnt lgkmcnt(0)
	s_barrier
	s_setprio 1
	s_waitcnt lgkmcnt(0)
	v_mfma_f32_16x16x32_bf16 v[126:129], v[146:149], v[184:187], v[126:129]
	v_mfma_f32_16x16x32_bf16 v[122:125], v[160:163], v[184:187], v[122:125]
	v_mfma_f32_16x16x32_bf16 v[106:109], v[160:163], v[192:195], v[106:109]
	v_mfma_f32_16x16x32_bf16 v[110:113], v[146:149], v[192:195], v[110:113]
	v_mfma_f32_16x16x32_bf16 v[94:97], v[146:149], v[200:203], v[94:97]
	v_mfma_f32_16x16x32_bf16 v[90:93], v[160:163], v[200:203], v[90:93]
	v_mfma_f32_16x16x32_bf16 v[74:77], v[160:163], v[208:211], v[74:77]
	v_mfma_f32_16x16x32_bf16 v[78:81], v[146:149], v[208:211], v[78:81]
	v_mfma_f32_16x16x32_bf16 v[126:129], v[156:159], v[188:191], v[126:129]
	v_mfma_f32_16x16x32_bf16 v[122:125], v[164:167], v[188:191], v[122:125]
	v_mfma_f32_16x16x32_bf16 v[106:109], v[164:167], v[196:199], v[106:109]
	v_mfma_f32_16x16x32_bf16 v[110:113], v[156:159], v[196:199], v[110:113]
	v_mfma_f32_16x16x32_bf16 v[94:97], v[156:159], v[204:207], v[94:97]
	v_mfma_f32_16x16x32_bf16 v[90:93], v[164:167], v[204:207], v[90:93]
	v_mfma_f32_16x16x32_bf16 v[74:77], v[164:167], v[212:215], v[74:77]
	v_mfma_f32_16x16x32_bf16 v[78:81], v[156:159], v[212:215], v[78:81]
	s_setprio 0
	s_setprio 1
	v_mfma_f32_16x16x32_bf16 v[118:121], v[168:171], v[184:187], v[118:121]
	v_mfma_f32_16x16x32_bf16 v[114:117], v[176:179], v[184:187], v[114:117]
	v_mfma_f32_16x16x32_bf16 v[98:101], v[176:179], v[192:195], v[98:101]
	v_mfma_f32_16x16x32_bf16 v[102:105], v[168:171], v[192:195], v[102:105]
	v_mfma_f32_16x16x32_bf16 v[86:89], v[168:171], v[200:203], v[86:89]
	v_mfma_f32_16x16x32_bf16 v[82:85], v[176:179], v[200:203], v[82:85]
	v_mfma_f32_16x16x32_bf16 v[66:69], v[176:179], v[208:211], v[66:69]
	v_mfma_f32_16x16x32_bf16 v[70:73], v[168:171], v[208:211], v[70:73]
	v_mfma_f32_16x16x32_bf16 v[118:121], v[172:175], v[188:191], v[118:121]
	v_mfma_f32_16x16x32_bf16 v[114:117], v[180:183], v[188:191], v[114:117]
	v_mfma_f32_16x16x32_bf16 v[98:101], v[180:183], v[196:199], v[98:101]
	v_mfma_f32_16x16x32_bf16 v[102:105], v[172:175], v[196:199], v[102:105]
	v_mfma_f32_16x16x32_bf16 v[86:89], v[172:175], v[204:207], v[86:89]
	v_mfma_f32_16x16x32_bf16 v[82:85], v[180:183], v[204:207], v[82:85]
	v_mfma_f32_16x16x32_bf16 v[66:69], v[180:183], v[212:215], v[66:69]
	v_mfma_f32_16x16x32_bf16 v[70:73], v[172:175], v[212:215], v[70:73]
	s_setprio 0
	s_barrier
; #define PG8_STAGE(bufoff, gbase, voff) do { _Pragma("unroll") for (int _i = 0; _i < 2; ++_i) \
;         __builtin_amdgcn_global_load_lds((const unsigned*)((const char*)(gbase) + (voff)[_i]), (PG8_LAS unsigned*)(lds + (bufoff) + ldsw + _i * 8192), 16, 0, 0); } while (0)
; #define PG8_LDA(dst, b, h) do { _Pragma("unroll") for (int m = 0; m < 4; ++m) _Pragma("unroll") for (int k = 0; k < 2; ++k) dst[m][k] = *(const PG8_LAS bf16x8*)(lds + PG8_SA(b, h) + aoff + m * 2048 + k * 1024); } while (0)
; #define PG8_MMA(ai, bj, At, Bt) do { __builtin_amdgcn_s_setprio(1); _Pragma("unroll") for (int m = 0; m < 4; ++m) _Pragma("unroll") for (int n = 0; n < 2; ++n) _Pragma("unroll") for (int k = 0; k < 2; ++k) \
;         acc[ai][bj][m][n] = __builtin_amdgcn_mfma_f32_16x16x32_bf16(Bt[n][k], At[m][k], acc[ai][bj][m][n], 0, 0, 0); __builtin_amdgcn_s_setprio(0); } while (0)
; #define PG8_WAIT_V(n) asm volatile("s_waitcnt vmcnt(" #n ")" ::: "memory")
; #define PG8_WAIT_L(n) asm volatile("s_waitcnt lgkmcnt(" #n ")" ::: "memory")
; #define PG8_BAR __builtin_amdgcn_s_barrier()
; #define PG8_SCHED __builtin_amdgcn_sched_barrier(0)
; template <class Epi, class Sched, bool ALIGN_EPI = false, bool SP2 = false>
; __device__ __forceinline__ void gemm_phase(PG8_LAS unsigned char* lds, const Gemm g, const Sched& S, const Epi& E) {
;     ...
;         for (int t = 0; t < nt; t += 2) {
;             if constexpr (Epi::MIDHOOK) { if (t == (nt >> 1)) E.mid(acc, cur, wr, wc, fr, fq); }
;             const bool last = (t == nt - 2);
;             const char* a1 = cA + (size_t)(t + 1) * kstep;
;             const char* a2 = last ? nA : cA + (size_t)(t + 2) * kstep; const char* b2 = last ? nB : cB + (size_t)(t + 2) * kstep;
;             const char* a3 = a2 + kstep; const char* b3 = b2 + kstep;
;             if (last && has_next) S.a_ready(nxt);
;     ...
;             PG8_LDA(At, 1, 1); PG8_STAGE(PG8_SB(1, 0), b3, voffB); PG8_STAGE(PG8_SB(1, 1), b3 + hstep, voffB); PG8_STAGE(PG8_SA(1, 0), a3, voffA);
;             PG8_WAIT_V(8); PG8_WAIT_L(0); PG8_BAR; PG8_MMA(1, 0, At, B0); PG8_MMA(1, 1, At, B1); PG8_BAR; PG8_SCHED;
	s_add_i32 s44, s53, s16
	v_lshl_add_u64 v[216:217], v[216:217], 0, s[10:11]
	s_mov_b32 m0, s44
	ds_read_b128 v[184:187], v155 offset:49152
	ds_read_b128 v[188:191], v155 offset:50176
	ds_read_b128 v[192:195], v155 offset:51200
	ds_read_b128 v[196:199], v155 offset:52224
	ds_read_b128 v[200:203], v155 offset:53248
	ds_read_b128 v[204:207], v155 offset:54272
	ds_read_b128 v[208:211], v155 offset:55296
	ds_read_b128 v[212:215], v155 offset:56320
	global_load_lds_dwordx4 v[216:217], off
	s_add_i32 m0, s44, 0x2000
	s_add_u32 s42, s42, 0x80080
	v_lshl_add_u64 v[216:217], v[218:219], 0, s[10:11]
	s_addc_u32 s43, s43, 0
	s_add_i32 s44, s54, s16
	global_load_lds_dwordx4 v[216:217], off
	v_lshl_add_u64 v[216:217], s[42:43], 0, v[134:135]
	s_mov_b32 m0, s44
	s_nop 0
	global_load_lds_dwordx4 v[216:217], off
	v_lshl_add_u64 v[216:217], s[42:43], 0, v[130:131]
	s_add_i32 m0, s44, 0x2000
	s_nop 0
	global_load_lds_dwordx4 v[216:217], off
	v_lshl_add_u64 v[216:217], v[220:221], 0, s[10:11]
	s_mov_b32 m0, s29
	s_nop 0
	global_load_lds_dwordx4 v[216:217], off
	v_lshl_add_u64 v[216:217], v[222:223], 0, s[10:11]
	s_mov_b32 m0, s30
	s_nop 0
	global_load_lds_dwordx4 v[216:217], off
	s_waitcnt vmcnt(8)
	s_waitcnt lgkmcnt(0)
	s_barrier
	s_setprio 1
	s_waitcnt lgkmcnt(0)
	v_mfma_f32_16x16x32_bf16 v[62:65], v[146:149], v[184:187], v[62:65]
	v_mfma_f32_16x16x32_bf16 v[58:61], v[160:163], v[184:187], v[58:61]
	v_mfma_f32_16x16x32_bf16 v[42:45], v[160:163], v[192:195], v[42:45]
	v_mfma_f32_16x16x32_bf16 v[46:49], v[146:149], v[192:195], v[46:49]
	v_mfma_f32_16x16x32_bf16 v[30:33], v[146:149], v[200:203], v[30:33]
	v_mfma_f32_16x16x32_bf16 v[26:29], v[160:163], v[200:203], v[26:29]
	v_mfma_f32_16x16x32_bf16 v[10:13], v[160:163], v[208:211], v[10:13]
	v_mfma_f32_16x16x32_bf16 v[14:17], v[146:149], v[208:211], v[14:17]
	v_mfma_f32_16x16x32_bf16 v[62:65], v[156:159], v[188:191], v[62:65]
	v_mfma_f32_16x16x32_bf16 v[58:61], v[164:167], v[188:191], v[58:61]
	v_mfma_f32_16x16x32_bf16 v[42:45], v[164:167], v[196:199], v[42:45]
	v_mfma_f32_16x16x32_bf16 v[46:49], v[156:159], v[196:199], v[46:49]
	v_mfma_f32_16x16x32_bf16 v[30:33], v[156:159], v[204:207], v[30:33]
	v_mfma_f32_16x16x32_bf16 v[26:29], v[164:167], v[204:207], v[26:29]
	v_mfma_f32_16x16x32_bf16 v[10:13], v[164:167], v[212:215], v[10:13]
	v_mfma_f32_16x16x32_bf16 v[14:17], v[156:159], v[212:215], v[14:17]
	s_setprio 0
	s_setprio 1
	v_mfma_f32_16x16x32_bf16 v[54:57], v[168:171], v[184:187], v[54:57]
	v_mfma_f32_16x16x32_bf16 v[50:53], v[176:179], v[184:187], v[50:53]
	v_mfma_f32_16x16x32_bf16 v[34:37], v[176:179], v[192:195], v[34:37]
	v_mfma_f32_16x16x32_bf16 v[38:41], v[168:171], v[192:195], v[38:41]
	v_mfma_f32_16x16x32_bf16 v[22:25], v[168:171], v[200:203], v[22:25]
	v_mfma_f32_16x16x32_bf16 v[18:21], v[176:179], v[200:203], v[18:21]
	v_mfma_f32_16x16x32_bf16 v[2:5], v[176:179], v[208:211], v[2:5]
	v_mfma_f32_16x16x32_bf16 v[6:9], v[168:171], v[208:211], v[6:9]
	v_mfma_f32_16x16x32_bf16 v[54:57], v[172:175], v[188:191], v[54:57]
	v_mfma_f32_16x16x32_bf16 v[50:53], v[180:183], v[188:191], v[50:53]
	v_mfma_f32_16x16x32_bf16 v[34:37], v[180:183], v[196:199], v[34:37]
	v_mfma_f32_16x16x32_bf16 v[38:41], v[172:175], v[196:199], v[38:41]
	v_mfma_f32_16x16x32_bf16 v[22:25], v[172:175], v[204:207], v[22:25]
	v_mfma_f32_16x16x32_bf16 v[18:21], v[180:183], v[204:207], v[18:21]
	v_mfma_f32_16x16x32_bf16 v[2:5], v[180:183], v[212:215], v[2:5]
	v_mfma_f32_16x16x32_bf16 v[6:9], v[172:175], v[212:215], v[6:9]
	s_setprio 0
	s_barrier
	s_add_i32 s52, s52, 2
	s_add_u32 s40, s40, 0x100
	s_addc_u32 s41, s41, 0
	s_add_u32 s50, s50, 0x100
	s_addc_u32 s51, s51, 0
	s_cmp_gt_u32 s52, 29
	s_cbranch_scc0 .LBB0_88
	s_and_b64 vcc, exec, s[12:13]
	s_cbranch_vccz .LBB0_91
	s_barrier

; #define PG8_STAGE(bufoff, gbase, voff) do { _Pragma("unroll") for (int _i = 0; _i < 2; ++_i) \
;         __builtin_amdgcn_global_load_lds((const unsigned*)((const char*)(gbase) + (voff)[_i]), (PG8_LAS unsigned*)(lds + (bufoff) + ldsw + _i * 8192), 16, 0, 0); } while (0)
; #define PG8_LDA(dst, b, h) do { _Pragma("unroll") for (int m = 0; m < 4; ++m) _Pragma("unroll") for (int k = 0; k < 2; ++k) dst[m][k] = *(const PG8_LAS bf16x8*)(lds + PG8_SA(b, h) + aoff + m * 2048 + k * 1024); } while (0)
; #define PG8_LDB(dst, b, h) do { _Pragma("unroll") for (int n = 0; n < 2; ++n) _Pragma("unroll") for (int k = 0; k < 2; ++k) dst[n][k] = *(const PG8_LAS bf16x8*)(lds + PG8_SB(b, h) + boff + n * 2048 + k * 1024); } while (0)
; #define PG8_MMA(ai, bj, At, Bt) do { __builtin_amdgcn_s_setprio(1); _Pragma("unroll") for (int m = 0; m < 4; ++m) _Pragma("unroll") for (int n = 0; n < 2; ++n) _Pragma("unroll") for (int k = 0; k < 2; ++k) \
;         acc[ai][bj][m][n] = __builtin_amdgcn_mfma_f32_16x16x32_bf16(Bt[n][k], At[m][k], acc[ai][bj][m][n], 0, 0, 0); __builtin_amdgcn_s_setprio(0); } while (0)
; #define PG8_WAIT_V(n) asm volatile("s_waitcnt vmcnt(" #n ")" ::: "memory")
; #define PG8_WAIT_L(n) asm volatile("s_waitcnt lgkmcnt(" #n ")" ::: "memory")
; #define PG8_BAR __builtin_amdgcn_s_barrier()
; #define PG8_SCHED __builtin_amdgcn_sched_barrier(0)
; template <class Epi, class Sched, bool ALIGN_EPI = false, bool SP2 = false>
; __device__ __forceinline__ void gemm_phase(PG8_LAS unsigned char* lds, const Gemm g, const Sched& S, const Epi& E) {
;     ...
;             PG8_LDB(B0, 0, 0); PG8_LDB(B1, 0, 1); PG8_SCHED; PG8_LDA(At, 0, 0); PG8_STAGE(PG8_SA(1, 1), a1 + hstep, voffA);
;             PG8_WAIT_V(8); PG8_WAIT_L(0); PG8_BAR; PG8_MMA(0, 0, At, B0); PG8_MMA(0, 1, At, B1); PG8_BAR; PG8_SCHED;
;             PG8_LDA(At, 0, 1); PG8_STAGE(PG8_SB(0, 0), b2, voffB); PG8_STAGE(PG8_SB(0, 1), b2 + hstep, voffB); PG8_STAGE(PG8_SA(0, 0), a2, voffA);
;             PG8_WAIT_V(8); PG8_WAIT_L(0); PG8_BAR; PG8_MMA(1, 0, At, B0); PG8_MMA(1, 1, At, B1); PG8_BAR; PG8_SCHED;
.LBB0_173:
	ds_read_b128 v[154:157], v151
	ds_read_b128 v[158:161], v151 offset:1024
	ds_read_b128 v[162:165], v151 offset:2048
	ds_read_b128 v[166:169], v151 offset:3072
	ds_read_b128 v[170:173], v152
	ds_read_b128 v[174:177], v152 offset:1024
	ds_read_b128 v[178:181], v152 offset:2048
	ds_read_b128 v[182:185], v152 offset:3072
	s_add_u32 s36, s22, 0x100
	s_addc_u32 s37, s23, 0
	s_cmpk_eq_i32 s48, 0x54
	s_cselect_b32 s41, s7, s37
	s_cselect_b32 s40, s6, s36
	s_cselect_b32 s39, s21, s47
	s_cselect_b32 s38, s20, s46
	v_lshl_add_u64 v[146:147], s[22:23], 0, v[138:139]
	s_add_i32 m0, s18, 0xc000
	ds_read_b128 v[186:189], v153
	ds_read_b128 v[190:193], v153 offset:1024
	ds_read_b128 v[194:197], v153 offset:2048
	ds_read_b128 v[198:201], v153 offset:3072
	ds_read_b128 v[202:205], v153 offset:4096
	ds_read_b128 v[206:209], v153 offset:5120
	ds_read_b128 v[210:213], v153 offset:6144
	ds_read_b128 v[214:217], v153 offset:7168
	global_load_lds_dwordx4 v[146:147], off
	v_lshl_add_u64 v[146:147], s[22:23], 0, v[140:141]
	s_add_i32 m0, s18, 0xe000
	s_nop 0
	global_load_lds_dwordx4 v[146:147], off
	s_waitcnt vmcnt(8)
	s_waitcnt lgkmcnt(0)
	s_barrier
	s_setprio 1
	s_waitcnt lgkmcnt(0)
	v_mfma_f32_16x16x32_bf16 v[126:129], v[154:157], v[186:189], v[126:129]
	v_mfma_f32_16x16x32_bf16 v[122:125], v[162:165], v[186:189], v[122:125]
	v_mfma_f32_16x16x32_bf16 v[110:113], v[162:165], v[194:197], v[110:113]
	v_mfma_f32_16x16x32_bf16 v[118:121], v[154:157], v[194:197], v[118:121]
	v_mfma_f32_16x16x32_bf16 v[102:105], v[154:157], v[202:205], v[102:105]
	v_mfma_f32_16x16x32_bf16 v[94:97], v[162:165], v[202:205], v[94:97]
	v_mfma_f32_16x16x32_bf16 v[78:81], v[162:165], v[210:213], v[78:81]
	v_mfma_f32_16x16x32_bf16 v[86:89], v[154:157], v[210:213], v[86:89]
	v_mfma_f32_16x16x32_bf16 v[126:129], v[158:161], v[190:193], v[126:129]
	v_mfma_f32_16x16x32_bf16 v[122:125], v[166:169], v[190:193], v[122:125]
	v_mfma_f32_16x16x32_bf16 v[110:113], v[166:169], v[198:201], v[110:113]
	v_mfma_f32_16x16x32_bf16 v[118:121], v[158:161], v[198:201], v[118:121]
	v_mfma_f32_16x16x32_bf16 v[102:105], v[158:161], v[206:209], v[102:105]
	v_mfma_f32_16x16x32_bf16 v[94:97], v[166:169], v[206:209], v[94:97]
	v_mfma_f32_16x16x32_bf16 v[78:81], v[166:169], v[214:217], v[78:81]
	v_mfma_f32_16x16x32_bf16 v[86:89], v[158:161], v[214:217], v[86:89]
	s_setprio 0
	s_setprio 1
	v_mfma_f32_16x16x32_bf16 v[114:117], v[170:173], v[186:189], v[114:117]
	v_mfma_f32_16x16x32_bf16 v[106:109], v[178:181], v[186:189], v[106:109]
	v_mfma_f32_16x16x32_bf16 v[90:93], v[178:181], v[194:197], v[90:93]
	v_mfma_f32_16x16x32_bf16 v[98:101], v[170:173], v[194:197], v[98:101]
	v_mfma_f32_16x16x32_bf16 v[82:85], v[170:173], v[202:205], v[82:85]
	v_mfma_f32_16x16x32_bf16 v[74:77], v[178:181], v[202:205], v[74:77]
	v_mfma_f32_16x16x32_bf16 v[66:69], v[178:181], v[210:213], v[66:69]
	v_mfma_f32_16x16x32_bf16 v[70:73], v[170:173], v[210:213], v[70:73]
	v_mfma_f32_16x16x32_bf16 v[114:117], v[174:177], v[190:193], v[114:117]
	v_mfma_f32_16x16x32_bf16 v[106:109], v[182:185], v[190:193], v[106:109]
	v_mfma_f32_16x16x32_bf16 v[90:93], v[182:185], v[198:201], v[90:93]
	v_mfma_f32_16x16x32_bf16 v[98:101], v[174:177], v[198:201], v[98:101]
	v_mfma_f32_16x16x32_bf16 v[82:85], v[174:177], v[206:209], v[82:85]
	v_mfma_f32_16x16x32_bf16 v[74:77], v[182:185], v[206:209], v[74:77]
	v_mfma_f32_16x16x32_bf16 v[66:69], v[182:185], v[214:217], v[66:69]
	v_mfma_f32_16x16x32_bf16 v[70:73], v[174:177], v[214:217], v[70:73]
	s_setprio 0
	s_barrier
	s_add_i32 s22, s30, s16
	v_lshl_add_u64 v[146:147], s[38:39], 0, v[134:135]
	s_mov_b32 m0, s22
	ds_read_b128 v[186:189], v153 offset:16384
	ds_read_b128 v[190:193], v153 offset:17408
	ds_read_b128 v[194:197], v153 offset:18432
	ds_read_b128 v[198:201], v153 offset:19456
	ds_read_b128 v[202:205], v153 offset:20480
	ds_read_b128 v[206:209], v153 offset:21504
	ds_read_b128 v[210:213], v153 offset:22528
	ds_read_b128 v[214:217], v153 offset:23552
	global_load_lds_dwordx4 v[146:147], off
	s_add_i32 m0, s22, 0x2000
	s_add_u32 s22, s38, 0x160000
	v_lshl_add_u64 v[218:219], s[38:39], 0, v[130:131]
	s_addc_u32 s23, s39, 0
	s_add_i32 s49, s31, s16
	global_load_lds_dwordx4 v[218:219], off
	v_lshl_add_u64 v[220:221], s[22:23], 0, v[134:135]
	s_mov_b32 m0, s49
	v_lshl_add_u64 v[222:223], s[40:41], 0, v[132:133]
	global_load_lds_dwordx4 v[220:221], off
	v_lshl_add_u64 v[220:221], s[22:23], 0, v[130:131]
	s_add_i32 m0, s49, 0x2000
	s_nop 0
	global_load_lds_dwordx4 v[220:221], off
	v_lshl_add_u64 v[220:221], s[40:41], 0, v[136:137]
	s_mov_b32 m0, s18
	s_nop 0
	global_load_lds_dwordx4 v[220:221], off
	s_mov_b32 m0, s19
	s_nop 0
	global_load_lds_dwordx4 v[222:223], off
	s_waitcnt vmcnt(8)
	s_waitcnt lgkmcnt(0)
	s_barrier
; #define PG8_STAGE(bufoff, gbase, voff) do { _Pragma("unroll") for (int _i = 0; _i < 2; ++_i) \
;         __builtin_amdgcn_global_load_lds((const unsigned*)((const char*)(gbase) + (voff)[_i]), (PG8_LAS unsigned*)(lds + (bufoff) + ldsw + _i * 8192), 16, 0, 0); } while (0)
; #define PG8_LDA(dst, b, h) do { _Pragma("unroll") for (int m = 0; m < 4; ++m) _Pragma("unroll") for (int k = 0; k < 2; ++k) dst[m][k] = *(const PG8_LAS bf16x8*)(lds + PG8_SA(b, h) + aoff + m * 2048 + k * 1024); } while (0)
; #define PG8_LDB(dst, b, h) do { _Pragma("unroll") for (int n = 0; n < 2; ++n) _Pragma("unroll") for (int k = 0; k < 2; ++k) dst[n][k] = *(const PG8_LAS bf16x8*)(lds + PG8_SB(b, h) + boff + n * 2048 + k * 1024); } while (0)
; #define PG8_MMA(ai, bj, At, Bt) do { __builtin_amdgcn_s_setprio(1); _Pragma("unroll") for (int m = 0; m < 4; ++m) _Pragma("unroll") for (int n = 0; n < 2; ++n) _Pragma("unroll") for (int k = 0; k < 2; ++k) \
;         acc[ai][bj][m][n] = __builtin_amdgcn_mfma_f32_16x16x32_bf16(Bt[n][k], At[m][k], acc[ai][bj][m][n], 0, 0, 0); __builtin_amdgcn_s_setprio(0); } while (0)
; #define PG8_WAIT_V(n) asm volatile("s_waitcnt vmcnt(" #n ")" ::: "memory")
; #define PG8_WAIT_L(n) asm volatile("s_waitcnt lgkmcnt(" #n ")" ::: "memory")
; #define PG8_BAR __builtin_amdgcn_s_barrier()
; #define PG8_SCHED __builtin_amdgcn_sched_barrier(0)
; template <class Epi, class Sched, bool ALIGN_EPI = false, bool SP2 = false>
; __device__ __forceinline__ void gemm_phase(PG8_LAS unsigned char* lds, const Gemm g, const Sched& S, const Epi& E) {
;     ...
;             PG8_WAIT_V(8); PG8_WAIT_L(0); PG8_BAR; PG8_MMA(1, 0, At, B0); PG8_MMA(1, 1, At, B1); PG8_BAR; PG8_SCHED;
;             PG8_LDB(B0, 1, 0); PG8_LDB(B1, 1, 1); PG8_SCHED; PG8_LDA(At, 1, 0); PG8_STAGE(PG8_SA(0, 1), a2 + hstep, voffA);
;             PG8_WAIT_V(8); PG8_WAIT_L(0); PG8_BAR; PG8_MMA(0, 0, At, B0); PG8_MMA(0, 1, At, B1); PG8_BAR; PG8_SCHED;
	s_setprio 1
	s_waitcnt lgkmcnt(0)
	v_mfma_f32_16x16x32_bf16 v[62:65], v[154:157], v[186:189], v[62:65]
	v_mfma_f32_16x16x32_bf16 v[58:61], v[162:165], v[186:189], v[58:61]
	v_mfma_f32_16x16x32_bf16 v[46:49], v[162:165], v[194:197], v[46:49]
	v_mfma_f32_16x16x32_bf16 v[54:57], v[154:157], v[194:197], v[54:57]
	v_mfma_f32_16x16x32_bf16 v[38:41], v[154:157], v[202:205], v[38:41]
	v_mfma_f32_16x16x32_bf16 v[30:33], v[162:165], v[202:205], v[30:33]
	v_mfma_f32_16x16x32_bf16 v[14:17], v[162:165], v[210:213], v[14:17]
	v_mfma_f32_16x16x32_bf16 v[22:25], v[154:157], v[210:213], v[22:25]
	v_mfma_f32_16x16x32_bf16 v[62:65], v[158:161], v[190:193], v[62:65]
	v_mfma_f32_16x16x32_bf16 v[58:61], v[166:169], v[190:193], v[58:61]
	v_mfma_f32_16x16x32_bf16 v[46:49], v[166:169], v[198:201], v[46:49]
	v_mfma_f32_16x16x32_bf16 v[54:57], v[158:161], v[198:201], v[54:57]
	v_mfma_f32_16x16x32_bf16 v[38:41], v[158:161], v[206:209], v[38:41]
	v_mfma_f32_16x16x32_bf16 v[30:33], v[166:169], v[206:209], v[30:33]
	v_mfma_f32_16x16x32_bf16 v[14:17], v[166:169], v[214:217], v[14:17]
	v_mfma_f32_16x16x32_bf16 v[22:25], v[158:161], v[214:217], v[22:25]
	s_setprio 0
	s_setprio 1
	v_mfma_f32_16x16x32_bf16 v[50:53], v[170:173], v[186:189], v[50:53]
	v_mfma_f32_16x16x32_bf16 v[42:45], v[178:181], v[186:189], v[42:45]
	v_mfma_f32_16x16x32_bf16 v[26:29], v[178:181], v[194:197], v[26:29]
	v_mfma_f32_16x16x32_bf16 v[34:37], v[170:173], v[194:197], v[34:37]
	v_mfma_f32_16x16x32_bf16 v[18:21], v[170:173], v[202:205], v[18:21]
	v_mfma_f32_16x16x32_bf16 v[10:13], v[178:181], v[202:205], v[10:13]
	v_mfma_f32_16x16x32_bf16 v[2:5], v[178:181], v[210:213], v[2:5]
	v_mfma_f32_16x16x32_bf16 v[6:9], v[170:173], v[210:213], v[6:9]
	v_mfma_f32_16x16x32_bf16 v[50:53], v[174:177], v[190:193], v[50:53]
	v_mfma_f32_16x16x32_bf16 v[42:45], v[182:185], v[190:193], v[42:45]
	v_mfma_f32_16x16x32_bf16 v[26:29], v[182:185], v[198:201], v[26:29]
	v_mfma_f32_16x16x32_bf16 v[34:37], v[174:177], v[198:201], v[34:37]
	v_mfma_f32_16x16x32_bf16 v[18:21], v[174:177], v[206:209], v[18:21]
	v_mfma_f32_16x16x32_bf16 v[10:13], v[182:185], v[206:209], v[10:13]
	v_mfma_f32_16x16x32_bf16 v[2:5], v[182:185], v[214:217], v[2:5]
	v_mfma_f32_16x16x32_bf16 v[6:9], v[174:177], v[214:217], v[6:9]
	s_setprio 0
	s_barrier
	s_add_i32 s49, 0, 0x18000
	s_add_i32 s50, 0, 0x1c000
	v_add_u32_e32 v166, s49, v149
	v_add_u32_e32 v182, s50, v149
	ds_read_b128 v[154:157], v166
	ds_read_b128 v[158:161], v166 offset:1024
	ds_read_b128 v[162:165], v166 offset:2048
	ds_read_b128 v[166:169], v166 offset:3072
	ds_read_b128 v[170:173], v182
	ds_read_b128 v[174:177], v182 offset:1024
	ds_read_b128 v[178:181], v182 offset:2048
	ds_read_b128 v[182:185], v182 offset:3072
	s_add_u32 s22, s40, 0x160000
	s_addc_u32 s23, s41, 0
	s_mov_b32 m0, s24
	v_lshl_add_u64 v[224:225], s[22:23], 0, v[136:137]
	ds_read_b128 v[186:189], v153 offset:32768
	ds_read_b128 v[190:193], v153 offset:33792
	ds_read_b128 v[194:197], v153 offset:34816
	ds_read_b128 v[198:201], v153 offset:35840
	ds_read_b128 v[202:205], v153 offset:36864
	ds_read_b128 v[206:209], v153 offset:37888
	ds_read_b128 v[210:213], v153 offset:38912
	ds_read_b128 v[214:217], v153 offset:39936
	global_load_lds_dwordx4 v[224:225], off
	v_lshl_add_u64 v[224:225], s[22:23], 0, v[132:133]
	s_mov_b32 m0, s25
	s_nop 0
	global_load_lds_dwordx4 v[224:225], off
	s_waitcnt vmcnt(8)
	s_waitcnt lgkmcnt(0)
	s_barrier
	s_setprio 1
	s_waitcnt lgkmcnt(0)
	v_mfma_f32_16x16x32_bf16 v[126:129], v[154:157], v[186:189], v[126:129]
	v_mfma_f32_16x16x32_bf16 v[122:125], v[162:165], v[186:189], v[122:125]
	v_mfma_f32_16x16x32_bf16 v[110:113], v[162:165], v[194:197], v[110:113]
	v_mfma_f32_16x16x32_bf16 v[118:121], v[154:157], v[194:197], v[118:121]
	v_mfma_f32_16x16x32_bf16 v[102:105], v[154:157], v[202:205], v[102:105]
	v_mfma_f32_16x16x32_bf16 v[94:97], v[162:165], v[202:205], v[94:97]
	v_mfma_f32_16x16x32_bf16 v[78:81], v[162:165], v[210:213], v[78:81]
	v_mfma_f32_16x16x32_bf16 v[86:89], v[154:157], v[210:213], v[86:89]
	v_mfma_f32_16x16x32_bf16 v[126:129], v[158:161], v[190:193], v[126:129]
	v_mfma_f32_16x16x32_bf16 v[122:125], v[166:169], v[190:193], v[122:125]
	v_mfma_f32_16x16x32_bf16 v[110:113], v[166:169], v[198:201], v[110:113]
	v_mfma_f32_16x16x32_bf16 v[118:121], v[158:161], v[198:201], v[118:121]
	v_mfma_f32_16x16x32_bf16 v[102:105], v[158:161], v[206:209], v[102:105]
	v_mfma_f32_16x16x32_bf16 v[94:97], v[166:169], v[206:209], v[94:97]
	v_mfma_f32_16x16x32_bf16 v[78:81], v[166:169], v[214:217], v[78:81]
	v_mfma_f32_16x16x32_bf16 v[86:89], v[158:161], v[214:217], v[86:89]
	s_setprio 0
	s_setprio 1
	v_mfma_f32_16x16x32_bf16 v[114:117], v[170:173], v[186:189], v[114:117]
	v_mfma_f32_16x16x32_bf16 v[106:109], v[178:181], v[186:189], v[106:109]
	v_mfma_f32_16x16x32_bf16 v[90:93], v[178:181], v[194:197], v[90:93]
	v_mfma_f32_16x16x32_bf16 v[98:101], v[170:173], v[194:197], v[98:101]
	v_mfma_f32_16x16x32_bf16 v[82:85], v[170:173], v[202:205], v[82:85]
	v_mfma_f32_16x16x32_bf16 v[74:77], v[178:181], v[202:205], v[74:77]
	v_mfma_f32_16x16x32_bf16 v[66:69], v[178:181], v[210:213], v[66:69]
	v_mfma_f32_16x16x32_bf16 v[70:73], v[170:173], v[210:213], v[70:73]
	v_mfma_f32_16x16x32_bf16 v[114:117], v[174:177], v[190:193], v[114:117]
	v_mfma_f32_16x16x32_bf16 v[106:109], v[182:185], v[190:193], v[106:109]
	v_mfma_f32_16x16x32_bf16 v[90:93], v[182:185], v[198:201], v[90:93]
	v_mfma_f32_16x16x32_bf16 v[98:101], v[174:177], v[198:201], v[98:101]
	v_mfma_f32_16x16x32_bf16 v[82:85], v[174:177], v[206:209], v[82:85]
	v_mfma_f32_16x16x32_bf16 v[74:77], v[182:185], v[206:209], v[74:77]
	v_mfma_f32_16x16x32_bf16 v[66:69], v[182:185], v[214:217], v[66:69]
	v_mfma_f32_16x16x32_bf16 v[70:73], v[174:177], v[214:217], v[70:73]
	s_setprio 0
	s_barrier
; #define PG8_STAGE(bufoff, gbase, voff) do { _Pragma("unroll") for (int _i = 0; _i < 2; ++_i) \
;         __builtin_amdgcn_global_load_lds((const unsigned*)((const char*)(gbase) + (voff)[_i]), (PG8_LAS unsigned*)(lds + (bufoff) + ldsw + _i * 8192), 16, 0, 0); } while (0)
; #define PG8_LDA(dst, b, h) do { _Pragma("unroll") for (int m = 0; m < 4; ++m) _Pragma("unroll") for (int k = 0; k < 2; ++k) dst[m][k] = *(const PG8_LAS bf16x8*)(lds + PG8_SA(b, h) + aoff + m * 2048 + k * 1024); } while (0)
; #define PG8_MMA(ai, bj, At, Bt) do { __builtin_amdgcn_s_setprio(1); _Pragma("unroll") for (int m = 0; m < 4; ++m) _Pragma("unroll") for (int n = 0; n < 2; ++n) _Pragma("unroll") for (int k = 0; k < 2; ++k) \
;         acc[ai][bj][m][n] = __builtin_amdgcn_mfma_f32_16x16x32_bf16(Bt[n][k], At[m][k], acc[ai][bj][m][n], 0, 0, 0); __builtin_amdgcn_s_setprio(0); } while (0)
; #define PG8_WAIT_V(n) asm volatile("s_waitcnt vmcnt(" #n ")" ::: "memory")
; #define PG8_WAIT_L(n) asm volatile("s_waitcnt lgkmcnt(" #n ")" ::: "memory")
; #define PG8_BAR __builtin_amdgcn_s_barrier()
; #define PG8_SCHED __builtin_amdgcn_sched_barrier(0)
; template <class Epi, class Sched, bool ALIGN_EPI = false, bool SP2 = false>
; __device__ __forceinline__ void gemm_phase(PG8_LAS unsigned char* lds, const Gemm g, const Sched& S, const Epi& E) {
;     ...
;         for (int t = 0; t < nt; t += 2) {
;             if constexpr (Epi::MIDHOOK) { if (t == (nt >> 1)) E.mid(acc, cur, wr, wc, fr, fq); }
;             const bool last = (t == nt - 2);
;             const char* a1 = cA + (size_t)(t + 1) * kstep;
;             const char* a2 = last ? nA : cA + (size_t)(t + 2) * kstep; const char* b2 = last ? nB : cB + (size_t)(t + 2) * kstep;
;             const char* a3 = a2 + kstep; const char* b3 = b2 + kstep;
;             if (last && has_next) S.a_ready(nxt);
;     ...
;             PG8_LDA(At, 1, 1); PG8_STAGE(PG8_SB(1, 0), b3, voffB); PG8_STAGE(PG8_SB(1, 1), b3 + hstep, voffB); PG8_STAGE(PG8_SA(1, 0), a3, voffA);
;             PG8_WAIT_V(8); PG8_WAIT_L(0); PG8_BAR; PG8_MMA(1, 0, At, B0); PG8_MMA(1, 1, At, B1); PG8_BAR; PG8_SCHED;
	s_add_i32 s22, s49, s16
	v_lshl_add_u64 v[146:147], v[146:147], 0, s[12:13]
	s_mov_b32 m0, s22
	ds_read_b128 v[186:189], v153 offset:49152
	ds_read_b128 v[190:193], v153 offset:50176
	ds_read_b128 v[194:197], v153 offset:51200
	ds_read_b128 v[198:201], v153 offset:52224
	ds_read_b128 v[202:205], v153 offset:53248
	ds_read_b128 v[206:209], v153 offset:54272
	ds_read_b128 v[210:213], v153 offset:55296
	ds_read_b128 v[214:217], v153 offset:56320
	global_load_lds_dwordx4 v[146:147], off
	s_add_i32 m0, s22, 0x2000
	s_add_u32 s22, s38, 0x160080
	v_lshl_add_u64 v[146:147], v[218:219], 0, s[12:13]
	s_addc_u32 s23, s39, 0
	s_add_i32 s38, s50, s16
	global_load_lds_dwordx4 v[146:147], off
	v_lshl_add_u64 v[146:147], s[22:23], 0, v[134:135]
	s_mov_b32 m0, s38
	s_nop 0
	global_load_lds_dwordx4 v[146:147], off
	v_lshl_add_u64 v[146:147], s[22:23], 0, v[130:131]
	s_add_i32 m0, s38, 0x2000
	s_nop 0
	global_load_lds_dwordx4 v[146:147], off
	v_lshl_add_u64 v[146:147], v[220:221], 0, s[12:13]
	s_mov_b32 m0, s28
	s_nop 0
	global_load_lds_dwordx4 v[146:147], off
	v_lshl_add_u64 v[146:147], v[222:223], 0, s[12:13]
	s_mov_b32 m0, s29
	s_nop 0
	global_load_lds_dwordx4 v[146:147], off
	s_waitcnt vmcnt(8)
	s_waitcnt lgkmcnt(0)
	s_barrier
	s_setprio 1
	s_waitcnt lgkmcnt(0)
	v_mfma_f32_16x16x32_bf16 v[62:65], v[154:157], v[186:189], v[62:65]
	v_mfma_f32_16x16x32_bf16 v[58:61], v[162:165], v[186:189], v[58:61]
	v_mfma_f32_16x16x32_bf16 v[46:49], v[162:165], v[194:197], v[46:49]
	v_mfma_f32_16x16x32_bf16 v[54:57], v[154:157], v[194:197], v[54:57]
	v_mfma_f32_16x16x32_bf16 v[38:41], v[154:157], v[202:205], v[38:41]
	v_mfma_f32_16x16x32_bf16 v[30:33], v[162:165], v[202:205], v[30:33]
	v_mfma_f32_16x16x32_bf16 v[14:17], v[162:165], v[210:213], v[14:17]
	v_mfma_f32_16x16x32_bf16 v[22:25], v[154:157], v[210:213], v[22:25]
	v_mfma_f32_16x16x32_bf16 v[62:65], v[158:161], v[190:193], v[62:65]
	v_mfma_f32_16x16x32_bf16 v[58:61], v[166:169], v[190:193], v[58:61]
	v_mfma_f32_16x16x32_bf16 v[46:49], v[166:169], v[198:201], v[46:49]
	v_mfma_f32_16x16x32_bf16 v[54:57], v[158:161], v[198:201], v[54:57]
	v_mfma_f32_16x16x32_bf16 v[38:41], v[158:161], v[206:209], v[38:41]
	v_mfma_f32_16x16x32_bf16 v[30:33], v[166:169], v[206:209], v[30:33]
	v_mfma_f32_16x16x32_bf16 v[14:17], v[166:169], v[214:217], v[14:17]
	v_mfma_f32_16x16x32_bf16 v[22:25], v[158:161], v[214:217], v[22:25]
	s_setprio 0
	s_setprio 1
	v_mfma_f32_16x16x32_bf16 v[50:53], v[170:173], v[186:189], v[50:53]
	v_mfma_f32_16x16x32_bf16 v[42:45], v[178:181], v[186:189], v[42:45]
	v_mfma_f32_16x16x32_bf16 v[26:29], v[178:181], v[194:197], v[26:29]
	v_mfma_f32_16x16x32_bf16 v[34:37], v[170:173], v[194:197], v[34:37]
	v_mfma_f32_16x16x32_bf16 v[18:21], v[170:173], v[202:205], v[18:21]
	v_mfma_f32_16x16x32_bf16 v[10:13], v[178:181], v[202:205], v[10:13]
	v_mfma_f32_16x16x32_bf16 v[2:5], v[178:181], v[210:213], v[2:5]
	v_mfma_f32_16x16x32_bf16 v[6:9], v[170:173], v[210:213], v[6:9]
	v_mfma_f32_16x16x32_bf16 v[50:53], v[174:177], v[190:193], v[50:53]
	v_mfma_f32_16x16x32_bf16 v[42:45], v[182:185], v[190:193], v[42:45]
	v_mfma_f32_16x16x32_bf16 v[26:29], v[182:185], v[198:201], v[26:29]
	v_mfma_f32_16x16x32_bf16 v[34:37], v[174:177], v[198:201], v[34:37]
	v_mfma_f32_16x16x32_bf16 v[18:21], v[174:177], v[206:209], v[18:21]
	v_mfma_f32_16x16x32_bf16 v[10:13], v[182:185], v[206:209], v[10:13]
	v_mfma_f32_16x16x32_bf16 v[2:5], v[182:185], v[214:217], v[2:5]
	v_mfma_f32_16x16x32_bf16 v[6:9], v[174:177], v[214:217], v[6:9]
	s_setprio 0
	s_barrier
	s_add_i32 s48, s48, 2
	s_add_u32 s46, s46, 0x100
	s_addc_u32 s47, s47, 0
	s_cmpk_gt_u32 s48, 0x55
	s_mov_b64 s[22:23], s[36:37]
	s_cbranch_scc0 .LBB0_173
	s_and_b64 vcc, exec, s[14:15]
	s_cbranch_vccz .LBB0_176
	s_barrier

; #define PG8_STAGE(bufoff, gbase, voff) do { _Pragma("unroll") for (int _i = 0; _i < 2; ++_i) \
;         __builtin_amdgcn_global_load_lds((const unsigned*)((const char*)(gbase) + (voff)[_i]), (PG8_LAS unsigned*)(lds + (bufoff) + ldsw + _i * 8192), 16, 0, 0); } while (0)
; #define PG8_LDA(dst, b, h) do { _Pragma("unroll") for (int m = 0; m < 4; ++m) _Pragma("unroll") for (int k = 0; k < 2; ++k) dst[m][k] = *(const PG8_LAS bf16x8*)(lds + PG8_SA(b, h) + aoff + m * 2048 + k * 1024); } while (0)
; #define PG8_LDB(dst, b, h) do { _Pragma("unroll") for (int n = 0; n < 2; ++n) _Pragma("unroll") for (int k = 0; k < 2; ++k) dst[n][k] = *(const PG8_LAS bf16x8*)(lds + PG8_SB(b, h) + boff + n * 2048 + k * 1024); } while (0)
; #define PG8_MMA(ai, bj, At, Bt) do { __builtin_amdgcn_s_setprio(1); _Pragma("unroll") for (int m = 0; m < 4; ++m) _Pragma("unroll") for (int n = 0; n < 2; ++n) _Pragma("unroll") for (int k = 0; k < 2; ++k) \
;         acc[ai][bj][m][n] = __builtin_amdgcn_mfma_f32_16x16x32_bf16(Bt[n][k], At[m][k], acc[ai][bj][m][n], 0, 0, 0); __builtin_amdgcn_s_setprio(0); } while (0)
; #define PG8_WAIT_V(n) asm volatile("s_waitcnt vmcnt(" #n ")" ::: "memory")
; #define PG8_WAIT_L(n) asm volatile("s_waitcnt lgkmcnt(" #n ")" ::: "memory")
; #define PG8_BAR __builtin_amdgcn_s_barrier()
; #define PG8_SCHED __builtin_amdgcn_sched_barrier(0)
; template <class Epi, class Sched, bool ALIGN_EPI = false, bool SP2 = false>
; __device__ __forceinline__ void gemm_phase(PG8_LAS unsigned char* lds, const Gemm g, const Sched& S, const Epi& E) {
;     ...
;             PG8_LDB(B0, 0, 0); PG8_LDB(B1, 0, 1); PG8_SCHED; PG8_LDA(At, 0, 0); PG8_STAGE(PG8_SA(1, 1), a1 + hstep, voffA);
;             PG8_WAIT_V(8); PG8_WAIT_L(0); PG8_BAR; PG8_MMA(0, 0, At, B0); PG8_MMA(0, 1, At, B1); PG8_BAR; PG8_SCHED;
;             PG8_LDA(At, 0, 1); PG8_STAGE(PG8_SB(0, 0), b2, voffB); PG8_STAGE(PG8_SB(0, 1), b2 + hstep, voffB); PG8_STAGE(PG8_SA(0, 0), a2, voffA);
;             PG8_WAIT_V(8); PG8_WAIT_L(0); PG8_BAR; PG8_MMA(1, 0, At, B0); PG8_MMA(1, 1, At, B1); PG8_BAR; PG8_SCHED;
.LBB0_193:
	ds_read_b128 v[144:147], v141
	ds_read_b128 v[148:151], v141 offset:1024
	ds_read_b128 v[152:155], v141 offset:2048
	ds_read_b128 v[156:159], v141 offset:3072
	ds_read_b128 v[160:163], v142
	ds_read_b128 v[164:167], v142 offset:1024
	ds_read_b128 v[168:171], v142 offset:2048
	ds_read_b128 v[172:175], v142 offset:3072
	s_add_u32 s40, s38, 0x100
	s_addc_u32 s41, s39, 0
	s_cmp_eq_u32 s53, 18
	s_cselect_b32 s45, s23, s41
	s_cselect_b32 s44, s22, s40
	s_cselect_b32 s43, s37, s52
	s_cselect_b32 s42, s36, s11
	v_lshl_add_u64 v[208:209], s[38:39], 0, v[134:135]
	s_add_i32 m0, s19, 0xc000
	ds_read_b128 v[176:179], v143
	ds_read_b128 v[180:183], v143 offset:1024
	ds_read_b128 v[184:187], v143 offset:2048
	ds_read_b128 v[188:191], v143 offset:3072
	ds_read_b128 v[192:195], v143 offset:4096
	ds_read_b128 v[196:199], v143 offset:5120
	ds_read_b128 v[200:203], v143 offset:6144
	ds_read_b128 v[204:207], v143 offset:7168
	global_load_lds_dwordx4 v[208:209], off
	v_lshl_add_u64 v[208:209], s[38:39], 0, v[136:137]
	s_add_i32 m0, s19, 0xe000
	s_nop 0
	global_load_lds_dwordx4 v[208:209], off
	s_waitcnt vmcnt(8)
	s_waitcnt lgkmcnt(0)
	s_barrier
	s_setprio 1
	s_waitcnt lgkmcnt(0)
	v_mfma_f32_16x16x32_bf16 v[126:129], v[144:147], v[176:179], v[126:129]
	v_mfma_f32_16x16x32_bf16 v[122:125], v[152:155], v[176:179], v[122:125]
	v_mfma_f32_16x16x32_bf16 v[114:117], v[152:155], v[184:187], v[114:117]
	v_mfma_f32_16x16x32_bf16 v[118:121], v[144:147], v[184:187], v[118:121]
	v_mfma_f32_16x16x32_bf16 v[106:109], v[144:147], v[192:195], v[106:109]
	v_mfma_f32_16x16x32_bf16 v[98:101], v[152:155], v[192:195], v[98:101]
	v_mfma_f32_16x16x32_bf16 v[82:85], v[152:155], v[200:203], v[82:85]
	v_mfma_f32_16x16x32_bf16 v[90:93], v[144:147], v[200:203], v[90:93]
	v_mfma_f32_16x16x32_bf16 v[126:129], v[148:151], v[180:183], v[126:129]
	v_mfma_f32_16x16x32_bf16 v[122:125], v[156:159], v[180:183], v[122:125]
	v_mfma_f32_16x16x32_bf16 v[114:117], v[156:159], v[188:191], v[114:117]
	v_mfma_f32_16x16x32_bf16 v[118:121], v[148:151], v[188:191], v[118:121]
	v_mfma_f32_16x16x32_bf16 v[106:109], v[148:151], v[196:199], v[106:109]
	v_mfma_f32_16x16x32_bf16 v[98:101], v[156:159], v[196:199], v[98:101]
	v_mfma_f32_16x16x32_bf16 v[82:85], v[156:159], v[204:207], v[82:85]
	v_mfma_f32_16x16x32_bf16 v[90:93], v[148:151], v[204:207], v[90:93]
	s_setprio 0
	s_setprio 1
	v_mfma_f32_16x16x32_bf16 v[110:113], v[160:163], v[176:179], v[110:113]
	v_mfma_f32_16x16x32_bf16 v[102:105], v[168:171], v[176:179], v[102:105]
	v_mfma_f32_16x16x32_bf16 v[86:89], v[168:171], v[184:187], v[86:89]
	v_mfma_f32_16x16x32_bf16 v[94:97], v[160:163], v[184:187], v[94:97]
	v_mfma_f32_16x16x32_bf16 v[78:81], v[160:163], v[192:195], v[78:81]
	v_mfma_f32_16x16x32_bf16 v[74:77], v[168:171], v[192:195], v[74:77]
	v_mfma_f32_16x16x32_bf16 v[66:69], v[168:171], v[200:203], v[66:69]
	v_mfma_f32_16x16x32_bf16 v[70:73], v[160:163], v[200:203], v[70:73]
	v_mfma_f32_16x16x32_bf16 v[110:113], v[164:167], v[180:183], v[110:113]
	v_mfma_f32_16x16x32_bf16 v[102:105], v[172:175], v[180:183], v[102:105]
	v_mfma_f32_16x16x32_bf16 v[86:89], v[172:175], v[188:191], v[86:89]
	v_mfma_f32_16x16x32_bf16 v[94:97], v[164:167], v[188:191], v[94:97]
	v_mfma_f32_16x16x32_bf16 v[78:81], v[164:167], v[196:199], v[78:81]
	v_mfma_f32_16x16x32_bf16 v[74:77], v[172:175], v[196:199], v[74:77]
	v_mfma_f32_16x16x32_bf16 v[66:69], v[172:175], v[204:207], v[66:69]
	v_mfma_f32_16x16x32_bf16 v[70:73], v[164:167], v[204:207], v[70:73]
	s_setprio 0
	s_barrier
	s_add_i32 s38, s46, s16
	v_lshl_add_u64 v[208:209], s[42:43], 0, v[132:133]
	s_mov_b32 m0, s38
	ds_read_b128 v[176:179], v143 offset:16384
	ds_read_b128 v[180:183], v143 offset:17408
	ds_read_b128 v[184:187], v143 offset:18432
	ds_read_b128 v[188:191], v143 offset:19456
	ds_read_b128 v[192:195], v143 offset:20480
	ds_read_b128 v[196:199], v143 offset:21504
	ds_read_b128 v[200:203], v143 offset:22528
	ds_read_b128 v[204:207], v143 offset:23552
	global_load_lds_dwordx4 v[208:209], off
	s_add_i32 m0, s38, 0x2000
	s_add_u32 s38, s42, 0x160000
	v_lshl_add_u64 v[210:211], s[42:43], 0, v[130:131]
	s_addc_u32 s39, s43, 0
	s_add_i32 s54, s47, s16
	global_load_lds_dwordx4 v[210:211], off
	v_lshl_add_u64 v[212:213], s[38:39], 0, v[132:133]
	s_mov_b32 m0, s54
	v_lshl_add_u64 v[214:215], s[44:45], 0, v[130:131]
	global_load_lds_dwordx4 v[212:213], off
	v_lshl_add_u64 v[212:213], s[38:39], 0, v[130:131]
	s_add_i32 m0, s54, 0x2000
	s_nop 0
	global_load_lds_dwordx4 v[212:213], off
	v_lshl_add_u64 v[212:213], s[44:45], 0, v[132:133]
	s_mov_b32 m0, s19
	s_nop 0
	global_load_lds_dwordx4 v[212:213], off
	s_mov_b32 m0, s24
	s_nop 0
	global_load_lds_dwordx4 v[214:215], off
	s_waitcnt vmcnt(8)
	s_waitcnt lgkmcnt(0)
	s_barrier
; #define PG8_STAGE(bufoff, gbase, voff) do { _Pragma("unroll") for (int _i = 0; _i < 2; ++_i) \
;         __builtin_amdgcn_global_load_lds((const unsigned*)((const char*)(gbase) + (voff)[_i]), (PG8_LAS unsigned*)(lds + (bufoff) + ldsw + _i * 8192), 16, 0, 0); } while (0)
; #define PG8_LDA(dst, b, h) do { _Pragma("unroll") for (int m = 0; m < 4; ++m) _Pragma("unroll") for (int k = 0; k < 2; ++k) dst[m][k] = *(const PG8_LAS bf16x8*)(lds + PG8_SA(b, h) + aoff + m * 2048 + k * 1024); } while (0)
; #define PG8_LDB(dst, b, h) do { _Pragma("unroll") for (int n = 0; n < 2; ++n) _Pragma("unroll") for (int k = 0; k < 2; ++k) dst[n][k] = *(const PG8_LAS bf16x8*)(lds + PG8_SB(b, h) + boff + n * 2048 + k * 1024); } while (0)
; #define PG8_MMA(ai, bj, At, Bt) do { __builtin_amdgcn_s_setprio(1); _Pragma("unroll") for (int m = 0; m < 4; ++m) _Pragma("unroll") for (int n = 0; n < 2; ++n) _Pragma("unroll") for (int k = 0; k < 2; ++k) \
;         acc[ai][bj][m][n] = __builtin_amdgcn_mfma_f32_16x16x32_bf16(Bt[n][k], At[m][k], acc[ai][bj][m][n], 0, 0, 0); __builtin_amdgcn_s_setprio(0); } while (0)
; #define PG8_WAIT_V(n) asm volatile("s_waitcnt vmcnt(" #n ")" ::: "memory")
; #define PG8_WAIT_L(n) asm volatile("s_waitcnt lgkmcnt(" #n ")" ::: "memory")
; #define PG8_BAR __builtin_amdgcn_s_barrier()
; #define PG8_SCHED __builtin_amdgcn_sched_barrier(0)
; template <class Epi, class Sched, bool ALIGN_EPI = false, bool SP2 = false>
; __device__ __forceinline__ void gemm_phase(PG8_LAS unsigned char* lds, const Gemm g, const Sched& S, const Epi& E) {
;     ...
;             PG8_WAIT_V(8); PG8_WAIT_L(0); PG8_BAR; PG8_MMA(1, 0, At, B0); PG8_MMA(1, 1, At, B1); PG8_BAR; PG8_SCHED;
;             PG8_LDB(B0, 1, 0); PG8_LDB(B1, 1, 1); PG8_SCHED; PG8_LDA(At, 1, 0); PG8_STAGE(PG8_SA(0, 1), a2 + hstep, voffA);
;             PG8_WAIT_V(8); PG8_WAIT_L(0); PG8_BAR; PG8_MMA(0, 0, At, B0); PG8_MMA(0, 1, At, B1); PG8_BAR; PG8_SCHED;
	s_setprio 1
	s_waitcnt lgkmcnt(0)
	v_mfma_f32_16x16x32_bf16 v[62:65], v[144:147], v[176:179], v[62:65]
	v_mfma_f32_16x16x32_bf16 v[58:61], v[152:155], v[176:179], v[58:61]
	v_mfma_f32_16x16x32_bf16 v[50:53], v[152:155], v[184:187], v[50:53]
	v_mfma_f32_16x16x32_bf16 v[54:57], v[144:147], v[184:187], v[54:57]
	v_mfma_f32_16x16x32_bf16 v[38:41], v[144:147], v[192:195], v[38:41]
	v_mfma_f32_16x16x32_bf16 v[34:37], v[152:155], v[192:195], v[34:37]
	v_mfma_f32_16x16x32_bf16 v[18:21], v[152:155], v[200:203], v[18:21]
	v_mfma_f32_16x16x32_bf16 v[22:25], v[144:147], v[200:203], v[22:25]
	v_mfma_f32_16x16x32_bf16 v[62:65], v[148:151], v[180:183], v[62:65]
	v_mfma_f32_16x16x32_bf16 v[58:61], v[156:159], v[180:183], v[58:61]
	v_mfma_f32_16x16x32_bf16 v[50:53], v[156:159], v[188:191], v[50:53]
	v_mfma_f32_16x16x32_bf16 v[54:57], v[148:151], v[188:191], v[54:57]
	v_mfma_f32_16x16x32_bf16 v[38:41], v[148:151], v[196:199], v[38:41]
	v_mfma_f32_16x16x32_bf16 v[34:37], v[156:159], v[196:199], v[34:37]
	v_mfma_f32_16x16x32_bf16 v[18:21], v[156:159], v[204:207], v[18:21]
	v_mfma_f32_16x16x32_bf16 v[22:25], v[148:151], v[204:207], v[22:25]
	s_setprio 0
	s_setprio 1
	v_mfma_f32_16x16x32_bf16 v[46:49], v[160:163], v[176:179], v[46:49]
	v_mfma_f32_16x16x32_bf16 v[42:45], v[168:171], v[176:179], v[42:45]
	v_mfma_f32_16x16x32_bf16 v[26:29], v[168:171], v[184:187], v[26:29]
	v_mfma_f32_16x16x32_bf16 v[30:33], v[160:163], v[184:187], v[30:33]
	v_mfma_f32_16x16x32_bf16 v[14:17], v[160:163], v[192:195], v[14:17]
	v_mfma_f32_16x16x32_bf16 v[10:13], v[168:171], v[192:195], v[10:13]
	v_mfma_f32_16x16x32_bf16 v[2:5], v[168:171], v[200:203], v[2:5]
	v_mfma_f32_16x16x32_bf16 v[6:9], v[160:163], v[200:203], v[6:9]
	v_mfma_f32_16x16x32_bf16 v[46:49], v[164:167], v[180:183], v[46:49]
	v_mfma_f32_16x16x32_bf16 v[42:45], v[172:175], v[180:183], v[42:45]
	v_mfma_f32_16x16x32_bf16 v[26:29], v[172:175], v[188:191], v[26:29]
	v_mfma_f32_16x16x32_bf16 v[30:33], v[164:167], v[188:191], v[30:33]
	v_mfma_f32_16x16x32_bf16 v[14:17], v[164:167], v[196:199], v[14:17]
	v_mfma_f32_16x16x32_bf16 v[10:13], v[172:175], v[196:199], v[10:13]
	v_mfma_f32_16x16x32_bf16 v[2:5], v[172:175], v[204:207], v[2:5]
	v_mfma_f32_16x16x32_bf16 v[6:9], v[164:167], v[204:207], v[6:9]
	s_setprio 0
	s_barrier
	s_add_i32 s54, 0, 0x18000
	s_add_i32 s55, 0, 0x1c000
	v_add_u32_e32 v156, s54, v138
	v_add_u32_e32 v172, s55, v138
	ds_read_b128 v[144:147], v156
	ds_read_b128 v[148:151], v156 offset:1024
	ds_read_b128 v[152:155], v156 offset:2048
	ds_read_b128 v[156:159], v156 offset:3072
	ds_read_b128 v[160:163], v172
	ds_read_b128 v[164:167], v172 offset:1024
	ds_read_b128 v[168:171], v172 offset:2048
	ds_read_b128 v[172:175], v172 offset:3072
	s_add_u32 s38, s44, 0x160000
	s_addc_u32 s39, s45, 0
	s_mov_b32 m0, s25
	v_lshl_add_u64 v[216:217], s[38:39], 0, v[132:133]
	ds_read_b128 v[176:179], v143 offset:32768
	ds_read_b128 v[180:183], v143 offset:33792
	ds_read_b128 v[184:187], v143 offset:34816
	ds_read_b128 v[188:191], v143 offset:35840
	ds_read_b128 v[192:195], v143 offset:36864
	ds_read_b128 v[196:199], v143 offset:37888
	ds_read_b128 v[200:203], v143 offset:38912
	ds_read_b128 v[204:207], v143 offset:39936
	global_load_lds_dwordx4 v[216:217], off
	v_lshl_add_u64 v[216:217], s[38:39], 0, v[130:131]
	s_mov_b32 m0, s26
	s_nop 0
	global_load_lds_dwordx4 v[216:217], off
	s_waitcnt vmcnt(8)
	s_waitcnt lgkmcnt(0)
	s_barrier
	s_setprio 1
	s_waitcnt lgkmcnt(0)
	v_mfma_f32_16x16x32_bf16 v[126:129], v[144:147], v[176:179], v[126:129]
	v_mfma_f32_16x16x32_bf16 v[122:125], v[152:155], v[176:179], v[122:125]
	v_mfma_f32_16x16x32_bf16 v[114:117], v[152:155], v[184:187], v[114:117]
	v_mfma_f32_16x16x32_bf16 v[118:121], v[144:147], v[184:187], v[118:121]
	v_mfma_f32_16x16x32_bf16 v[106:109], v[144:147], v[192:195], v[106:109]
	v_mfma_f32_16x16x32_bf16 v[98:101], v[152:155], v[192:195], v[98:101]
	v_mfma_f32_16x16x32_bf16 v[82:85], v[152:155], v[200:203], v[82:85]
	v_mfma_f32_16x16x32_bf16 v[90:93], v[144:147], v[200:203], v[90:93]
	v_mfma_f32_16x16x32_bf16 v[126:129], v[148:151], v[180:183], v[126:129]
	v_mfma_f32_16x16x32_bf16 v[122:125], v[156:159], v[180:183], v[122:125]
	v_mfma_f32_16x16x32_bf16 v[114:117], v[156:159], v[188:191], v[114:117]
	v_mfma_f32_16x16x32_bf16 v[118:121], v[148:151], v[188:191], v[118:121]
	v_mfma_f32_16x16x32_bf16 v[106:109], v[148:151], v[196:199], v[106:109]
	v_mfma_f32_16x16x32_bf16 v[98:101], v[156:159], v[196:199], v[98:101]
	v_mfma_f32_16x16x32_bf16 v[82:85], v[156:159], v[204:207], v[82:85]
	v_mfma_f32_16x16x32_bf16 v[90:93], v[148:151], v[204:207], v[90:93]
	s_setprio 0
	s_setprio 1
	v_mfma_f32_16x16x32_bf16 v[110:113], v[160:163], v[176:179], v[110:113]
	v_mfma_f32_16x16x32_bf16 v[102:105], v[168:171], v[176:179], v[102:105]
	v_mfma_f32_16x16x32_bf16 v[86:89], v[168:171], v[184:187], v[86:89]
	v_mfma_f32_16x16x32_bf16 v[94:97], v[160:163], v[184:187], v[94:97]
	v_mfma_f32_16x16x32_bf16 v[78:81], v[160:163], v[192:195], v[78:81]
	v_mfma_f32_16x16x32_bf16 v[74:77], v[168:171], v[192:195], v[74:77]
	v_mfma_f32_16x16x32_bf16 v[66:69], v[168:171], v[200:203], v[66:69]
	v_mfma_f32_16x16x32_bf16 v[70:73], v[160:163], v[200:203], v[70:73]
	v_mfma_f32_16x16x32_bf16 v[110:113], v[164:167], v[180:183], v[110:113]
	v_mfma_f32_16x16x32_bf16 v[102:105], v[172:175], v[180:183], v[102:105]
	v_mfma_f32_16x16x32_bf16 v[86:89], v[172:175], v[188:191], v[86:89]
	v_mfma_f32_16x16x32_bf16 v[94:97], v[164:167], v[188:191], v[94:97]
	v_mfma_f32_16x16x32_bf16 v[78:81], v[164:167], v[196:199], v[78:81]
	v_mfma_f32_16x16x32_bf16 v[74:77], v[172:175], v[196:199], v[74:77]
	v_mfma_f32_16x16x32_bf16 v[66:69], v[172:175], v[204:207], v[66:69]
	v_mfma_f32_16x16x32_bf16 v[70:73], v[164:167], v[204:207], v[70:73]
	s_setprio 0
	s_barrier
; #define PG8_STAGE(bufoff, gbase, voff) do { _Pragma("unroll") for (int _i = 0; _i < 2; ++_i) \
;         __builtin_amdgcn_global_load_lds((const unsigned*)((const char*)(gbase) + (voff)[_i]), (PG8_LAS unsigned*)(lds + (bufoff) + ldsw + _i * 8192), 16, 0, 0); } while (0)
; #define PG8_LDA(dst, b, h) do { _Pragma("unroll") for (int m = 0; m < 4; ++m) _Pragma("unroll") for (int k = 0; k < 2; ++k) dst[m][k] = *(const PG8_LAS bf16x8*)(lds + PG8_SA(b, h) + aoff + m * 2048 + k * 1024); } while (0)
; #define PG8_MMA(ai, bj, At, Bt) do { __builtin_amdgcn_s_setprio(1); _Pragma("unroll") for (int m = 0; m < 4; ++m) _Pragma("unroll") for (int n = 0; n < 2; ++n) _Pragma("unroll") for (int k = 0; k < 2; ++k) \
;         acc[ai][bj][m][n] = __builtin_amdgcn_mfma_f32_16x16x32_bf16(Bt[n][k], At[m][k], acc[ai][bj][m][n], 0, 0, 0); __builtin_amdgcn_s_setprio(0); } while (0)
; #define PG8_WAIT_V(n) asm volatile("s_waitcnt vmcnt(" #n ")" ::: "memory")
; #define PG8_WAIT_L(n) asm volatile("s_waitcnt lgkmcnt(" #n ")" ::: "memory")
; #define PG8_BAR __builtin_amdgcn_s_barrier()
; #define PG8_SCHED __builtin_amdgcn_sched_barrier(0)
; template <class Epi, class Sched, bool ALIGN_EPI = false, bool SP2 = false>
; __device__ __forceinline__ void gemm_phase(PG8_LAS unsigned char* lds, const Gemm g, const Sched& S, const Epi& E) {
;     ...
;         for (int t = 0; t < nt; t += 2) {
;             if constexpr (Epi::MIDHOOK) { if (t == (nt >> 1)) E.mid(acc, cur, wr, wc, fr, fq); }
;             const bool last = (t == nt - 2);
;             const char* a1 = cA + (size_t)(t + 1) * kstep;
;             const char* a2 = last ? nA : cA + (size_t)(t + 2) * kstep; const char* b2 = last ? nB : cB + (size_t)(t + 2) * kstep;
;             const char* a3 = a2 + kstep; const char* b3 = b2 + kstep;
;             if (last && has_next) S.a_ready(nxt);
;     ...
;             PG8_LDA(At, 1, 1); PG8_STAGE(PG8_SB(1, 0), b3, voffB); PG8_STAGE(PG8_SB(1, 1), b3 + hstep, voffB); PG8_STAGE(PG8_SA(1, 0), a3, voffA);
;             PG8_WAIT_V(8); PG8_WAIT_L(0); PG8_BAR; PG8_MMA(1, 0, At, B0); PG8_MMA(1, 1, At, B1); PG8_BAR; PG8_SCHED;
	s_add_i32 s38, s54, s16
	v_lshl_add_u64 v[208:209], v[208:209], 0, s[14:15]
	s_mov_b32 m0, s38
	ds_read_b128 v[176:179], v143 offset:49152
	ds_read_b128 v[180:183], v143 offset:50176
	ds_read_b128 v[184:187], v143 offset:51200
	ds_read_b128 v[188:191], v143 offset:52224
	ds_read_b128 v[192:195], v143 offset:53248
	ds_read_b128 v[196:199], v143 offset:54272
	ds_read_b128 v[200:203], v143 offset:55296
	ds_read_b128 v[204:207], v143 offset:56320
	global_load_lds_dwordx4 v[208:209], off
	s_add_i32 m0, s38, 0x2000
	s_add_u32 s38, s42, 0x160080
	v_lshl_add_u64 v[208:209], v[210:211], 0, s[14:15]
	s_addc_u32 s39, s43, 0
	s_add_i32 s42, s55, s16
	global_load_lds_dwordx4 v[208:209], off
	v_lshl_add_u64 v[208:209], s[38:39], 0, v[132:133]
	s_mov_b32 m0, s42
	s_nop 0
	global_load_lds_dwordx4 v[208:209], off
	v_lshl_add_u64 v[208:209], s[38:39], 0, v[130:131]
	s_add_i32 m0, s42, 0x2000
	s_nop 0
	global_load_lds_dwordx4 v[208:209], off
	v_lshl_add_u64 v[208:209], v[212:213], 0, s[14:15]
	s_mov_b32 m0, s29
	s_nop 0
	global_load_lds_dwordx4 v[208:209], off
	v_lshl_add_u64 v[208:209], v[214:215], 0, s[14:15]
	s_mov_b32 m0, s30
	s_nop 0
	global_load_lds_dwordx4 v[208:209], off
	s_waitcnt vmcnt(8)
	s_waitcnt lgkmcnt(0)
	s_barrier
	s_setprio 1
	s_waitcnt lgkmcnt(0)
	v_mfma_f32_16x16x32_bf16 v[62:65], v[144:147], v[176:179], v[62:65]
	v_mfma_f32_16x16x32_bf16 v[58:61], v[152:155], v[176:179], v[58:61]
	v_mfma_f32_16x16x32_bf16 v[50:53], v[152:155], v[184:187], v[50:53]
	v_mfma_f32_16x16x32_bf16 v[54:57], v[144:147], v[184:187], v[54:57]
	v_mfma_f32_16x16x32_bf16 v[38:41], v[144:147], v[192:195], v[38:41]
	v_mfma_f32_16x16x32_bf16 v[34:37], v[152:155], v[192:195], v[34:37]
	v_mfma_f32_16x16x32_bf16 v[18:21], v[152:155], v[200:203], v[18:21]
	v_mfma_f32_16x16x32_bf16 v[22:25], v[144:147], v[200:203], v[22:25]
	v_mfma_f32_16x16x32_bf16 v[62:65], v[148:151], v[180:183], v[62:65]
	v_mfma_f32_16x16x32_bf16 v[58:61], v[156:159], v[180:183], v[58:61]
	v_mfma_f32_16x16x32_bf16 v[50:53], v[156:159], v[188:191], v[50:53]
	v_mfma_f32_16x16x32_bf16 v[54:57], v[148:151], v[188:191], v[54:57]
	v_mfma_f32_16x16x32_bf16 v[38:41], v[148:151], v[196:199], v[38:41]
	v_mfma_f32_16x16x32_bf16 v[34:37], v[156:159], v[196:199], v[34:37]
	v_mfma_f32_16x16x32_bf16 v[18:21], v[156:159], v[204:207], v[18:21]
	v_mfma_f32_16x16x32_bf16 v[22:25], v[148:151], v[204:207], v[22:25]
	s_setprio 0
	s_setprio 1
	v_mfma_f32_16x16x32_bf16 v[46:49], v[160:163], v[176:179], v[46:49]
	v_mfma_f32_16x16x32_bf16 v[42:45], v[168:171], v[176:179], v[42:45]
	v_mfma_f32_16x16x32_bf16 v[26:29], v[168:171], v[184:187], v[26:29]
	v_mfma_f32_16x16x32_bf16 v[30:33], v[160:163], v[184:187], v[30:33]
	v_mfma_f32_16x16x32_bf16 v[14:17], v[160:163], v[192:195], v[14:17]
	v_mfma_f32_16x16x32_bf16 v[10:13], v[168:171], v[192:195], v[10:13]
	v_mfma_f32_16x16x32_bf16 v[2:5], v[168:171], v[200:203], v[2:5]
	v_mfma_f32_16x16x32_bf16 v[6:9], v[160:163], v[200:203], v[6:9]
	v_mfma_f32_16x16x32_bf16 v[46:49], v[164:167], v[180:183], v[46:49]
	v_mfma_f32_16x16x32_bf16 v[42:45], v[172:175], v[180:183], v[42:45]
	v_mfma_f32_16x16x32_bf16 v[26:29], v[172:175], v[188:191], v[26:29]
	v_mfma_f32_16x16x32_bf16 v[30:33], v[164:167], v[188:191], v[30:33]
	v_mfma_f32_16x16x32_bf16 v[14:17], v[164:167], v[196:199], v[14:17]
	v_mfma_f32_16x16x32_bf16 v[10:13], v[172:175], v[196:199], v[10:13]
	v_mfma_f32_16x16x32_bf16 v[2:5], v[172:175], v[204:207], v[2:5]
	v_mfma_f32_16x16x32_bf16 v[6:9], v[164:167], v[204:207], v[6:9]
	s_setprio 0
	s_barrier
	s_add_i32 s53, s53, 2
	s_add_u32 s11, s11, 0x100
	s_addc_u32 s52, s52, 0
	s_cmp_gt_u32 s53, 19
	s_mov_b64 s[38:39], s[40:41]
	s_cbranch_scc0 .LBB0_193
	s_and_b64 vcc, exec, s[20:21]
	s_cbranch_vccz .LBB0_196
	s_barrier

; #define GAS __attribute__((address_space(1)))
; #define LAS __attribute__((address_space(3)))
; #define LDS_WAIT() asm volatile("s_waitcnt lgkmcnt(0)" ::: "memory")
;     if (ldt == 0) ldt = K;
;     asm volatile("" : "+v"(lane));
;     const int kb = item / nblk, nb = item % nblk, k0 = 64 * kb, n0 = 32 * nb;
;     { float wv[32];
;       const float* wp = W + (size_t)(k0 + (lane >> 5)) * ldw + n0 + (lane & 31);
; #pragma unroll
;       for (int i = 0; i < 32; ++i) wv[i] = wp[(size_t)(2 * i) * ldw];
; #pragma unroll
;       for (int i = 0; i < 32; ++i) scr[(2 * i + (lane >> 5)) * 33 + (lane & 31)] = wv[i]; }
;     LDS_WAIT(); asm volatile("" ::: "memory");
;     const int c = lane & 7;
;     const int r0 = (mode == 0) ? n0 : (256 * (n0 >> 7) + (n0 & 127) + (mode == 2 ? 128 : 0));
; #pragma unroll
;     for (int j = 0; j < 4; ++j) { const int n = (lane >> 3) + 8 * j; const LAS float* s = scr + (8 * c) * 33 + n;
;         v4u o; o.x = pk2(s[0 * 33], s[1 * 33]); o.y = pk2(s[2 * 33], s[3 * 33]); o.z = pk2(s[4 * 33], s[5 * 33]); o.w = pk2(s[6 * 33], s[7 * 33]);
;         *(GAS v4u*)(WT + (size_t)(r0 + n) * ldt + k0 + 8 * c) = o; }
;     LDS_WAIT(); asm volatile("" ::: "memory");
; }
; __device__ __forceinline__ void transpose_early(const Args& a, Frame& F, LAS float* scr, int r) {
;     bf16 *W1 = WSP(bf16, WS_W1), *W1D = WSP(bf16, WS_W1D), *WIN = WSP(bf16, WS_WIN);
;     if (r < IT_FG) { p0_transpose_item(a.in[I_W1G], FF, D, W1, 1, FF / 32, scr, r, F.lane); return; } r -= IT_FG;
;     if (r < IT_FG) { p0_transpose_item(a.in[I_W1U], FF, D, W1, 2, FF / 32, scr, r, F.lane); return; } r -= IT_FG;
;     if (r < IT_FD) { p0_transpose_item(a.in[I_W1D], D, FF, W1D, 0, D / 32, scr, r, F.lane); return; } r -= IT_FD;
;     if (r < IT_INA) { p0_transpose_item(a.in[I_WIN], 14344, D, WIN, 0, 6144 / 32, scr, r, F.lane); return; } r -= IT_INA;
;     p0_transpose_item(a.in[I_WIN] + 6152, 14344, D, WIN + (size_t)6144 * D, 0, 8192 / 32, scr, r, F.lane);
; template <bool LATE = false>
; __device__ __forceinline__ void transpose_tail(Frame& F, const Args& a, int bx, int lo, int first, int count) {
;     if (F.G != 256 || bx < lo) return;
;     LAS float* scr = (LAS float*)(F.lds + F.wave * 16384);
;     for (int j = (bx - lo) * NWAVES + F.wave; j < count; j += (F.G - lo) * NWAVES) { if (LATE) transpose_late(a, F, scr, first + j); else transpose_early(a, F, scr, first + j); }
; }
.LBB0_200:
	s_lshl_b32 s6, s2, 3
	s_add_i32 s10, s97, s6
	s_cmpk_lg_i32 s96, 0x100
	s_cselect_b64 s[6:7], -1, 0
	s_or_b64 s[6:7], s[8:9], s[6:7]
	s_add_i32 s8, s10, 0xfffffe00
	s_cmpk_gt_i32 s8, 0x37ff
	s_cselect_b64 s[8:9], -1, 0
	s_or_b64 s[6:7], s[6:7], s[8:9]
	v_mov_b32_e32 v2, v1
	s_and_b64 vcc, exec, s[6:7]
	s_cbranch_vccnz .LBB0_220
	s_load_dwordx2 s[42:43], s[0:1], 0x70
	s_add_u32 s44, s34, 0x4300000
	s_addc_u32 s45, s35, 0
	s_lshl_b32 s46, s2, 3
	s_add_i32 s46, s46, s97
	s_addk_i32 s46, 0xfe00
	s_lshl_b32 s47, s97, 14
	v_mbcnt_lo_u32_b32 v2, -1, 0
	v_mbcnt_hi_u32_b32 v2, -1, v2
	v_lshrrev_b32_e32 v88, 3, v2
	v_and_b32_e32 v89, 7, v2
	v_mul_u32_u24_e32 v3, 0xe020, v88
	v_lshl_add_u32 v3, v89, 4, v3
	v_add_u32_e32 v4, 0x70100, v3
	v_add_u32_e32 v5, 0xe0200, v3
	v_add_u32_e32 v6, 0x150300, v3
	v_add_u32_e32 v7, 0x1c0400, v3
	v_add_u32_e32 v8, 0x230500, v3
	v_add_u32_e32 v9, 0x2a0600, v3
	v_add_u32_e32 v10, 0x310700, v3
	v_lshlrev_b32_e32 v11, 12, v88
	v_lshl_add_u32 v11, v89, 4, v11
	v_add_u32_e32 v12, 0x8000, v11
	v_add_u32_e32 v13, 0x10000, v11
	v_add_u32_e32 v14, 0x18000, v11
	v_mul_u32_u24_e32 v15, 132, v88
	v_lshl_add_u32 v15, v89, 4, v15
	v_add_u32_e32 v15, s47, v15
	v_add_u32_e32 v16, 1056, v15
	v_add_u32_e32 v17, 2112, v15
	v_add_u32_e32 v18, 3168, v15
	v_add_u32_e32 v19, 4224, v15
	v_add_u32_e32 v20, 5280, v15
	v_add_u32_e32 v21, 6336, v15
	v_add_u32_e32 v22, 7392, v15
	v_mul_u32_u24_e32 v23, 1056, v89
	v_lshl_add_u32 v23, v88, 2, v23
	v_add_u32_e32 v23, s47, v23
	s_waitcnt lgkmcnt(0)
	s_cmpk_lt_u32 s46, 0x1800
	s_cbranch_scc0 .Ltr2_b0
	s_lshr_b32 s57, s46, 6
	s_mul_i32 s57, s57, 171
	s_lshr_b32 s57, s57, 9
	s_mul_i32 s60, s57, 192
	s_sub_u32 s58, s46, s60
	s_mov_b32 s60, 0
	s_mov_b32 s61, 0
	s_branch .Ltr2_c0
.Ltr2_b0:
	s_sub_u32 s60, s46, 0x1800
	s_lshr_b32 s57, s60, 8
	s_and_b32 s58, s60, 0xff
	s_movk_i32 s60, 0x6020
	s_mov_b32 s61, 0x1800000
.Ltr2_c0:
	s_mul_i32 s48, s57, 0x380800
	s_lshl_b32 s49, s58, 7
	s_add_u32 s48, s48, s49
	s_add_u32 s48, s48, s60
	s_add_u32 s48, s48, s42
	s_addc_u32 s49, s43, 0
	s_lshl_b32 s50, s58, 17
	s_lshl_b32 s51, s57, 7
	s_add_u32 s50, s50, s51
	s_add_u32 s50, s50, s61
	s_add_u32 s50, s50, s44
	s_addc_u32 s51, s45, 0
	global_load_dwordx4 v[24:27], v3, s[48:49]
	global_load_dwordx4 v[28:31], v4, s[48:49]
	global_load_dwordx4 v[32:35], v5, s[48:49]
	global_load_dwordx4 v[36:39], v6, s[48:49]
	global_load_dwordx4 v[40:43], v7, s[48:49]
	global_load_dwordx4 v[44:47], v8, s[48:49]
	global_load_dwordx4 v[48:51], v9, s[48:49]
	global_load_dwordx4 v[52:55], v10, s[48:49]
	s_waitcnt vmcnt(0)
.Ltr2_A:
	ds_write2_b32 v15, v24, v25 offset1:1
	ds_write2_b32 v15, v26, v27 offset0:2 offset1:3
	ds_write2_b32 v16, v28, v29 offset1:1
	ds_write2_b32 v16, v30, v31 offset0:2 offset1:3
	ds_write2_b32 v17, v32, v33 offset1:1
	ds_write2_b32 v17, v34, v35 offset0:2 offset1:3
	ds_write2_b32 v18, v36, v37 offset1:1
	ds_write2_b32 v18, v38, v39 offset0:2 offset1:3
	ds_write2_b32 v19, v40, v41 offset1:1
	ds_write2_b32 v19, v42, v43 offset0:2 offset1:3
	ds_write2_b32 v20, v44, v45 offset1:1
	ds_write2_b32 v20, v46, v47 offset0:2 offset1:3
	ds_write2_b32 v21, v48, v49 offset1:1
	ds_write2_b32 v21, v50, v51 offset0:2 offset1:3
	ds_write2_b32 v22, v52, v53 offset1:1
	ds_write2_b32 v22, v54, v55 offset0:2 offset1:3
	s_mov_b64 s[62:63], s[50:51]
	s_add_i32 s46, s46, 0x600
	s_cmpk_lt_u32 s46, 0x3800
	s_cselect_b32 s59, 1, 0
	s_cbranch_scc0 .Ltr2_np_A
	s_cmpk_lt_u32 s46, 0x1800
	s_cbranch_scc0 .Ltr2_b1
	s_lshr_b32 s57, s46, 6
	s_mul_i32 s57, s57, 171
	s_lshr_b32 s57, s57, 9
	s_mul_i32 s60, s57, 192
	s_sub_u32 s58, s46, s60
	s_mov_b32 s60, 0
	s_mov_b32 s61, 0
	s_branch .Ltr2_c1

; #define GAS __attribute__((address_space(1)))
; #define LAS __attribute__((address_space(3)))
; #define LDS_WAIT() asm volatile("s_waitcnt lgkmcnt(0)" ::: "memory")
; __device__ __forceinline__ unsigned pk2(float lo, float hi) { return f2bf(lo) | (f2bf(hi) << 16); }
;     ...
;     { float wv[32];
;       const float* wp = W + (size_t)(k0 + (lane >> 5)) * ldw + n0 + (lane & 31);
; #pragma unroll
;       for (int i = 0; i < 32; ++i) wv[i] = wp[(size_t)(2 * i) * ldw];
; #pragma unroll
;       for (int i = 0; i < 32; ++i) scr[(2 * i + (lane >> 5)) * 33 + (lane & 31)] = wv[i]; }
;     LDS_WAIT(); asm volatile("" ::: "memory");
;     const int c = lane & 7;
;     const int r0 = (mode == 0) ? n0 : (256 * (n0 >> 7) + (n0 & 127) + (mode == 2 ? 128 : 0));
; #pragma unroll
;     for (int j = 0; j < 4; ++j) { const int n = (lane >> 3) + 8 * j; const LAS float* s = scr + (8 * c) * 33 + n;
;         v4u o; o.x = pk2(s[0 * 33], s[1 * 33]); o.y = pk2(s[2 * 33], s[3 * 33]); o.z = pk2(s[4 * 33], s[5 * 33]); o.w = pk2(s[6 * 33], s[7 * 33]);
;         *(GAS v4u*)(WT + (size_t)(r0 + n) * ldt + k0 + 8 * c) = o; }
.Ltr2_c1:
	s_mul_i32 s48, s57, 0x380800
	s_lshl_b32 s49, s58, 7
	s_add_u32 s48, s48, s49
	s_add_u32 s48, s48, s60
	s_add_u32 s48, s48, s42
	s_addc_u32 s49, s43, 0
	s_lshl_b32 s50, s58, 17
	s_lshl_b32 s51, s57, 7
	s_add_u32 s50, s50, s51
	s_add_u32 s50, s50, s61
	s_add_u32 s50, s50, s44
	s_addc_u32 s51, s45, 0
	global_load_dwordx4 v[56:59], v3, s[48:49]
	global_load_dwordx4 v[60:63], v4, s[48:49]
	global_load_dwordx4 v[64:67], v5, s[48:49]
	global_load_dwordx4 v[68:71], v6, s[48:49]
	global_load_dwordx4 v[72:75], v7, s[48:49]
	global_load_dwordx4 v[76:79], v8, s[48:49]
	global_load_dwordx4 v[80:83], v9, s[48:49]
	global_load_dwordx4 v[84:87], v10, s[48:49]
.Ltr2_np_A:
	s_waitcnt lgkmcnt(0)
	ds_read2_b32 v[88:89], v23 offset0:0 offset1:33
	ds_read2_b32 v[90:91], v23 offset0:66 offset1:99
	ds_read2_b32 v[92:93], v23 offset0:132 offset1:165
	ds_read2_b32 v[94:95], v23 offset0:198 offset1:231
	s_waitcnt lgkmcnt(0)
	v_cvt_pk_bf16_f32 v96, v88, v89
	v_cvt_pk_bf16_f32 v97, v90, v91
	v_cvt_pk_bf16_f32 v98, v92, v93
	v_cvt_pk_bf16_f32 v99, v94, v95
	global_store_dwordx4 v11, v[96:99], s[62:63]
	s_nop 1
	ds_read2_b32 v[88:89], v23 offset0:8 offset1:41
	ds_read2_b32 v[90:91], v23 offset0:74 offset1:107
	ds_read2_b32 v[92:93], v23 offset0:140 offset1:173
	ds_read2_b32 v[94:95], v23 offset0:206 offset1:239
	s_waitcnt lgkmcnt(0)
	v_cvt_pk_bf16_f32 v96, v88, v89
	v_cvt_pk_bf16_f32 v97, v90, v91
	v_cvt_pk_bf16_f32 v98, v92, v93
	v_cvt_pk_bf16_f32 v99, v94, v95
	global_store_dwordx4 v12, v[96:99], s[62:63]
	s_nop 1
	ds_read2_b32 v[88:89], v23 offset0:16 offset1:49
	ds_read2_b32 v[90:91], v23 offset0:82 offset1:115
	ds_read2_b32 v[92:93], v23 offset0:148 offset1:181
	ds_read2_b32 v[94:95], v23 offset0:214 offset1:247
	s_waitcnt lgkmcnt(0)
	v_cvt_pk_bf16_f32 v96, v88, v89
	v_cvt_pk_bf16_f32 v97, v90, v91
	v_cvt_pk_bf16_f32 v98, v92, v93
	v_cvt_pk_bf16_f32 v99, v94, v95
	global_store_dwordx4 v13, v[96:99], s[62:63]
	s_nop 1
	ds_read2_b32 v[88:89], v23 offset0:24 offset1:57
	ds_read2_b32 v[90:91], v23 offset0:90 offset1:123
	ds_read2_b32 v[92:93], v23 offset0:156 offset1:189
	ds_read2_b32 v[94:95], v23 offset0:222 offset1:255
	s_waitcnt lgkmcnt(0)
	v_cvt_pk_bf16_f32 v96, v88, v89
	v_cvt_pk_bf16_f32 v97, v90, v91
	v_cvt_pk_bf16_f32 v98, v92, v93
	v_cvt_pk_bf16_f32 v99, v94, v95
	global_store_dwordx4 v14, v[96:99], s[62:63]
	s_nop 1
	s_cmp_eq_u32 s59, 0
	s_cbranch_scc1 .Ltr2_done
	s_waitcnt vmcnt(4)
.Ltr2_B:
	ds_write2_b32 v15, v56, v57 offset1:1
	ds_write2_b32 v15, v58, v59 offset0:2 offset1:3
	ds_write2_b32 v16, v60, v61 offset1:1
	ds_write2_b32 v16, v62, v63 offset0:2 offset1:3
	ds_write2_b32 v17, v64, v65 offset1:1
	ds_write2_b32 v17, v66, v67 offset0:2 offset1:3
	ds_write2_b32 v18, v68, v69 offset1:1
	ds_write2_b32 v18, v70, v71 offset0:2 offset1:3
	ds_write2_b32 v19, v72, v73 offset1:1
	ds_write2_b32 v19, v74, v75 offset0:2 offset1:3
	ds_write2_b32 v20, v76, v77 offset1:1
	ds_write2_b32 v20, v78, v79 offset0:2 offset1:3
	ds_write2_b32 v21, v80, v81 offset1:1
	ds_write2_b32 v21, v82, v83 offset0:2 offset1:3
	ds_write2_b32 v22, v84, v85 offset1:1
	ds_write2_b32 v22, v86, v87 offset0:2 offset1:3
	s_mov_b64 s[62:63], s[50:51]
	s_add_i32 s46, s46, 0x600
	s_cmpk_lt_u32 s46, 0x3800
	s_cselect_b32 s59, 1, 0
	s_cbranch_scc0 .Ltr2_np_B
	s_cmpk_lt_u32 s46, 0x1800
	s_cbranch_scc0 .Ltr2_b2
	s_lshr_b32 s57, s46, 6
	s_mul_i32 s57, s57, 171
	s_lshr_b32 s57, s57, 9
	s_mul_i32 s60, s57, 192
	s_sub_u32 s58, s46, s60
	s_mov_b32 s60, 0
	s_mov_b32 s61, 0
	s_branch .Ltr2_c2

; #define GAS __attribute__((address_space(1)))
; #define LAS __attribute__((address_space(3)))
; #define LDS_WAIT() asm volatile("s_waitcnt lgkmcnt(0)" ::: "memory")
; __device__ __forceinline__ unsigned pk2(float lo, float hi) { return f2bf(lo) | (f2bf(hi) << 16); }
; __device__ __forceinline__ unsigned xb_ld(unsigned* p)              { return __hip_atomic_load(p, __ATOMIC_RELAXED, __HIP_MEMORY_SCOPE_AGENT); }
; __device__ __forceinline__ void xcd_barrier_complete(unsigned* bar, unsigned x, unsigned& nloc, unsigned& nx) {
;     const unsigned G = gridDim.x * gridDim.y * gridDim.z;
;     unsigned sum, cnt, mine, sp = 0u;
;     for (;;) {
;         sum = 0u; cnt = 0u; mine = 0u;
; #pragma unroll
;         for (unsigned j = 0; j < 16; ++j) { const unsigned c = xb_ld(&bar[XB_XCNT(j)]); sum += c; cnt += (c > 0u) ? 1u : 0u; mine = (j == x) ? c : mine; }
;         if (sum == G) break;
;         __builtin_amdgcn_s_sleep(1);
;         if ((++sp & 255u) == 0u) { if (xb_ld(&bar[XB_TMO])) break; if (sp > XB_SPIN_CAP) { atomicAdd(&bar[XB_TMO], 1u); break; } }
;     }
;     nloc = mine > 0u ? mine : 1u; nx = cnt > 0u ? cnt : 1u;
; }
; __device__ __forceinline__ void xcd_barrier(const XcdBarrier& b) {
;     asm volatile("s_waitcnt vmcnt(0)" ::: "memory");
;     __syncthreads();
;     if (threadIdx.x == 0) {
;         unsigned* bar = b.bar;
;         __builtin_amdgcn_s_waitcnt(0);
;         unsigned nloc = b.st[0], nx = b.st[1];
;         if (nloc == 0u) { xcd_barrier_complete(bar, b.x, nloc, nx); b.st[0] = nloc; b.st[1] = nx; }
;     ...
;     { float wv[32];
;       const float* wp = W + (size_t)(k0 + (lane >> 5)) * ldw + n0 + (lane & 31);
; #pragma unroll
;       for (int i = 0; i < 32; ++i) wv[i] = wp[(size_t)(2 * i) * ldw];
; #pragma unroll
;       for (int i = 0; i < 32; ++i) scr[(2 * i + (lane >> 5)) * 33 + (lane & 31)] = wv[i]; }
;     LDS_WAIT(); asm volatile("" ::: "memory");
;     const int c = lane & 7;
;     const int r0 = (mode == 0) ? n0 : (256 * (n0 >> 7) + (n0 & 127) + (mode == 2 ? 128 : 0));
; #pragma unroll
;     for (int j = 0; j < 4; ++j) { const int n = (lane >> 3) + 8 * j; const LAS float* s = scr + (8 * c) * 33 + n;
;         v4u o; o.x = pk2(s[0 * 33], s[1 * 33]); o.y = pk2(s[2 * 33], s[3 * 33]); o.z = pk2(s[4 * 33], s[5 * 33]); o.w = pk2(s[6 * 33], s[7 * 33]);
;         *(GAS v4u*)(WT + (size_t)(r0 + n) * ldt + k0 + 8 * c) = o; }
.Ltr2_c2:
	s_mul_i32 s48, s57, 0x380800
	s_lshl_b32 s49, s58, 7
	s_add_u32 s48, s48, s49
	s_add_u32 s48, s48, s60
	s_add_u32 s48, s48, s42
	s_addc_u32 s49, s43, 0
	s_lshl_b32 s50, s58, 17
	s_lshl_b32 s51, s57, 7
	s_add_u32 s50, s50, s51
	s_add_u32 s50, s50, s61
	s_add_u32 s50, s50, s44
	s_addc_u32 s51, s45, 0
	global_load_dwordx4 v[24:27], v3, s[48:49]
	global_load_dwordx4 v[28:31], v4, s[48:49]
	global_load_dwordx4 v[32:35], v5, s[48:49]
	global_load_dwordx4 v[36:39], v6, s[48:49]
	global_load_dwordx4 v[40:43], v7, s[48:49]
	global_load_dwordx4 v[44:47], v8, s[48:49]
	global_load_dwordx4 v[48:51], v9, s[48:49]
	global_load_dwordx4 v[52:55], v10, s[48:49]
.Ltr2_np_B:
	s_waitcnt lgkmcnt(0)
	ds_read2_b32 v[88:89], v23 offset0:0 offset1:33
	ds_read2_b32 v[90:91], v23 offset0:66 offset1:99
	ds_read2_b32 v[92:93], v23 offset0:132 offset1:165
	ds_read2_b32 v[94:95], v23 offset0:198 offset1:231
	s_waitcnt lgkmcnt(0)
	v_cvt_pk_bf16_f32 v96, v88, v89
	v_cvt_pk_bf16_f32 v97, v90, v91
	v_cvt_pk_bf16_f32 v98, v92, v93
	v_cvt_pk_bf16_f32 v99, v94, v95
	global_store_dwordx4 v11, v[96:99], s[62:63]
	s_nop 1
	ds_read2_b32 v[88:89], v23 offset0:8 offset1:41
	ds_read2_b32 v[90:91], v23 offset0:74 offset1:107
	ds_read2_b32 v[92:93], v23 offset0:140 offset1:173
	ds_read2_b32 v[94:95], v23 offset0:206 offset1:239
	s_waitcnt lgkmcnt(0)
	v_cvt_pk_bf16_f32 v96, v88, v89
	v_cvt_pk_bf16_f32 v97, v90, v91
	v_cvt_pk_bf16_f32 v98, v92, v93
	v_cvt_pk_bf16_f32 v99, v94, v95
	global_store_dwordx4 v12, v[96:99], s[62:63]
	s_nop 1
	ds_read2_b32 v[88:89], v23 offset0:16 offset1:49
	ds_read2_b32 v[90:91], v23 offset0:82 offset1:115
	ds_read2_b32 v[92:93], v23 offset0:148 offset1:181
	ds_read2_b32 v[94:95], v23 offset0:214 offset1:247
	s_waitcnt lgkmcnt(0)
	v_cvt_pk_bf16_f32 v96, v88, v89
	v_cvt_pk_bf16_f32 v97, v90, v91
	v_cvt_pk_bf16_f32 v98, v92, v93
	v_cvt_pk_bf16_f32 v99, v94, v95
	global_store_dwordx4 v13, v[96:99], s[62:63]
	s_nop 1
	ds_read2_b32 v[88:89], v23 offset0:24 offset1:57
	ds_read2_b32 v[90:91], v23 offset0:90 offset1:123
	ds_read2_b32 v[92:93], v23 offset0:156 offset1:189
	ds_read2_b32 v[94:95], v23 offset0:222 offset1:255
	s_waitcnt lgkmcnt(0)
	v_cvt_pk_bf16_f32 v96, v88, v89
	v_cvt_pk_bf16_f32 v97, v90, v91
	v_cvt_pk_bf16_f32 v98, v92, v93
	v_cvt_pk_bf16_f32 v99, v94, v95
	global_store_dwordx4 v14, v[96:99], s[62:63]
	s_nop 1
	s_cmp_eq_u32 s59, 0
	s_cbranch_scc1 .Ltr2_done
	s_waitcnt vmcnt(4)
	s_branch .Ltr2_A
.Ltr2_done:
.LBB0_220:
	s_waitcnt lgkmcnt(0)
	s_cmp_gt_i32 s93, 3
	s_cselect_b64 s[6:7], -1, 0
	s_and_b64 s[4:5], s[4:5], s[6:7]
	s_andn2_b64 vcc, exec, s[4:5]
	s_cbranch_vccnz .LBB0_268
	s_cmp_gt_i32 s92, -1
	s_mov_b64 s[4:5], -1
	s_cbranch_scc0 .LBB0_255
	s_waitcnt vmcnt(0)
	s_waitcnt vmcnt(0)
	s_barrier
	s_mov_b64 s[4:5], exec
	v_readlane_b32 s8, v245, 31
	v_readlane_b32 s9, v245, 32
	s_and_b64 s[8:9], s[4:5], s[8:9]
	s_mov_b64 exec, s[8:9]
	s_cbranch_execz .LBB0_254
	s_add_i32 s3, 0, 0x26020
	v_mov_b32_e32 v2, s3
	s_waitcnt vmcnt(0) expcnt(0) lgkmcnt(0)
	ds_read_b32 v2, v2
	s_add_i32 s3, 0, 0x26024
	v_mov_b32_e32 v3, s3
	ds_read_b32 v5, v3
	s_waitcnt lgkmcnt(1)
	v_cmp_ne_u32_e32 vcc, 0, v2
	s_cbranch_vccnz .LBB0_247
	v_readlane_b32 s8, v245, 8
	v_readlane_b32 s9, v245, 9
	s_load_dwordx2 s[12:13], s[8:9], 0x4
	s_add_u32 s8, s34, 0x4200
	s_addc_u32 s9, s35, 0
	s_add_u32 s10, s34, 0x4400
	s_addc_u32 s11, s35, 0
	s_waitcnt lgkmcnt(0)
	s_mul_i32 s3, s12, s96
	s_add_u32 s12, s34, 0x4500
	s_mul_i32 s3, s3, s13
	s_addc_u32 s13, s35, 0
	s_add_u32 s14, s34, 0x4600
	s_addc_u32 s15, s35, 0
	s_add_u32 s20, s34, 0x4700
	s_addc_u32 s21, s35, 0
	s_add_u32 s22, s34, 0x4800
	s_addc_u32 s23, s35, 0
	s_add_u32 s36, s34, 0x4900
	s_addc_u32 s37, s35, 0
	s_add_u32 s38, s34, 0x4a00
	s_addc_u32 s39, s35, 0
	s_add_u32 s40, s34, 0x4b00
	s_addc_u32 s41, s35, 0
	s_add_u32 s42, s34, 0x4c00
	s_addc_u32 s43, s35, 0
	s_add_u32 s44, s34, 0x4d00
	s_addc_u32 s45, s35, 0
	s_add_u32 s46, s34, 0x4e00
	s_addc_u32 s47, s35, 0
	s_add_u32 s48, s34, 0x4f00
	s_addc_u32 s49, s35, 0
	s_add_u32 s50, s34, 0x5000
	s_addc_u32 s51, s35, 0
	s_add_u32 s52, s34, 0x5100
	s_addc_u32 s53, s35, 0
	s_add_u32 s54, s34, 0x5200
	s_addc_u32 s55, s35, 0
	s_add_u32 s56, s34, 0x5300
	s_addc_u32 s57, s35, 0
	s_mov_b32 s16, 1
	v_mov_b32_e32 v18, 0
	s_branch .LBB0_226

;     __device__ bool next(int i, Unit& u) const { if (!s.next(i, u)) return false; const int p = u.pn; u.pn = p < 56 ? (p % 7) * 8 + p / 7 : p; return true; }
;     __device__ bool next(int i, Unit& u) const { Unit t; if (!s.next(i >> 1, t)) return false; const int pass = i & 1; u.pm = t.pm + pass * (M / BM); u.pn = t.pn + pass * (D / BM); u.kt0 = 0; return true; }
; #define PG8_STAGE(bufoff, gbase, voff) do { _Pragma("unroll") for (int _i = 0; _i < 2; ++_i) \
;         __builtin_amdgcn_global_load_lds((const unsigned*)((const char*)(gbase) + (voff)[_i]), (PG8_LAS unsigned*)(lds + (bufoff) + ldsw + _i * 8192), 16, 0, 0); } while (0)
; #define PG8_LDA(dst, b, h) do { _Pragma("unroll") for (int m = 0; m < 4; ++m) _Pragma("unroll") for (int k = 0; k < 2; ++k) dst[m][k] = *(const PG8_LAS bf16x8*)(lds + PG8_SA(b, h) + aoff + m * 2048 + k * 1024); } while (0)
; template <class Epi, class Sched, bool ALIGN_EPI = false, bool SP2 = false>
; __device__ __forceinline__ void gemm_phase(PG8_LAS unsigned char* lds, const Gemm g, const Sched& S, const Epi& E) {
;     ...
;         const bool has_next = S.next(ui + 1, nxt);
;         const char* nA = has_next ? (const char*)g.A + (size_t)nxt.pm * tstep + (size_t)nxt.kt0 * kstep : cA; const char* nB = has_next ? (const char*)g.Bt + (size_t)nxt.pn * tstep + (size_t)nxt.kt0 * kstep : cB;
;         for (int t = 0; t < nt; t += 2) {
;             if constexpr (Epi::MIDHOOK) { if (t == (nt >> 1)) E.mid(acc, cur, wr, wc, fr, fq); }
;             const bool last = (t == nt - 2);
;             const char* a1 = cA + (size_t)(t + 1) * kstep;
;             const char* a2 = last ? nA : cA + (size_t)(t + 2) * kstep; const char* b2 = last ? nB : cB + (size_t)(t + 2) * kstep;
;             const char* a3 = a2 + kstep; const char* b3 = b2 + kstep;
;             if (last && has_next) S.a_ready(nxt);
;             if constexpr (SP2) {
;             PG8_LDB(B0, 0, 0); PG8_LDB(B1, 0, 1); PG8_SCHED; PG8_LDA(At, 0, 0); PG8_STAGE(PG8_SA(1, 1), a1 + hstep, voffA);
;             PG8_WAIT_V(8); PG8_WAIT_L(0); PG8_BAR; PG8_MMA(0, 0, At, B0); PG8_MMA(0, 1, At, B1); PG8_BAR; PG8_SCHED;
;             PG8_LDA(At, 0, 1); PG8_STAGE(PG8_SB(0, 0), b2, voffB); PG8_STAGE(PG8_SB(0, 1), b2 + hstep, voffB); PG8_STAGE(PG8_SA(0, 0), a2, voffA);
;             PG8_WAIT_V(8); PG8_WAIT_L(0); PG8_BAR; PG8_MMA(1, 0, At, B0); PG8_MMA(1, 1, At, B1); PG8_BAR; PG8_SCHED;
.LBB0_346:
	ds_read_b128 v[150:153], v177
	ds_read_b128 v[154:157], v177 offset:1024
	ds_read_b128 v[158:161], v177 offset:2048
	ds_read_b128 v[162:165], v177 offset:3072
	ds_read_b128 v[166:169], v178
	ds_read_b128 v[182:185], v178 offset:1024
	ds_read_b128 v[186:189], v178 offset:2048
	ds_read_b128 v[190:193], v178 offset:3072
	s_add_u32 s14, s10, 0xfff80080
	s_addc_u32 s15, s11, -1
	s_cmp_eq_u32 s23, 28
	s_cselect_b32 s17, s6, s15
	s_cselect_b32 s16, s7, s14
	s_cselect_b32 s15, s13, s22
	s_cselect_b32 s14, s18, s19
	v_lshl_add_u64 v[170:171], s[10:11], 0, v[142:143]
	s_add_i32 m0, s59, 0xc000
	ds_read_b128 v[194:197], v179
	ds_read_b128 v[198:201], v179 offset:1024
	ds_read_b128 v[202:205], v179 offset:2048
	ds_read_b128 v[206:209], v179 offset:3072
	ds_read_b128 v[210:213], v179 offset:4096
	ds_read_b128 v[214:217], v179 offset:5120
	ds_read_b128 v[218:221], v179 offset:6144
	ds_read_b128 v[222:225], v179 offset:7168
	global_load_lds_dwordx4 v[170:171], off
	v_lshl_add_u64 v[170:171], s[10:11], 0, v[144:145]
	s_add_i32 m0, s59, 0xe000
	s_nop 0
	global_load_lds_dwordx4 v[170:171], off
	s_waitcnt vmcnt(8)
	s_waitcnt lgkmcnt(0)
	s_barrier
	s_setprio 1
	s_waitcnt lgkmcnt(0)
	v_mfma_f32_16x16x32_bf16 v[58:61], v[150:153], v[194:197], v[58:61]
	v_mfma_f32_16x16x32_bf16 v[62:65], v[158:161], v[194:197], v[62:65]
	v_mfma_f32_16x16x32_bf16 v[54:57], v[158:161], v[202:205], v[54:57]
	v_mfma_f32_16x16x32_bf16 v[50:53], v[150:153], v[202:205], v[50:53]
	v_mfma_f32_16x16x32_bf16 v[42:45], v[150:153], v[210:213], v[42:45]
	v_mfma_f32_16x16x32_bf16 v[46:49], v[158:161], v[210:213], v[46:49]
	v_mfma_f32_16x16x32_bf16 v[38:41], v[158:161], v[218:221], v[38:41]
	v_mfma_f32_16x16x32_bf16 v[34:37], v[150:153], v[218:221], v[34:37]
	v_mfma_f32_16x16x32_bf16 v[58:61], v[154:157], v[198:201], v[58:61]
	v_mfma_f32_16x16x32_bf16 v[62:65], v[162:165], v[198:201], v[62:65]
	v_mfma_f32_16x16x32_bf16 v[54:57], v[162:165], v[206:209], v[54:57]
	v_mfma_f32_16x16x32_bf16 v[50:53], v[154:157], v[206:209], v[50:53]
	v_mfma_f32_16x16x32_bf16 v[42:45], v[154:157], v[214:217], v[42:45]
	v_mfma_f32_16x16x32_bf16 v[46:49], v[162:165], v[214:217], v[46:49]
	v_mfma_f32_16x16x32_bf16 v[38:41], v[162:165], v[222:225], v[38:41]
	v_mfma_f32_16x16x32_bf16 v[34:37], v[154:157], v[222:225], v[34:37]
	s_setprio 0
	s_setprio 1
	v_mfma_f32_16x16x32_bf16 v[126:129], v[166:169], v[194:197], v[126:129]
	v_mfma_f32_16x16x32_bf16 v[122:125], v[186:189], v[194:197], v[122:125]
	v_mfma_f32_16x16x32_bf16 v[114:117], v[186:189], v[202:205], v[114:117]
	v_mfma_f32_16x16x32_bf16 v[118:121], v[166:169], v[202:205], v[118:121]
	v_mfma_f32_16x16x32_bf16 v[110:113], v[166:169], v[210:213], v[110:113]
	v_mfma_f32_16x16x32_bf16 v[106:109], v[186:189], v[210:213], v[106:109]
	v_mfma_f32_16x16x32_bf16 v[98:101], v[186:189], v[218:221], v[98:101]
	v_mfma_f32_16x16x32_bf16 v[102:105], v[166:169], v[218:221], v[102:105]
	v_mfma_f32_16x16x32_bf16 v[126:129], v[182:185], v[198:201], v[126:129]
	v_mfma_f32_16x16x32_bf16 v[122:125], v[190:193], v[198:201], v[122:125]
	v_mfma_f32_16x16x32_bf16 v[114:117], v[190:193], v[206:209], v[114:117]
	v_mfma_f32_16x16x32_bf16 v[118:121], v[182:185], v[206:209], v[118:121]
	v_mfma_f32_16x16x32_bf16 v[110:113], v[182:185], v[214:217], v[110:113]
	v_mfma_f32_16x16x32_bf16 v[106:109], v[190:193], v[214:217], v[106:109]
	v_mfma_f32_16x16x32_bf16 v[98:101], v[190:193], v[222:225], v[98:101]
	v_mfma_f32_16x16x32_bf16 v[102:105], v[182:185], v[222:225], v[102:105]
	s_setprio 0
	s_barrier
	s_add_i32 s24, s95, s55
	v_lshl_add_u64 v[170:171], s[14:15], 0, v[132:133]
	s_mov_b32 m0, s24
	ds_read_b128 v[194:197], v179 offset:16384
	ds_read_b128 v[198:201], v179 offset:17408
	ds_read_b128 v[202:205], v179 offset:18432
	ds_read_b128 v[206:209], v179 offset:19456
	ds_read_b128 v[210:213], v179 offset:20480
	ds_read_b128 v[214:217], v179 offset:21504
	ds_read_b128 v[218:221], v179 offset:22528
	ds_read_b128 v[222:225], v179 offset:23552
	global_load_lds_dwordx4 v[170:171], off
	s_add_i32 m0, s24, 0x2000
	s_add_u32 s24, s14, 0x80000
	v_lshl_add_u64 v[226:227], s[14:15], 0, v[136:137]
	s_addc_u32 s25, s15, 0
	s_add_i32 s26, s81, s55
	global_load_lds_dwordx4 v[226:227], off
	v_lshl_add_u64 v[228:229], s[24:25], 0, v[132:133]
	s_mov_b32 m0, s26
	v_lshl_add_u64 v[230:231], s[16:17], 0, v[134:135]
	global_load_lds_dwordx4 v[228:229], off
	v_lshl_add_u64 v[228:229], s[24:25], 0, v[136:137]
	s_add_i32 m0, s26, 0x2000
	s_nop 0
	global_load_lds_dwordx4 v[228:229], off
	v_lshl_add_u64 v[228:229], s[16:17], 0, v[130:131]
	s_mov_b32 m0, s59
	s_nop 0
	global_load_lds_dwordx4 v[228:229], off
	s_mov_b32 m0, s61
	s_nop 0
	global_load_lds_dwordx4 v[230:231], off
	s_waitcnt vmcnt(8)
	s_waitcnt lgkmcnt(0)
	s_barrier
; #define PG8_STAGE(bufoff, gbase, voff) do { _Pragma("unroll") for (int _i = 0; _i < 2; ++_i) \
;         __builtin_amdgcn_global_load_lds((const unsigned*)((const char*)(gbase) + (voff)[_i]), (PG8_LAS unsigned*)(lds + (bufoff) + ldsw + _i * 8192), 16, 0, 0); } while (0)
; #define PG8_LDA(dst, b, h) do { _Pragma("unroll") for (int m = 0; m < 4; ++m) _Pragma("unroll") for (int k = 0; k < 2; ++k) dst[m][k] = *(const PG8_LAS bf16x8*)(lds + PG8_SA(b, h) + aoff + m * 2048 + k * 1024); } while (0)
; #define PG8_LDB(dst, b, h) do { _Pragma("unroll") for (int n = 0; n < 2; ++n) _Pragma("unroll") for (int k = 0; k < 2; ++k) dst[n][k] = *(const PG8_LAS bf16x8*)(lds + PG8_SB(b, h) + boff + n * 2048 + k * 1024); } while (0)
; #define PG8_MMA(ai, bj, At, Bt) do { __builtin_amdgcn_s_setprio(1); _Pragma("unroll") for (int m = 0; m < 4; ++m) _Pragma("unroll") for (int n = 0; n < 2; ++n) _Pragma("unroll") for (int k = 0; k < 2; ++k) \
;         acc[ai][bj][m][n] = __builtin_amdgcn_mfma_f32_16x16x32_bf16(Bt[n][k], At[m][k], acc[ai][bj][m][n], 0, 0, 0); __builtin_amdgcn_s_setprio(0); } while (0)
; #define PG8_WAIT_V(n) asm volatile("s_waitcnt vmcnt(" #n ")" ::: "memory")
; #define PG8_WAIT_L(n) asm volatile("s_waitcnt lgkmcnt(" #n ")" ::: "memory")
; #define PG8_BAR __builtin_amdgcn_s_barrier()
; #define PG8_SCHED __builtin_amdgcn_sched_barrier(0)
; template <class Epi, class Sched, bool ALIGN_EPI = false, bool SP2 = false>
; __device__ __forceinline__ void gemm_phase(PG8_LAS unsigned char* lds, const Gemm g, const Sched& S, const Epi& E) {
;     ...
;             PG8_WAIT_V(8); PG8_WAIT_L(0); PG8_BAR; PG8_MMA(1, 0, At, B0); PG8_MMA(1, 1, At, B1); PG8_BAR; PG8_SCHED;
;             PG8_LDB(B0, 1, 0); PG8_LDB(B1, 1, 1); PG8_SCHED; PG8_LDA(At, 1, 0); PG8_STAGE(PG8_SA(0, 1), a2 + hstep, voffA);
;             PG8_WAIT_V(8); PG8_WAIT_L(0); PG8_BAR; PG8_MMA(0, 0, At, B0); PG8_MMA(0, 1, At, B1); PG8_BAR; PG8_SCHED;
	s_setprio 1
	s_waitcnt lgkmcnt(0)
	v_mfma_f32_16x16x32_bf16 v[26:29], v[150:153], v[194:197], v[26:29]
	v_mfma_f32_16x16x32_bf16 v[30:33], v[158:161], v[194:197], v[30:33]
	v_mfma_f32_16x16x32_bf16 v[22:25], v[158:161], v[202:205], v[22:25]
	v_mfma_f32_16x16x32_bf16 v[18:21], v[150:153], v[202:205], v[18:21]
	v_mfma_f32_16x16x32_bf16 v[10:13], v[150:153], v[210:213], v[10:13]
	v_mfma_f32_16x16x32_bf16 v[14:17], v[158:161], v[210:213], v[14:17]
	v_mfma_f32_16x16x32_bf16 v[6:9], v[158:161], v[218:221], v[6:9]
	v_mfma_f32_16x16x32_bf16 v[2:5], v[150:153], v[218:221], v[2:5]
	v_mfma_f32_16x16x32_bf16 v[26:29], v[154:157], v[198:201], v[26:29]
	v_mfma_f32_16x16x32_bf16 v[30:33], v[162:165], v[198:201], v[30:33]
	v_mfma_f32_16x16x32_bf16 v[22:25], v[162:165], v[206:209], v[22:25]
	v_mfma_f32_16x16x32_bf16 v[18:21], v[154:157], v[206:209], v[18:21]
	v_mfma_f32_16x16x32_bf16 v[10:13], v[154:157], v[214:217], v[10:13]
	v_mfma_f32_16x16x32_bf16 v[14:17], v[162:165], v[214:217], v[14:17]
	v_mfma_f32_16x16x32_bf16 v[6:9], v[162:165], v[222:225], v[6:9]
	v_mfma_f32_16x16x32_bf16 v[2:5], v[154:157], v[222:225], v[2:5]
	s_setprio 0
	s_setprio 1
	v_mfma_f32_16x16x32_bf16 v[94:97], v[166:169], v[194:197], v[94:97]
	v_mfma_f32_16x16x32_bf16 v[90:93], v[186:189], v[194:197], v[90:93]
	v_mfma_f32_16x16x32_bf16 v[82:85], v[186:189], v[202:205], v[82:85]
	v_mfma_f32_16x16x32_bf16 v[86:89], v[166:169], v[202:205], v[86:89]
	v_mfma_f32_16x16x32_bf16 v[78:81], v[166:169], v[210:213], v[78:81]
	v_mfma_f32_16x16x32_bf16 v[74:77], v[186:189], v[210:213], v[74:77]
	v_mfma_f32_16x16x32_bf16 v[66:69], v[186:189], v[218:221], v[66:69]
	v_mfma_f32_16x16x32_bf16 v[70:73], v[166:169], v[218:221], v[70:73]
	v_mfma_f32_16x16x32_bf16 v[94:97], v[182:185], v[198:201], v[94:97]
	v_mfma_f32_16x16x32_bf16 v[90:93], v[190:193], v[198:201], v[90:93]
	v_mfma_f32_16x16x32_bf16 v[82:85], v[190:193], v[206:209], v[82:85]
	v_mfma_f32_16x16x32_bf16 v[86:89], v[182:185], v[206:209], v[86:89]
	v_mfma_f32_16x16x32_bf16 v[78:81], v[182:185], v[214:217], v[78:81]
	v_mfma_f32_16x16x32_bf16 v[74:77], v[190:193], v[214:217], v[74:77]
	v_mfma_f32_16x16x32_bf16 v[66:69], v[190:193], v[222:225], v[66:69]
	v_mfma_f32_16x16x32_bf16 v[70:73], v[182:185], v[222:225], v[70:73]
	s_setprio 0
	s_barrier
	s_add_i32 s24, 0, 0x18000
	v_add_u32_e32 v138, s24, v172
	s_add_i32 s25, 0, 0x1c000
	ds_read_b128 v[150:153], v138
	ds_read_b128 v[154:157], v138 offset:1024
	ds_read_b128 v[158:161], v138 offset:2048
	ds_read_b128 v[162:165], v138 offset:3072
	v_add_u32_e32 v138, s25, v172
	ds_read_b128 v[166:169], v138
	ds_read_b128 v[182:185], v138 offset:1024
	ds_read_b128 v[186:189], v138 offset:2048
	ds_read_b128 v[190:193], v138 offset:3072
	s_add_u32 s16, s16, 0x80000
	s_addc_u32 s17, s17, 0
	s_mov_b32 m0, s63
	v_lshl_add_u64 v[232:233], s[16:17], 0, v[130:131]
	ds_read_b128 v[194:197], v179 offset:32768
	ds_read_b128 v[198:201], v179 offset:33792
	ds_read_b128 v[202:205], v179 offset:34816
	ds_read_b128 v[206:209], v179 offset:35840
	ds_read_b128 v[210:213], v179 offset:36864
	ds_read_b128 v[214:217], v179 offset:37888
	ds_read_b128 v[218:221], v179 offset:38912
	ds_read_b128 v[222:225], v179 offset:39936
	global_load_lds_dwordx4 v[232:233], off
	v_lshl_add_u64 v[232:233], s[16:17], 0, v[134:135]
	s_mov_b32 m0, s65
	s_nop 0
	global_load_lds_dwordx4 v[232:233], off
	s_waitcnt vmcnt(8)
	s_waitcnt lgkmcnt(0)
	s_barrier
	s_setprio 1
	s_waitcnt lgkmcnt(0)
	v_mfma_f32_16x16x32_bf16 v[58:61], v[150:153], v[194:197], v[58:61]
	v_mfma_f32_16x16x32_bf16 v[62:65], v[158:161], v[194:197], v[62:65]
	v_mfma_f32_16x16x32_bf16 v[54:57], v[158:161], v[202:205], v[54:57]
	v_mfma_f32_16x16x32_bf16 v[50:53], v[150:153], v[202:205], v[50:53]
	v_mfma_f32_16x16x32_bf16 v[42:45], v[150:153], v[210:213], v[42:45]
	v_mfma_f32_16x16x32_bf16 v[46:49], v[158:161], v[210:213], v[46:49]
	v_mfma_f32_16x16x32_bf16 v[38:41], v[158:161], v[218:221], v[38:41]
	v_mfma_f32_16x16x32_bf16 v[34:37], v[150:153], v[218:221], v[34:37]
	v_mfma_f32_16x16x32_bf16 v[58:61], v[154:157], v[198:201], v[58:61]
	v_mfma_f32_16x16x32_bf16 v[62:65], v[162:165], v[198:201], v[62:65]
	v_mfma_f32_16x16x32_bf16 v[54:57], v[162:165], v[206:209], v[54:57]
	v_mfma_f32_16x16x32_bf16 v[50:53], v[154:157], v[206:209], v[50:53]
	v_mfma_f32_16x16x32_bf16 v[42:45], v[154:157], v[214:217], v[42:45]
	v_mfma_f32_16x16x32_bf16 v[46:49], v[162:165], v[214:217], v[46:49]
	v_mfma_f32_16x16x32_bf16 v[38:41], v[162:165], v[222:225], v[38:41]
	v_mfma_f32_16x16x32_bf16 v[34:37], v[154:157], v[222:225], v[34:37]
	s_setprio 0
	s_setprio 1
	v_mfma_f32_16x16x32_bf16 v[126:129], v[166:169], v[194:197], v[126:129]
	v_mfma_f32_16x16x32_bf16 v[122:125], v[186:189], v[194:197], v[122:125]
	v_mfma_f32_16x16x32_bf16 v[114:117], v[186:189], v[202:205], v[114:117]
	v_mfma_f32_16x16x32_bf16 v[118:121], v[166:169], v[202:205], v[118:121]
	v_mfma_f32_16x16x32_bf16 v[110:113], v[166:169], v[210:213], v[110:113]
	v_mfma_f32_16x16x32_bf16 v[106:109], v[186:189], v[210:213], v[106:109]
	v_mfma_f32_16x16x32_bf16 v[98:101], v[186:189], v[218:221], v[98:101]
	v_mfma_f32_16x16x32_bf16 v[102:105], v[166:169], v[218:221], v[102:105]
	v_mfma_f32_16x16x32_bf16 v[126:129], v[182:185], v[198:201], v[126:129]
	v_mfma_f32_16x16x32_bf16 v[122:125], v[190:193], v[198:201], v[122:125]
	v_mfma_f32_16x16x32_bf16 v[114:117], v[190:193], v[206:209], v[114:117]
	v_mfma_f32_16x16x32_bf16 v[118:121], v[182:185], v[206:209], v[118:121]
	v_mfma_f32_16x16x32_bf16 v[110:113], v[182:185], v[214:217], v[110:113]
	v_mfma_f32_16x16x32_bf16 v[106:109], v[190:193], v[214:217], v[106:109]
	v_mfma_f32_16x16x32_bf16 v[98:101], v[190:193], v[222:225], v[98:101]
	v_mfma_f32_16x16x32_bf16 v[102:105], v[182:185], v[222:225], v[102:105]
	s_setprio 0
	s_barrier
; #define PG8_STAGE(bufoff, gbase, voff) do { _Pragma("unroll") for (int _i = 0; _i < 2; ++_i) \
;         __builtin_amdgcn_global_load_lds((const unsigned*)((const char*)(gbase) + (voff)[_i]), (PG8_LAS unsigned*)(lds + (bufoff) + ldsw + _i * 8192), 16, 0, 0); } while (0)
; #define PG8_LDA(dst, b, h) do { _Pragma("unroll") for (int m = 0; m < 4; ++m) _Pragma("unroll") for (int k = 0; k < 2; ++k) dst[m][k] = *(const PG8_LAS bf16x8*)(lds + PG8_SA(b, h) + aoff + m * 2048 + k * 1024); } while (0)
; #define PG8_MMA(ai, bj, At, Bt) do { __builtin_amdgcn_s_setprio(1); _Pragma("unroll") for (int m = 0; m < 4; ++m) _Pragma("unroll") for (int n = 0; n < 2; ++n) _Pragma("unroll") for (int k = 0; k < 2; ++k) \
;         acc[ai][bj][m][n] = __builtin_amdgcn_mfma_f32_16x16x32_bf16(Bt[n][k], At[m][k], acc[ai][bj][m][n], 0, 0, 0); __builtin_amdgcn_s_setprio(0); } while (0)
; #define PG8_WAIT_V(n) asm volatile("s_waitcnt vmcnt(" #n ")" ::: "memory")
; #define PG8_WAIT_L(n) asm volatile("s_waitcnt lgkmcnt(" #n ")" ::: "memory")
; #define PG8_BAR __builtin_amdgcn_s_barrier()
; #define PG8_SCHED __builtin_amdgcn_sched_barrier(0)
; template <class Epi, class Sched, bool ALIGN_EPI = false, bool SP2 = false>
; __device__ __forceinline__ void gemm_phase(PG8_LAS unsigned char* lds, const Gemm g, const Sched& S, const Epi& E) {
;     ...
;             PG8_LDA(At, 1, 1); PG8_STAGE(PG8_SB(1, 0), b3, voffB); PG8_STAGE(PG8_SB(1, 1), b3 + hstep, voffB); PG8_STAGE(PG8_SA(1, 0), a3, voffA);
;             PG8_WAIT_V(8); PG8_WAIT_L(0); PG8_BAR; PG8_MMA(1, 0, At, B0); PG8_MMA(1, 1, At, B1); PG8_BAR; PG8_SCHED;
	s_add_i32 s16, s24, s55
	v_lshl_add_u64 v[170:171], v[170:171], 0, s[90:91]
	s_mov_b32 m0, s16
	ds_read_b128 v[194:197], v179 offset:49152
	ds_read_b128 v[198:201], v179 offset:50176
	ds_read_b128 v[202:205], v179 offset:51200
	ds_read_b128 v[206:209], v179 offset:52224
	ds_read_b128 v[210:213], v179 offset:53248
	ds_read_b128 v[214:217], v179 offset:54272
	ds_read_b128 v[218:221], v179 offset:55296
	ds_read_b128 v[222:225], v179 offset:56320
	global_load_lds_dwordx4 v[170:171], off
	s_add_i32 m0, s16, 0x2000
	s_add_u32 s14, s14, 0x80080
	v_lshl_add_u64 v[170:171], v[226:227], 0, s[90:91]
	s_addc_u32 s15, s15, 0
	s_add_i32 s16, s25, s55
	global_load_lds_dwordx4 v[170:171], off
	v_lshl_add_u64 v[170:171], s[14:15], 0, v[132:133]
	s_mov_b32 m0, s16
	s_nop 0
	global_load_lds_dwordx4 v[170:171], off
	v_lshl_add_u64 v[170:171], s[14:15], 0, v[136:137]
	s_add_i32 m0, s16, 0x2000
	s_nop 0
	global_load_lds_dwordx4 v[170:171], off
	v_lshl_add_u64 v[170:171], v[228:229], 0, s[90:91]
	s_mov_b32 m0, s92
	s_nop 0
	global_load_lds_dwordx4 v[170:171], off
	v_lshl_add_u64 v[170:171], v[230:231], 0, s[90:91]
	s_mov_b32 m0, s93
	s_nop 0
	global_load_lds_dwordx4 v[170:171], off
	s_waitcnt vmcnt(8)
	s_waitcnt lgkmcnt(0)
	s_barrier
	s_setprio 1
	s_waitcnt lgkmcnt(0)
	v_mfma_f32_16x16x32_bf16 v[26:29], v[150:153], v[194:197], v[26:29]
	v_mfma_f32_16x16x32_bf16 v[30:33], v[158:161], v[194:197], v[30:33]
	v_mfma_f32_16x16x32_bf16 v[22:25], v[158:161], v[202:205], v[22:25]
	v_mfma_f32_16x16x32_bf16 v[18:21], v[150:153], v[202:205], v[18:21]
	v_mfma_f32_16x16x32_bf16 v[10:13], v[150:153], v[210:213], v[10:13]
	v_mfma_f32_16x16x32_bf16 v[14:17], v[158:161], v[210:213], v[14:17]
	v_mfma_f32_16x16x32_bf16 v[6:9], v[158:161], v[218:221], v[6:9]
	v_mfma_f32_16x16x32_bf16 v[2:5], v[150:153], v[218:221], v[2:5]
	v_mfma_f32_16x16x32_bf16 v[26:29], v[154:157], v[198:201], v[26:29]
	v_mfma_f32_16x16x32_bf16 v[30:33], v[162:165], v[198:201], v[30:33]
	v_mfma_f32_16x16x32_bf16 v[22:25], v[162:165], v[206:209], v[22:25]
	v_mfma_f32_16x16x32_bf16 v[18:21], v[154:157], v[206:209], v[18:21]
	v_mfma_f32_16x16x32_bf16 v[10:13], v[154:157], v[214:217], v[10:13]
	v_mfma_f32_16x16x32_bf16 v[14:17], v[162:165], v[214:217], v[14:17]
	v_mfma_f32_16x16x32_bf16 v[6:9], v[162:165], v[222:225], v[6:9]
	v_mfma_f32_16x16x32_bf16 v[2:5], v[154:157], v[222:225], v[2:5]
	s_setprio 0
	s_setprio 1
	v_mfma_f32_16x16x32_bf16 v[94:97], v[166:169], v[194:197], v[94:97]
	v_mfma_f32_16x16x32_bf16 v[90:93], v[186:189], v[194:197], v[90:93]
	v_mfma_f32_16x16x32_bf16 v[82:85], v[186:189], v[202:205], v[82:85]
	v_mfma_f32_16x16x32_bf16 v[86:89], v[166:169], v[202:205], v[86:89]
	v_mfma_f32_16x16x32_bf16 v[78:81], v[166:169], v[210:213], v[78:81]
	v_mfma_f32_16x16x32_bf16 v[74:77], v[186:189], v[210:213], v[74:77]
	v_mfma_f32_16x16x32_bf16 v[66:69], v[186:189], v[218:221], v[66:69]
	v_mfma_f32_16x16x32_bf16 v[70:73], v[166:169], v[218:221], v[70:73]
	v_mfma_f32_16x16x32_bf16 v[94:97], v[182:185], v[198:201], v[94:97]
	v_mfma_f32_16x16x32_bf16 v[90:93], v[190:193], v[198:201], v[90:93]
	v_mfma_f32_16x16x32_bf16 v[82:85], v[190:193], v[206:209], v[82:85]
	v_mfma_f32_16x16x32_bf16 v[86:89], v[182:185], v[206:209], v[86:89]
	v_mfma_f32_16x16x32_bf16 v[78:81], v[182:185], v[214:217], v[78:81]
	v_mfma_f32_16x16x32_bf16 v[74:77], v[190:193], v[214:217], v[74:77]
	v_mfma_f32_16x16x32_bf16 v[66:69], v[190:193], v[222:225], v[66:69]
	v_mfma_f32_16x16x32_bf16 v[70:73], v[182:185], v[222:225], v[70:73]
	s_setprio 0
	s_barrier
	s_add_i32 s23, s23, 2
	s_add_u32 s10, s10, 0x100
	s_addc_u32 s11, s11, 0
	s_add_u32 s19, s19, 0x100
	s_addc_u32 s22, s22, 0
	s_cmp_gt_u32 s23, 29
	s_cbranch_scc0 .LBB0_346
	v_readlane_b32 s6, v244, 18
	v_readlane_b32 s7, v244, 19
	s_and_b64 vcc, exec, s[6:7]
	s_cbranch_vccnz .LBB0_351
	s_ashr_i32 s13, s12, 3
	s_cmp_lg_u32 s13, 7
	s_mov_b64 s[6:7], -1
	s_cbranch_scc1 .LBB0_352

;     __device__ bool next(int i, Unit& u) const { if (!s.next(i, u)) return false; const int p = u.pn; u.pn = p < 56 ? (p % 7) * 8 + p / 7 : p; return true; }
;     __device__ bool next(int i, Unit& u) const { Unit t; if (!s.next(i >> 1, t)) return false; const int pass = i & 1; u.pm = t.pm + pass * (M / BM); u.pn = t.pn + pass * (D / BM); u.kt0 = 0; return true; }
; #define PG8_STAGE(bufoff, gbase, voff) do { _Pragma("unroll") for (int _i = 0; _i < 2; ++_i) \
;         __builtin_amdgcn_global_load_lds((const unsigned*)((const char*)(gbase) + (voff)[_i]), (PG8_LAS unsigned*)(lds + (bufoff) + ldsw + _i * 8192), 16, 0, 0); } while (0)
; #define PG8_LDA(dst, b, h) do { _Pragma("unroll") for (int m = 0; m < 4; ++m) _Pragma("unroll") for (int k = 0; k < 2; ++k) dst[m][k] = *(const PG8_LAS bf16x8*)(lds + PG8_SA(b, h) + aoff + m * 2048 + k * 1024); } while (0)
; template <class Epi, class Sched, bool ALIGN_EPI = false, bool SP2 = false>
; __device__ __forceinline__ void gemm_phase(PG8_LAS unsigned char* lds, const Gemm g, const Sched& S, const Epi& E) {
;     ...
;         const bool has_next = S.next(ui + 1, nxt);
;         const char* nA = has_next ? (const char*)g.A + (size_t)nxt.pm * tstep + (size_t)nxt.kt0 * kstep : cA; const char* nB = has_next ? (const char*)g.Bt + (size_t)nxt.pn * tstep + (size_t)nxt.kt0 * kstep : cB;
;         for (int t = 0; t < nt; t += 2) {
;             if constexpr (Epi::MIDHOOK) { if (t == (nt >> 1)) E.mid(acc, cur, wr, wc, fr, fq); }
;             const bool last = (t == nt - 2);
;             const char* a1 = cA + (size_t)(t + 1) * kstep;
;             const char* a2 = last ? nA : cA + (size_t)(t + 2) * kstep; const char* b2 = last ? nB : cB + (size_t)(t + 2) * kstep;
;             const char* a3 = a2 + kstep; const char* b3 = b2 + kstep;
;             if (last && has_next) S.a_ready(nxt);
;             if constexpr (SP2) {
;             PG8_LDB(B0, 0, 0); PG8_LDB(B1, 0, 1); PG8_SCHED; PG8_LDA(At, 0, 0); PG8_STAGE(PG8_SA(1, 1), a1 + hstep, voffA);
;             PG8_WAIT_V(8); PG8_WAIT_L(0); PG8_BAR; PG8_MMA(0, 0, At, B0); PG8_MMA(0, 1, At, B1); PG8_BAR; PG8_SCHED;
;             PG8_LDA(At, 0, 1); PG8_STAGE(PG8_SB(0, 0), b2, voffB); PG8_STAGE(PG8_SB(0, 1), b2 + hstep, voffB); PG8_STAGE(PG8_SA(0, 0), a2, voffA);
;             PG8_WAIT_V(8); PG8_WAIT_L(0); PG8_BAR; PG8_MMA(1, 0, At, B0); PG8_MMA(1, 1, At, B1); PG8_BAR; PG8_SCHED;
.LBB0_1199:
	s_add_u32 s36, s28, s30
	s_addc_u32 s37, s29, s31
	s_add_u32 s36, s36, 0x100
	s_addc_u32 s37, s37, 0
	s_add_u32 s44, s59, s30
	s_addc_u32 s45, s60, s31
	s_add_i32 s62, 0, 0x10000
	v_add_u32_e32 v146, s62, v161
	ds_read_b128 v[130:133], v146
	ds_read_b128 v[134:137], v146 offset:1024
	ds_read_b128 v[166:169], v146 offset:2048
	ds_read_b128 v[170:173], v146 offset:3072
	v_add_u32_e32 v146, s54, v161
	ds_read_b128 v[174:177], v146
	ds_read_b128 v[178:181], v146 offset:1024
	ds_read_b128 v[182:185], v146 offset:2048
	ds_read_b128 v[186:189], v146 offset:3072
	s_cmpk_eq_i32 s30, 0x1f00
	s_cselect_b32 s39, s21, s37
	s_cselect_b32 s38, s55, s36
	s_cselect_b32 s37, s56, s45
	s_cselect_b32 s36, s57, s44
	v_lshl_add_u64 v[222:223], v[156:157], 0, s[30:31]
	s_add_i32 m0, s27, 0xc000
	ds_read_b128 v[190:193], v164
	ds_read_b128 v[194:197], v164 offset:1024
	ds_read_b128 v[198:201], v164 offset:2048
	ds_read_b128 v[202:205], v164 offset:3072
	ds_read_b128 v[206:209], v164 offset:4096
	ds_read_b128 v[210:213], v164 offset:5120
	ds_read_b128 v[214:217], v164 offset:6144
	ds_read_b128 v[218:221], v164 offset:7168
	global_load_lds_dwordx4 v[222:223], off
	v_lshl_add_u64 v[222:223], v[158:159], 0, s[30:31]
	s_add_i32 m0, s27, 0xe000
	s_nop 0
	global_load_lds_dwordx4 v[222:223], off
	s_waitcnt vmcnt(8)
	s_waitcnt lgkmcnt(0)
	s_barrier
	s_setprio 1
	s_waitcnt lgkmcnt(0)
	v_mfma_f32_16x16x32_bf16 v[126:129], v[130:133], v[190:193], v[126:129]
	v_mfma_f32_16x16x32_bf16 v[122:125], v[166:169], v[190:193], v[122:125]
	v_mfma_f32_16x16x32_bf16 v[106:109], v[166:169], v[198:201], v[106:109]
	v_mfma_f32_16x16x32_bf16 v[110:113], v[130:133], v[198:201], v[110:113]
	v_mfma_f32_16x16x32_bf16 v[94:97], v[130:133], v[206:209], v[94:97]
	v_mfma_f32_16x16x32_bf16 v[90:93], v[166:169], v[206:209], v[90:93]
	v_mfma_f32_16x16x32_bf16 v[74:77], v[166:169], v[214:217], v[74:77]
	v_mfma_f32_16x16x32_bf16 v[78:81], v[130:133], v[214:217], v[78:81]
	v_mfma_f32_16x16x32_bf16 v[126:129], v[134:137], v[194:197], v[126:129]
	v_mfma_f32_16x16x32_bf16 v[122:125], v[170:173], v[194:197], v[122:125]
	v_mfma_f32_16x16x32_bf16 v[106:109], v[170:173], v[202:205], v[106:109]
	v_mfma_f32_16x16x32_bf16 v[110:113], v[134:137], v[202:205], v[110:113]
	v_mfma_f32_16x16x32_bf16 v[94:97], v[134:137], v[210:213], v[94:97]
	v_mfma_f32_16x16x32_bf16 v[90:93], v[170:173], v[210:213], v[90:93]
	v_mfma_f32_16x16x32_bf16 v[74:77], v[170:173], v[218:221], v[74:77]
	v_mfma_f32_16x16x32_bf16 v[78:81], v[134:137], v[218:221], v[78:81]
	s_setprio 0
	s_setprio 1
	v_mfma_f32_16x16x32_bf16 v[118:121], v[174:177], v[190:193], v[118:121]
	v_mfma_f32_16x16x32_bf16 v[114:117], v[182:185], v[190:193], v[114:117]
	v_mfma_f32_16x16x32_bf16 v[98:101], v[182:185], v[198:201], v[98:101]
	v_mfma_f32_16x16x32_bf16 v[102:105], v[174:177], v[198:201], v[102:105]
	v_mfma_f32_16x16x32_bf16 v[86:89], v[174:177], v[206:209], v[86:89]
	v_mfma_f32_16x16x32_bf16 v[82:85], v[182:185], v[206:209], v[82:85]
	v_mfma_f32_16x16x32_bf16 v[66:69], v[182:185], v[214:217], v[66:69]
	v_mfma_f32_16x16x32_bf16 v[70:73], v[174:177], v[214:217], v[70:73]
	v_mfma_f32_16x16x32_bf16 v[118:121], v[178:181], v[194:197], v[118:121]
	v_mfma_f32_16x16x32_bf16 v[114:117], v[186:189], v[194:197], v[114:117]
	v_mfma_f32_16x16x32_bf16 v[98:101], v[186:189], v[202:205], v[98:101]
	v_mfma_f32_16x16x32_bf16 v[102:105], v[178:181], v[202:205], v[102:105]
	v_mfma_f32_16x16x32_bf16 v[86:89], v[178:181], v[210:213], v[86:89]
	v_mfma_f32_16x16x32_bf16 v[82:85], v[186:189], v[210:213], v[82:85]
	v_mfma_f32_16x16x32_bf16 v[66:69], v[186:189], v[218:221], v[66:69]
	v_mfma_f32_16x16x32_bf16 v[70:73], v[178:181], v[218:221], v[70:73]
	s_setprio 0
	s_barrier
	s_add_i32 s44, s62, s42
	v_lshl_add_u64 v[222:223], s[36:37], 0, v[142:143]
	s_mov_b32 m0, s44
	ds_read_b128 v[190:193], v164 offset:16384
	ds_read_b128 v[194:197], v164 offset:17408
	ds_read_b128 v[198:201], v164 offset:18432
	ds_read_b128 v[202:205], v164 offset:19456
	ds_read_b128 v[206:209], v164 offset:20480
	ds_read_b128 v[210:213], v164 offset:21504
	ds_read_b128 v[214:217], v164 offset:22528
	ds_read_b128 v[218:221], v164 offset:23552
	global_load_lds_dwordx4 v[222:223], off
	s_add_i32 m0, s44, 0x2000
	s_add_u32 s44, s36, 0x100000
	v_lshl_add_u64 v[224:225], s[36:37], 0, v[138:139]
	s_addc_u32 s45, s37, 0
	s_add_i32 s62, s54, s42
	global_load_lds_dwordx4 v[224:225], off
	v_lshl_add_u64 v[226:227], s[44:45], 0, v[142:143]
	s_mov_b32 m0, s62
	v_lshl_add_u64 v[228:229], s[38:39], 0, v[140:141]
	global_load_lds_dwordx4 v[226:227], off
	v_lshl_add_u64 v[226:227], s[44:45], 0, v[138:139]
	s_add_i32 m0, s62, 0x2000
	s_nop 0
	global_load_lds_dwordx4 v[226:227], off
	v_lshl_add_u64 v[226:227], s[38:39], 0, v[144:145]
	s_mov_b32 m0, s27
	s_nop 0
	global_load_lds_dwordx4 v[226:227], off
	s_mov_b32 m0, s46
	s_nop 0
	global_load_lds_dwordx4 v[228:229], off
	s_waitcnt vmcnt(8)
	s_waitcnt lgkmcnt(0)
	s_barrier
; #define PG8_STAGE(bufoff, gbase, voff) do { _Pragma("unroll") for (int _i = 0; _i < 2; ++_i) \
;         __builtin_amdgcn_global_load_lds((const unsigned*)((const char*)(gbase) + (voff)[_i]), (PG8_LAS unsigned*)(lds + (bufoff) + ldsw + _i * 8192), 16, 0, 0); } while (0)
; #define PG8_LDA(dst, b, h) do { _Pragma("unroll") for (int m = 0; m < 4; ++m) _Pragma("unroll") for (int k = 0; k < 2; ++k) dst[m][k] = *(const PG8_LAS bf16x8*)(lds + PG8_SA(b, h) + aoff + m * 2048 + k * 1024); } while (0)
; #define PG8_LDB(dst, b, h) do { _Pragma("unroll") for (int n = 0; n < 2; ++n) _Pragma("unroll") for (int k = 0; k < 2; ++k) dst[n][k] = *(const PG8_LAS bf16x8*)(lds + PG8_SB(b, h) + boff + n * 2048 + k * 1024); } while (0)
; #define PG8_MMA(ai, bj, At, Bt) do { __builtin_amdgcn_s_setprio(1); _Pragma("unroll") for (int m = 0; m < 4; ++m) _Pragma("unroll") for (int n = 0; n < 2; ++n) _Pragma("unroll") for (int k = 0; k < 2; ++k) \
;         acc[ai][bj][m][n] = __builtin_amdgcn_mfma_f32_16x16x32_bf16(Bt[n][k], At[m][k], acc[ai][bj][m][n], 0, 0, 0); __builtin_amdgcn_s_setprio(0); } while (0)
; #define PG8_WAIT_V(n) asm volatile("s_waitcnt vmcnt(" #n ")" ::: "memory")
; #define PG8_WAIT_L(n) asm volatile("s_waitcnt lgkmcnt(" #n ")" ::: "memory")
; #define PG8_BAR __builtin_amdgcn_s_barrier()
; #define PG8_SCHED __builtin_amdgcn_sched_barrier(0)
; template <class Epi, class Sched, bool ALIGN_EPI = false, bool SP2 = false>
; __device__ __forceinline__ void gemm_phase(PG8_LAS unsigned char* lds, const Gemm g, const Sched& S, const Epi& E) {
;     ...
;             PG8_WAIT_V(8); PG8_WAIT_L(0); PG8_BAR; PG8_MMA(1, 0, At, B0); PG8_MMA(1, 1, At, B1); PG8_BAR; PG8_SCHED;
;             PG8_LDB(B0, 1, 0); PG8_LDB(B1, 1, 1); PG8_SCHED; PG8_LDA(At, 1, 0); PG8_STAGE(PG8_SA(0, 1), a2 + hstep, voffA);
;             PG8_WAIT_V(8); PG8_WAIT_L(0); PG8_BAR; PG8_MMA(0, 0, At, B0); PG8_MMA(0, 1, At, B1); PG8_BAR; PG8_SCHED;
	s_setprio 1
	s_waitcnt lgkmcnt(0)
	v_mfma_f32_16x16x32_bf16 v[62:65], v[130:133], v[190:193], v[62:65]
	v_mfma_f32_16x16x32_bf16 v[58:61], v[166:169], v[190:193], v[58:61]
	v_mfma_f32_16x16x32_bf16 v[42:45], v[166:169], v[198:201], v[42:45]
	v_mfma_f32_16x16x32_bf16 v[46:49], v[130:133], v[198:201], v[46:49]
	v_mfma_f32_16x16x32_bf16 v[30:33], v[130:133], v[206:209], v[30:33]
	v_mfma_f32_16x16x32_bf16 v[26:29], v[166:169], v[206:209], v[26:29]
	v_mfma_f32_16x16x32_bf16 v[10:13], v[166:169], v[214:217], v[10:13]
	v_mfma_f32_16x16x32_bf16 v[14:17], v[130:133], v[214:217], v[14:17]
	v_mfma_f32_16x16x32_bf16 v[62:65], v[134:137], v[194:197], v[62:65]
	v_mfma_f32_16x16x32_bf16 v[58:61], v[170:173], v[194:197], v[58:61]
	v_mfma_f32_16x16x32_bf16 v[42:45], v[170:173], v[202:205], v[42:45]
	v_mfma_f32_16x16x32_bf16 v[46:49], v[134:137], v[202:205], v[46:49]
	v_mfma_f32_16x16x32_bf16 v[30:33], v[134:137], v[210:213], v[30:33]
	v_mfma_f32_16x16x32_bf16 v[26:29], v[170:173], v[210:213], v[26:29]
	v_mfma_f32_16x16x32_bf16 v[10:13], v[170:173], v[218:221], v[10:13]
	v_mfma_f32_16x16x32_bf16 v[14:17], v[134:137], v[218:221], v[14:17]
	s_setprio 0
	s_setprio 1
	v_mfma_f32_16x16x32_bf16 v[54:57], v[174:177], v[190:193], v[54:57]
	v_mfma_f32_16x16x32_bf16 v[50:53], v[182:185], v[190:193], v[50:53]
	v_mfma_f32_16x16x32_bf16 v[34:37], v[182:185], v[198:201], v[34:37]
	v_mfma_f32_16x16x32_bf16 v[38:41], v[174:177], v[198:201], v[38:41]
	v_mfma_f32_16x16x32_bf16 v[22:25], v[174:177], v[206:209], v[22:25]
	v_mfma_f32_16x16x32_bf16 v[18:21], v[182:185], v[206:209], v[18:21]
	v_mfma_f32_16x16x32_bf16 v[2:5], v[182:185], v[214:217], v[2:5]
	v_mfma_f32_16x16x32_bf16 v[6:9], v[174:177], v[214:217], v[6:9]
	v_mfma_f32_16x16x32_bf16 v[54:57], v[178:181], v[194:197], v[54:57]
	v_mfma_f32_16x16x32_bf16 v[50:53], v[186:189], v[194:197], v[50:53]
	v_mfma_f32_16x16x32_bf16 v[34:37], v[186:189], v[202:205], v[34:37]
	v_mfma_f32_16x16x32_bf16 v[38:41], v[178:181], v[202:205], v[38:41]
	v_mfma_f32_16x16x32_bf16 v[22:25], v[178:181], v[210:213], v[22:25]
	v_mfma_f32_16x16x32_bf16 v[18:21], v[186:189], v[210:213], v[18:21]
	v_mfma_f32_16x16x32_bf16 v[2:5], v[186:189], v[218:221], v[2:5]
	v_mfma_f32_16x16x32_bf16 v[6:9], v[178:181], v[218:221], v[6:9]
	s_setprio 0
	s_barrier
	s_add_i32 s44, 0, 0x18000
	v_add_u32_e32 v146, s44, v161
	s_add_i32 s45, 0, 0x1c000
	ds_read_b128 v[130:133], v146
	ds_read_b128 v[134:137], v146 offset:1024
	ds_read_b128 v[166:169], v146 offset:2048
	ds_read_b128 v[170:173], v146 offset:3072
	v_add_u32_e32 v146, s45, v161
	ds_read_b128 v[174:177], v146
	ds_read_b128 v[178:181], v146 offset:1024
	ds_read_b128 v[182:185], v146 offset:2048
	ds_read_b128 v[186:189], v146 offset:3072
	s_add_u32 s38, s38, 0x100000
	s_addc_u32 s39, s39, 0
	s_mov_b32 m0, s47
	v_lshl_add_u64 v[230:231], s[38:39], 0, v[144:145]
	ds_read_b128 v[190:193], v164 offset:32768
	ds_read_b128 v[194:197], v164 offset:33792
	ds_read_b128 v[198:201], v164 offset:34816
	ds_read_b128 v[202:205], v164 offset:35840
	ds_read_b128 v[206:209], v164 offset:36864
	ds_read_b128 v[210:213], v164 offset:37888
	ds_read_b128 v[214:217], v164 offset:38912
	ds_read_b128 v[218:221], v164 offset:39936
	global_load_lds_dwordx4 v[230:231], off
	v_lshl_add_u64 v[230:231], s[38:39], 0, v[140:141]
	s_mov_b32 m0, s48
	s_nop 0
	global_load_lds_dwordx4 v[230:231], off
	s_waitcnt vmcnt(8)
	s_waitcnt lgkmcnt(0)
	s_barrier
	s_setprio 1
	s_waitcnt lgkmcnt(0)
	v_mfma_f32_16x16x32_bf16 v[126:129], v[130:133], v[190:193], v[126:129]
	v_mfma_f32_16x16x32_bf16 v[122:125], v[166:169], v[190:193], v[122:125]
	v_mfma_f32_16x16x32_bf16 v[106:109], v[166:169], v[198:201], v[106:109]
	v_mfma_f32_16x16x32_bf16 v[110:113], v[130:133], v[198:201], v[110:113]
	v_mfma_f32_16x16x32_bf16 v[94:97], v[130:133], v[206:209], v[94:97]
	v_mfma_f32_16x16x32_bf16 v[90:93], v[166:169], v[206:209], v[90:93]
	v_mfma_f32_16x16x32_bf16 v[74:77], v[166:169], v[214:217], v[74:77]
	v_mfma_f32_16x16x32_bf16 v[78:81], v[130:133], v[214:217], v[78:81]
	v_mfma_f32_16x16x32_bf16 v[126:129], v[134:137], v[194:197], v[126:129]
	v_mfma_f32_16x16x32_bf16 v[122:125], v[170:173], v[194:197], v[122:125]
	v_mfma_f32_16x16x32_bf16 v[106:109], v[170:173], v[202:205], v[106:109]
	v_mfma_f32_16x16x32_bf16 v[110:113], v[134:137], v[202:205], v[110:113]
	v_mfma_f32_16x16x32_bf16 v[94:97], v[134:137], v[210:213], v[94:97]
	v_mfma_f32_16x16x32_bf16 v[90:93], v[170:173], v[210:213], v[90:93]
	v_mfma_f32_16x16x32_bf16 v[74:77], v[170:173], v[218:221], v[74:77]
	v_mfma_f32_16x16x32_bf16 v[78:81], v[134:137], v[218:221], v[78:81]
	s_setprio 0
	s_setprio 1
	v_mfma_f32_16x16x32_bf16 v[118:121], v[174:177], v[190:193], v[118:121]
	v_mfma_f32_16x16x32_bf16 v[114:117], v[182:185], v[190:193], v[114:117]
	v_mfma_f32_16x16x32_bf16 v[98:101], v[182:185], v[198:201], v[98:101]
	v_mfma_f32_16x16x32_bf16 v[102:105], v[174:177], v[198:201], v[102:105]
	v_mfma_f32_16x16x32_bf16 v[86:89], v[174:177], v[206:209], v[86:89]
	v_mfma_f32_16x16x32_bf16 v[82:85], v[182:185], v[206:209], v[82:85]
	v_mfma_f32_16x16x32_bf16 v[66:69], v[182:185], v[214:217], v[66:69]
	v_mfma_f32_16x16x32_bf16 v[70:73], v[174:177], v[214:217], v[70:73]
	v_mfma_f32_16x16x32_bf16 v[118:121], v[178:181], v[194:197], v[118:121]
	v_mfma_f32_16x16x32_bf16 v[114:117], v[186:189], v[194:197], v[114:117]
	v_mfma_f32_16x16x32_bf16 v[98:101], v[186:189], v[202:205], v[98:101]
	v_mfma_f32_16x16x32_bf16 v[102:105], v[178:181], v[202:205], v[102:105]
	v_mfma_f32_16x16x32_bf16 v[86:89], v[178:181], v[210:213], v[86:89]
	v_mfma_f32_16x16x32_bf16 v[82:85], v[186:189], v[210:213], v[82:85]
	v_mfma_f32_16x16x32_bf16 v[66:69], v[186:189], v[218:221], v[66:69]
	v_mfma_f32_16x16x32_bf16 v[70:73], v[178:181], v[218:221], v[70:73]
	s_setprio 0
	s_barrier
; #define PG8_STAGE(bufoff, gbase, voff) do { _Pragma("unroll") for (int _i = 0; _i < 2; ++_i) \
;         __builtin_amdgcn_global_load_lds((const unsigned*)((const char*)(gbase) + (voff)[_i]), (PG8_LAS unsigned*)(lds + (bufoff) + ldsw + _i * 8192), 16, 0, 0); } while (0)
; #define PG8_LDA(dst, b, h) do { _Pragma("unroll") for (int m = 0; m < 4; ++m) _Pragma("unroll") for (int k = 0; k < 2; ++k) dst[m][k] = *(const PG8_LAS bf16x8*)(lds + PG8_SA(b, h) + aoff + m * 2048 + k * 1024); } while (0)
; #define PG8_MMA(ai, bj, At, Bt) do { __builtin_amdgcn_s_setprio(1); _Pragma("unroll") for (int m = 0; m < 4; ++m) _Pragma("unroll") for (int n = 0; n < 2; ++n) _Pragma("unroll") for (int k = 0; k < 2; ++k) \
;         acc[ai][bj][m][n] = __builtin_amdgcn_mfma_f32_16x16x32_bf16(Bt[n][k], At[m][k], acc[ai][bj][m][n], 0, 0, 0); __builtin_amdgcn_s_setprio(0); } while (0)
; #define PG8_WAIT_V(n) asm volatile("s_waitcnt vmcnt(" #n ")" ::: "memory")
; #define PG8_WAIT_L(n) asm volatile("s_waitcnt lgkmcnt(" #n ")" ::: "memory")
; #define PG8_BAR __builtin_amdgcn_s_barrier()
; #define PG8_SCHED __builtin_amdgcn_sched_barrier(0)
; template <class Epi, class Sched, bool ALIGN_EPI = false, bool SP2 = false>
; __device__ __forceinline__ void gemm_phase(PG8_LAS unsigned char* lds, const Gemm g, const Sched& S, const Epi& E) {
;     ...
;             PG8_LDA(At, 1, 1); PG8_STAGE(PG8_SB(1, 0), b3, voffB); PG8_STAGE(PG8_SB(1, 1), b3 + hstep, voffB); PG8_STAGE(PG8_SA(1, 0), a3, voffA);
;             PG8_WAIT_V(8); PG8_WAIT_L(0); PG8_BAR; PG8_MMA(1, 0, At, B0); PG8_MMA(1, 1, At, B1); PG8_BAR; PG8_SCHED;
	s_add_i32 s38, s44, s42
	v_lshl_add_u64 v[222:223], v[222:223], 0, s[14:15]
	s_mov_b32 m0, s38
	ds_read_b128 v[190:193], v164 offset:49152
	ds_read_b128 v[194:197], v164 offset:50176
	ds_read_b128 v[198:201], v164 offset:51200
	ds_read_b128 v[202:205], v164 offset:52224
	ds_read_b128 v[206:209], v164 offset:53248
	ds_read_b128 v[210:213], v164 offset:54272
	ds_read_b128 v[214:217], v164 offset:55296
	ds_read_b128 v[218:221], v164 offset:56320
	global_load_lds_dwordx4 v[222:223], off
	s_add_i32 m0, s38, 0x2000
	s_add_u32 s36, s36, 0x100080
	v_lshl_add_u64 v[222:223], v[224:225], 0, s[14:15]
	s_addc_u32 s37, s37, 0
	s_add_i32 s38, s45, s42
	global_load_lds_dwordx4 v[222:223], off
	v_lshl_add_u64 v[222:223], s[36:37], 0, v[142:143]
	s_mov_b32 m0, s38
	s_nop 0
	global_load_lds_dwordx4 v[222:223], off
	v_lshl_add_u64 v[222:223], s[36:37], 0, v[138:139]
	s_add_i32 m0, s38, 0x2000
	s_nop 0
	global_load_lds_dwordx4 v[222:223], off
	v_lshl_add_u64 v[222:223], v[226:227], 0, s[14:15]
	s_mov_b32 m0, s51
	s_nop 0
	global_load_lds_dwordx4 v[222:223], off
	v_lshl_add_u64 v[222:223], v[228:229], 0, s[14:15]
	s_mov_b32 m0, s52
	s_nop 0
	global_load_lds_dwordx4 v[222:223], off
	s_waitcnt vmcnt(8)
	s_waitcnt lgkmcnt(0)
	s_barrier
	s_setprio 1
	s_waitcnt lgkmcnt(0)
	v_mfma_f32_16x16x32_bf16 v[62:65], v[130:133], v[190:193], v[62:65]
	v_mfma_f32_16x16x32_bf16 v[58:61], v[166:169], v[190:193], v[58:61]
	v_mfma_f32_16x16x32_bf16 v[42:45], v[166:169], v[198:201], v[42:45]
	v_mfma_f32_16x16x32_bf16 v[46:49], v[130:133], v[198:201], v[46:49]
	v_mfma_f32_16x16x32_bf16 v[30:33], v[130:133], v[206:209], v[30:33]
	v_mfma_f32_16x16x32_bf16 v[26:29], v[166:169], v[206:209], v[26:29]
	v_mfma_f32_16x16x32_bf16 v[10:13], v[166:169], v[214:217], v[10:13]
	v_mfma_f32_16x16x32_bf16 v[14:17], v[130:133], v[214:217], v[14:17]
	v_mfma_f32_16x16x32_bf16 v[62:65], v[134:137], v[194:197], v[62:65]
	v_mfma_f32_16x16x32_bf16 v[58:61], v[170:173], v[194:197], v[58:61]
	v_mfma_f32_16x16x32_bf16 v[42:45], v[170:173], v[202:205], v[42:45]
	v_mfma_f32_16x16x32_bf16 v[46:49], v[134:137], v[202:205], v[46:49]
	v_mfma_f32_16x16x32_bf16 v[30:33], v[134:137], v[210:213], v[30:33]
	v_mfma_f32_16x16x32_bf16 v[26:29], v[170:173], v[210:213], v[26:29]
	v_mfma_f32_16x16x32_bf16 v[10:13], v[170:173], v[218:221], v[10:13]
	v_mfma_f32_16x16x32_bf16 v[14:17], v[134:137], v[218:221], v[14:17]
	s_setprio 0
	s_setprio 1
	v_mfma_f32_16x16x32_bf16 v[54:57], v[174:177], v[190:193], v[54:57]
	v_mfma_f32_16x16x32_bf16 v[50:53], v[182:185], v[190:193], v[50:53]
	v_mfma_f32_16x16x32_bf16 v[34:37], v[182:185], v[198:201], v[34:37]
	v_mfma_f32_16x16x32_bf16 v[38:41], v[174:177], v[198:201], v[38:41]
	v_mfma_f32_16x16x32_bf16 v[22:25], v[174:177], v[206:209], v[22:25]
	v_mfma_f32_16x16x32_bf16 v[18:21], v[182:185], v[206:209], v[18:21]
	v_mfma_f32_16x16x32_bf16 v[2:5], v[182:185], v[214:217], v[2:5]
	v_mfma_f32_16x16x32_bf16 v[6:9], v[174:177], v[214:217], v[6:9]
	v_mfma_f32_16x16x32_bf16 v[54:57], v[178:181], v[194:197], v[54:57]
	v_mfma_f32_16x16x32_bf16 v[50:53], v[186:189], v[194:197], v[50:53]
	v_mfma_f32_16x16x32_bf16 v[34:37], v[186:189], v[202:205], v[34:37]
	v_mfma_f32_16x16x32_bf16 v[38:41], v[178:181], v[202:205], v[38:41]
	v_mfma_f32_16x16x32_bf16 v[22:25], v[178:181], v[210:213], v[22:25]
	v_mfma_f32_16x16x32_bf16 v[18:21], v[186:189], v[210:213], v[18:21]
	v_mfma_f32_16x16x32_bf16 v[2:5], v[186:189], v[218:221], v[2:5]
	v_mfma_f32_16x16x32_bf16 v[6:9], v[178:181], v[218:221], v[6:9]
	s_setprio 0
	s_barrier
	s_add_i32 s61, s61, 2
	s_add_u32 s30, s30, 0x100
	s_addc_u32 s31, s31, 0
	s_cmp_gt_u32 s61, 61
	s_cbranch_scc1 .LBB0_1202

;     __device__ bool next(int i, Unit& u) const { if (!s.next(i, u)) return false; const int p = u.pn; u.pn = p < 56 ? (p % 7) * 8 + p / 7 : p; return true; }
;     __device__ bool next(int i, Unit& u) const { Unit t; if (!s.next(i >> 1, t)) return false; const int pass = i & 1; u.pm = t.pm + pass * (M / BM); u.pn = t.pn + pass * (D / BM); u.kt0 = 0; return true; }
; #define PG8_STAGE(bufoff, gbase, voff) do { _Pragma("unroll") for (int _i = 0; _i < 2; ++_i) \
;         __builtin_amdgcn_global_load_lds((const unsigned*)((const char*)(gbase) + (voff)[_i]), (PG8_LAS unsigned*)(lds + (bufoff) + ldsw + _i * 8192), 16, 0, 0); } while (0)
; #define PG8_LDA(dst, b, h) do { _Pragma("unroll") for (int m = 0; m < 4; ++m) _Pragma("unroll") for (int k = 0; k < 2; ++k) dst[m][k] = *(const PG8_LAS bf16x8*)(lds + PG8_SA(b, h) + aoff + m * 2048 + k * 1024); } while (0)
; template <class Epi, class Sched, bool ALIGN_EPI = false, bool SP2 = false>
; __device__ __forceinline__ void gemm_phase(PG8_LAS unsigned char* lds, const Gemm g, const Sched& S, const Epi& E) {
;     ...
;         const bool has_next = S.next(ui + 1, nxt);
;         const char* nA = has_next ? (const char*)g.A + (size_t)nxt.pm * tstep + (size_t)nxt.kt0 * kstep : cA; const char* nB = has_next ? (const char*)g.Bt + (size_t)nxt.pn * tstep + (size_t)nxt.kt0 * kstep : cB;
;         for (int t = 0; t < nt; t += 2) {
;             if constexpr (Epi::MIDHOOK) { if (t == (nt >> 1)) E.mid(acc, cur, wr, wc, fr, fq); }
;             const bool last = (t == nt - 2);
;             const char* a1 = cA + (size_t)(t + 1) * kstep;
;             const char* a2 = last ? nA : cA + (size_t)(t + 2) * kstep; const char* b2 = last ? nB : cB + (size_t)(t + 2) * kstep;
;             const char* a3 = a2 + kstep; const char* b3 = b2 + kstep;
;             if (last && has_next) S.a_ready(nxt);
;             if constexpr (SP2) {
;             PG8_LDB(B0, 0, 0); PG8_LDB(B1, 0, 1); PG8_SCHED; PG8_LDA(At, 0, 0); PG8_STAGE(PG8_SA(1, 1), a1 + hstep, voffA);
;             PG8_WAIT_V(8); PG8_WAIT_L(0); PG8_BAR; PG8_MMA(0, 0, At, B0); PG8_MMA(0, 1, At, B1); PG8_BAR; PG8_SCHED;
;             PG8_LDA(At, 0, 1); PG8_STAGE(PG8_SB(0, 0), b2, voffB); PG8_STAGE(PG8_SB(0, 1), b2 + hstep, voffB); PG8_STAGE(PG8_SA(0, 0), a2, voffA);
;             PG8_WAIT_V(8); PG8_WAIT_L(0); PG8_BAR; PG8_MMA(1, 0, At, B0); PG8_MMA(1, 1, At, B1); PG8_BAR; PG8_SCHED;
.LBB0_1219:
	ds_read_b128 v[138:141], v147
	ds_read_b128 v[150:153], v147 offset:1024
	ds_read_b128 v[154:157], v147 offset:2048
	ds_read_b128 v[158:161], v147 offset:3072
	ds_read_b128 v[162:165], v148
	ds_read_b128 v[166:169], v148 offset:1024
	ds_read_b128 v[170:173], v148 offset:2048
	ds_read_b128 v[174:177], v148 offset:3072
	s_add_u32 s36, s30, 0xfff00080
	s_addc_u32 s37, s31, -1
	s_cmp_eq_u32 s61, 4
	s_cselect_b32 s39, s11, s37
	s_cselect_b32 s38, s21, s36
	s_cselect_b32 s37, s23, s60
	s_cselect_b32 s36, s58, s59
	v_lshl_add_u64 v[142:143], s[30:31], 0, v[134:135]
	s_add_i32 m0, s45, 0xc000
	ds_read_b128 v[178:181], v149
	ds_read_b128 v[182:185], v149 offset:1024
	ds_read_b128 v[186:189], v149 offset:2048
	ds_read_b128 v[190:193], v149 offset:3072
	ds_read_b128 v[194:197], v149 offset:4096
	ds_read_b128 v[198:201], v149 offset:5120
	ds_read_b128 v[202:205], v149 offset:6144
	ds_read_b128 v[206:209], v149 offset:7168
	global_load_lds_dwordx4 v[142:143], off
	v_lshl_add_u64 v[142:143], s[30:31], 0, v[136:137]
	s_add_i32 m0, s45, 0xe000
	s_nop 0
	global_load_lds_dwordx4 v[142:143], off
	s_waitcnt vmcnt(8)
	s_waitcnt lgkmcnt(0)
	s_barrier
	s_setprio 1
	s_waitcnt lgkmcnt(0)
	v_mfma_f32_16x16x32_bf16 v[126:129], v[138:141], v[178:181], v[126:129]
	v_mfma_f32_16x16x32_bf16 v[122:125], v[154:157], v[178:181], v[122:125]
	v_mfma_f32_16x16x32_bf16 v[106:109], v[154:157], v[186:189], v[106:109]
	v_mfma_f32_16x16x32_bf16 v[110:113], v[138:141], v[186:189], v[110:113]
	v_mfma_f32_16x16x32_bf16 v[94:97], v[138:141], v[194:197], v[94:97]
	v_mfma_f32_16x16x32_bf16 v[90:93], v[154:157], v[194:197], v[90:93]
	v_mfma_f32_16x16x32_bf16 v[74:77], v[154:157], v[202:205], v[74:77]
	v_mfma_f32_16x16x32_bf16 v[78:81], v[138:141], v[202:205], v[78:81]
	v_mfma_f32_16x16x32_bf16 v[126:129], v[150:153], v[182:185], v[126:129]
	v_mfma_f32_16x16x32_bf16 v[122:125], v[158:161], v[182:185], v[122:125]
	v_mfma_f32_16x16x32_bf16 v[106:109], v[158:161], v[190:193], v[106:109]
	v_mfma_f32_16x16x32_bf16 v[110:113], v[150:153], v[190:193], v[110:113]
	v_mfma_f32_16x16x32_bf16 v[94:97], v[150:153], v[198:201], v[94:97]
	v_mfma_f32_16x16x32_bf16 v[90:93], v[158:161], v[198:201], v[90:93]
	v_mfma_f32_16x16x32_bf16 v[74:77], v[158:161], v[206:209], v[74:77]
	v_mfma_f32_16x16x32_bf16 v[78:81], v[150:153], v[206:209], v[78:81]
	s_setprio 0
	s_setprio 1
	v_mfma_f32_16x16x32_bf16 v[118:121], v[162:165], v[178:181], v[118:121]
	v_mfma_f32_16x16x32_bf16 v[114:117], v[170:173], v[178:181], v[114:117]
	v_mfma_f32_16x16x32_bf16 v[98:101], v[170:173], v[186:189], v[98:101]
	v_mfma_f32_16x16x32_bf16 v[102:105], v[162:165], v[186:189], v[102:105]
	v_mfma_f32_16x16x32_bf16 v[86:89], v[162:165], v[194:197], v[86:89]
	v_mfma_f32_16x16x32_bf16 v[82:85], v[170:173], v[194:197], v[82:85]
	v_mfma_f32_16x16x32_bf16 v[66:69], v[170:173], v[202:205], v[66:69]
	v_mfma_f32_16x16x32_bf16 v[70:73], v[162:165], v[202:205], v[70:73]
	v_mfma_f32_16x16x32_bf16 v[118:121], v[166:169], v[182:185], v[118:121]
	v_mfma_f32_16x16x32_bf16 v[114:117], v[174:177], v[182:185], v[114:117]
	v_mfma_f32_16x16x32_bf16 v[98:101], v[174:177], v[190:193], v[98:101]
	v_mfma_f32_16x16x32_bf16 v[102:105], v[166:169], v[190:193], v[102:105]
	v_mfma_f32_16x16x32_bf16 v[86:89], v[166:169], v[198:201], v[86:89]
	v_mfma_f32_16x16x32_bf16 v[82:85], v[174:177], v[198:201], v[82:85]
	v_mfma_f32_16x16x32_bf16 v[66:69], v[174:177], v[206:209], v[66:69]
	v_mfma_f32_16x16x32_bf16 v[70:73], v[166:169], v[206:209], v[70:73]
	s_setprio 0
	s_barrier
	s_add_i32 s62, s54, s42
	v_lshl_add_u64 v[142:143], s[36:37], 0, v[132:133]
	s_mov_b32 m0, s62
	ds_read_b128 v[178:181], v149 offset:16384
	ds_read_b128 v[182:185], v149 offset:17408
	ds_read_b128 v[186:189], v149 offset:18432
	ds_read_b128 v[190:193], v149 offset:19456
	ds_read_b128 v[194:197], v149 offset:20480
	ds_read_b128 v[198:201], v149 offset:21504
	ds_read_b128 v[202:205], v149 offset:22528
	ds_read_b128 v[206:209], v149 offset:23552
	global_load_lds_dwordx4 v[142:143], off
	s_add_i32 m0, s62, 0x2000
	s_add_u32 s62, s36, 0x100000
	v_lshl_add_u64 v[210:211], s[36:37], 0, v[130:131]
	s_addc_u32 s63, s37, 0
	s_add_i32 s64, s55, s42
	global_load_lds_dwordx4 v[210:211], off
	v_lshl_add_u64 v[212:213], s[62:63], 0, v[132:133]
	s_mov_b32 m0, s64
	v_lshl_add_u64 v[214:215], s[38:39], 0, v[130:131]
	global_load_lds_dwordx4 v[212:213], off
	v_lshl_add_u64 v[212:213], s[62:63], 0, v[130:131]
	s_add_i32 m0, s64, 0x2000
	s_nop 0
	global_load_lds_dwordx4 v[212:213], off
	v_lshl_add_u64 v[212:213], s[38:39], 0, v[132:133]
	s_mov_b32 m0, s45
	s_nop 0
	global_load_lds_dwordx4 v[212:213], off
	s_mov_b32 m0, s46
	s_nop 0
	global_load_lds_dwordx4 v[214:215], off
	s_waitcnt vmcnt(8)
	s_waitcnt lgkmcnt(0)
	s_barrier
; #define PG8_STAGE(bufoff, gbase, voff) do { _Pragma("unroll") for (int _i = 0; _i < 2; ++_i) \
;         __builtin_amdgcn_global_load_lds((const unsigned*)((const char*)(gbase) + (voff)[_i]), (PG8_LAS unsigned*)(lds + (bufoff) + ldsw + _i * 8192), 16, 0, 0); } while (0)
; #define PG8_LDA(dst, b, h) do { _Pragma("unroll") for (int m = 0; m < 4; ++m) _Pragma("unroll") for (int k = 0; k < 2; ++k) dst[m][k] = *(const PG8_LAS bf16x8*)(lds + PG8_SA(b, h) + aoff + m * 2048 + k * 1024); } while (0)
; #define PG8_LDB(dst, b, h) do { _Pragma("unroll") for (int n = 0; n < 2; ++n) _Pragma("unroll") for (int k = 0; k < 2; ++k) dst[n][k] = *(const PG8_LAS bf16x8*)(lds + PG8_SB(b, h) + boff + n * 2048 + k * 1024); } while (0)
; #define PG8_MMA(ai, bj, At, Bt) do { __builtin_amdgcn_s_setprio(1); _Pragma("unroll") for (int m = 0; m < 4; ++m) _Pragma("unroll") for (int n = 0; n < 2; ++n) _Pragma("unroll") for (int k = 0; k < 2; ++k) \
;         acc[ai][bj][m][n] = __builtin_amdgcn_mfma_f32_16x16x32_bf16(Bt[n][k], At[m][k], acc[ai][bj][m][n], 0, 0, 0); __builtin_amdgcn_s_setprio(0); } while (0)
; #define PG8_WAIT_V(n) asm volatile("s_waitcnt vmcnt(" #n ")" ::: "memory")
; #define PG8_WAIT_L(n) asm volatile("s_waitcnt lgkmcnt(" #n ")" ::: "memory")
; #define PG8_BAR __builtin_amdgcn_s_barrier()
; #define PG8_SCHED __builtin_amdgcn_sched_barrier(0)
; template <class Epi, class Sched, bool ALIGN_EPI = false, bool SP2 = false>
; __device__ __forceinline__ void gemm_phase(PG8_LAS unsigned char* lds, const Gemm g, const Sched& S, const Epi& E) {
;     ...
;             PG8_WAIT_V(8); PG8_WAIT_L(0); PG8_BAR; PG8_MMA(1, 0, At, B0); PG8_MMA(1, 1, At, B1); PG8_BAR; PG8_SCHED;
;             PG8_LDB(B0, 1, 0); PG8_LDB(B1, 1, 1); PG8_SCHED; PG8_LDA(At, 1, 0); PG8_STAGE(PG8_SA(0, 1), a2 + hstep, voffA);
;             PG8_WAIT_V(8); PG8_WAIT_L(0); PG8_BAR; PG8_MMA(0, 0, At, B0); PG8_MMA(0, 1, At, B1); PG8_BAR; PG8_SCHED;
	s_setprio 1
	s_waitcnt lgkmcnt(0)
	v_mfma_f32_16x16x32_bf16 v[62:65], v[138:141], v[178:181], v[62:65]
	v_mfma_f32_16x16x32_bf16 v[58:61], v[154:157], v[178:181], v[58:61]
	v_mfma_f32_16x16x32_bf16 v[42:45], v[154:157], v[186:189], v[42:45]
	v_mfma_f32_16x16x32_bf16 v[46:49], v[138:141], v[186:189], v[46:49]
	v_mfma_f32_16x16x32_bf16 v[30:33], v[138:141], v[194:197], v[30:33]
	v_mfma_f32_16x16x32_bf16 v[26:29], v[154:157], v[194:197], v[26:29]
	v_mfma_f32_16x16x32_bf16 v[10:13], v[154:157], v[202:205], v[10:13]
	v_mfma_f32_16x16x32_bf16 v[14:17], v[138:141], v[202:205], v[14:17]
	v_mfma_f32_16x16x32_bf16 v[62:65], v[150:153], v[182:185], v[62:65]
	v_mfma_f32_16x16x32_bf16 v[58:61], v[158:161], v[182:185], v[58:61]
	v_mfma_f32_16x16x32_bf16 v[42:45], v[158:161], v[190:193], v[42:45]
	v_mfma_f32_16x16x32_bf16 v[46:49], v[150:153], v[190:193], v[46:49]
	v_mfma_f32_16x16x32_bf16 v[30:33], v[150:153], v[198:201], v[30:33]
	v_mfma_f32_16x16x32_bf16 v[26:29], v[158:161], v[198:201], v[26:29]
	v_mfma_f32_16x16x32_bf16 v[10:13], v[158:161], v[206:209], v[10:13]
	v_mfma_f32_16x16x32_bf16 v[14:17], v[150:153], v[206:209], v[14:17]
	s_setprio 0
	s_setprio 1
	v_mfma_f32_16x16x32_bf16 v[54:57], v[162:165], v[178:181], v[54:57]
	v_mfma_f32_16x16x32_bf16 v[50:53], v[170:173], v[178:181], v[50:53]
	v_mfma_f32_16x16x32_bf16 v[34:37], v[170:173], v[186:189], v[34:37]
	v_mfma_f32_16x16x32_bf16 v[38:41], v[162:165], v[186:189], v[38:41]
	v_mfma_f32_16x16x32_bf16 v[22:25], v[162:165], v[194:197], v[22:25]
	v_mfma_f32_16x16x32_bf16 v[18:21], v[170:173], v[194:197], v[18:21]
	v_mfma_f32_16x16x32_bf16 v[2:5], v[170:173], v[202:205], v[2:5]
	v_mfma_f32_16x16x32_bf16 v[6:9], v[162:165], v[202:205], v[6:9]
	v_mfma_f32_16x16x32_bf16 v[54:57], v[166:169], v[182:185], v[54:57]
	v_mfma_f32_16x16x32_bf16 v[50:53], v[174:177], v[182:185], v[50:53]
	v_mfma_f32_16x16x32_bf16 v[34:37], v[174:177], v[190:193], v[34:37]
	v_mfma_f32_16x16x32_bf16 v[38:41], v[166:169], v[190:193], v[38:41]
	v_mfma_f32_16x16x32_bf16 v[22:25], v[166:169], v[198:201], v[22:25]
	v_mfma_f32_16x16x32_bf16 v[18:21], v[174:177], v[198:201], v[18:21]
	v_mfma_f32_16x16x32_bf16 v[2:5], v[174:177], v[206:209], v[2:5]
	v_mfma_f32_16x16x32_bf16 v[6:9], v[166:169], v[206:209], v[6:9]
	s_setprio 0
	s_barrier
	s_add_i32 s62, 0, 0x18000
	s_add_i32 s63, 0, 0x1c000
	v_add_u32_e32 v158, s62, v144
	v_add_u32_e32 v174, s63, v144
	ds_read_b128 v[138:141], v158
	ds_read_b128 v[150:153], v158 offset:1024
	ds_read_b128 v[154:157], v158 offset:2048
	ds_read_b128 v[158:161], v158 offset:3072
	ds_read_b128 v[162:165], v174
	ds_read_b128 v[166:169], v174 offset:1024
	ds_read_b128 v[170:173], v174 offset:2048
	ds_read_b128 v[174:177], v174 offset:3072
	s_add_u32 s38, s38, 0x100000
	s_addc_u32 s39, s39, 0
	s_mov_b32 m0, s47
	v_lshl_add_u64 v[216:217], s[38:39], 0, v[132:133]
	ds_read_b128 v[178:181], v149 offset:32768
	ds_read_b128 v[182:185], v149 offset:33792
	ds_read_b128 v[186:189], v149 offset:34816
	ds_read_b128 v[190:193], v149 offset:35840
	ds_read_b128 v[194:197], v149 offset:36864
	ds_read_b128 v[198:201], v149 offset:37888
	ds_read_b128 v[202:205], v149 offset:38912
	ds_read_b128 v[206:209], v149 offset:39936
	global_load_lds_dwordx4 v[216:217], off
	v_lshl_add_u64 v[216:217], s[38:39], 0, v[130:131]
	s_mov_b32 m0, s48
	s_nop 0
	global_load_lds_dwordx4 v[216:217], off
	s_waitcnt vmcnt(8)
	s_waitcnt lgkmcnt(0)
	s_barrier
	s_setprio 1
	s_waitcnt lgkmcnt(0)
	v_mfma_f32_16x16x32_bf16 v[126:129], v[138:141], v[178:181], v[126:129]
	v_mfma_f32_16x16x32_bf16 v[122:125], v[154:157], v[178:181], v[122:125]
	v_mfma_f32_16x16x32_bf16 v[106:109], v[154:157], v[186:189], v[106:109]
	v_mfma_f32_16x16x32_bf16 v[110:113], v[138:141], v[186:189], v[110:113]
	v_mfma_f32_16x16x32_bf16 v[94:97], v[138:141], v[194:197], v[94:97]
	v_mfma_f32_16x16x32_bf16 v[90:93], v[154:157], v[194:197], v[90:93]
	v_mfma_f32_16x16x32_bf16 v[74:77], v[154:157], v[202:205], v[74:77]
	v_mfma_f32_16x16x32_bf16 v[78:81], v[138:141], v[202:205], v[78:81]
	v_mfma_f32_16x16x32_bf16 v[126:129], v[150:153], v[182:185], v[126:129]
	v_mfma_f32_16x16x32_bf16 v[122:125], v[158:161], v[182:185], v[122:125]
	v_mfma_f32_16x16x32_bf16 v[106:109], v[158:161], v[190:193], v[106:109]
	v_mfma_f32_16x16x32_bf16 v[110:113], v[150:153], v[190:193], v[110:113]
	v_mfma_f32_16x16x32_bf16 v[94:97], v[150:153], v[198:201], v[94:97]
	v_mfma_f32_16x16x32_bf16 v[90:93], v[158:161], v[198:201], v[90:93]
	v_mfma_f32_16x16x32_bf16 v[74:77], v[158:161], v[206:209], v[74:77]
	v_mfma_f32_16x16x32_bf16 v[78:81], v[150:153], v[206:209], v[78:81]
	s_setprio 0
	s_setprio 1
	v_mfma_f32_16x16x32_bf16 v[118:121], v[162:165], v[178:181], v[118:121]
	v_mfma_f32_16x16x32_bf16 v[114:117], v[170:173], v[178:181], v[114:117]
	v_mfma_f32_16x16x32_bf16 v[98:101], v[170:173], v[186:189], v[98:101]
	v_mfma_f32_16x16x32_bf16 v[102:105], v[162:165], v[186:189], v[102:105]
	v_mfma_f32_16x16x32_bf16 v[86:89], v[162:165], v[194:197], v[86:89]
	v_mfma_f32_16x16x32_bf16 v[82:85], v[170:173], v[194:197], v[82:85]
	v_mfma_f32_16x16x32_bf16 v[66:69], v[170:173], v[202:205], v[66:69]
	v_mfma_f32_16x16x32_bf16 v[70:73], v[162:165], v[202:205], v[70:73]
	v_mfma_f32_16x16x32_bf16 v[118:121], v[166:169], v[182:185], v[118:121]
	v_mfma_f32_16x16x32_bf16 v[114:117], v[174:177], v[182:185], v[114:117]
	v_mfma_f32_16x16x32_bf16 v[98:101], v[174:177], v[190:193], v[98:101]
	v_mfma_f32_16x16x32_bf16 v[102:105], v[166:169], v[190:193], v[102:105]
	v_mfma_f32_16x16x32_bf16 v[86:89], v[166:169], v[198:201], v[86:89]
	v_mfma_f32_16x16x32_bf16 v[82:85], v[174:177], v[198:201], v[82:85]
	v_mfma_f32_16x16x32_bf16 v[66:69], v[174:177], v[206:209], v[66:69]
	v_mfma_f32_16x16x32_bf16 v[70:73], v[166:169], v[206:209], v[70:73]
	s_setprio 0
	s_barrier
; #define PG8_STAGE(bufoff, gbase, voff) do { _Pragma("unroll") for (int _i = 0; _i < 2; ++_i) \
;         __builtin_amdgcn_global_load_lds((const unsigned*)((const char*)(gbase) + (voff)[_i]), (PG8_LAS unsigned*)(lds + (bufoff) + ldsw + _i * 8192), 16, 0, 0); } while (0)
; #define PG8_LDA(dst, b, h) do { _Pragma("unroll") for (int m = 0; m < 4; ++m) _Pragma("unroll") for (int k = 0; k < 2; ++k) dst[m][k] = *(const PG8_LAS bf16x8*)(lds + PG8_SA(b, h) + aoff + m * 2048 + k * 1024); } while (0)
; #define PG8_MMA(ai, bj, At, Bt) do { __builtin_amdgcn_s_setprio(1); _Pragma("unroll") for (int m = 0; m < 4; ++m) _Pragma("unroll") for (int n = 0; n < 2; ++n) _Pragma("unroll") for (int k = 0; k < 2; ++k) \
;         acc[ai][bj][m][n] = __builtin_amdgcn_mfma_f32_16x16x32_bf16(Bt[n][k], At[m][k], acc[ai][bj][m][n], 0, 0, 0); __builtin_amdgcn_s_setprio(0); } while (0)
; #define PG8_WAIT_V(n) asm volatile("s_waitcnt vmcnt(" #n ")" ::: "memory")
; #define PG8_WAIT_L(n) asm volatile("s_waitcnt lgkmcnt(" #n ")" ::: "memory")
; #define PG8_BAR __builtin_amdgcn_s_barrier()
; #define PG8_SCHED __builtin_amdgcn_sched_barrier(0)
; template <class Epi, class Sched, bool ALIGN_EPI = false, bool SP2 = false>
; __device__ __forceinline__ void gemm_phase(PG8_LAS unsigned char* lds, const Gemm g, const Sched& S, const Epi& E) {
;     ...
;             PG8_LDA(At, 1, 1); PG8_STAGE(PG8_SB(1, 0), b3, voffB); PG8_STAGE(PG8_SB(1, 1), b3 + hstep, voffB); PG8_STAGE(PG8_SA(1, 0), a3, voffA);
;             PG8_WAIT_V(8); PG8_WAIT_L(0); PG8_BAR; PG8_MMA(1, 0, At, B0); PG8_MMA(1, 1, At, B1); PG8_BAR; PG8_SCHED;
	s_add_i32 s38, s62, s42
	v_lshl_add_u64 v[142:143], v[142:143], 0, s[16:17]
	s_mov_b32 m0, s38
	ds_read_b128 v[178:181], v149 offset:49152
	ds_read_b128 v[182:185], v149 offset:50176
	ds_read_b128 v[186:189], v149 offset:51200
	ds_read_b128 v[190:193], v149 offset:52224
	ds_read_b128 v[194:197], v149 offset:53248
	ds_read_b128 v[198:201], v149 offset:54272
	ds_read_b128 v[202:205], v149 offset:55296
	ds_read_b128 v[206:209], v149 offset:56320
	global_load_lds_dwordx4 v[142:143], off
	s_add_i32 m0, s38, 0x2000
	s_add_u32 s36, s36, 0x100080
	v_lshl_add_u64 v[142:143], v[210:211], 0, s[16:17]
	s_addc_u32 s37, s37, 0
	s_add_i32 s38, s63, s42
	global_load_lds_dwordx4 v[142:143], off
	v_lshl_add_u64 v[142:143], s[36:37], 0, v[132:133]
	s_mov_b32 m0, s38
	s_nop 0
	global_load_lds_dwordx4 v[142:143], off
	v_lshl_add_u64 v[142:143], s[36:37], 0, v[130:131]
	s_add_i32 m0, s38, 0x2000
	s_nop 0
	global_load_lds_dwordx4 v[142:143], off
	v_lshl_add_u64 v[142:143], v[212:213], 0, s[16:17]
	s_mov_b32 m0, s51
	s_nop 0
	global_load_lds_dwordx4 v[142:143], off
	v_lshl_add_u64 v[142:143], v[214:215], 0, s[16:17]
	s_mov_b32 m0, s52
	s_nop 0
	global_load_lds_dwordx4 v[142:143], off
	s_waitcnt vmcnt(8)
	s_waitcnt lgkmcnt(0)
	s_barrier
	s_setprio 1
	s_waitcnt lgkmcnt(0)
	v_mfma_f32_16x16x32_bf16 v[62:65], v[138:141], v[178:181], v[62:65]
	v_mfma_f32_16x16x32_bf16 v[58:61], v[154:157], v[178:181], v[58:61]
	v_mfma_f32_16x16x32_bf16 v[42:45], v[154:157], v[186:189], v[42:45]
	v_mfma_f32_16x16x32_bf16 v[46:49], v[138:141], v[186:189], v[46:49]
	v_mfma_f32_16x16x32_bf16 v[30:33], v[138:141], v[194:197], v[30:33]
	v_mfma_f32_16x16x32_bf16 v[26:29], v[154:157], v[194:197], v[26:29]
	v_mfma_f32_16x16x32_bf16 v[10:13], v[154:157], v[202:205], v[10:13]
	v_mfma_f32_16x16x32_bf16 v[14:17], v[138:141], v[202:205], v[14:17]
	v_mfma_f32_16x16x32_bf16 v[62:65], v[150:153], v[182:185], v[62:65]
	v_mfma_f32_16x16x32_bf16 v[58:61], v[158:161], v[182:185], v[58:61]
	v_mfma_f32_16x16x32_bf16 v[42:45], v[158:161], v[190:193], v[42:45]
	v_mfma_f32_16x16x32_bf16 v[46:49], v[150:153], v[190:193], v[46:49]
	v_mfma_f32_16x16x32_bf16 v[30:33], v[150:153], v[198:201], v[30:33]
	v_mfma_f32_16x16x32_bf16 v[26:29], v[158:161], v[198:201], v[26:29]
	v_mfma_f32_16x16x32_bf16 v[10:13], v[158:161], v[206:209], v[10:13]
	v_mfma_f32_16x16x32_bf16 v[14:17], v[150:153], v[206:209], v[14:17]
	s_setprio 0
	s_setprio 1
	v_mfma_f32_16x16x32_bf16 v[54:57], v[162:165], v[178:181], v[54:57]
	v_mfma_f32_16x16x32_bf16 v[50:53], v[170:173], v[178:181], v[50:53]
	v_mfma_f32_16x16x32_bf16 v[34:37], v[170:173], v[186:189], v[34:37]
	v_mfma_f32_16x16x32_bf16 v[38:41], v[162:165], v[186:189], v[38:41]
	v_mfma_f32_16x16x32_bf16 v[22:25], v[162:165], v[194:197], v[22:25]
	v_mfma_f32_16x16x32_bf16 v[18:21], v[170:173], v[194:197], v[18:21]
	v_mfma_f32_16x16x32_bf16 v[2:5], v[170:173], v[202:205], v[2:5]
	v_mfma_f32_16x16x32_bf16 v[6:9], v[162:165], v[202:205], v[6:9]
	v_mfma_f32_16x16x32_bf16 v[54:57], v[166:169], v[182:185], v[54:57]
	v_mfma_f32_16x16x32_bf16 v[50:53], v[174:177], v[182:185], v[50:53]
	v_mfma_f32_16x16x32_bf16 v[34:37], v[174:177], v[190:193], v[34:37]
	v_mfma_f32_16x16x32_bf16 v[38:41], v[166:169], v[190:193], v[38:41]
	v_mfma_f32_16x16x32_bf16 v[22:25], v[166:169], v[198:201], v[22:25]
	v_mfma_f32_16x16x32_bf16 v[18:21], v[174:177], v[198:201], v[18:21]
	v_mfma_f32_16x16x32_bf16 v[2:5], v[174:177], v[206:209], v[2:5]
	v_mfma_f32_16x16x32_bf16 v[6:9], v[166:169], v[206:209], v[6:9]
	s_setprio 0
	s_barrier
	s_add_i32 s61, s61, 2
	s_add_u32 s30, s30, 0x100
	s_addc_u32 s31, s31, 0
	s_add_u32 s59, s59, 0x100
	s_addc_u32 s60, s60, 0
	s_cmp_gt_u32 s61, 5
	s_cbranch_scc0 .LBB0_1219
	s_and_b64 vcc, exec, s[18:19]
	s_cbranch_vccz .LBB0_1222
	s_barrier

;     __device__ bool next(int i, Unit& u) const { if (!s.next(i, u)) return false; const int p = u.pn; u.pn = p < 56 ? (p % 7) * 8 + p / 7 : p; return true; }
;     __device__ bool next(int i, Unit& u) const { Unit t; if (!s.next(i >> 1, t)) return false; const int pass = i & 1; u.pm = t.pm + pass * (M / BM); u.pn = t.pn + pass * (D / BM); u.kt0 = 0; return true; }
; #define PG8_STAGE(bufoff, gbase, voff) do { _Pragma("unroll") for (int _i = 0; _i < 2; ++_i) \
;         __builtin_amdgcn_global_load_lds((const unsigned*)((const char*)(gbase) + (voff)[_i]), (PG8_LAS unsigned*)(lds + (bufoff) + ldsw + _i * 8192), 16, 0, 0); } while (0)
; #define PG8_LDA(dst, b, h) do { _Pragma("unroll") for (int m = 0; m < 4; ++m) _Pragma("unroll") for (int k = 0; k < 2; ++k) dst[m][k] = *(const PG8_LAS bf16x8*)(lds + PG8_SA(b, h) + aoff + m * 2048 + k * 1024); } while (0)
; template <class Epi, class Sched, bool ALIGN_EPI = false, bool SP2 = false>
; __device__ __forceinline__ void gemm_phase(PG8_LAS unsigned char* lds, const Gemm g, const Sched& S, const Epi& E) {
;     ...
;         const bool has_next = S.next(ui + 1, nxt);
;         const char* nA = has_next ? (const char*)g.A + (size_t)nxt.pm * tstep + (size_t)nxt.kt0 * kstep : cA; const char* nB = has_next ? (const char*)g.Bt + (size_t)nxt.pn * tstep + (size_t)nxt.kt0 * kstep : cB;
;         for (int t = 0; t < nt; t += 2) {
;             if constexpr (Epi::MIDHOOK) { if (t == (nt >> 1)) E.mid(acc, cur, wr, wc, fr, fq); }
;             const bool last = (t == nt - 2);
;             const char* a1 = cA + (size_t)(t + 1) * kstep;
;             const char* a2 = last ? nA : cA + (size_t)(t + 2) * kstep; const char* b2 = last ? nB : cB + (size_t)(t + 2) * kstep;
;             const char* a3 = a2 + kstep; const char* b3 = b2 + kstep;
;             if (last && has_next) S.a_ready(nxt);
;             if constexpr (SP2) {
;             PG8_LDB(B0, 0, 0); PG8_LDB(B1, 0, 1); PG8_SCHED; PG8_LDA(At, 0, 0); PG8_STAGE(PG8_SA(1, 1), a1 + hstep, voffA);
;             PG8_WAIT_V(8); PG8_WAIT_L(0); PG8_BAR; PG8_MMA(0, 0, At, B0); PG8_MMA(0, 1, At, B1); PG8_BAR; PG8_SCHED;
;             PG8_LDA(At, 0, 1); PG8_STAGE(PG8_SB(0, 0), b2, voffB); PG8_STAGE(PG8_SB(0, 1), b2 + hstep, voffB); PG8_STAGE(PG8_SA(0, 0), a2, voffA);
;             PG8_WAIT_V(8); PG8_WAIT_L(0); PG8_BAR; PG8_MMA(1, 0, At, B0); PG8_MMA(1, 1, At, B1); PG8_BAR; PG8_SCHED;
.LBB0_1318:
	s_add_u32 s39, s28, s38
	s_addc_u32 s46, s29, 0
	s_add_u32 s42, s39, 0x100
	s_addc_u32 s43, s46, 0
	s_and_b64 s[40:41], s[36:37], exec
	s_cselect_b32 s41, s19, s43
	s_cselect_b32 s40, s62, s42
	s_add_u32 s38, s26, s38
	s_addc_u32 s42, s27, 0
	s_add_u32 s38, s38, 0x100
	s_addc_u32 s42, s42, 0
	s_and_b64 s[36:37], s[36:37], exec
	s_cselect_b32 s43, s17, s42
	s_cselect_b32 s42, s63, s38
	s_add_u32 s48, s39, 0x10080
	ds_read_b128 v[152:155], v148
	ds_read_b128 v[156:159], v148 offset:1024
	ds_read_b128 v[160:163], v148 offset:2048
	ds_read_b128 v[164:167], v148 offset:3072
	ds_read_b128 v[168:171], v149
	ds_read_b128 v[172:175], v149 offset:1024
	ds_read_b128 v[176:179], v149 offset:2048
	ds_read_b128 v[180:183], v149 offset:3072
	s_addc_u32 s49, s46, 0
	s_add_i32 s73, s59, s3
	s_add_i32 m0, s25, 0xc000
	s_add_i32 s74, s25, 0xe000
	s_add_i32 s70, s73, 0x2000
	s_add_u32 s46, s42, 0x10000
	s_addc_u32 s47, s43, 0
	s_add_i32 s72, s60, s3
	s_add_i32 s71, s72, 0x2000
	s_add_i32 s69, 0, 0x18000
	s_add_i32 s68, 0, 0x1c000
	s_add_u32 s38, s40, 0x10000
	s_addc_u32 s39, s41, 0
	s_add_i32 s67, s69, s3
	s_add_i32 s65, s67, 0x2000
	s_add_u32 s36, s42, 0x10080
	s_addc_u32 s37, s43, 0
	s_add_i32 s66, s68, s3
	s_add_i32 s64, s66, 0x2000
	v_lshl_add_u64 v[142:143], s[48:49], 0, v[136:137]
	ds_read_b128 v[184:187], v150
	ds_read_b128 v[188:191], v150 offset:1024
	ds_read_b128 v[192:195], v150 offset:2048
	ds_read_b128 v[196:199], v150 offset:3072
	ds_read_b128 v[200:203], v150 offset:4096
	ds_read_b128 v[204:207], v150 offset:5120
	ds_read_b128 v[208:211], v150 offset:6144
	ds_read_b128 v[212:215], v150 offset:7168
	global_load_lds_dwordx4 v[142:143], off
	v_lshl_add_u64 v[142:143], s[48:49], 0, v[132:133]
	s_mov_b32 m0, s74
	s_nop 0
	global_load_lds_dwordx4 v[142:143], off
	s_waitcnt vmcnt(8)
	s_waitcnt lgkmcnt(0)
	s_barrier
	s_setprio 1
	s_waitcnt lgkmcnt(0)
	v_mfma_f32_16x16x32_bf16 v[126:129], v[152:155], v[184:187], v[126:129]
	v_mfma_f32_16x16x32_bf16 v[122:125], v[160:163], v[184:187], v[122:125]
	v_mfma_f32_16x16x32_bf16 v[110:113], v[160:163], v[192:195], v[110:113]
	v_mfma_f32_16x16x32_bf16 v[118:121], v[152:155], v[192:195], v[118:121]
	v_mfma_f32_16x16x32_bf16 v[102:105], v[152:155], v[200:203], v[102:105]
	v_mfma_f32_16x16x32_bf16 v[94:97], v[160:163], v[200:203], v[94:97]
	v_mfma_f32_16x16x32_bf16 v[78:81], v[160:163], v[208:211], v[78:81]
	v_mfma_f32_16x16x32_bf16 v[86:89], v[152:155], v[208:211], v[86:89]
	v_mfma_f32_16x16x32_bf16 v[126:129], v[156:159], v[188:191], v[126:129]
	v_mfma_f32_16x16x32_bf16 v[122:125], v[164:167], v[188:191], v[122:125]
	v_mfma_f32_16x16x32_bf16 v[110:113], v[164:167], v[196:199], v[110:113]
	v_mfma_f32_16x16x32_bf16 v[118:121], v[156:159], v[196:199], v[118:121]
	v_mfma_f32_16x16x32_bf16 v[102:105], v[156:159], v[204:207], v[102:105]
	v_mfma_f32_16x16x32_bf16 v[94:97], v[164:167], v[204:207], v[94:97]
	v_mfma_f32_16x16x32_bf16 v[78:81], v[164:167], v[212:215], v[78:81]
	v_mfma_f32_16x16x32_bf16 v[86:89], v[156:159], v[212:215], v[86:89]
	s_setprio 0
	s_setprio 1
	v_mfma_f32_16x16x32_bf16 v[114:117], v[168:171], v[184:187], v[114:117]
	v_mfma_f32_16x16x32_bf16 v[106:109], v[176:179], v[184:187], v[106:109]
	v_mfma_f32_16x16x32_bf16 v[90:93], v[176:179], v[192:195], v[90:93]
	v_mfma_f32_16x16x32_bf16 v[98:101], v[168:171], v[192:195], v[98:101]
	v_mfma_f32_16x16x32_bf16 v[82:85], v[168:171], v[200:203], v[82:85]
	v_mfma_f32_16x16x32_bf16 v[74:77], v[176:179], v[200:203], v[74:77]
	v_mfma_f32_16x16x32_bf16 v[66:69], v[176:179], v[208:211], v[66:69]
	v_mfma_f32_16x16x32_bf16 v[70:73], v[168:171], v[208:211], v[70:73]
	v_mfma_f32_16x16x32_bf16 v[114:117], v[172:175], v[188:191], v[114:117]
	v_mfma_f32_16x16x32_bf16 v[106:109], v[180:183], v[188:191], v[106:109]
	v_mfma_f32_16x16x32_bf16 v[90:93], v[180:183], v[196:199], v[90:93]
	v_mfma_f32_16x16x32_bf16 v[98:101], v[172:175], v[196:199], v[98:101]
	v_mfma_f32_16x16x32_bf16 v[82:85], v[172:175], v[204:207], v[82:85]
	v_mfma_f32_16x16x32_bf16 v[74:77], v[180:183], v[204:207], v[74:77]
	v_mfma_f32_16x16x32_bf16 v[66:69], v[180:183], v[212:215], v[66:69]
	v_mfma_f32_16x16x32_bf16 v[70:73], v[172:175], v[212:215], v[70:73]
	s_setprio 0
	s_barrier
	s_mov_b32 m0, s73
	v_lshl_add_u64 v[142:143], s[42:43], 0, v[134:135]
	ds_read_b128 v[184:187], v150 offset:16384
	ds_read_b128 v[188:191], v150 offset:17408
	ds_read_b128 v[192:195], v150 offset:18432
	ds_read_b128 v[196:199], v150 offset:19456
	ds_read_b128 v[200:203], v150 offset:20480
	ds_read_b128 v[204:207], v150 offset:21504
	ds_read_b128 v[208:211], v150 offset:22528
	ds_read_b128 v[212:215], v150 offset:23552
	global_load_lds_dwordx4 v[142:143], off
	v_lshl_add_u64 v[216:217], s[42:43], 0, v[130:131]
	s_mov_b32 m0, s70
	v_lshl_add_u64 v[218:219], s[46:47], 0, v[134:135]
	global_load_lds_dwordx4 v[216:217], off
	s_mov_b32 m0, s72
	v_lshl_add_u64 v[220:221], s[40:41], 0, v[132:133]
	global_load_lds_dwordx4 v[218:219], off
	v_lshl_add_u64 v[218:219], s[46:47], 0, v[130:131]
	s_mov_b32 m0, s71
	s_nop 0
	global_load_lds_dwordx4 v[218:219], off
	v_lshl_add_u64 v[218:219], s[40:41], 0, v[136:137]
	s_mov_b32 m0, s25
	s_nop 0
	global_load_lds_dwordx4 v[218:219], off
	s_mov_b32 m0, s52
	s_nop 0
	global_load_lds_dwordx4 v[220:221], off
	s_waitcnt vmcnt(8)
	s_waitcnt lgkmcnt(0)
	s_barrier
; #define PG8_STAGE(bufoff, gbase, voff) do { _Pragma("unroll") for (int _i = 0; _i < 2; ++_i) \
;         __builtin_amdgcn_global_load_lds((const unsigned*)((const char*)(gbase) + (voff)[_i]), (PG8_LAS unsigned*)(lds + (bufoff) + ldsw + _i * 8192), 16, 0, 0); } while (0)
; #define PG8_LDA(dst, b, h) do { _Pragma("unroll") for (int m = 0; m < 4; ++m) _Pragma("unroll") for (int k = 0; k < 2; ++k) dst[m][k] = *(const PG8_LAS bf16x8*)(lds + PG8_SA(b, h) + aoff + m * 2048 + k * 1024); } while (0)
; #define PG8_LDB(dst, b, h) do { _Pragma("unroll") for (int n = 0; n < 2; ++n) _Pragma("unroll") for (int k = 0; k < 2; ++k) dst[n][k] = *(const PG8_LAS bf16x8*)(lds + PG8_SB(b, h) + boff + n * 2048 + k * 1024); } while (0)
; #define PG8_MMA(ai, bj, At, Bt) do { __builtin_amdgcn_s_setprio(1); _Pragma("unroll") for (int m = 0; m < 4; ++m) _Pragma("unroll") for (int n = 0; n < 2; ++n) _Pragma("unroll") for (int k = 0; k < 2; ++k) \
;         acc[ai][bj][m][n] = __builtin_amdgcn_mfma_f32_16x16x32_bf16(Bt[n][k], At[m][k], acc[ai][bj][m][n], 0, 0, 0); __builtin_amdgcn_s_setprio(0); } while (0)
; #define PG8_WAIT_V(n) asm volatile("s_waitcnt vmcnt(" #n ")" ::: "memory")
; #define PG8_WAIT_L(n) asm volatile("s_waitcnt lgkmcnt(" #n ")" ::: "memory")
; #define PG8_BAR __builtin_amdgcn_s_barrier()
; #define PG8_SCHED __builtin_amdgcn_sched_barrier(0)
; template <class Epi, class Sched, bool ALIGN_EPI = false, bool SP2 = false>
; __device__ __forceinline__ void gemm_phase(PG8_LAS unsigned char* lds, const Gemm g, const Sched& S, const Epi& E) {
;     ...
;             PG8_WAIT_V(8); PG8_WAIT_L(0); PG8_BAR; PG8_MMA(1, 0, At, B0); PG8_MMA(1, 1, At, B1); PG8_BAR; PG8_SCHED;
;             PG8_LDB(B0, 1, 0); PG8_LDB(B1, 1, 1); PG8_SCHED; PG8_LDA(At, 1, 0); PG8_STAGE(PG8_SA(0, 1), a2 + hstep, voffA);
;             PG8_WAIT_V(8); PG8_WAIT_L(0); PG8_BAR; PG8_MMA(0, 0, At, B0); PG8_MMA(0, 1, At, B1); PG8_BAR; PG8_SCHED;
	s_setprio 1
	s_waitcnt lgkmcnt(0)
	v_mfma_f32_16x16x32_bf16 v[62:65], v[152:155], v[184:187], v[62:65]
	v_mfma_f32_16x16x32_bf16 v[58:61], v[160:163], v[184:187], v[58:61]
	v_mfma_f32_16x16x32_bf16 v[46:49], v[160:163], v[192:195], v[46:49]
	v_mfma_f32_16x16x32_bf16 v[54:57], v[152:155], v[192:195], v[54:57]
	v_mfma_f32_16x16x32_bf16 v[38:41], v[152:155], v[200:203], v[38:41]
	v_mfma_f32_16x16x32_bf16 v[30:33], v[160:163], v[200:203], v[30:33]
	v_mfma_f32_16x16x32_bf16 v[14:17], v[160:163], v[208:211], v[14:17]
	v_mfma_f32_16x16x32_bf16 v[22:25], v[152:155], v[208:211], v[22:25]
	v_mfma_f32_16x16x32_bf16 v[62:65], v[156:159], v[188:191], v[62:65]
	v_mfma_f32_16x16x32_bf16 v[58:61], v[164:167], v[188:191], v[58:61]
	v_mfma_f32_16x16x32_bf16 v[46:49], v[164:167], v[196:199], v[46:49]
	v_mfma_f32_16x16x32_bf16 v[54:57], v[156:159], v[196:199], v[54:57]
	v_mfma_f32_16x16x32_bf16 v[38:41], v[156:159], v[204:207], v[38:41]
	v_mfma_f32_16x16x32_bf16 v[30:33], v[164:167], v[204:207], v[30:33]
	v_mfma_f32_16x16x32_bf16 v[14:17], v[164:167], v[212:215], v[14:17]
	v_mfma_f32_16x16x32_bf16 v[22:25], v[156:159], v[212:215], v[22:25]
	s_setprio 0
	s_setprio 1
	v_mfma_f32_16x16x32_bf16 v[50:53], v[168:171], v[184:187], v[50:53]
	v_mfma_f32_16x16x32_bf16 v[42:45], v[176:179], v[184:187], v[42:45]
	v_mfma_f32_16x16x32_bf16 v[26:29], v[176:179], v[192:195], v[26:29]
	v_mfma_f32_16x16x32_bf16 v[34:37], v[168:171], v[192:195], v[34:37]
	v_mfma_f32_16x16x32_bf16 v[18:21], v[168:171], v[200:203], v[18:21]
	v_mfma_f32_16x16x32_bf16 v[10:13], v[176:179], v[200:203], v[10:13]
	v_mfma_f32_16x16x32_bf16 v[2:5], v[176:179], v[208:211], v[2:5]
	v_mfma_f32_16x16x32_bf16 v[6:9], v[168:171], v[208:211], v[6:9]
	v_mfma_f32_16x16x32_bf16 v[50:53], v[172:175], v[188:191], v[50:53]
	v_mfma_f32_16x16x32_bf16 v[42:45], v[180:183], v[188:191], v[42:45]
	v_mfma_f32_16x16x32_bf16 v[26:29], v[180:183], v[196:199], v[26:29]
	v_mfma_f32_16x16x32_bf16 v[34:37], v[172:175], v[196:199], v[34:37]
	v_mfma_f32_16x16x32_bf16 v[18:21], v[172:175], v[204:207], v[18:21]
	v_mfma_f32_16x16x32_bf16 v[10:13], v[180:183], v[204:207], v[10:13]
	v_mfma_f32_16x16x32_bf16 v[2:5], v[180:183], v[212:215], v[2:5]
	v_mfma_f32_16x16x32_bf16 v[6:9], v[172:175], v[212:215], v[6:9]
	s_setprio 0
	s_barrier
	v_add_u32_e32 v151, s69, v146
	ds_read_b128 v[152:155], v151
	ds_read_b128 v[156:159], v151 offset:1024
	ds_read_b128 v[160:163], v151 offset:2048
	ds_read_b128 v[164:167], v151 offset:3072
	v_add_u32_e32 v151, s68, v146
	ds_read_b128 v[168:171], v151
	ds_read_b128 v[172:175], v151 offset:1024
	ds_read_b128 v[176:179], v151 offset:2048
	ds_read_b128 v[180:183], v151 offset:3072
	s_mov_b32 m0, s53
	v_lshl_add_u64 v[222:223], s[38:39], 0, v[136:137]
	ds_read_b128 v[184:187], v150 offset:32768
	ds_read_b128 v[188:191], v150 offset:33792
	ds_read_b128 v[192:195], v150 offset:34816
	ds_read_b128 v[196:199], v150 offset:35840
	ds_read_b128 v[200:203], v150 offset:36864
	ds_read_b128 v[204:207], v150 offset:37888
	ds_read_b128 v[208:211], v150 offset:38912
	ds_read_b128 v[212:215], v150 offset:39936
	global_load_lds_dwordx4 v[222:223], off
	v_lshl_add_u64 v[222:223], s[38:39], 0, v[132:133]
	s_mov_b32 m0, s54
	s_nop 0
	global_load_lds_dwordx4 v[222:223], off
	s_waitcnt vmcnt(8)
	s_waitcnt lgkmcnt(0)
	s_barrier
	s_setprio 1
	s_waitcnt lgkmcnt(0)
	v_mfma_f32_16x16x32_bf16 v[126:129], v[152:155], v[184:187], v[126:129]
	v_mfma_f32_16x16x32_bf16 v[122:125], v[160:163], v[184:187], v[122:125]
	v_mfma_f32_16x16x32_bf16 v[110:113], v[160:163], v[192:195], v[110:113]
	v_mfma_f32_16x16x32_bf16 v[118:121], v[152:155], v[192:195], v[118:121]
	v_mfma_f32_16x16x32_bf16 v[102:105], v[152:155], v[200:203], v[102:105]
	v_mfma_f32_16x16x32_bf16 v[94:97], v[160:163], v[200:203], v[94:97]
	v_mfma_f32_16x16x32_bf16 v[78:81], v[160:163], v[208:211], v[78:81]
	v_mfma_f32_16x16x32_bf16 v[86:89], v[152:155], v[208:211], v[86:89]
	v_mfma_f32_16x16x32_bf16 v[126:129], v[156:159], v[188:191], v[126:129]
	v_mfma_f32_16x16x32_bf16 v[122:125], v[164:167], v[188:191], v[122:125]
	v_mfma_f32_16x16x32_bf16 v[110:113], v[164:167], v[196:199], v[110:113]
	v_mfma_f32_16x16x32_bf16 v[118:121], v[156:159], v[196:199], v[118:121]
	v_mfma_f32_16x16x32_bf16 v[102:105], v[156:159], v[204:207], v[102:105]
	v_mfma_f32_16x16x32_bf16 v[94:97], v[164:167], v[204:207], v[94:97]
	v_mfma_f32_16x16x32_bf16 v[78:81], v[164:167], v[212:215], v[78:81]
	v_mfma_f32_16x16x32_bf16 v[86:89], v[156:159], v[212:215], v[86:89]
	s_setprio 0
	s_setprio 1
	v_mfma_f32_16x16x32_bf16 v[114:117], v[168:171], v[184:187], v[114:117]
	v_mfma_f32_16x16x32_bf16 v[106:109], v[176:179], v[184:187], v[106:109]
	v_mfma_f32_16x16x32_bf16 v[90:93], v[176:179], v[192:195], v[90:93]
	v_mfma_f32_16x16x32_bf16 v[98:101], v[168:171], v[192:195], v[98:101]
	v_mfma_f32_16x16x32_bf16 v[82:85], v[168:171], v[200:203], v[82:85]
	v_mfma_f32_16x16x32_bf16 v[74:77], v[176:179], v[200:203], v[74:77]
	v_mfma_f32_16x16x32_bf16 v[66:69], v[176:179], v[208:211], v[66:69]
	v_mfma_f32_16x16x32_bf16 v[70:73], v[168:171], v[208:211], v[70:73]
	v_mfma_f32_16x16x32_bf16 v[114:117], v[172:175], v[188:191], v[114:117]
	v_mfma_f32_16x16x32_bf16 v[106:109], v[180:183], v[188:191], v[106:109]
	v_mfma_f32_16x16x32_bf16 v[90:93], v[180:183], v[196:199], v[90:93]
	v_mfma_f32_16x16x32_bf16 v[98:101], v[172:175], v[196:199], v[98:101]
	v_mfma_f32_16x16x32_bf16 v[82:85], v[172:175], v[204:207], v[82:85]
	v_mfma_f32_16x16x32_bf16 v[74:77], v[180:183], v[204:207], v[74:77]
	v_mfma_f32_16x16x32_bf16 v[66:69], v[180:183], v[212:215], v[66:69]
	v_mfma_f32_16x16x32_bf16 v[70:73], v[172:175], v[212:215], v[70:73]
	s_setprio 0
	s_barrier
; #define PG8_STAGE(bufoff, gbase, voff) do { _Pragma("unroll") for (int _i = 0; _i < 2; ++_i) \
;         __builtin_amdgcn_global_load_lds((const unsigned*)((const char*)(gbase) + (voff)[_i]), (PG8_LAS unsigned*)(lds + (bufoff) + ldsw + _i * 8192), 16, 0, 0); } while (0)
; #define PG8_LDA(dst, b, h) do { _Pragma("unroll") for (int m = 0; m < 4; ++m) _Pragma("unroll") for (int k = 0; k < 2; ++k) dst[m][k] = *(const PG8_LAS bf16x8*)(lds + PG8_SA(b, h) + aoff + m * 2048 + k * 1024); } while (0)
; #define PG8_MMA(ai, bj, At, Bt) do { __builtin_amdgcn_s_setprio(1); _Pragma("unroll") for (int m = 0; m < 4; ++m) _Pragma("unroll") for (int n = 0; n < 2; ++n) _Pragma("unroll") for (int k = 0; k < 2; ++k) \
;         acc[ai][bj][m][n] = __builtin_amdgcn_mfma_f32_16x16x32_bf16(Bt[n][k], At[m][k], acc[ai][bj][m][n], 0, 0, 0); __builtin_amdgcn_s_setprio(0); } while (0)
; #define PG8_WAIT_V(n) asm volatile("s_waitcnt vmcnt(" #n ")" ::: "memory")
; #define PG8_WAIT_L(n) asm volatile("s_waitcnt lgkmcnt(" #n ")" ::: "memory")
; #define PG8_BAR __builtin_amdgcn_s_barrier()
; #define PG8_SCHED __builtin_amdgcn_sched_barrier(0)
; template <class Epi, class Sched, bool ALIGN_EPI = false, bool SP2 = false>
; __device__ __forceinline__ void gemm_phase(PG8_LAS unsigned char* lds, const Gemm g, const Sched& S, const Epi& E) {
;     ...
;             PG8_LDA(At, 1, 1); PG8_STAGE(PG8_SB(1, 0), b3, voffB); PG8_STAGE(PG8_SB(1, 1), b3 + hstep, voffB); PG8_STAGE(PG8_SA(1, 0), a3, voffA);
;             PG8_WAIT_V(8); PG8_WAIT_L(0); PG8_BAR; PG8_MMA(1, 0, At, B0); PG8_MMA(1, 1, At, B1); PG8_BAR; PG8_SCHED;
	s_mov_b32 m0, s67
	v_lshl_add_u64 v[142:143], v[142:143], 0, s[12:13]
	ds_read_b128 v[184:187], v150 offset:49152
	ds_read_b128 v[188:191], v150 offset:50176
	ds_read_b128 v[192:195], v150 offset:51200
	ds_read_b128 v[196:199], v150 offset:52224
	ds_read_b128 v[200:203], v150 offset:53248
	ds_read_b128 v[204:207], v150 offset:54272
	ds_read_b128 v[208:211], v150 offset:55296
	ds_read_b128 v[212:215], v150 offset:56320
	global_load_lds_dwordx4 v[142:143], off
	v_lshl_add_u64 v[142:143], v[216:217], 0, s[12:13]
	s_mov_b32 m0, s65
	s_nop 0
	global_load_lds_dwordx4 v[142:143], off
	v_lshl_add_u64 v[142:143], s[36:37], 0, v[134:135]
	s_mov_b32 m0, s66
	s_nop 0
	global_load_lds_dwordx4 v[142:143], off
	v_lshl_add_u64 v[142:143], s[36:37], 0, v[130:131]
	s_mov_b32 m0, s64
	s_nop 0
	global_load_lds_dwordx4 v[142:143], off
	v_lshl_add_u64 v[142:143], v[218:219], 0, s[12:13]
	s_mov_b32 m0, s57
	s_nop 0
	global_load_lds_dwordx4 v[142:143], off
	v_lshl_add_u64 v[142:143], v[220:221], 0, s[12:13]
	s_mov_b32 m0, s58
	s_nop 0
	global_load_lds_dwordx4 v[142:143], off
	s_waitcnt vmcnt(8)
	s_waitcnt lgkmcnt(0)
	s_barrier
	s_setprio 1
	s_waitcnt lgkmcnt(0)
	v_mfma_f32_16x16x32_bf16 v[62:65], v[152:155], v[184:187], v[62:65]
	v_mfma_f32_16x16x32_bf16 v[58:61], v[160:163], v[184:187], v[58:61]
	v_mfma_f32_16x16x32_bf16 v[46:49], v[160:163], v[192:195], v[46:49]
	v_mfma_f32_16x16x32_bf16 v[54:57], v[152:155], v[192:195], v[54:57]
	v_mfma_f32_16x16x32_bf16 v[38:41], v[152:155], v[200:203], v[38:41]
	v_mfma_f32_16x16x32_bf16 v[30:33], v[160:163], v[200:203], v[30:33]
	v_mfma_f32_16x16x32_bf16 v[14:17], v[160:163], v[208:211], v[14:17]
	v_mfma_f32_16x16x32_bf16 v[22:25], v[152:155], v[208:211], v[22:25]
	v_mfma_f32_16x16x32_bf16 v[62:65], v[156:159], v[188:191], v[62:65]
	v_mfma_f32_16x16x32_bf16 v[58:61], v[164:167], v[188:191], v[58:61]
	v_mfma_f32_16x16x32_bf16 v[46:49], v[164:167], v[196:199], v[46:49]
	v_mfma_f32_16x16x32_bf16 v[54:57], v[156:159], v[196:199], v[54:57]
	v_mfma_f32_16x16x32_bf16 v[38:41], v[156:159], v[204:207], v[38:41]
	v_mfma_f32_16x16x32_bf16 v[30:33], v[164:167], v[204:207], v[30:33]
	v_mfma_f32_16x16x32_bf16 v[14:17], v[164:167], v[212:215], v[14:17]
	v_mfma_f32_16x16x32_bf16 v[22:25], v[156:159], v[212:215], v[22:25]
	s_setprio 0
	s_setprio 1
	v_mfma_f32_16x16x32_bf16 v[50:53], v[168:171], v[184:187], v[50:53]
	v_mfma_f32_16x16x32_bf16 v[42:45], v[176:179], v[184:187], v[42:45]
	v_mfma_f32_16x16x32_bf16 v[26:29], v[176:179], v[192:195], v[26:29]
	v_mfma_f32_16x16x32_bf16 v[34:37], v[168:171], v[192:195], v[34:37]
	v_mfma_f32_16x16x32_bf16 v[18:21], v[168:171], v[200:203], v[18:21]
	v_mfma_f32_16x16x32_bf16 v[10:13], v[176:179], v[200:203], v[10:13]
	v_mfma_f32_16x16x32_bf16 v[2:5], v[176:179], v[208:211], v[2:5]
	v_mfma_f32_16x16x32_bf16 v[6:9], v[168:171], v[208:211], v[6:9]
	v_mfma_f32_16x16x32_bf16 v[50:53], v[172:175], v[188:191], v[50:53]
	v_mfma_f32_16x16x32_bf16 v[42:45], v[180:183], v[188:191], v[42:45]
	v_mfma_f32_16x16x32_bf16 v[26:29], v[180:183], v[196:199], v[26:29]
	v_mfma_f32_16x16x32_bf16 v[34:37], v[172:175], v[196:199], v[34:37]
	v_mfma_f32_16x16x32_bf16 v[18:21], v[172:175], v[204:207], v[18:21]
	v_mfma_f32_16x16x32_bf16 v[10:13], v[180:183], v[204:207], v[10:13]
	v_mfma_f32_16x16x32_bf16 v[2:5], v[180:183], v[212:215], v[2:5]
	v_mfma_f32_16x16x32_bf16 v[6:9], v[172:175], v[212:215], v[6:9]
	s_setprio 0
	s_barrier
	s_movk_i32 s38, 0x100
	s_andn2_b64 vcc, exec, s[30:31]
	s_mov_b64 s[36:37], -1
	s_mov_b64 s[30:31], 0
	s_cbranch_vccz .LBB0_1318
	s_and_b64 vcc, exec, s[14:15]
	s_cbranch_vccz .LBB0_1321
	s_barrier

;     __device__ bool next(int i, Unit& u) const { if (!s.next(i, u)) return false; const int p = u.pn; u.pn = p < 56 ? (p % 7) * 8 + p / 7 : p; return true; }
;     __device__ bool next(int i, Unit& u) const { Unit t; if (!s.next(i >> 1, t)) return false; const int pass = i & 1; u.pm = t.pm + pass * (M / BM); u.pn = t.pn + pass * (D / BM); u.kt0 = 0; return true; }
; #define PG8_STAGE(bufoff, gbase, voff) do { _Pragma("unroll") for (int _i = 0; _i < 2; ++_i) \
;         __builtin_amdgcn_global_load_lds((const unsigned*)((const char*)(gbase) + (voff)[_i]), (PG8_LAS unsigned*)(lds + (bufoff) + ldsw + _i * 8192), 16, 0, 0); } while (0)
; #define PG8_LDA(dst, b, h) do { _Pragma("unroll") for (int m = 0; m < 4; ++m) _Pragma("unroll") for (int k = 0; k < 2; ++k) dst[m][k] = *(const PG8_LAS bf16x8*)(lds + PG8_SA(b, h) + aoff + m * 2048 + k * 1024); } while (0)
; template <class Epi, class Sched, bool ALIGN_EPI = false, bool SP2 = false>
; __device__ __forceinline__ void gemm_phase(PG8_LAS unsigned char* lds, const Gemm g, const Sched& S, const Epi& E) {
;     ...
;         const bool has_next = S.next(ui + 1, nxt);
;         const char* nA = has_next ? (const char*)g.A + (size_t)nxt.pm * tstep + (size_t)nxt.kt0 * kstep : cA; const char* nB = has_next ? (const char*)g.Bt + (size_t)nxt.pn * tstep + (size_t)nxt.kt0 * kstep : cB;
;         for (int t = 0; t < nt; t += 2) {
;             if constexpr (Epi::MIDHOOK) { if (t == (nt >> 1)) E.mid(acc, cur, wr, wc, fr, fq); }
;             const bool last = (t == nt - 2);
;             const char* a1 = cA + (size_t)(t + 1) * kstep;
;             const char* a2 = last ? nA : cA + (size_t)(t + 2) * kstep; const char* b2 = last ? nB : cB + (size_t)(t + 2) * kstep;
;             const char* a3 = a2 + kstep; const char* b3 = b2 + kstep;
;             if (last && has_next) S.a_ready(nxt);
;             if constexpr (SP2) {
;             PG8_LDB(B0, 0, 0); PG8_LDB(B1, 0, 1); PG8_SCHED; PG8_LDA(At, 0, 0); PG8_STAGE(PG8_SA(1, 1), a1 + hstep, voffA);
;             PG8_WAIT_V(8); PG8_WAIT_L(0); PG8_BAR; PG8_MMA(0, 0, At, B0); PG8_MMA(0, 1, At, B1); PG8_BAR; PG8_SCHED;
;             PG8_LDA(At, 0, 1); PG8_STAGE(PG8_SB(0, 0), b2, voffB); PG8_STAGE(PG8_SB(0, 1), b2 + hstep, voffB); PG8_STAGE(PG8_SA(0, 0), a2, voffA);
;             PG8_WAIT_V(8); PG8_WAIT_L(0); PG8_BAR; PG8_MMA(1, 0, At, B0); PG8_MMA(1, 1, At, B1); PG8_BAR; PG8_SCHED;
.LBB0_1393:
	ds_read_b128 v[156:159], v152
	ds_read_b128 v[160:163], v152 offset:1024
	ds_read_b128 v[164:167], v152 offset:2048
	ds_read_b128 v[168:171], v152 offset:3072
	ds_read_b128 v[172:175], v153
	ds_read_b128 v[176:179], v153 offset:1024
	ds_read_b128 v[180:183], v153 offset:2048
	ds_read_b128 v[184:187], v153 offset:3072
	s_add_u32 s28, s26, 0xfff80080
	s_addc_u32 s29, s27, -1
	s_cmp_eq_u32 s54, 28
	s_cselect_b32 s31, s19, s29
	s_cselect_b32 s30, s50, s28
	s_cselect_b32 s29, s17, s53
	s_cselect_b32 s28, s51, s52
	v_lshl_add_u64 v[146:147], s[26:27], 0, v[138:139]
	s_add_i32 m0, s25, 0xc000
	ds_read_b128 v[188:191], v154
	ds_read_b128 v[192:195], v154 offset:1024
	ds_read_b128 v[196:199], v154 offset:2048
	ds_read_b128 v[200:203], v154 offset:3072
	ds_read_b128 v[204:207], v154 offset:4096
	ds_read_b128 v[208:211], v154 offset:5120
	ds_read_b128 v[212:215], v154 offset:6144
	ds_read_b128 v[216:219], v154 offset:7168
	global_load_lds_dwordx4 v[146:147], off
	v_lshl_add_u64 v[146:147], s[26:27], 0, v[140:141]
	s_add_i32 m0, s25, 0xe000
	s_nop 0
	global_load_lds_dwordx4 v[146:147], off
	s_waitcnt vmcnt(8)
	s_waitcnt lgkmcnt(0)
	s_barrier
	s_setprio 1
	s_waitcnt lgkmcnt(0)
	v_mfma_f32_16x16x32_bf16 v[126:129], v[156:159], v[188:191], v[126:129]
	v_mfma_f32_16x16x32_bf16 v[122:125], v[164:167], v[188:191], v[122:125]
	v_mfma_f32_16x16x32_bf16 v[110:113], v[164:167], v[196:199], v[110:113]
	v_mfma_f32_16x16x32_bf16 v[118:121], v[156:159], v[196:199], v[118:121]
	v_mfma_f32_16x16x32_bf16 v[102:105], v[156:159], v[204:207], v[102:105]
	v_mfma_f32_16x16x32_bf16 v[94:97], v[164:167], v[204:207], v[94:97]
	v_mfma_f32_16x16x32_bf16 v[78:81], v[164:167], v[212:215], v[78:81]
	v_mfma_f32_16x16x32_bf16 v[86:89], v[156:159], v[212:215], v[86:89]
	v_mfma_f32_16x16x32_bf16 v[126:129], v[160:163], v[192:195], v[126:129]
	v_mfma_f32_16x16x32_bf16 v[122:125], v[168:171], v[192:195], v[122:125]
	v_mfma_f32_16x16x32_bf16 v[110:113], v[168:171], v[200:203], v[110:113]
	v_mfma_f32_16x16x32_bf16 v[118:121], v[160:163], v[200:203], v[118:121]
	v_mfma_f32_16x16x32_bf16 v[102:105], v[160:163], v[208:211], v[102:105]
	v_mfma_f32_16x16x32_bf16 v[94:97], v[168:171], v[208:211], v[94:97]
	v_mfma_f32_16x16x32_bf16 v[78:81], v[168:171], v[216:219], v[78:81]
	v_mfma_f32_16x16x32_bf16 v[86:89], v[160:163], v[216:219], v[86:89]
	s_setprio 0
	s_setprio 1
	v_mfma_f32_16x16x32_bf16 v[114:117], v[172:175], v[188:191], v[114:117]
	v_mfma_f32_16x16x32_bf16 v[106:109], v[180:183], v[188:191], v[106:109]
	v_mfma_f32_16x16x32_bf16 v[90:93], v[180:183], v[196:199], v[90:93]
	v_mfma_f32_16x16x32_bf16 v[98:101], v[172:175], v[196:199], v[98:101]
	v_mfma_f32_16x16x32_bf16 v[82:85], v[172:175], v[204:207], v[82:85]
	v_mfma_f32_16x16x32_bf16 v[74:77], v[180:183], v[204:207], v[74:77]
	v_mfma_f32_16x16x32_bf16 v[66:69], v[180:183], v[212:215], v[66:69]
	v_mfma_f32_16x16x32_bf16 v[70:73], v[172:175], v[212:215], v[70:73]
	v_mfma_f32_16x16x32_bf16 v[114:117], v[176:179], v[192:195], v[114:117]
	v_mfma_f32_16x16x32_bf16 v[106:109], v[184:187], v[192:195], v[106:109]
	v_mfma_f32_16x16x32_bf16 v[90:93], v[184:187], v[200:203], v[90:93]
	v_mfma_f32_16x16x32_bf16 v[98:101], v[176:179], v[200:203], v[98:101]
	v_mfma_f32_16x16x32_bf16 v[82:85], v[176:179], v[208:211], v[82:85]
	v_mfma_f32_16x16x32_bf16 v[74:77], v[184:187], v[208:211], v[74:77]
	v_mfma_f32_16x16x32_bf16 v[66:69], v[184:187], v[216:219], v[66:69]
	v_mfma_f32_16x16x32_bf16 v[70:73], v[176:179], v[216:219], v[70:73]
	s_setprio 0
	s_barrier
	s_add_i32 s55, s45, s36
	v_lshl_add_u64 v[146:147], s[28:29], 0, v[134:135]
	s_mov_b32 m0, s55
	ds_read_b128 v[188:191], v154 offset:16384
	ds_read_b128 v[192:195], v154 offset:17408
	ds_read_b128 v[196:199], v154 offset:18432
	ds_read_b128 v[200:203], v154 offset:19456
	ds_read_b128 v[204:207], v154 offset:20480
	ds_read_b128 v[208:211], v154 offset:21504
	ds_read_b128 v[212:215], v154 offset:22528
	ds_read_b128 v[216:219], v154 offset:23552
	global_load_lds_dwordx4 v[146:147], off
	s_add_i32 m0, s55, 0x2000
	s_add_u32 s56, s28, 0x80000
	v_lshl_add_u64 v[220:221], s[28:29], 0, v[130:131]
	s_addc_u32 s57, s29, 0
	s_add_i32 s55, s46, s36
	global_load_lds_dwordx4 v[220:221], off
	v_lshl_add_u64 v[222:223], s[56:57], 0, v[134:135]
	s_mov_b32 m0, s55
	v_lshl_add_u64 v[224:225], s[30:31], 0, v[132:133]
	global_load_lds_dwordx4 v[222:223], off
	v_lshl_add_u64 v[222:223], s[56:57], 0, v[130:131]
	s_add_i32 m0, s55, 0x2000
	s_nop 0
	global_load_lds_dwordx4 v[222:223], off
	v_lshl_add_u64 v[222:223], s[30:31], 0, v[136:137]
	s_mov_b32 m0, s25
	s_nop 0
	global_load_lds_dwordx4 v[222:223], off
	s_mov_b32 m0, s38
	s_nop 0
	global_load_lds_dwordx4 v[224:225], off
	s_waitcnt vmcnt(8)
	s_waitcnt lgkmcnt(0)
	s_barrier
; #define PG8_STAGE(bufoff, gbase, voff) do { _Pragma("unroll") for (int _i = 0; _i < 2; ++_i) \
;         __builtin_amdgcn_global_load_lds((const unsigned*)((const char*)(gbase) + (voff)[_i]), (PG8_LAS unsigned*)(lds + (bufoff) + ldsw + _i * 8192), 16, 0, 0); } while (0)
; #define PG8_LDA(dst, b, h) do { _Pragma("unroll") for (int m = 0; m < 4; ++m) _Pragma("unroll") for (int k = 0; k < 2; ++k) dst[m][k] = *(const PG8_LAS bf16x8*)(lds + PG8_SA(b, h) + aoff + m * 2048 + k * 1024); } while (0)
; #define PG8_LDB(dst, b, h) do { _Pragma("unroll") for (int n = 0; n < 2; ++n) _Pragma("unroll") for (int k = 0; k < 2; ++k) dst[n][k] = *(const PG8_LAS bf16x8*)(lds + PG8_SB(b, h) + boff + n * 2048 + k * 1024); } while (0)
; #define PG8_MMA(ai, bj, At, Bt) do { __builtin_amdgcn_s_setprio(1); _Pragma("unroll") for (int m = 0; m < 4; ++m) _Pragma("unroll") for (int n = 0; n < 2; ++n) _Pragma("unroll") for (int k = 0; k < 2; ++k) \
;         acc[ai][bj][m][n] = __builtin_amdgcn_mfma_f32_16x16x32_bf16(Bt[n][k], At[m][k], acc[ai][bj][m][n], 0, 0, 0); __builtin_amdgcn_s_setprio(0); } while (0)
; #define PG8_WAIT_V(n) asm volatile("s_waitcnt vmcnt(" #n ")" ::: "memory")
; #define PG8_WAIT_L(n) asm volatile("s_waitcnt lgkmcnt(" #n ")" ::: "memory")
; #define PG8_BAR __builtin_amdgcn_s_barrier()
; #define PG8_SCHED __builtin_amdgcn_sched_barrier(0)
; template <class Epi, class Sched, bool ALIGN_EPI = false, bool SP2 = false>
; __device__ __forceinline__ void gemm_phase(PG8_LAS unsigned char* lds, const Gemm g, const Sched& S, const Epi& E) {
;     ...
;             PG8_WAIT_V(8); PG8_WAIT_L(0); PG8_BAR; PG8_MMA(1, 0, At, B0); PG8_MMA(1, 1, At, B1); PG8_BAR; PG8_SCHED;
;             PG8_LDB(B0, 1, 0); PG8_LDB(B1, 1, 1); PG8_SCHED; PG8_LDA(At, 1, 0); PG8_STAGE(PG8_SA(0, 1), a2 + hstep, voffA);
;             PG8_WAIT_V(8); PG8_WAIT_L(0); PG8_BAR; PG8_MMA(0, 0, At, B0); PG8_MMA(0, 1, At, B1); PG8_BAR; PG8_SCHED;
	s_setprio 1
	s_waitcnt lgkmcnt(0)
	v_mfma_f32_16x16x32_bf16 v[62:65], v[156:159], v[188:191], v[62:65]
	v_mfma_f32_16x16x32_bf16 v[58:61], v[164:167], v[188:191], v[58:61]
	v_mfma_f32_16x16x32_bf16 v[46:49], v[164:167], v[196:199], v[46:49]
	v_mfma_f32_16x16x32_bf16 v[54:57], v[156:159], v[196:199], v[54:57]
	v_mfma_f32_16x16x32_bf16 v[38:41], v[156:159], v[204:207], v[38:41]
	v_mfma_f32_16x16x32_bf16 v[30:33], v[164:167], v[204:207], v[30:33]
	v_mfma_f32_16x16x32_bf16 v[14:17], v[164:167], v[212:215], v[14:17]
	v_mfma_f32_16x16x32_bf16 v[22:25], v[156:159], v[212:215], v[22:25]
	v_mfma_f32_16x16x32_bf16 v[62:65], v[160:163], v[192:195], v[62:65]
	v_mfma_f32_16x16x32_bf16 v[58:61], v[168:171], v[192:195], v[58:61]
	v_mfma_f32_16x16x32_bf16 v[46:49], v[168:171], v[200:203], v[46:49]
	v_mfma_f32_16x16x32_bf16 v[54:57], v[160:163], v[200:203], v[54:57]
	v_mfma_f32_16x16x32_bf16 v[38:41], v[160:163], v[208:211], v[38:41]
	v_mfma_f32_16x16x32_bf16 v[30:33], v[168:171], v[208:211], v[30:33]
	v_mfma_f32_16x16x32_bf16 v[14:17], v[168:171], v[216:219], v[14:17]
	v_mfma_f32_16x16x32_bf16 v[22:25], v[160:163], v[216:219], v[22:25]
	s_setprio 0
	s_setprio 1
	v_mfma_f32_16x16x32_bf16 v[50:53], v[172:175], v[188:191], v[50:53]
	v_mfma_f32_16x16x32_bf16 v[42:45], v[180:183], v[188:191], v[42:45]
	v_mfma_f32_16x16x32_bf16 v[26:29], v[180:183], v[196:199], v[26:29]
	v_mfma_f32_16x16x32_bf16 v[34:37], v[172:175], v[196:199], v[34:37]
	v_mfma_f32_16x16x32_bf16 v[18:21], v[172:175], v[204:207], v[18:21]
	v_mfma_f32_16x16x32_bf16 v[10:13], v[180:183], v[204:207], v[10:13]
	v_mfma_f32_16x16x32_bf16 v[2:5], v[180:183], v[212:215], v[2:5]
	v_mfma_f32_16x16x32_bf16 v[6:9], v[172:175], v[212:215], v[6:9]
	v_mfma_f32_16x16x32_bf16 v[50:53], v[176:179], v[192:195], v[50:53]
	v_mfma_f32_16x16x32_bf16 v[42:45], v[184:187], v[192:195], v[42:45]
	v_mfma_f32_16x16x32_bf16 v[26:29], v[184:187], v[200:203], v[26:29]
	v_mfma_f32_16x16x32_bf16 v[34:37], v[176:179], v[200:203], v[34:37]
	v_mfma_f32_16x16x32_bf16 v[18:21], v[176:179], v[208:211], v[18:21]
	v_mfma_f32_16x16x32_bf16 v[10:13], v[184:187], v[208:211], v[10:13]
	v_mfma_f32_16x16x32_bf16 v[2:5], v[184:187], v[216:219], v[2:5]
	v_mfma_f32_16x16x32_bf16 v[6:9], v[176:179], v[216:219], v[6:9]
	s_setprio 0
	s_barrier
	s_add_i32 s55, 0, 0x18000
	v_add_u32_e32 v155, s55, v150
	s_add_i32 s56, 0, 0x1c000
	ds_read_b128 v[156:159], v155
	ds_read_b128 v[160:163], v155 offset:1024
	ds_read_b128 v[164:167], v155 offset:2048
	ds_read_b128 v[168:171], v155 offset:3072
	v_add_u32_e32 v155, s56, v150
	ds_read_b128 v[172:175], v155
	ds_read_b128 v[176:179], v155 offset:1024
	ds_read_b128 v[180:183], v155 offset:2048
	ds_read_b128 v[184:187], v155 offset:3072
	s_add_u32 s30, s30, 0x80000
	s_addc_u32 s31, s31, 0
	s_mov_b32 m0, s39
	v_lshl_add_u64 v[226:227], s[30:31], 0, v[136:137]
	ds_read_b128 v[188:191], v154 offset:32768
	ds_read_b128 v[192:195], v154 offset:33792
	ds_read_b128 v[196:199], v154 offset:34816
	ds_read_b128 v[200:203], v154 offset:35840
	ds_read_b128 v[204:207], v154 offset:36864
	ds_read_b128 v[208:211], v154 offset:37888
	ds_read_b128 v[212:215], v154 offset:38912
	ds_read_b128 v[216:219], v154 offset:39936
	global_load_lds_dwordx4 v[226:227], off
	v_lshl_add_u64 v[226:227], s[30:31], 0, v[132:133]
	s_mov_b32 m0, s40
	s_nop 0
	global_load_lds_dwordx4 v[226:227], off
	s_waitcnt vmcnt(8)
	s_waitcnt lgkmcnt(0)
	s_barrier
	s_setprio 1
	s_waitcnt lgkmcnt(0)
	v_mfma_f32_16x16x32_bf16 v[126:129], v[156:159], v[188:191], v[126:129]
	v_mfma_f32_16x16x32_bf16 v[122:125], v[164:167], v[188:191], v[122:125]
	v_mfma_f32_16x16x32_bf16 v[110:113], v[164:167], v[196:199], v[110:113]
	v_mfma_f32_16x16x32_bf16 v[118:121], v[156:159], v[196:199], v[118:121]
	v_mfma_f32_16x16x32_bf16 v[102:105], v[156:159], v[204:207], v[102:105]
	v_mfma_f32_16x16x32_bf16 v[94:97], v[164:167], v[204:207], v[94:97]
	v_mfma_f32_16x16x32_bf16 v[78:81], v[164:167], v[212:215], v[78:81]
	v_mfma_f32_16x16x32_bf16 v[86:89], v[156:159], v[212:215], v[86:89]
	v_mfma_f32_16x16x32_bf16 v[126:129], v[160:163], v[192:195], v[126:129]
	v_mfma_f32_16x16x32_bf16 v[122:125], v[168:171], v[192:195], v[122:125]
	v_mfma_f32_16x16x32_bf16 v[110:113], v[168:171], v[200:203], v[110:113]
	v_mfma_f32_16x16x32_bf16 v[118:121], v[160:163], v[200:203], v[118:121]
	v_mfma_f32_16x16x32_bf16 v[102:105], v[160:163], v[208:211], v[102:105]
	v_mfma_f32_16x16x32_bf16 v[94:97], v[168:171], v[208:211], v[94:97]
	v_mfma_f32_16x16x32_bf16 v[78:81], v[168:171], v[216:219], v[78:81]
	v_mfma_f32_16x16x32_bf16 v[86:89], v[160:163], v[216:219], v[86:89]
	s_setprio 0
	s_setprio 1
	v_mfma_f32_16x16x32_bf16 v[114:117], v[172:175], v[188:191], v[114:117]
	v_mfma_f32_16x16x32_bf16 v[106:109], v[180:183], v[188:191], v[106:109]
	v_mfma_f32_16x16x32_bf16 v[90:93], v[180:183], v[196:199], v[90:93]
	v_mfma_f32_16x16x32_bf16 v[98:101], v[172:175], v[196:199], v[98:101]
	v_mfma_f32_16x16x32_bf16 v[82:85], v[172:175], v[204:207], v[82:85]
	v_mfma_f32_16x16x32_bf16 v[74:77], v[180:183], v[204:207], v[74:77]
	v_mfma_f32_16x16x32_bf16 v[66:69], v[180:183], v[212:215], v[66:69]
	v_mfma_f32_16x16x32_bf16 v[70:73], v[172:175], v[212:215], v[70:73]
	v_mfma_f32_16x16x32_bf16 v[114:117], v[176:179], v[192:195], v[114:117]
	v_mfma_f32_16x16x32_bf16 v[106:109], v[184:187], v[192:195], v[106:109]
	v_mfma_f32_16x16x32_bf16 v[90:93], v[184:187], v[200:203], v[90:93]
	v_mfma_f32_16x16x32_bf16 v[98:101], v[176:179], v[200:203], v[98:101]
	v_mfma_f32_16x16x32_bf16 v[82:85], v[176:179], v[208:211], v[82:85]
	v_mfma_f32_16x16x32_bf16 v[74:77], v[184:187], v[208:211], v[74:77]
	v_mfma_f32_16x16x32_bf16 v[66:69], v[184:187], v[216:219], v[66:69]
	v_mfma_f32_16x16x32_bf16 v[70:73], v[176:179], v[216:219], v[70:73]
	s_setprio 0
	s_barrier
; #define PG8_STAGE(bufoff, gbase, voff) do { _Pragma("unroll") for (int _i = 0; _i < 2; ++_i) \
;         __builtin_amdgcn_global_load_lds((const unsigned*)((const char*)(gbase) + (voff)[_i]), (PG8_LAS unsigned*)(lds + (bufoff) + ldsw + _i * 8192), 16, 0, 0); } while (0)
; #define PG8_LDA(dst, b, h) do { _Pragma("unroll") for (int m = 0; m < 4; ++m) _Pragma("unroll") for (int k = 0; k < 2; ++k) dst[m][k] = *(const PG8_LAS bf16x8*)(lds + PG8_SA(b, h) + aoff + m * 2048 + k * 1024); } while (0)
; #define PG8_MMA(ai, bj, At, Bt) do { __builtin_amdgcn_s_setprio(1); _Pragma("unroll") for (int m = 0; m < 4; ++m) _Pragma("unroll") for (int n = 0; n < 2; ++n) _Pragma("unroll") for (int k = 0; k < 2; ++k) \
;         acc[ai][bj][m][n] = __builtin_amdgcn_mfma_f32_16x16x32_bf16(Bt[n][k], At[m][k], acc[ai][bj][m][n], 0, 0, 0); __builtin_amdgcn_s_setprio(0); } while (0)
; #define PG8_WAIT_V(n) asm volatile("s_waitcnt vmcnt(" #n ")" ::: "memory")
; #define PG8_WAIT_L(n) asm volatile("s_waitcnt lgkmcnt(" #n ")" ::: "memory")
; #define PG8_BAR __builtin_amdgcn_s_barrier()
; #define PG8_SCHED __builtin_amdgcn_sched_barrier(0)
; template <class Epi, class Sched, bool ALIGN_EPI = false, bool SP2 = false>
; __device__ __forceinline__ void gemm_phase(PG8_LAS unsigned char* lds, const Gemm g, const Sched& S, const Epi& E) {
;     ...
;             PG8_LDA(At, 1, 1); PG8_STAGE(PG8_SB(1, 0), b3, voffB); PG8_STAGE(PG8_SB(1, 1), b3 + hstep, voffB); PG8_STAGE(PG8_SA(1, 0), a3, voffA);
;             PG8_WAIT_V(8); PG8_WAIT_L(0); PG8_BAR; PG8_MMA(1, 0, At, B0); PG8_MMA(1, 1, At, B1); PG8_BAR; PG8_SCHED;
	s_add_i32 s30, s55, s36
	v_lshl_add_u64 v[146:147], v[146:147], 0, s[12:13]
	s_mov_b32 m0, s30
	ds_read_b128 v[188:191], v154 offset:49152
	ds_read_b128 v[192:195], v154 offset:50176
	ds_read_b128 v[196:199], v154 offset:51200
	ds_read_b128 v[200:203], v154 offset:52224
	ds_read_b128 v[204:207], v154 offset:53248
	ds_read_b128 v[208:211], v154 offset:54272
	ds_read_b128 v[212:215], v154 offset:55296
	ds_read_b128 v[216:219], v154 offset:56320
	global_load_lds_dwordx4 v[146:147], off
	s_add_i32 m0, s30, 0x2000
	s_add_u32 s28, s28, 0x80080
	v_lshl_add_u64 v[146:147], v[220:221], 0, s[12:13]
	s_addc_u32 s29, s29, 0
	s_add_i32 s30, s56, s36
	global_load_lds_dwordx4 v[146:147], off
	v_lshl_add_u64 v[146:147], s[28:29], 0, v[134:135]
	s_mov_b32 m0, s30
	s_nop 0
	global_load_lds_dwordx4 v[146:147], off
	v_lshl_add_u64 v[146:147], s[28:29], 0, v[130:131]
	s_add_i32 m0, s30, 0x2000
	s_nop 0
	global_load_lds_dwordx4 v[146:147], off
	v_lshl_add_u64 v[146:147], v[222:223], 0, s[12:13]
	s_mov_b32 m0, s43
	s_nop 0
	global_load_lds_dwordx4 v[146:147], off
	v_lshl_add_u64 v[146:147], v[224:225], 0, s[12:13]
	s_mov_b32 m0, s44
	s_nop 0
	global_load_lds_dwordx4 v[146:147], off
	s_waitcnt vmcnt(8)
	s_waitcnt lgkmcnt(0)
	s_barrier
	s_setprio 1
	s_waitcnt lgkmcnt(0)
	v_mfma_f32_16x16x32_bf16 v[62:65], v[156:159], v[188:191], v[62:65]
	v_mfma_f32_16x16x32_bf16 v[58:61], v[164:167], v[188:191], v[58:61]
	v_mfma_f32_16x16x32_bf16 v[46:49], v[164:167], v[196:199], v[46:49]
	v_mfma_f32_16x16x32_bf16 v[54:57], v[156:159], v[196:199], v[54:57]
	v_mfma_f32_16x16x32_bf16 v[38:41], v[156:159], v[204:207], v[38:41]
	v_mfma_f32_16x16x32_bf16 v[30:33], v[164:167], v[204:207], v[30:33]
	v_mfma_f32_16x16x32_bf16 v[14:17], v[164:167], v[212:215], v[14:17]
	v_mfma_f32_16x16x32_bf16 v[22:25], v[156:159], v[212:215], v[22:25]
	v_mfma_f32_16x16x32_bf16 v[62:65], v[160:163], v[192:195], v[62:65]
	v_mfma_f32_16x16x32_bf16 v[58:61], v[168:171], v[192:195], v[58:61]
	v_mfma_f32_16x16x32_bf16 v[46:49], v[168:171], v[200:203], v[46:49]
	v_mfma_f32_16x16x32_bf16 v[54:57], v[160:163], v[200:203], v[54:57]
	v_mfma_f32_16x16x32_bf16 v[38:41], v[160:163], v[208:211], v[38:41]
	v_mfma_f32_16x16x32_bf16 v[30:33], v[168:171], v[208:211], v[30:33]
	v_mfma_f32_16x16x32_bf16 v[14:17], v[168:171], v[216:219], v[14:17]
	v_mfma_f32_16x16x32_bf16 v[22:25], v[160:163], v[216:219], v[22:25]
	s_setprio 0
	s_setprio 1
	v_mfma_f32_16x16x32_bf16 v[50:53], v[172:175], v[188:191], v[50:53]
	v_mfma_f32_16x16x32_bf16 v[42:45], v[180:183], v[188:191], v[42:45]
	v_mfma_f32_16x16x32_bf16 v[26:29], v[180:183], v[196:199], v[26:29]
	v_mfma_f32_16x16x32_bf16 v[34:37], v[172:175], v[196:199], v[34:37]
	v_mfma_f32_16x16x32_bf16 v[18:21], v[172:175], v[204:207], v[18:21]
	v_mfma_f32_16x16x32_bf16 v[10:13], v[180:183], v[204:207], v[10:13]
	v_mfma_f32_16x16x32_bf16 v[2:5], v[180:183], v[212:215], v[2:5]
	v_mfma_f32_16x16x32_bf16 v[6:9], v[172:175], v[212:215], v[6:9]
	v_mfma_f32_16x16x32_bf16 v[50:53], v[176:179], v[192:195], v[50:53]
	v_mfma_f32_16x16x32_bf16 v[42:45], v[184:187], v[192:195], v[42:45]
	v_mfma_f32_16x16x32_bf16 v[26:29], v[184:187], v[200:203], v[26:29]
	v_mfma_f32_16x16x32_bf16 v[34:37], v[176:179], v[200:203], v[34:37]
	v_mfma_f32_16x16x32_bf16 v[18:21], v[176:179], v[208:211], v[18:21]
	v_mfma_f32_16x16x32_bf16 v[10:13], v[184:187], v[208:211], v[10:13]
	v_mfma_f32_16x16x32_bf16 v[2:5], v[184:187], v[216:219], v[2:5]
	v_mfma_f32_16x16x32_bf16 v[6:9], v[176:179], v[216:219], v[6:9]
	s_setprio 0
	s_barrier
	s_add_i32 s54, s54, 2
	s_add_u32 s26, s26, 0x100
	s_addc_u32 s27, s27, 0
	s_add_u32 s52, s52, 0x100
	s_addc_u32 s53, s53, 0
	s_cmp_gt_u32 s54, 29
	s_cbranch_scc0 .LBB0_1393
	s_and_b64 vcc, exec, s[14:15]
	s_cbranch_vccz .LBB0_1396
	s_barrier

;     __device__ bool next(int i, Unit& u) const { if (!s.next(i, u)) return false; const int p = u.pn; u.pn = p < 56 ? (p % 7) * 8 + p / 7 : p; return true; }
;     __device__ bool next(int i, Unit& u) const { Unit t; if (!s.next(i >> 1, t)) return false; const int pass = i & 1; u.pm = t.pm + pass * (M / BM); u.pn = t.pn + pass * (D / BM); u.kt0 = 0; return true; }
; #define PG8_STAGE(bufoff, gbase, voff) do { _Pragma("unroll") for (int _i = 0; _i < 2; ++_i) \
;         __builtin_amdgcn_global_load_lds((const unsigned*)((const char*)(gbase) + (voff)[_i]), (PG8_LAS unsigned*)(lds + (bufoff) + ldsw + _i * 8192), 16, 0, 0); } while (0)
; #define PG8_LDA(dst, b, h) do { _Pragma("unroll") for (int m = 0; m < 4; ++m) _Pragma("unroll") for (int k = 0; k < 2; ++k) dst[m][k] = *(const PG8_LAS bf16x8*)(lds + PG8_SA(b, h) + aoff + m * 2048 + k * 1024); } while (0)
; template <class Epi, class Sched, bool ALIGN_EPI = false, bool SP2 = false>
; __device__ __forceinline__ void gemm_phase(PG8_LAS unsigned char* lds, const Gemm g, const Sched& S, const Epi& E) {
;     ...
;         const bool has_next = S.next(ui + 1, nxt);
;         const char* nA = has_next ? (const char*)g.A + (size_t)nxt.pm * tstep + (size_t)nxt.kt0 * kstep : cA; const char* nB = has_next ? (const char*)g.Bt + (size_t)nxt.pn * tstep + (size_t)nxt.kt0 * kstep : cB;
;         for (int t = 0; t < nt; t += 2) {
;             if constexpr (Epi::MIDHOOK) { if (t == (nt >> 1)) E.mid(acc, cur, wr, wc, fr, fq); }
;             const bool last = (t == nt - 2);
;             const char* a1 = cA + (size_t)(t + 1) * kstep;
;             const char* a2 = last ? nA : cA + (size_t)(t + 2) * kstep; const char* b2 = last ? nB : cB + (size_t)(t + 2) * kstep;
;             const char* a3 = a2 + kstep; const char* b3 = b2 + kstep;
;             if (last && has_next) S.a_ready(nxt);
;             if constexpr (SP2) {
;             PG8_LDB(B0, 0, 0); PG8_LDB(B1, 0, 1); PG8_SCHED; PG8_LDA(At, 0, 0); PG8_STAGE(PG8_SA(1, 1), a1 + hstep, voffA);
;             PG8_WAIT_V(8); PG8_WAIT_L(0); PG8_BAR; PG8_MMA(0, 0, At, B0); PG8_MMA(0, 1, At, B1); PG8_BAR; PG8_SCHED;
;             PG8_LDA(At, 0, 1); PG8_STAGE(PG8_SB(0, 0), b2, voffB); PG8_STAGE(PG8_SB(0, 1), b2 + hstep, voffB); PG8_STAGE(PG8_SA(0, 0), a2, voffA);
;             PG8_WAIT_V(8); PG8_WAIT_L(0); PG8_BAR; PG8_MMA(1, 0, At, B0); PG8_MMA(1, 1, At, B1); PG8_BAR; PG8_SCHED;
.LBB0_1428:
	s_add_u32 s21, s16, s7
	s_addc_u32 s23, s17, 0
	s_add_u32 s38, s21, 0x100
	s_addc_u32 s39, s23, 0
	s_and_b64 s[36:37], s[30:31], exec
	s_cselect_b32 s39, s25, s39
	s_cselect_b32 s38, s24, s38
	s_add_u32 s7, s14, s7
	s_addc_u32 s36, s15, 0
	s_add_u32 s7, s7, 0x100
	s_addc_u32 s36, s36, 0
	s_and_b64 s[30:31], s[30:31], exec
	s_cselect_b32 s41, s27, s36
	s_cselect_b32 s40, s26, s7
	s_add_u32 s46, s21, 0x80080
	s_addc_u32 s47, s23, 0
	s_add_i32 s70, s60, s44
	ds_read_b128 v[140:143], v137
	ds_read_b128 v[144:147], v137 offset:1024
	ds_read_b128 v[148:151], v137 offset:2048
	ds_read_b128 v[152:155], v137 offset:3072
	ds_read_b128 v[156:159], v138
	ds_read_b128 v[160:163], v138 offset:1024
	ds_read_b128 v[164:167], v138 offset:2048
	ds_read_b128 v[168:171], v138 offset:3072
	s_add_i32 m0, s51, 0xc000
	s_add_i32 s71, s51, 0xe000
	s_add_i32 s67, s70, 0x2000
	s_add_u32 s42, s40, 0x80000
	s_addc_u32 s43, s41, 0
	s_add_i32 s69, s61, s44
	s_add_i32 s68, s69, 0x2000
	s_add_i32 s66, 0, 0x18000
	s_add_i32 s65, 0, 0x1c000
	s_add_u32 s36, s38, 0x80000
	s_addc_u32 s37, s39, 0
	s_add_i32 s64, s66, s44
	s_add_i32 s21, s64, 0x2000
	s_add_u32 s30, s40, 0x80080
	s_addc_u32 s31, s41, 0
	s_add_i32 s23, s65, s44
	s_add_i32 s7, s23, 0x2000
	v_lshl_add_u64 v[204:205], s[46:47], 0, v[132:133]
	ds_read_b128 v[172:175], v139
	ds_read_b128 v[176:179], v139 offset:1024
	ds_read_b128 v[180:183], v139 offset:2048
	ds_read_b128 v[184:187], v139 offset:3072
	ds_read_b128 v[188:191], v139 offset:4096
	ds_read_b128 v[192:195], v139 offset:5120
	ds_read_b128 v[196:199], v139 offset:6144
	ds_read_b128 v[200:203], v139 offset:7168
	global_load_lds_dwordx4 v[204:205], off
	v_lshl_add_u64 v[204:205], s[46:47], 0, v[130:131]
	s_mov_b32 m0, s71
	s_nop 0
	global_load_lds_dwordx4 v[204:205], off
	s_waitcnt vmcnt(8)
	s_waitcnt lgkmcnt(0)
	s_barrier
	s_setprio 1
	s_waitcnt lgkmcnt(0)
	v_mfma_f32_16x16x32_bf16 v[126:129], v[140:143], v[172:175], v[126:129]
	v_mfma_f32_16x16x32_bf16 v[122:125], v[148:151], v[172:175], v[122:125]
	v_mfma_f32_16x16x32_bf16 v[114:117], v[148:151], v[180:183], v[114:117]
	v_mfma_f32_16x16x32_bf16 v[118:121], v[140:143], v[180:183], v[118:121]
	v_mfma_f32_16x16x32_bf16 v[106:109], v[140:143], v[188:191], v[106:109]
	v_mfma_f32_16x16x32_bf16 v[98:101], v[148:151], v[188:191], v[98:101]
	v_mfma_f32_16x16x32_bf16 v[82:85], v[148:151], v[196:199], v[82:85]
	v_mfma_f32_16x16x32_bf16 v[90:93], v[140:143], v[196:199], v[90:93]
	v_mfma_f32_16x16x32_bf16 v[126:129], v[144:147], v[176:179], v[126:129]
	v_mfma_f32_16x16x32_bf16 v[122:125], v[152:155], v[176:179], v[122:125]
	v_mfma_f32_16x16x32_bf16 v[114:117], v[152:155], v[184:187], v[114:117]
	v_mfma_f32_16x16x32_bf16 v[118:121], v[144:147], v[184:187], v[118:121]
	v_mfma_f32_16x16x32_bf16 v[106:109], v[144:147], v[192:195], v[106:109]
	v_mfma_f32_16x16x32_bf16 v[98:101], v[152:155], v[192:195], v[98:101]
	v_mfma_f32_16x16x32_bf16 v[82:85], v[152:155], v[200:203], v[82:85]
	v_mfma_f32_16x16x32_bf16 v[90:93], v[144:147], v[200:203], v[90:93]
	s_setprio 0
	s_setprio 1
	v_mfma_f32_16x16x32_bf16 v[110:113], v[156:159], v[172:175], v[110:113]
	v_mfma_f32_16x16x32_bf16 v[102:105], v[164:167], v[172:175], v[102:105]
	v_mfma_f32_16x16x32_bf16 v[86:89], v[164:167], v[180:183], v[86:89]
	v_mfma_f32_16x16x32_bf16 v[94:97], v[156:159], v[180:183], v[94:97]
	v_mfma_f32_16x16x32_bf16 v[78:81], v[156:159], v[188:191], v[78:81]
	v_mfma_f32_16x16x32_bf16 v[74:77], v[164:167], v[188:191], v[74:77]
	v_mfma_f32_16x16x32_bf16 v[66:69], v[164:167], v[196:199], v[66:69]
	v_mfma_f32_16x16x32_bf16 v[70:73], v[156:159], v[196:199], v[70:73]
	v_mfma_f32_16x16x32_bf16 v[110:113], v[160:163], v[176:179], v[110:113]
	v_mfma_f32_16x16x32_bf16 v[102:105], v[168:171], v[176:179], v[102:105]
	v_mfma_f32_16x16x32_bf16 v[86:89], v[168:171], v[184:187], v[86:89]
	v_mfma_f32_16x16x32_bf16 v[94:97], v[160:163], v[184:187], v[94:97]
	v_mfma_f32_16x16x32_bf16 v[78:81], v[160:163], v[192:195], v[78:81]
	v_mfma_f32_16x16x32_bf16 v[74:77], v[168:171], v[192:195], v[74:77]
	v_mfma_f32_16x16x32_bf16 v[66:69], v[168:171], v[200:203], v[66:69]
	v_mfma_f32_16x16x32_bf16 v[70:73], v[160:163], v[200:203], v[70:73]
	s_setprio 0
	s_barrier
	s_mov_b32 m0, s70
	v_lshl_add_u64 v[204:205], s[40:41], 0, v[132:133]
	ds_read_b128 v[172:175], v139 offset:16384
	ds_read_b128 v[176:179], v139 offset:17408
	ds_read_b128 v[180:183], v139 offset:18432
	ds_read_b128 v[184:187], v139 offset:19456
	ds_read_b128 v[188:191], v139 offset:20480
	ds_read_b128 v[192:195], v139 offset:21504
	ds_read_b128 v[196:199], v139 offset:22528
	ds_read_b128 v[200:203], v139 offset:23552
	global_load_lds_dwordx4 v[204:205], off
	v_lshl_add_u64 v[206:207], s[40:41], 0, v[130:131]
	s_mov_b32 m0, s67
	v_lshl_add_u64 v[208:209], s[42:43], 0, v[132:133]
	global_load_lds_dwordx4 v[206:207], off
	s_mov_b32 m0, s69
	v_lshl_add_u64 v[210:211], s[38:39], 0, v[130:131]
	global_load_lds_dwordx4 v[208:209], off
	v_lshl_add_u64 v[208:209], s[42:43], 0, v[130:131]
	s_mov_b32 m0, s68
	s_nop 0
	global_load_lds_dwordx4 v[208:209], off
	v_lshl_add_u64 v[208:209], s[38:39], 0, v[132:133]
	s_mov_b32 m0, s51
	s_nop 0
	global_load_lds_dwordx4 v[208:209], off
	s_mov_b32 m0, s52
	s_nop 0
	global_load_lds_dwordx4 v[210:211], off
	s_waitcnt vmcnt(8)
	s_waitcnt lgkmcnt(0)
	s_barrier
; #define PG8_STAGE(bufoff, gbase, voff) do { _Pragma("unroll") for (int _i = 0; _i < 2; ++_i) \
;         __builtin_amdgcn_global_load_lds((const unsigned*)((const char*)(gbase) + (voff)[_i]), (PG8_LAS unsigned*)(lds + (bufoff) + ldsw + _i * 8192), 16, 0, 0); } while (0)
; #define PG8_LDA(dst, b, h) do { _Pragma("unroll") for (int m = 0; m < 4; ++m) _Pragma("unroll") for (int k = 0; k < 2; ++k) dst[m][k] = *(const PG8_LAS bf16x8*)(lds + PG8_SA(b, h) + aoff + m * 2048 + k * 1024); } while (0)
; #define PG8_LDB(dst, b, h) do { _Pragma("unroll") for (int n = 0; n < 2; ++n) _Pragma("unroll") for (int k = 0; k < 2; ++k) dst[n][k] = *(const PG8_LAS bf16x8*)(lds + PG8_SB(b, h) + boff + n * 2048 + k * 1024); } while (0)
; #define PG8_MMA(ai, bj, At, Bt) do { __builtin_amdgcn_s_setprio(1); _Pragma("unroll") for (int m = 0; m < 4; ++m) _Pragma("unroll") for (int n = 0; n < 2; ++n) _Pragma("unroll") for (int k = 0; k < 2; ++k) \
;         acc[ai][bj][m][n] = __builtin_amdgcn_mfma_f32_16x16x32_bf16(Bt[n][k], At[m][k], acc[ai][bj][m][n], 0, 0, 0); __builtin_amdgcn_s_setprio(0); } while (0)
; #define PG8_WAIT_V(n) asm volatile("s_waitcnt vmcnt(" #n ")" ::: "memory")
; #define PG8_WAIT_L(n) asm volatile("s_waitcnt lgkmcnt(" #n ")" ::: "memory")
; #define PG8_BAR __builtin_amdgcn_s_barrier()
; #define PG8_SCHED __builtin_amdgcn_sched_barrier(0)
; template <class Epi, class Sched, bool ALIGN_EPI = false, bool SP2 = false>
; __device__ __forceinline__ void gemm_phase(PG8_LAS unsigned char* lds, const Gemm g, const Sched& S, const Epi& E) {
;     ...
;             PG8_WAIT_V(8); PG8_WAIT_L(0); PG8_BAR; PG8_MMA(1, 0, At, B0); PG8_MMA(1, 1, At, B1); PG8_BAR; PG8_SCHED;
;             PG8_LDB(B0, 1, 0); PG8_LDB(B1, 1, 1); PG8_SCHED; PG8_LDA(At, 1, 0); PG8_STAGE(PG8_SA(0, 1), a2 + hstep, voffA);
;             PG8_WAIT_V(8); PG8_WAIT_L(0); PG8_BAR; PG8_MMA(0, 0, At, B0); PG8_MMA(0, 1, At, B1); PG8_BAR; PG8_SCHED;
	s_setprio 1
	s_waitcnt lgkmcnt(0)
	v_mfma_f32_16x16x32_bf16 v[62:65], v[140:143], v[172:175], v[62:65]
	v_mfma_f32_16x16x32_bf16 v[58:61], v[148:151], v[172:175], v[58:61]
	v_mfma_f32_16x16x32_bf16 v[50:53], v[148:151], v[180:183], v[50:53]
	v_mfma_f32_16x16x32_bf16 v[54:57], v[140:143], v[180:183], v[54:57]
	v_mfma_f32_16x16x32_bf16 v[38:41], v[140:143], v[188:191], v[38:41]
	v_mfma_f32_16x16x32_bf16 v[34:37], v[148:151], v[188:191], v[34:37]
	v_mfma_f32_16x16x32_bf16 v[18:21], v[148:151], v[196:199], v[18:21]
	v_mfma_f32_16x16x32_bf16 v[22:25], v[140:143], v[196:199], v[22:25]
	v_mfma_f32_16x16x32_bf16 v[62:65], v[144:147], v[176:179], v[62:65]
	v_mfma_f32_16x16x32_bf16 v[58:61], v[152:155], v[176:179], v[58:61]
	v_mfma_f32_16x16x32_bf16 v[50:53], v[152:155], v[184:187], v[50:53]
	v_mfma_f32_16x16x32_bf16 v[54:57], v[144:147], v[184:187], v[54:57]
	v_mfma_f32_16x16x32_bf16 v[38:41], v[144:147], v[192:195], v[38:41]
	v_mfma_f32_16x16x32_bf16 v[34:37], v[152:155], v[192:195], v[34:37]
	v_mfma_f32_16x16x32_bf16 v[18:21], v[152:155], v[200:203], v[18:21]
	v_mfma_f32_16x16x32_bf16 v[22:25], v[144:147], v[200:203], v[22:25]
	s_setprio 0
	s_setprio 1
	v_mfma_f32_16x16x32_bf16 v[46:49], v[156:159], v[172:175], v[46:49]
	v_mfma_f32_16x16x32_bf16 v[42:45], v[164:167], v[172:175], v[42:45]
	v_mfma_f32_16x16x32_bf16 v[26:29], v[164:167], v[180:183], v[26:29]
	v_mfma_f32_16x16x32_bf16 v[30:33], v[156:159], v[180:183], v[30:33]
	v_mfma_f32_16x16x32_bf16 v[14:17], v[156:159], v[188:191], v[14:17]
	v_mfma_f32_16x16x32_bf16 v[10:13], v[164:167], v[188:191], v[10:13]
	v_mfma_f32_16x16x32_bf16 v[2:5], v[164:167], v[196:199], v[2:5]
	v_mfma_f32_16x16x32_bf16 v[6:9], v[156:159], v[196:199], v[6:9]
	v_mfma_f32_16x16x32_bf16 v[46:49], v[160:163], v[176:179], v[46:49]
	v_mfma_f32_16x16x32_bf16 v[42:45], v[168:171], v[176:179], v[42:45]
	v_mfma_f32_16x16x32_bf16 v[26:29], v[168:171], v[184:187], v[26:29]
	v_mfma_f32_16x16x32_bf16 v[30:33], v[160:163], v[184:187], v[30:33]
	v_mfma_f32_16x16x32_bf16 v[14:17], v[160:163], v[192:195], v[14:17]
	v_mfma_f32_16x16x32_bf16 v[10:13], v[168:171], v[192:195], v[10:13]
	v_mfma_f32_16x16x32_bf16 v[2:5], v[168:171], v[200:203], v[2:5]
	v_mfma_f32_16x16x32_bf16 v[6:9], v[160:163], v[200:203], v[6:9]
	s_setprio 0
	s_barrier
	v_add_u32_e32 v152, s66, v134
	v_add_u32_e32 v168, s65, v134
	ds_read_b128 v[140:143], v152
	ds_read_b128 v[144:147], v152 offset:1024
	ds_read_b128 v[148:151], v152 offset:2048
	ds_read_b128 v[152:155], v152 offset:3072
	ds_read_b128 v[156:159], v168
	ds_read_b128 v[160:163], v168 offset:1024
	ds_read_b128 v[164:167], v168 offset:2048
	ds_read_b128 v[168:171], v168 offset:3072
	s_mov_b32 m0, s53
	v_lshl_add_u64 v[212:213], s[36:37], 0, v[132:133]
	ds_read_b128 v[172:175], v139 offset:32768
	ds_read_b128 v[176:179], v139 offset:33792
	ds_read_b128 v[180:183], v139 offset:34816
	ds_read_b128 v[184:187], v139 offset:35840
	ds_read_b128 v[188:191], v139 offset:36864
	ds_read_b128 v[192:195], v139 offset:37888
	ds_read_b128 v[196:199], v139 offset:38912
	ds_read_b128 v[200:203], v139 offset:39936
	global_load_lds_dwordx4 v[212:213], off
	v_lshl_add_u64 v[212:213], s[36:37], 0, v[130:131]
	s_mov_b32 m0, s54
	s_nop 0
	global_load_lds_dwordx4 v[212:213], off
	s_waitcnt vmcnt(8)
	s_waitcnt lgkmcnt(0)
	s_barrier
	s_setprio 1
	s_waitcnt lgkmcnt(0)
	v_mfma_f32_16x16x32_bf16 v[126:129], v[140:143], v[172:175], v[126:129]
	v_mfma_f32_16x16x32_bf16 v[122:125], v[148:151], v[172:175], v[122:125]
	v_mfma_f32_16x16x32_bf16 v[114:117], v[148:151], v[180:183], v[114:117]
	v_mfma_f32_16x16x32_bf16 v[118:121], v[140:143], v[180:183], v[118:121]
	v_mfma_f32_16x16x32_bf16 v[106:109], v[140:143], v[188:191], v[106:109]
	v_mfma_f32_16x16x32_bf16 v[98:101], v[148:151], v[188:191], v[98:101]
	v_mfma_f32_16x16x32_bf16 v[82:85], v[148:151], v[196:199], v[82:85]
	v_mfma_f32_16x16x32_bf16 v[90:93], v[140:143], v[196:199], v[90:93]
	v_mfma_f32_16x16x32_bf16 v[126:129], v[144:147], v[176:179], v[126:129]
	v_mfma_f32_16x16x32_bf16 v[122:125], v[152:155], v[176:179], v[122:125]
	v_mfma_f32_16x16x32_bf16 v[114:117], v[152:155], v[184:187], v[114:117]
	v_mfma_f32_16x16x32_bf16 v[118:121], v[144:147], v[184:187], v[118:121]
	v_mfma_f32_16x16x32_bf16 v[106:109], v[144:147], v[192:195], v[106:109]
	v_mfma_f32_16x16x32_bf16 v[98:101], v[152:155], v[192:195], v[98:101]
	v_mfma_f32_16x16x32_bf16 v[82:85], v[152:155], v[200:203], v[82:85]
	v_mfma_f32_16x16x32_bf16 v[90:93], v[144:147], v[200:203], v[90:93]
	s_setprio 0
	s_setprio 1
	v_mfma_f32_16x16x32_bf16 v[110:113], v[156:159], v[172:175], v[110:113]
	v_mfma_f32_16x16x32_bf16 v[102:105], v[164:167], v[172:175], v[102:105]
	v_mfma_f32_16x16x32_bf16 v[86:89], v[164:167], v[180:183], v[86:89]
	v_mfma_f32_16x16x32_bf16 v[94:97], v[156:159], v[180:183], v[94:97]
	v_mfma_f32_16x16x32_bf16 v[78:81], v[156:159], v[188:191], v[78:81]
	v_mfma_f32_16x16x32_bf16 v[74:77], v[164:167], v[188:191], v[74:77]
	v_mfma_f32_16x16x32_bf16 v[66:69], v[164:167], v[196:199], v[66:69]
	v_mfma_f32_16x16x32_bf16 v[70:73], v[156:159], v[196:199], v[70:73]
	v_mfma_f32_16x16x32_bf16 v[110:113], v[160:163], v[176:179], v[110:113]
	v_mfma_f32_16x16x32_bf16 v[102:105], v[168:171], v[176:179], v[102:105]
	v_mfma_f32_16x16x32_bf16 v[86:89], v[168:171], v[184:187], v[86:89]
	v_mfma_f32_16x16x32_bf16 v[94:97], v[160:163], v[184:187], v[94:97]
	v_mfma_f32_16x16x32_bf16 v[78:81], v[160:163], v[192:195], v[78:81]
	v_mfma_f32_16x16x32_bf16 v[74:77], v[168:171], v[192:195], v[74:77]
	v_mfma_f32_16x16x32_bf16 v[66:69], v[168:171], v[200:203], v[66:69]
	v_mfma_f32_16x16x32_bf16 v[70:73], v[160:163], v[200:203], v[70:73]
	s_setprio 0
	s_barrier
; #define PG8_STAGE(bufoff, gbase, voff) do { _Pragma("unroll") for (int _i = 0; _i < 2; ++_i) \
;         __builtin_amdgcn_global_load_lds((const unsigned*)((const char*)(gbase) + (voff)[_i]), (PG8_LAS unsigned*)(lds + (bufoff) + ldsw + _i * 8192), 16, 0, 0); } while (0)
; #define PG8_LDA(dst, b, h) do { _Pragma("unroll") for (int m = 0; m < 4; ++m) _Pragma("unroll") for (int k = 0; k < 2; ++k) dst[m][k] = *(const PG8_LAS bf16x8*)(lds + PG8_SA(b, h) + aoff + m * 2048 + k * 1024); } while (0)
; #define PG8_MMA(ai, bj, At, Bt) do { __builtin_amdgcn_s_setprio(1); _Pragma("unroll") for (int m = 0; m < 4; ++m) _Pragma("unroll") for (int n = 0; n < 2; ++n) _Pragma("unroll") for (int k = 0; k < 2; ++k) \
;         acc[ai][bj][m][n] = __builtin_amdgcn_mfma_f32_16x16x32_bf16(Bt[n][k], At[m][k], acc[ai][bj][m][n], 0, 0, 0); __builtin_amdgcn_s_setprio(0); } while (0)
; #define PG8_WAIT_V(n) asm volatile("s_waitcnt vmcnt(" #n ")" ::: "memory")
; #define PG8_WAIT_L(n) asm volatile("s_waitcnt lgkmcnt(" #n ")" ::: "memory")
; #define PG8_BAR __builtin_amdgcn_s_barrier()
; #define PG8_SCHED __builtin_amdgcn_sched_barrier(0)
; template <class Epi, class Sched, bool ALIGN_EPI = false, bool SP2 = false>
; __device__ __forceinline__ void gemm_phase(PG8_LAS unsigned char* lds, const Gemm g, const Sched& S, const Epi& E) {
;     ...
;             PG8_LDA(At, 1, 1); PG8_STAGE(PG8_SB(1, 0), b3, voffB); PG8_STAGE(PG8_SB(1, 1), b3 + hstep, voffB); PG8_STAGE(PG8_SA(1, 0), a3, voffA);
;             PG8_WAIT_V(8); PG8_WAIT_L(0); PG8_BAR; PG8_MMA(1, 0, At, B0); PG8_MMA(1, 1, At, B1); PG8_BAR; PG8_SCHED;
	s_mov_b32 m0, s64
	v_lshl_add_u64 v[204:205], v[204:205], 0, s[12:13]
	ds_read_b128 v[172:175], v139 offset:49152
	ds_read_b128 v[176:179], v139 offset:50176
	ds_read_b128 v[180:183], v139 offset:51200
	ds_read_b128 v[184:187], v139 offset:52224
	ds_read_b128 v[188:191], v139 offset:53248
	ds_read_b128 v[192:195], v139 offset:54272
	ds_read_b128 v[196:199], v139 offset:55296
	ds_read_b128 v[200:203], v139 offset:56320
	global_load_lds_dwordx4 v[204:205], off
	v_lshl_add_u64 v[204:205], v[206:207], 0, s[12:13]
	s_mov_b32 m0, s21
	s_nop 0
	global_load_lds_dwordx4 v[204:205], off
	v_lshl_add_u64 v[204:205], s[30:31], 0, v[132:133]
	s_mov_b32 m0, s23
	s_nop 0
	global_load_lds_dwordx4 v[204:205], off
	v_lshl_add_u64 v[204:205], s[30:31], 0, v[130:131]
	s_mov_b32 m0, s7
	s_nop 0
	global_load_lds_dwordx4 v[204:205], off
	v_lshl_add_u64 v[204:205], v[208:209], 0, s[12:13]
	s_mov_b32 m0, s57
	s_nop 0
	global_load_lds_dwordx4 v[204:205], off
	v_lshl_add_u64 v[204:205], v[210:211], 0, s[12:13]
	s_mov_b32 m0, s58
	s_nop 0
	global_load_lds_dwordx4 v[204:205], off
	s_waitcnt vmcnt(8)
	s_waitcnt lgkmcnt(0)
	s_barrier
	s_setprio 1
	s_waitcnt lgkmcnt(0)
	v_mfma_f32_16x16x32_bf16 v[62:65], v[140:143], v[172:175], v[62:65]
	v_mfma_f32_16x16x32_bf16 v[58:61], v[148:151], v[172:175], v[58:61]
	v_mfma_f32_16x16x32_bf16 v[50:53], v[148:151], v[180:183], v[50:53]
	v_mfma_f32_16x16x32_bf16 v[54:57], v[140:143], v[180:183], v[54:57]
	v_mfma_f32_16x16x32_bf16 v[38:41], v[140:143], v[188:191], v[38:41]
	v_mfma_f32_16x16x32_bf16 v[34:37], v[148:151], v[188:191], v[34:37]
	v_mfma_f32_16x16x32_bf16 v[18:21], v[148:151], v[196:199], v[18:21]
	v_mfma_f32_16x16x32_bf16 v[22:25], v[140:143], v[196:199], v[22:25]
	v_mfma_f32_16x16x32_bf16 v[62:65], v[144:147], v[176:179], v[62:65]
	v_mfma_f32_16x16x32_bf16 v[58:61], v[152:155], v[176:179], v[58:61]
	v_mfma_f32_16x16x32_bf16 v[50:53], v[152:155], v[184:187], v[50:53]
	v_mfma_f32_16x16x32_bf16 v[54:57], v[144:147], v[184:187], v[54:57]
	v_mfma_f32_16x16x32_bf16 v[38:41], v[144:147], v[192:195], v[38:41]
	v_mfma_f32_16x16x32_bf16 v[34:37], v[152:155], v[192:195], v[34:37]
	v_mfma_f32_16x16x32_bf16 v[18:21], v[152:155], v[200:203], v[18:21]
	v_mfma_f32_16x16x32_bf16 v[22:25], v[144:147], v[200:203], v[22:25]
	s_setprio 0
	s_setprio 1
	v_mfma_f32_16x16x32_bf16 v[46:49], v[156:159], v[172:175], v[46:49]
	v_mfma_f32_16x16x32_bf16 v[42:45], v[164:167], v[172:175], v[42:45]
	v_mfma_f32_16x16x32_bf16 v[26:29], v[164:167], v[180:183], v[26:29]
	v_mfma_f32_16x16x32_bf16 v[30:33], v[156:159], v[180:183], v[30:33]
	v_mfma_f32_16x16x32_bf16 v[14:17], v[156:159], v[188:191], v[14:17]
	v_mfma_f32_16x16x32_bf16 v[10:13], v[164:167], v[188:191], v[10:13]
	v_mfma_f32_16x16x32_bf16 v[2:5], v[164:167], v[196:199], v[2:5]
	v_mfma_f32_16x16x32_bf16 v[6:9], v[156:159], v[196:199], v[6:9]
	v_mfma_f32_16x16x32_bf16 v[46:49], v[160:163], v[176:179], v[46:49]
	v_mfma_f32_16x16x32_bf16 v[42:45], v[168:171], v[176:179], v[42:45]
	v_mfma_f32_16x16x32_bf16 v[26:29], v[168:171], v[184:187], v[26:29]
	v_mfma_f32_16x16x32_bf16 v[30:33], v[160:163], v[184:187], v[30:33]
	v_mfma_f32_16x16x32_bf16 v[14:17], v[160:163], v[192:195], v[14:17]
	v_mfma_f32_16x16x32_bf16 v[10:13], v[168:171], v[192:195], v[10:13]
	v_mfma_f32_16x16x32_bf16 v[2:5], v[168:171], v[200:203], v[2:5]
	v_mfma_f32_16x16x32_bf16 v[6:9], v[160:163], v[200:203], v[6:9]
	s_setprio 0
	s_barrier
	s_movk_i32 s7, 0x100
	s_andn2_b64 vcc, exec, s[28:29]
	s_mov_b64 s[30:31], -1
	s_mov_b64 s[28:29], 0
	s_cbranch_vccz .LBB0_1428
	s_and_b64 vcc, exec, s[18:19]
	s_cbranch_vccz .LBB0_1431
	s_barrier

;     __device__ bool next(int i, Unit& u) const { if (!s.next(i, u)) return false; const int p = u.pn; u.pn = p < 56 ? (p % 7) * 8 + p / 7 : p; return true; }
;     __device__ bool next(int i, Unit& u) const { Unit t; if (!s.next(i >> 1, t)) return false; const int pass = i & 1; u.pm = t.pm + pass * (M / BM); u.pn = t.pn + pass * (D / BM); u.kt0 = 0; return true; }
; #define PG8_STAGE(bufoff, gbase, voff) do { _Pragma("unroll") for (int _i = 0; _i < 2; ++_i) \
;         __builtin_amdgcn_global_load_lds((const unsigned*)((const char*)(gbase) + (voff)[_i]), (PG8_LAS unsigned*)(lds + (bufoff) + ldsw + _i * 8192), 16, 0, 0); } while (0)
; #define PG8_LDA(dst, b, h) do { _Pragma("unroll") for (int m = 0; m < 4; ++m) _Pragma("unroll") for (int k = 0; k < 2; ++k) dst[m][k] = *(const PG8_LAS bf16x8*)(lds + PG8_SA(b, h) + aoff + m * 2048 + k * 1024); } while (0)
; template <class Epi, class Sched, bool ALIGN_EPI = false, bool SP2 = false>
; __device__ __forceinline__ void gemm_phase(PG8_LAS unsigned char* lds, const Gemm g, const Sched& S, const Epi& E) {
;     ...
;         const bool has_next = S.next(ui + 1, nxt);
;         const char* nA = has_next ? (const char*)g.A + (size_t)nxt.pm * tstep + (size_t)nxt.kt0 * kstep : cA; const char* nB = has_next ? (const char*)g.Bt + (size_t)nxt.pn * tstep + (size_t)nxt.kt0 * kstep : cB;
;         for (int t = 0; t < nt; t += 2) {
;             if constexpr (Epi::MIDHOOK) { if (t == (nt >> 1)) E.mid(acc, cur, wr, wc, fr, fq); }
;             const bool last = (t == nt - 2);
;             const char* a1 = cA + (size_t)(t + 1) * kstep;
;             const char* a2 = last ? nA : cA + (size_t)(t + 2) * kstep; const char* b2 = last ? nB : cB + (size_t)(t + 2) * kstep;
;             const char* a3 = a2 + kstep; const char* b3 = b2 + kstep;
;             if (last && has_next) S.a_ready(nxt);
;             if constexpr (SP2) {
;             PG8_LDB(B0, 0, 0); PG8_LDB(B1, 0, 1); PG8_SCHED; PG8_LDA(At, 0, 0); PG8_STAGE(PG8_SA(1, 1), a1 + hstep, voffA);
;             PG8_WAIT_V(8); PG8_WAIT_L(0); PG8_BAR; PG8_MMA(0, 0, At, B0); PG8_MMA(0, 1, At, B1); PG8_BAR; PG8_SCHED;
;             PG8_LDA(At, 0, 1); PG8_STAGE(PG8_SB(0, 0), b2, voffB); PG8_STAGE(PG8_SB(0, 1), b2 + hstep, voffB); PG8_STAGE(PG8_SA(0, 0), a2, voffA);
;             PG8_WAIT_V(8); PG8_WAIT_L(0); PG8_BAR; PG8_MMA(1, 0, At, B0); PG8_MMA(1, 1, At, B1); PG8_BAR; PG8_SCHED;
.LBB0_1551:
	ds_read_b128 v[146:149], v153
	ds_read_b128 v[156:159], v153 offset:1024
	ds_read_b128 v[160:163], v153 offset:2048
	ds_read_b128 v[164:167], v153 offset:3072
	ds_read_b128 v[168:171], v154
	ds_read_b128 v[172:175], v154 offset:1024
	ds_read_b128 v[176:179], v154 offset:2048
	ds_read_b128 v[180:183], v154 offset:3072
	s_add_u32 s26, s24, 0xfff80080
	s_addc_u32 s27, s25, -1
	s_cmp_eq_u32 s52, 28
	s_cselect_b32 s29, s17, s27
	s_cselect_b32 s28, s48, s26
	s_cselect_b32 s27, s15, s51
	s_cselect_b32 s26, s49, s50
	v_lshl_add_u64 v[216:217], s[24:25], 0, v[138:139]
	s_add_i32 m0, s23, 0xc000
	ds_read_b128 v[184:187], v155
	ds_read_b128 v[188:191], v155 offset:1024
	ds_read_b128 v[192:195], v155 offset:2048
	ds_read_b128 v[196:199], v155 offset:3072
	ds_read_b128 v[200:203], v155 offset:4096
	ds_read_b128 v[204:207], v155 offset:5120
	ds_read_b128 v[208:211], v155 offset:6144
	ds_read_b128 v[212:215], v155 offset:7168
	global_load_lds_dwordx4 v[216:217], off
	v_lshl_add_u64 v[216:217], s[24:25], 0, v[140:141]
	s_add_i32 m0, s23, 0xe000
	s_nop 0
	global_load_lds_dwordx4 v[216:217], off
	s_waitcnt vmcnt(8)
	s_waitcnt lgkmcnt(0)
	s_barrier
	s_setprio 1
	s_waitcnt lgkmcnt(0)
	v_mfma_f32_16x16x32_bf16 v[126:129], v[146:149], v[184:187], v[126:129]
	v_mfma_f32_16x16x32_bf16 v[122:125], v[160:163], v[184:187], v[122:125]
	v_mfma_f32_16x16x32_bf16 v[106:109], v[160:163], v[192:195], v[106:109]
	v_mfma_f32_16x16x32_bf16 v[110:113], v[146:149], v[192:195], v[110:113]
	v_mfma_f32_16x16x32_bf16 v[94:97], v[146:149], v[200:203], v[94:97]
	v_mfma_f32_16x16x32_bf16 v[90:93], v[160:163], v[200:203], v[90:93]
	v_mfma_f32_16x16x32_bf16 v[74:77], v[160:163], v[208:211], v[74:77]
	v_mfma_f32_16x16x32_bf16 v[78:81], v[146:149], v[208:211], v[78:81]
	v_mfma_f32_16x16x32_bf16 v[126:129], v[156:159], v[188:191], v[126:129]
	v_mfma_f32_16x16x32_bf16 v[122:125], v[164:167], v[188:191], v[122:125]
	v_mfma_f32_16x16x32_bf16 v[106:109], v[164:167], v[196:199], v[106:109]
	v_mfma_f32_16x16x32_bf16 v[110:113], v[156:159], v[196:199], v[110:113]
	v_mfma_f32_16x16x32_bf16 v[94:97], v[156:159], v[204:207], v[94:97]
	v_mfma_f32_16x16x32_bf16 v[90:93], v[164:167], v[204:207], v[90:93]
	v_mfma_f32_16x16x32_bf16 v[74:77], v[164:167], v[212:215], v[74:77]
	v_mfma_f32_16x16x32_bf16 v[78:81], v[156:159], v[212:215], v[78:81]
	s_setprio 0
	s_setprio 1
	v_mfma_f32_16x16x32_bf16 v[118:121], v[168:171], v[184:187], v[118:121]
	v_mfma_f32_16x16x32_bf16 v[114:117], v[176:179], v[184:187], v[114:117]
	v_mfma_f32_16x16x32_bf16 v[98:101], v[176:179], v[192:195], v[98:101]
	v_mfma_f32_16x16x32_bf16 v[102:105], v[168:171], v[192:195], v[102:105]
	v_mfma_f32_16x16x32_bf16 v[86:89], v[168:171], v[200:203], v[86:89]
	v_mfma_f32_16x16x32_bf16 v[82:85], v[176:179], v[200:203], v[82:85]
	v_mfma_f32_16x16x32_bf16 v[66:69], v[176:179], v[208:211], v[66:69]
	v_mfma_f32_16x16x32_bf16 v[70:73], v[168:171], v[208:211], v[70:73]
	v_mfma_f32_16x16x32_bf16 v[118:121], v[172:175], v[188:191], v[118:121]
	v_mfma_f32_16x16x32_bf16 v[114:117], v[180:183], v[188:191], v[114:117]
	v_mfma_f32_16x16x32_bf16 v[98:101], v[180:183], v[196:199], v[98:101]
	v_mfma_f32_16x16x32_bf16 v[102:105], v[172:175], v[196:199], v[102:105]
	v_mfma_f32_16x16x32_bf16 v[86:89], v[172:175], v[204:207], v[86:89]
	v_mfma_f32_16x16x32_bf16 v[82:85], v[180:183], v[204:207], v[82:85]
	v_mfma_f32_16x16x32_bf16 v[66:69], v[180:183], v[212:215], v[66:69]
	v_mfma_f32_16x16x32_bf16 v[70:73], v[172:175], v[212:215], v[70:73]
	s_setprio 0
	s_barrier
	s_add_i32 s53, s44, s31
	v_lshl_add_u64 v[216:217], s[26:27], 0, v[134:135]
	s_mov_b32 m0, s53
	ds_read_b128 v[184:187], v155 offset:16384
	ds_read_b128 v[188:191], v155 offset:17408
	ds_read_b128 v[192:195], v155 offset:18432
	ds_read_b128 v[196:199], v155 offset:19456
	ds_read_b128 v[200:203], v155 offset:20480
	ds_read_b128 v[204:207], v155 offset:21504
	ds_read_b128 v[208:211], v155 offset:22528
	ds_read_b128 v[212:215], v155 offset:23552
	global_load_lds_dwordx4 v[216:217], off
	s_add_i32 m0, s53, 0x2000
	s_add_u32 s54, s26, 0x80000
	v_lshl_add_u64 v[218:219], s[26:27], 0, v[130:131]
	s_addc_u32 s55, s27, 0
	s_add_i32 s53, s45, s31
	global_load_lds_dwordx4 v[218:219], off
	v_lshl_add_u64 v[220:221], s[54:55], 0, v[134:135]
	s_mov_b32 m0, s53
	v_lshl_add_u64 v[222:223], s[28:29], 0, v[132:133]
	global_load_lds_dwordx4 v[220:221], off
	v_lshl_add_u64 v[220:221], s[54:55], 0, v[130:131]
	s_add_i32 m0, s53, 0x2000
	s_nop 0
	global_load_lds_dwordx4 v[220:221], off
	v_lshl_add_u64 v[220:221], s[28:29], 0, v[136:137]
	s_mov_b32 m0, s23
	s_nop 0
	global_load_lds_dwordx4 v[220:221], off
	s_mov_b32 m0, s37
	s_nop 0
	global_load_lds_dwordx4 v[222:223], off
	s_waitcnt vmcnt(8)
	s_waitcnt lgkmcnt(0)
	s_barrier
; #define PG8_STAGE(bufoff, gbase, voff) do { _Pragma("unroll") for (int _i = 0; _i < 2; ++_i) \
;         __builtin_amdgcn_global_load_lds((const unsigned*)((const char*)(gbase) + (voff)[_i]), (PG8_LAS unsigned*)(lds + (bufoff) + ldsw + _i * 8192), 16, 0, 0); } while (0)
; #define PG8_LDA(dst, b, h) do { _Pragma("unroll") for (int m = 0; m < 4; ++m) _Pragma("unroll") for (int k = 0; k < 2; ++k) dst[m][k] = *(const PG8_LAS bf16x8*)(lds + PG8_SA(b, h) + aoff + m * 2048 + k * 1024); } while (0)
; #define PG8_LDB(dst, b, h) do { _Pragma("unroll") for (int n = 0; n < 2; ++n) _Pragma("unroll") for (int k = 0; k < 2; ++k) dst[n][k] = *(const PG8_LAS bf16x8*)(lds + PG8_SB(b, h) + boff + n * 2048 + k * 1024); } while (0)
; #define PG8_MMA(ai, bj, At, Bt) do { __builtin_amdgcn_s_setprio(1); _Pragma("unroll") for (int m = 0; m < 4; ++m) _Pragma("unroll") for (int n = 0; n < 2; ++n) _Pragma("unroll") for (int k = 0; k < 2; ++k) \
;         acc[ai][bj][m][n] = __builtin_amdgcn_mfma_f32_16x16x32_bf16(Bt[n][k], At[m][k], acc[ai][bj][m][n], 0, 0, 0); __builtin_amdgcn_s_setprio(0); } while (0)
; #define PG8_WAIT_V(n) asm volatile("s_waitcnt vmcnt(" #n ")" ::: "memory")
; #define PG8_WAIT_L(n) asm volatile("s_waitcnt lgkmcnt(" #n ")" ::: "memory")
; #define PG8_BAR __builtin_amdgcn_s_barrier()
; #define PG8_SCHED __builtin_amdgcn_sched_barrier(0)
; template <class Epi, class Sched, bool ALIGN_EPI = false, bool SP2 = false>
; __device__ __forceinline__ void gemm_phase(PG8_LAS unsigned char* lds, const Gemm g, const Sched& S, const Epi& E) {
;     ...
;             PG8_WAIT_V(8); PG8_WAIT_L(0); PG8_BAR; PG8_MMA(1, 0, At, B0); PG8_MMA(1, 1, At, B1); PG8_BAR; PG8_SCHED;
;             PG8_LDB(B0, 1, 0); PG8_LDB(B1, 1, 1); PG8_SCHED; PG8_LDA(At, 1, 0); PG8_STAGE(PG8_SA(0, 1), a2 + hstep, voffA);
;             PG8_WAIT_V(8); PG8_WAIT_L(0); PG8_BAR; PG8_MMA(0, 0, At, B0); PG8_MMA(0, 1, At, B1); PG8_BAR; PG8_SCHED;
	s_setprio 1
	s_waitcnt lgkmcnt(0)
	v_mfma_f32_16x16x32_bf16 v[62:65], v[146:149], v[184:187], v[62:65]
	v_mfma_f32_16x16x32_bf16 v[58:61], v[160:163], v[184:187], v[58:61]
	v_mfma_f32_16x16x32_bf16 v[42:45], v[160:163], v[192:195], v[42:45]
	v_mfma_f32_16x16x32_bf16 v[46:49], v[146:149], v[192:195], v[46:49]
	v_mfma_f32_16x16x32_bf16 v[30:33], v[146:149], v[200:203], v[30:33]
	v_mfma_f32_16x16x32_bf16 v[26:29], v[160:163], v[200:203], v[26:29]
	v_mfma_f32_16x16x32_bf16 v[10:13], v[160:163], v[208:211], v[10:13]
	v_mfma_f32_16x16x32_bf16 v[14:17], v[146:149], v[208:211], v[14:17]
	v_mfma_f32_16x16x32_bf16 v[62:65], v[156:159], v[188:191], v[62:65]
	v_mfma_f32_16x16x32_bf16 v[58:61], v[164:167], v[188:191], v[58:61]
	v_mfma_f32_16x16x32_bf16 v[42:45], v[164:167], v[196:199], v[42:45]
	v_mfma_f32_16x16x32_bf16 v[46:49], v[156:159], v[196:199], v[46:49]
	v_mfma_f32_16x16x32_bf16 v[30:33], v[156:159], v[204:207], v[30:33]
	v_mfma_f32_16x16x32_bf16 v[26:29], v[164:167], v[204:207], v[26:29]
	v_mfma_f32_16x16x32_bf16 v[10:13], v[164:167], v[212:215], v[10:13]
	v_mfma_f32_16x16x32_bf16 v[14:17], v[156:159], v[212:215], v[14:17]
	s_setprio 0
	s_setprio 1
	v_mfma_f32_16x16x32_bf16 v[54:57], v[168:171], v[184:187], v[54:57]
	v_mfma_f32_16x16x32_bf16 v[50:53], v[176:179], v[184:187], v[50:53]
	v_mfma_f32_16x16x32_bf16 v[34:37], v[176:179], v[192:195], v[34:37]
	v_mfma_f32_16x16x32_bf16 v[38:41], v[168:171], v[192:195], v[38:41]
	v_mfma_f32_16x16x32_bf16 v[22:25], v[168:171], v[200:203], v[22:25]
	v_mfma_f32_16x16x32_bf16 v[18:21], v[176:179], v[200:203], v[18:21]
	v_mfma_f32_16x16x32_bf16 v[2:5], v[176:179], v[208:211], v[2:5]
	v_mfma_f32_16x16x32_bf16 v[6:9], v[168:171], v[208:211], v[6:9]
	v_mfma_f32_16x16x32_bf16 v[54:57], v[172:175], v[188:191], v[54:57]
	v_mfma_f32_16x16x32_bf16 v[50:53], v[180:183], v[188:191], v[50:53]
	v_mfma_f32_16x16x32_bf16 v[34:37], v[180:183], v[196:199], v[34:37]
	v_mfma_f32_16x16x32_bf16 v[38:41], v[172:175], v[196:199], v[38:41]
	v_mfma_f32_16x16x32_bf16 v[22:25], v[172:175], v[204:207], v[22:25]
	v_mfma_f32_16x16x32_bf16 v[18:21], v[180:183], v[204:207], v[18:21]
	v_mfma_f32_16x16x32_bf16 v[2:5], v[180:183], v[212:215], v[2:5]
	v_mfma_f32_16x16x32_bf16 v[6:9], v[172:175], v[212:215], v[6:9]
	s_setprio 0
	s_barrier
	s_add_i32 s53, 0, 0x18000
	s_add_i32 s54, 0, 0x1c000
	v_add_u32_e32 v164, s53, v151
	v_add_u32_e32 v180, s54, v151
	ds_read_b128 v[146:149], v164
	ds_read_b128 v[156:159], v164 offset:1024
	ds_read_b128 v[160:163], v164 offset:2048
	ds_read_b128 v[164:167], v164 offset:3072
	ds_read_b128 v[168:171], v180
	ds_read_b128 v[172:175], v180 offset:1024
	ds_read_b128 v[176:179], v180 offset:2048
	ds_read_b128 v[180:183], v180 offset:3072
	s_add_u32 s28, s28, 0x80000
	s_addc_u32 s29, s29, 0
	s_mov_b32 m0, s38
	v_lshl_add_u64 v[224:225], s[28:29], 0, v[136:137]
	ds_read_b128 v[184:187], v155 offset:32768
	ds_read_b128 v[188:191], v155 offset:33792
	ds_read_b128 v[192:195], v155 offset:34816
	ds_read_b128 v[196:199], v155 offset:35840
	ds_read_b128 v[200:203], v155 offset:36864
	ds_read_b128 v[204:207], v155 offset:37888
	ds_read_b128 v[208:211], v155 offset:38912
	ds_read_b128 v[212:215], v155 offset:39936
	global_load_lds_dwordx4 v[224:225], off
	v_lshl_add_u64 v[224:225], s[28:29], 0, v[132:133]
	s_mov_b32 m0, s39
	s_nop 0
	global_load_lds_dwordx4 v[224:225], off
	s_waitcnt vmcnt(8)
	s_waitcnt lgkmcnt(0)
	s_barrier
	s_setprio 1
	s_waitcnt lgkmcnt(0)
	v_mfma_f32_16x16x32_bf16 v[126:129], v[146:149], v[184:187], v[126:129]
	v_mfma_f32_16x16x32_bf16 v[122:125], v[160:163], v[184:187], v[122:125]
	v_mfma_f32_16x16x32_bf16 v[106:109], v[160:163], v[192:195], v[106:109]
	v_mfma_f32_16x16x32_bf16 v[110:113], v[146:149], v[192:195], v[110:113]
	v_mfma_f32_16x16x32_bf16 v[94:97], v[146:149], v[200:203], v[94:97]
	v_mfma_f32_16x16x32_bf16 v[90:93], v[160:163], v[200:203], v[90:93]
	v_mfma_f32_16x16x32_bf16 v[74:77], v[160:163], v[208:211], v[74:77]
	v_mfma_f32_16x16x32_bf16 v[78:81], v[146:149], v[208:211], v[78:81]
	v_mfma_f32_16x16x32_bf16 v[126:129], v[156:159], v[188:191], v[126:129]
	v_mfma_f32_16x16x32_bf16 v[122:125], v[164:167], v[188:191], v[122:125]
	v_mfma_f32_16x16x32_bf16 v[106:109], v[164:167], v[196:199], v[106:109]
	v_mfma_f32_16x16x32_bf16 v[110:113], v[156:159], v[196:199], v[110:113]
	v_mfma_f32_16x16x32_bf16 v[94:97], v[156:159], v[204:207], v[94:97]
	v_mfma_f32_16x16x32_bf16 v[90:93], v[164:167], v[204:207], v[90:93]
	v_mfma_f32_16x16x32_bf16 v[74:77], v[164:167], v[212:215], v[74:77]
	v_mfma_f32_16x16x32_bf16 v[78:81], v[156:159], v[212:215], v[78:81]
	s_setprio 0
	s_setprio 1
	v_mfma_f32_16x16x32_bf16 v[118:121], v[168:171], v[184:187], v[118:121]
	v_mfma_f32_16x16x32_bf16 v[114:117], v[176:179], v[184:187], v[114:117]
	v_mfma_f32_16x16x32_bf16 v[98:101], v[176:179], v[192:195], v[98:101]
	v_mfma_f32_16x16x32_bf16 v[102:105], v[168:171], v[192:195], v[102:105]
	v_mfma_f32_16x16x32_bf16 v[86:89], v[168:171], v[200:203], v[86:89]
	v_mfma_f32_16x16x32_bf16 v[82:85], v[176:179], v[200:203], v[82:85]
	v_mfma_f32_16x16x32_bf16 v[66:69], v[176:179], v[208:211], v[66:69]
	v_mfma_f32_16x16x32_bf16 v[70:73], v[168:171], v[208:211], v[70:73]
	v_mfma_f32_16x16x32_bf16 v[118:121], v[172:175], v[188:191], v[118:121]
	v_mfma_f32_16x16x32_bf16 v[114:117], v[180:183], v[188:191], v[114:117]
	v_mfma_f32_16x16x32_bf16 v[98:101], v[180:183], v[196:199], v[98:101]
	v_mfma_f32_16x16x32_bf16 v[102:105], v[172:175], v[196:199], v[102:105]
	v_mfma_f32_16x16x32_bf16 v[86:89], v[172:175], v[204:207], v[86:89]
	v_mfma_f32_16x16x32_bf16 v[82:85], v[180:183], v[204:207], v[82:85]
	v_mfma_f32_16x16x32_bf16 v[66:69], v[180:183], v[212:215], v[66:69]
	v_mfma_f32_16x16x32_bf16 v[70:73], v[172:175], v[212:215], v[70:73]
	s_setprio 0
	s_barrier
; #define PG8_STAGE(bufoff, gbase, voff) do { _Pragma("unroll") for (int _i = 0; _i < 2; ++_i) \
;         __builtin_amdgcn_global_load_lds((const unsigned*)((const char*)(gbase) + (voff)[_i]), (PG8_LAS unsigned*)(lds + (bufoff) + ldsw + _i * 8192), 16, 0, 0); } while (0)
; #define PG8_LDA(dst, b, h) do { _Pragma("unroll") for (int m = 0; m < 4; ++m) _Pragma("unroll") for (int k = 0; k < 2; ++k) dst[m][k] = *(const PG8_LAS bf16x8*)(lds + PG8_SA(b, h) + aoff + m * 2048 + k * 1024); } while (0)
; #define PG8_MMA(ai, bj, At, Bt) do { __builtin_amdgcn_s_setprio(1); _Pragma("unroll") for (int m = 0; m < 4; ++m) _Pragma("unroll") for (int n = 0; n < 2; ++n) _Pragma("unroll") for (int k = 0; k < 2; ++k) \
;         acc[ai][bj][m][n] = __builtin_amdgcn_mfma_f32_16x16x32_bf16(Bt[n][k], At[m][k], acc[ai][bj][m][n], 0, 0, 0); __builtin_amdgcn_s_setprio(0); } while (0)
; #define PG8_WAIT_V(n) asm volatile("s_waitcnt vmcnt(" #n ")" ::: "memory")
; #define PG8_WAIT_L(n) asm volatile("s_waitcnt lgkmcnt(" #n ")" ::: "memory")
; #define PG8_BAR __builtin_amdgcn_s_barrier()
; #define PG8_SCHED __builtin_amdgcn_sched_barrier(0)
; template <class Epi, class Sched, bool ALIGN_EPI = false, bool SP2 = false>
; __device__ __forceinline__ void gemm_phase(PG8_LAS unsigned char* lds, const Gemm g, const Sched& S, const Epi& E) {
;     ...
;         for (int t = 0; t < nt; t += 2) {
;             if constexpr (Epi::MIDHOOK) { if (t == (nt >> 1)) E.mid(acc, cur, wr, wc, fr, fq); }
;             const bool last = (t == nt - 2);
;             const char* a1 = cA + (size_t)(t + 1) * kstep;
;             const char* a2 = last ? nA : cA + (size_t)(t + 2) * kstep; const char* b2 = last ? nB : cB + (size_t)(t + 2) * kstep;
;     ...
;             PG8_LDA(At, 1, 1); PG8_STAGE(PG8_SB(1, 0), b3, voffB); PG8_STAGE(PG8_SB(1, 1), b3 + hstep, voffB); PG8_STAGE(PG8_SA(1, 0), a3, voffA);
;             PG8_WAIT_V(8); PG8_WAIT_L(0); PG8_BAR; PG8_MMA(1, 0, At, B0); PG8_MMA(1, 1, At, B1); PG8_BAR; PG8_SCHED;
	s_add_i32 s28, s53, s31
	v_lshl_add_u64 v[216:217], v[216:217], 0, s[10:11]
	s_mov_b32 m0, s28
	ds_read_b128 v[184:187], v155 offset:49152
	ds_read_b128 v[188:191], v155 offset:50176
	ds_read_b128 v[192:195], v155 offset:51200
	ds_read_b128 v[196:199], v155 offset:52224
	ds_read_b128 v[200:203], v155 offset:53248
	ds_read_b128 v[204:207], v155 offset:54272
	ds_read_b128 v[208:211], v155 offset:55296
	ds_read_b128 v[212:215], v155 offset:56320
	global_load_lds_dwordx4 v[216:217], off
	s_add_i32 m0, s28, 0x2000
	s_add_u32 s26, s26, 0x80080
	v_lshl_add_u64 v[216:217], v[218:219], 0, s[10:11]
	s_addc_u32 s27, s27, 0
	s_add_i32 s28, s54, s31
	global_load_lds_dwordx4 v[216:217], off
	v_lshl_add_u64 v[216:217], s[26:27], 0, v[134:135]
	s_mov_b32 m0, s28
	s_nop 0
	global_load_lds_dwordx4 v[216:217], off
	v_lshl_add_u64 v[216:217], s[26:27], 0, v[130:131]
	s_add_i32 m0, s28, 0x2000
	s_nop 0
	global_load_lds_dwordx4 v[216:217], off
	v_lshl_add_u64 v[216:217], v[220:221], 0, s[10:11]
	s_mov_b32 m0, s42
	s_nop 0
	global_load_lds_dwordx4 v[216:217], off
	v_lshl_add_u64 v[216:217], v[222:223], 0, s[10:11]
	s_mov_b32 m0, s43
	s_nop 0
	global_load_lds_dwordx4 v[216:217], off
	s_waitcnt vmcnt(8)
	s_waitcnt lgkmcnt(0)
	s_barrier
	s_setprio 1
	s_waitcnt lgkmcnt(0)
	v_mfma_f32_16x16x32_bf16 v[62:65], v[146:149], v[184:187], v[62:65]
	v_mfma_f32_16x16x32_bf16 v[58:61], v[160:163], v[184:187], v[58:61]
	v_mfma_f32_16x16x32_bf16 v[42:45], v[160:163], v[192:195], v[42:45]
	v_mfma_f32_16x16x32_bf16 v[46:49], v[146:149], v[192:195], v[46:49]
	v_mfma_f32_16x16x32_bf16 v[30:33], v[146:149], v[200:203], v[30:33]
	v_mfma_f32_16x16x32_bf16 v[26:29], v[160:163], v[200:203], v[26:29]
	v_mfma_f32_16x16x32_bf16 v[10:13], v[160:163], v[208:211], v[10:13]
	v_mfma_f32_16x16x32_bf16 v[14:17], v[146:149], v[208:211], v[14:17]
	v_mfma_f32_16x16x32_bf16 v[62:65], v[156:159], v[188:191], v[62:65]
	v_mfma_f32_16x16x32_bf16 v[58:61], v[164:167], v[188:191], v[58:61]
	v_mfma_f32_16x16x32_bf16 v[42:45], v[164:167], v[196:199], v[42:45]
	v_mfma_f32_16x16x32_bf16 v[46:49], v[156:159], v[196:199], v[46:49]
	v_mfma_f32_16x16x32_bf16 v[30:33], v[156:159], v[204:207], v[30:33]
	v_mfma_f32_16x16x32_bf16 v[26:29], v[164:167], v[204:207], v[26:29]
	v_mfma_f32_16x16x32_bf16 v[10:13], v[164:167], v[212:215], v[10:13]
	v_mfma_f32_16x16x32_bf16 v[14:17], v[156:159], v[212:215], v[14:17]
	s_setprio 0
	s_setprio 1
	v_mfma_f32_16x16x32_bf16 v[54:57], v[168:171], v[184:187], v[54:57]
	v_mfma_f32_16x16x32_bf16 v[50:53], v[176:179], v[184:187], v[50:53]
	v_mfma_f32_16x16x32_bf16 v[34:37], v[176:179], v[192:195], v[34:37]
	v_mfma_f32_16x16x32_bf16 v[38:41], v[168:171], v[192:195], v[38:41]
	v_mfma_f32_16x16x32_bf16 v[22:25], v[168:171], v[200:203], v[22:25]
	v_mfma_f32_16x16x32_bf16 v[18:21], v[176:179], v[200:203], v[18:21]
	v_mfma_f32_16x16x32_bf16 v[2:5], v[176:179], v[208:211], v[2:5]
	v_mfma_f32_16x16x32_bf16 v[6:9], v[168:171], v[208:211], v[6:9]
	v_mfma_f32_16x16x32_bf16 v[54:57], v[172:175], v[188:191], v[54:57]
	v_mfma_f32_16x16x32_bf16 v[50:53], v[180:183], v[188:191], v[50:53]
	v_mfma_f32_16x16x32_bf16 v[34:37], v[180:183], v[196:199], v[34:37]
	v_mfma_f32_16x16x32_bf16 v[38:41], v[172:175], v[196:199], v[38:41]
	v_mfma_f32_16x16x32_bf16 v[22:25], v[172:175], v[204:207], v[22:25]
	v_mfma_f32_16x16x32_bf16 v[18:21], v[180:183], v[204:207], v[18:21]
	v_mfma_f32_16x16x32_bf16 v[2:5], v[180:183], v[212:215], v[2:5]
	v_mfma_f32_16x16x32_bf16 v[6:9], v[172:175], v[212:215], v[6:9]
	s_setprio 0
	s_barrier
	s_add_i32 s52, s52, 2
	s_add_u32 s24, s24, 0x100
	s_addc_u32 s25, s25, 0
	s_add_u32 s50, s50, 0x100
	s_addc_u32 s51, s51, 0
	s_cmp_gt_u32 s52, 29
	s_cbranch_scc0 .LBB0_1551
	s_and_b64 vcc, exec, s[12:13]
	s_cbranch_vccz .LBB0_1554
	s_barrier

; #define PG8_STAGE(bufoff, gbase, voff) do { _Pragma("unroll") for (int _i = 0; _i < 2; ++_i) \
;         __builtin_amdgcn_global_load_lds((const unsigned*)((const char*)(gbase) + (voff)[_i]), (PG8_LAS unsigned*)(lds + (bufoff) + ldsw + _i * 8192), 16, 0, 0); } while (0)
; #define PG8_LDA(dst, b, h) do { _Pragma("unroll") for (int m = 0; m < 4; ++m) _Pragma("unroll") for (int k = 0; k < 2; ++k) dst[m][k] = *(const PG8_LAS bf16x8*)(lds + PG8_SA(b, h) + aoff + m * 2048 + k * 1024); } while (0)
; #define PG8_LDB(dst, b, h) do { _Pragma("unroll") for (int n = 0; n < 2; ++n) _Pragma("unroll") for (int k = 0; k < 2; ++k) dst[n][k] = *(const PG8_LAS bf16x8*)(lds + PG8_SB(b, h) + boff + n * 2048 + k * 1024); } while (0)
; #define PG8_MMA(ai, bj, At, Bt) do { __builtin_amdgcn_s_setprio(1); _Pragma("unroll") for (int m = 0; m < 4; ++m) _Pragma("unroll") for (int n = 0; n < 2; ++n) _Pragma("unroll") for (int k = 0; k < 2; ++k) \
;         acc[ai][bj][m][n] = __builtin_amdgcn_mfma_f32_16x16x32_bf16(Bt[n][k], At[m][k], acc[ai][bj][m][n], 0, 0, 0); __builtin_amdgcn_s_setprio(0); } while (0)
; #define PG8_WAIT_V(n) asm volatile("s_waitcnt vmcnt(" #n ")" ::: "memory")
; #define PG8_WAIT_L(n) asm volatile("s_waitcnt lgkmcnt(" #n ")" ::: "memory")
; template <class Epi, class Sched, bool ALIGN_EPI = false, bool SP2 = false>
; __device__ __forceinline__ void gemm_phase(PG8_LAS unsigned char* lds, const Gemm g, const Sched& S, const Epi& E) {
;     ...
;         for (int t = 0; t < nt; t += 2) {
;             if constexpr (Epi::MIDHOOK) { if (t == (nt >> 1)) E.mid(acc, cur, wr, wc, fr, fq); }
;             const bool last = (t == nt - 2);
;             const char* a1 = cA + (size_t)(t + 1) * kstep;
;             const char* a2 = last ? nA : cA + (size_t)(t + 2) * kstep; const char* b2 = last ? nB : cB + (size_t)(t + 2) * kstep;
;             const char* a3 = a2 + kstep; const char* b3 = b2 + kstep;
;             if (last && has_next) S.a_ready(nxt);
;             if constexpr (SP2) {
;             PG8_LDB(B0, 0, 0); PG8_LDB(B1, 0, 1); PG8_SCHED; PG8_LDA(At, 0, 0); PG8_STAGE(PG8_SA(1, 1), a1 + hstep, voffA);
;             PG8_WAIT_V(8); PG8_WAIT_L(0); PG8_BAR; PG8_MMA(0, 0, At, B0); PG8_MMA(0, 1, At, B1); PG8_BAR; PG8_SCHED;
;             PG8_LDA(At, 0, 1); PG8_STAGE(PG8_SB(0, 0), b2, voffB); PG8_STAGE(PG8_SB(0, 1), b2 + hstep, voffB); PG8_STAGE(PG8_SA(0, 0), a2, voffA);
.LBB0_1656:
	ds_read_b128 v[154:157], v151
	ds_read_b128 v[158:161], v151 offset:1024
	ds_read_b128 v[162:165], v151 offset:2048
	ds_read_b128 v[166:169], v151 offset:3072
	ds_read_b128 v[170:173], v152
	ds_read_b128 v[174:177], v152 offset:1024
	ds_read_b128 v[178:181], v152 offset:2048
	ds_read_b128 v[182:185], v152 offset:3072
	s_add_u32 s26, s24, 0x100
	s_addc_u32 s27, s25, 0
	s_cmpk_eq_i32 s58, 0x54
	s_cselect_b32 s31, s7, s27
	s_cselect_b32 s30, s6, s26
	s_cselect_b32 s29, s23, s57
	s_cselect_b32 s28, s22, s56
	v_lshl_add_u64 v[146:147], s[24:25], 0, v[138:139]
	s_add_i32 m0, s38, 0xc000
	ds_read_b128 v[186:189], v153
	ds_read_b128 v[190:193], v153 offset:1024
	ds_read_b128 v[194:197], v153 offset:2048
	ds_read_b128 v[198:201], v153 offset:3072
	ds_read_b128 v[202:205], v153 offset:4096
	ds_read_b128 v[206:209], v153 offset:5120
	ds_read_b128 v[210:213], v153 offset:6144
	ds_read_b128 v[214:217], v153 offset:7168
	global_load_lds_dwordx4 v[146:147], off
	v_lshl_add_u64 v[146:147], s[24:25], 0, v[140:141]
	s_add_i32 m0, s38, 0xe000
	s_nop 0
	global_load_lds_dwordx4 v[146:147], off
	s_waitcnt vmcnt(8)
	s_waitcnt lgkmcnt(0)
	s_barrier
	s_setprio 1
	s_waitcnt lgkmcnt(0)
	v_mfma_f32_16x16x32_bf16 v[126:129], v[154:157], v[186:189], v[126:129]
	v_mfma_f32_16x16x32_bf16 v[122:125], v[162:165], v[186:189], v[122:125]
	v_mfma_f32_16x16x32_bf16 v[110:113], v[162:165], v[194:197], v[110:113]
	v_mfma_f32_16x16x32_bf16 v[118:121], v[154:157], v[194:197], v[118:121]
	v_mfma_f32_16x16x32_bf16 v[102:105], v[154:157], v[202:205], v[102:105]
	v_mfma_f32_16x16x32_bf16 v[94:97], v[162:165], v[202:205], v[94:97]
	v_mfma_f32_16x16x32_bf16 v[78:81], v[162:165], v[210:213], v[78:81]
	v_mfma_f32_16x16x32_bf16 v[86:89], v[154:157], v[210:213], v[86:89]
	v_mfma_f32_16x16x32_bf16 v[126:129], v[158:161], v[190:193], v[126:129]
	v_mfma_f32_16x16x32_bf16 v[122:125], v[166:169], v[190:193], v[122:125]
	v_mfma_f32_16x16x32_bf16 v[110:113], v[166:169], v[198:201], v[110:113]
	v_mfma_f32_16x16x32_bf16 v[118:121], v[158:161], v[198:201], v[118:121]
	v_mfma_f32_16x16x32_bf16 v[102:105], v[158:161], v[206:209], v[102:105]
	v_mfma_f32_16x16x32_bf16 v[94:97], v[166:169], v[206:209], v[94:97]
	v_mfma_f32_16x16x32_bf16 v[78:81], v[166:169], v[214:217], v[78:81]
	v_mfma_f32_16x16x32_bf16 v[86:89], v[158:161], v[214:217], v[86:89]
	s_setprio 0
	s_setprio 1
	v_mfma_f32_16x16x32_bf16 v[114:117], v[170:173], v[186:189], v[114:117]
	v_mfma_f32_16x16x32_bf16 v[106:109], v[178:181], v[186:189], v[106:109]
	v_mfma_f32_16x16x32_bf16 v[90:93], v[178:181], v[194:197], v[90:93]
	v_mfma_f32_16x16x32_bf16 v[98:101], v[170:173], v[194:197], v[98:101]
	v_mfma_f32_16x16x32_bf16 v[82:85], v[170:173], v[202:205], v[82:85]
	v_mfma_f32_16x16x32_bf16 v[74:77], v[178:181], v[202:205], v[74:77]
	v_mfma_f32_16x16x32_bf16 v[66:69], v[178:181], v[210:213], v[66:69]
	v_mfma_f32_16x16x32_bf16 v[70:73], v[170:173], v[210:213], v[70:73]
	v_mfma_f32_16x16x32_bf16 v[114:117], v[174:177], v[190:193], v[114:117]
	v_mfma_f32_16x16x32_bf16 v[106:109], v[182:185], v[190:193], v[106:109]
	v_mfma_f32_16x16x32_bf16 v[90:93], v[182:185], v[198:201], v[90:93]
	v_mfma_f32_16x16x32_bf16 v[98:101], v[174:177], v[198:201], v[98:101]
	v_mfma_f32_16x16x32_bf16 v[82:85], v[174:177], v[206:209], v[82:85]
	v_mfma_f32_16x16x32_bf16 v[74:77], v[182:185], v[206:209], v[74:77]
	v_mfma_f32_16x16x32_bf16 v[66:69], v[182:185], v[214:217], v[66:69]
	v_mfma_f32_16x16x32_bf16 v[70:73], v[174:177], v[214:217], v[70:73]
	s_setprio 0
	s_barrier
	s_add_i32 s24, s46, s36
	v_lshl_add_u64 v[146:147], s[28:29], 0, v[134:135]
	s_mov_b32 m0, s24
	ds_read_b128 v[186:189], v153 offset:16384
	ds_read_b128 v[190:193], v153 offset:17408
	ds_read_b128 v[194:197], v153 offset:18432
	ds_read_b128 v[198:201], v153 offset:19456
	ds_read_b128 v[202:205], v153 offset:20480
	ds_read_b128 v[206:209], v153 offset:21504
	ds_read_b128 v[210:213], v153 offset:22528
	ds_read_b128 v[214:217], v153 offset:23552
	global_load_lds_dwordx4 v[146:147], off
	s_add_i32 m0, s24, 0x2000
	s_add_u32 s24, s28, 0x160000
	v_lshl_add_u64 v[218:219], s[28:29], 0, v[130:131]
	s_addc_u32 s25, s29, 0
	s_add_i32 s59, s47, s36
	global_load_lds_dwordx4 v[218:219], off
	v_lshl_add_u64 v[220:221], s[24:25], 0, v[134:135]
	s_mov_b32 m0, s59
	v_lshl_add_u64 v[222:223], s[30:31], 0, v[132:133]
	global_load_lds_dwordx4 v[220:221], off
	v_lshl_add_u64 v[220:221], s[24:25], 0, v[130:131]
	s_add_i32 m0, s59, 0x2000
	s_nop 0
	global_load_lds_dwordx4 v[220:221], off
	v_lshl_add_u64 v[220:221], s[30:31], 0, v[136:137]
	s_mov_b32 m0, s38
	s_nop 0
	global_load_lds_dwordx4 v[220:221], off
	s_mov_b32 m0, s39
	s_nop 0
	global_load_lds_dwordx4 v[222:223], off
	s_waitcnt vmcnt(8)
	s_waitcnt lgkmcnt(0)
	s_barrier
; #define PG8_STAGE(bufoff, gbase, voff) do { _Pragma("unroll") for (int _i = 0; _i < 2; ++_i) \
;         __builtin_amdgcn_global_load_lds((const unsigned*)((const char*)(gbase) + (voff)[_i]), (PG8_LAS unsigned*)(lds + (bufoff) + ldsw + _i * 8192), 16, 0, 0); } while (0)
; #define PG8_LDA(dst, b, h) do { _Pragma("unroll") for (int m = 0; m < 4; ++m) _Pragma("unroll") for (int k = 0; k < 2; ++k) dst[m][k] = *(const PG8_LAS bf16x8*)(lds + PG8_SA(b, h) + aoff + m * 2048 + k * 1024); } while (0)
; #define PG8_LDB(dst, b, h) do { _Pragma("unroll") for (int n = 0; n < 2; ++n) _Pragma("unroll") for (int k = 0; k < 2; ++k) dst[n][k] = *(const PG8_LAS bf16x8*)(lds + PG8_SB(b, h) + boff + n * 2048 + k * 1024); } while (0)
; #define PG8_MMA(ai, bj, At, Bt) do { __builtin_amdgcn_s_setprio(1); _Pragma("unroll") for (int m = 0; m < 4; ++m) _Pragma("unroll") for (int n = 0; n < 2; ++n) _Pragma("unroll") for (int k = 0; k < 2; ++k) \
;         acc[ai][bj][m][n] = __builtin_amdgcn_mfma_f32_16x16x32_bf16(Bt[n][k], At[m][k], acc[ai][bj][m][n], 0, 0, 0); __builtin_amdgcn_s_setprio(0); } while (0)
; #define PG8_WAIT_V(n) asm volatile("s_waitcnt vmcnt(" #n ")" ::: "memory")
; #define PG8_WAIT_L(n) asm volatile("s_waitcnt lgkmcnt(" #n ")" ::: "memory")
; #define PG8_BAR __builtin_amdgcn_s_barrier()
; #define PG8_SCHED __builtin_amdgcn_sched_barrier(0)
; template <class Epi, class Sched, bool ALIGN_EPI = false, bool SP2 = false>
; __device__ __forceinline__ void gemm_phase(PG8_LAS unsigned char* lds, const Gemm g, const Sched& S, const Epi& E) {
;     ...
;             PG8_WAIT_V(8); PG8_WAIT_L(0); PG8_BAR; PG8_MMA(1, 0, At, B0); PG8_MMA(1, 1, At, B1); PG8_BAR; PG8_SCHED;
;             PG8_LDB(B0, 1, 0); PG8_LDB(B1, 1, 1); PG8_SCHED; PG8_LDA(At, 1, 0); PG8_STAGE(PG8_SA(0, 1), a2 + hstep, voffA);
;             PG8_WAIT_V(8); PG8_WAIT_L(0); PG8_BAR; PG8_MMA(0, 0, At, B0); PG8_MMA(0, 1, At, B1); PG8_BAR; PG8_SCHED;
	s_setprio 1
	s_waitcnt lgkmcnt(0)
	v_mfma_f32_16x16x32_bf16 v[62:65], v[154:157], v[186:189], v[62:65]
	v_mfma_f32_16x16x32_bf16 v[58:61], v[162:165], v[186:189], v[58:61]
	v_mfma_f32_16x16x32_bf16 v[46:49], v[162:165], v[194:197], v[46:49]
	v_mfma_f32_16x16x32_bf16 v[54:57], v[154:157], v[194:197], v[54:57]
	v_mfma_f32_16x16x32_bf16 v[38:41], v[154:157], v[202:205], v[38:41]
	v_mfma_f32_16x16x32_bf16 v[30:33], v[162:165], v[202:205], v[30:33]
	v_mfma_f32_16x16x32_bf16 v[14:17], v[162:165], v[210:213], v[14:17]
	v_mfma_f32_16x16x32_bf16 v[22:25], v[154:157], v[210:213], v[22:25]
	v_mfma_f32_16x16x32_bf16 v[62:65], v[158:161], v[190:193], v[62:65]
	v_mfma_f32_16x16x32_bf16 v[58:61], v[166:169], v[190:193], v[58:61]
	v_mfma_f32_16x16x32_bf16 v[46:49], v[166:169], v[198:201], v[46:49]
	v_mfma_f32_16x16x32_bf16 v[54:57], v[158:161], v[198:201], v[54:57]
	v_mfma_f32_16x16x32_bf16 v[38:41], v[158:161], v[206:209], v[38:41]
	v_mfma_f32_16x16x32_bf16 v[30:33], v[166:169], v[206:209], v[30:33]
	v_mfma_f32_16x16x32_bf16 v[14:17], v[166:169], v[214:217], v[14:17]
	v_mfma_f32_16x16x32_bf16 v[22:25], v[158:161], v[214:217], v[22:25]
	s_setprio 0
	s_setprio 1
	v_mfma_f32_16x16x32_bf16 v[50:53], v[170:173], v[186:189], v[50:53]
	v_mfma_f32_16x16x32_bf16 v[42:45], v[178:181], v[186:189], v[42:45]
	v_mfma_f32_16x16x32_bf16 v[26:29], v[178:181], v[194:197], v[26:29]
	v_mfma_f32_16x16x32_bf16 v[34:37], v[170:173], v[194:197], v[34:37]
	v_mfma_f32_16x16x32_bf16 v[18:21], v[170:173], v[202:205], v[18:21]
	v_mfma_f32_16x16x32_bf16 v[10:13], v[178:181], v[202:205], v[10:13]
	v_mfma_f32_16x16x32_bf16 v[2:5], v[178:181], v[210:213], v[2:5]
	v_mfma_f32_16x16x32_bf16 v[6:9], v[170:173], v[210:213], v[6:9]
	v_mfma_f32_16x16x32_bf16 v[50:53], v[174:177], v[190:193], v[50:53]
	v_mfma_f32_16x16x32_bf16 v[42:45], v[182:185], v[190:193], v[42:45]
	v_mfma_f32_16x16x32_bf16 v[26:29], v[182:185], v[198:201], v[26:29]
	v_mfma_f32_16x16x32_bf16 v[34:37], v[174:177], v[198:201], v[34:37]
	v_mfma_f32_16x16x32_bf16 v[18:21], v[174:177], v[206:209], v[18:21]
	v_mfma_f32_16x16x32_bf16 v[10:13], v[182:185], v[206:209], v[10:13]
	v_mfma_f32_16x16x32_bf16 v[2:5], v[182:185], v[214:217], v[2:5]
	v_mfma_f32_16x16x32_bf16 v[6:9], v[174:177], v[214:217], v[6:9]
	s_setprio 0
	s_barrier
	s_add_i32 s59, 0, 0x18000
	s_add_i32 s60, 0, 0x1c000
	v_add_u32_e32 v166, s59, v149
	v_add_u32_e32 v182, s60, v149
	ds_read_b128 v[154:157], v166
	ds_read_b128 v[158:161], v166 offset:1024
	ds_read_b128 v[162:165], v166 offset:2048
	ds_read_b128 v[166:169], v166 offset:3072
	ds_read_b128 v[170:173], v182
	ds_read_b128 v[174:177], v182 offset:1024
	ds_read_b128 v[178:181], v182 offset:2048
	ds_read_b128 v[182:185], v182 offset:3072
	s_add_u32 s24, s30, 0x160000
	s_addc_u32 s25, s31, 0
	s_mov_b32 m0, s40
	v_lshl_add_u64 v[224:225], s[24:25], 0, v[136:137]
	ds_read_b128 v[186:189], v153 offset:32768
	ds_read_b128 v[190:193], v153 offset:33792
	ds_read_b128 v[194:197], v153 offset:34816
	ds_read_b128 v[198:201], v153 offset:35840
	ds_read_b128 v[202:205], v153 offset:36864
	ds_read_b128 v[206:209], v153 offset:37888
	ds_read_b128 v[210:213], v153 offset:38912
	ds_read_b128 v[214:217], v153 offset:39936
	global_load_lds_dwordx4 v[224:225], off
	v_lshl_add_u64 v[224:225], s[24:25], 0, v[132:133]
	s_mov_b32 m0, s41
	s_nop 0
	global_load_lds_dwordx4 v[224:225], off
	s_waitcnt vmcnt(8)
	s_waitcnt lgkmcnt(0)
	s_barrier
	s_setprio 1
	s_waitcnt lgkmcnt(0)
	v_mfma_f32_16x16x32_bf16 v[126:129], v[154:157], v[186:189], v[126:129]
	v_mfma_f32_16x16x32_bf16 v[122:125], v[162:165], v[186:189], v[122:125]
	v_mfma_f32_16x16x32_bf16 v[110:113], v[162:165], v[194:197], v[110:113]
	v_mfma_f32_16x16x32_bf16 v[118:121], v[154:157], v[194:197], v[118:121]
	v_mfma_f32_16x16x32_bf16 v[102:105], v[154:157], v[202:205], v[102:105]
	v_mfma_f32_16x16x32_bf16 v[94:97], v[162:165], v[202:205], v[94:97]
	v_mfma_f32_16x16x32_bf16 v[78:81], v[162:165], v[210:213], v[78:81]
	v_mfma_f32_16x16x32_bf16 v[86:89], v[154:157], v[210:213], v[86:89]
	v_mfma_f32_16x16x32_bf16 v[126:129], v[158:161], v[190:193], v[126:129]
	v_mfma_f32_16x16x32_bf16 v[122:125], v[166:169], v[190:193], v[122:125]
	v_mfma_f32_16x16x32_bf16 v[110:113], v[166:169], v[198:201], v[110:113]
	v_mfma_f32_16x16x32_bf16 v[118:121], v[158:161], v[198:201], v[118:121]
	v_mfma_f32_16x16x32_bf16 v[102:105], v[158:161], v[206:209], v[102:105]
	v_mfma_f32_16x16x32_bf16 v[94:97], v[166:169], v[206:209], v[94:97]
	v_mfma_f32_16x16x32_bf16 v[78:81], v[166:169], v[214:217], v[78:81]
	v_mfma_f32_16x16x32_bf16 v[86:89], v[158:161], v[214:217], v[86:89]
	s_setprio 0
	s_setprio 1
	v_mfma_f32_16x16x32_bf16 v[114:117], v[170:173], v[186:189], v[114:117]
	v_mfma_f32_16x16x32_bf16 v[106:109], v[178:181], v[186:189], v[106:109]
	v_mfma_f32_16x16x32_bf16 v[90:93], v[178:181], v[194:197], v[90:93]
	v_mfma_f32_16x16x32_bf16 v[98:101], v[170:173], v[194:197], v[98:101]
	v_mfma_f32_16x16x32_bf16 v[82:85], v[170:173], v[202:205], v[82:85]
	v_mfma_f32_16x16x32_bf16 v[74:77], v[178:181], v[202:205], v[74:77]
	v_mfma_f32_16x16x32_bf16 v[66:69], v[178:181], v[210:213], v[66:69]
	v_mfma_f32_16x16x32_bf16 v[70:73], v[170:173], v[210:213], v[70:73]
	v_mfma_f32_16x16x32_bf16 v[114:117], v[174:177], v[190:193], v[114:117]
	v_mfma_f32_16x16x32_bf16 v[106:109], v[182:185], v[190:193], v[106:109]
	v_mfma_f32_16x16x32_bf16 v[90:93], v[182:185], v[198:201], v[90:93]
	v_mfma_f32_16x16x32_bf16 v[98:101], v[174:177], v[198:201], v[98:101]
	v_mfma_f32_16x16x32_bf16 v[82:85], v[174:177], v[206:209], v[82:85]
	v_mfma_f32_16x16x32_bf16 v[74:77], v[182:185], v[206:209], v[74:77]
	v_mfma_f32_16x16x32_bf16 v[66:69], v[182:185], v[214:217], v[66:69]
	v_mfma_f32_16x16x32_bf16 v[70:73], v[174:177], v[214:217], v[70:73]
	s_setprio 0
	s_barrier
; #define PG8_STAGE(bufoff, gbase, voff) do { _Pragma("unroll") for (int _i = 0; _i < 2; ++_i) \
;         __builtin_amdgcn_global_load_lds((const unsigned*)((const char*)(gbase) + (voff)[_i]), (PG8_LAS unsigned*)(lds + (bufoff) + ldsw + _i * 8192), 16, 0, 0); } while (0)
; #define PG8_LDA(dst, b, h) do { _Pragma("unroll") for (int m = 0; m < 4; ++m) _Pragma("unroll") for (int k = 0; k < 2; ++k) dst[m][k] = *(const PG8_LAS bf16x8*)(lds + PG8_SA(b, h) + aoff + m * 2048 + k * 1024); } while (0)
; #define PG8_MMA(ai, bj, At, Bt) do { __builtin_amdgcn_s_setprio(1); _Pragma("unroll") for (int m = 0; m < 4; ++m) _Pragma("unroll") for (int n = 0; n < 2; ++n) _Pragma("unroll") for (int k = 0; k < 2; ++k) \
;         acc[ai][bj][m][n] = __builtin_amdgcn_mfma_f32_16x16x32_bf16(Bt[n][k], At[m][k], acc[ai][bj][m][n], 0, 0, 0); __builtin_amdgcn_s_setprio(0); } while (0)
; #define PG8_WAIT_V(n) asm volatile("s_waitcnt vmcnt(" #n ")" ::: "memory")
; #define PG8_WAIT_L(n) asm volatile("s_waitcnt lgkmcnt(" #n ")" ::: "memory")
; #define PG8_BAR __builtin_amdgcn_s_barrier()
; #define PG8_SCHED __builtin_amdgcn_sched_barrier(0)
; template <class Epi, class Sched, bool ALIGN_EPI = false, bool SP2 = false>
; __device__ __forceinline__ void gemm_phase(PG8_LAS unsigned char* lds, const Gemm g, const Sched& S, const Epi& E) {
;     ...
;             PG8_LDA(At, 1, 1); PG8_STAGE(PG8_SB(1, 0), b3, voffB); PG8_STAGE(PG8_SB(1, 1), b3 + hstep, voffB); PG8_STAGE(PG8_SA(1, 0), a3, voffA);
;             PG8_WAIT_V(8); PG8_WAIT_L(0); PG8_BAR; PG8_MMA(1, 0, At, B0); PG8_MMA(1, 1, At, B1); PG8_BAR; PG8_SCHED;
;     ...
;         if constexpr (ALIGN_EPI) { if (wr == 0) PG8_BAR; }
	s_add_i32 s24, s59, s36
	v_lshl_add_u64 v[146:147], v[146:147], 0, s[10:11]
	s_mov_b32 m0, s24
	ds_read_b128 v[186:189], v153 offset:49152
	ds_read_b128 v[190:193], v153 offset:50176
	ds_read_b128 v[194:197], v153 offset:51200
	ds_read_b128 v[198:201], v153 offset:52224
	ds_read_b128 v[202:205], v153 offset:53248
	ds_read_b128 v[206:209], v153 offset:54272
	ds_read_b128 v[210:213], v153 offset:55296
	ds_read_b128 v[214:217], v153 offset:56320
	global_load_lds_dwordx4 v[146:147], off
	s_add_i32 m0, s24, 0x2000
	s_add_u32 s24, s28, 0x160080
	v_lshl_add_u64 v[146:147], v[218:219], 0, s[10:11]
	s_addc_u32 s25, s29, 0
	s_add_i32 s28, s60, s36
	global_load_lds_dwordx4 v[146:147], off
	v_lshl_add_u64 v[146:147], s[24:25], 0, v[134:135]
	s_mov_b32 m0, s28
	s_nop 0
	global_load_lds_dwordx4 v[146:147], off
	v_lshl_add_u64 v[146:147], s[24:25], 0, v[130:131]
	s_add_i32 m0, s28, 0x2000
	s_nop 0
	global_load_lds_dwordx4 v[146:147], off
	v_lshl_add_u64 v[146:147], v[220:221], 0, s[10:11]
	s_mov_b32 m0, s44
	s_nop 0
	global_load_lds_dwordx4 v[146:147], off
	v_lshl_add_u64 v[146:147], v[222:223], 0, s[10:11]
	s_mov_b32 m0, s45
	s_nop 0
	global_load_lds_dwordx4 v[146:147], off
	s_waitcnt vmcnt(8)
	s_waitcnt lgkmcnt(0)
	s_barrier
	s_setprio 1
	s_waitcnt lgkmcnt(0)
	v_mfma_f32_16x16x32_bf16 v[62:65], v[154:157], v[186:189], v[62:65]
	v_mfma_f32_16x16x32_bf16 v[58:61], v[162:165], v[186:189], v[58:61]
	v_mfma_f32_16x16x32_bf16 v[46:49], v[162:165], v[194:197], v[46:49]
	v_mfma_f32_16x16x32_bf16 v[54:57], v[154:157], v[194:197], v[54:57]
	v_mfma_f32_16x16x32_bf16 v[38:41], v[154:157], v[202:205], v[38:41]
	v_mfma_f32_16x16x32_bf16 v[30:33], v[162:165], v[202:205], v[30:33]
	v_mfma_f32_16x16x32_bf16 v[14:17], v[162:165], v[210:213], v[14:17]
	v_mfma_f32_16x16x32_bf16 v[22:25], v[154:157], v[210:213], v[22:25]
	v_mfma_f32_16x16x32_bf16 v[62:65], v[158:161], v[190:193], v[62:65]
	v_mfma_f32_16x16x32_bf16 v[58:61], v[166:169], v[190:193], v[58:61]
	v_mfma_f32_16x16x32_bf16 v[46:49], v[166:169], v[198:201], v[46:49]
	v_mfma_f32_16x16x32_bf16 v[54:57], v[158:161], v[198:201], v[54:57]
	v_mfma_f32_16x16x32_bf16 v[38:41], v[158:161], v[206:209], v[38:41]
	v_mfma_f32_16x16x32_bf16 v[30:33], v[166:169], v[206:209], v[30:33]
	v_mfma_f32_16x16x32_bf16 v[14:17], v[166:169], v[214:217], v[14:17]
	v_mfma_f32_16x16x32_bf16 v[22:25], v[158:161], v[214:217], v[22:25]
	s_setprio 0
	s_setprio 1
	v_mfma_f32_16x16x32_bf16 v[50:53], v[170:173], v[186:189], v[50:53]
	v_mfma_f32_16x16x32_bf16 v[42:45], v[178:181], v[186:189], v[42:45]
	v_mfma_f32_16x16x32_bf16 v[26:29], v[178:181], v[194:197], v[26:29]
	v_mfma_f32_16x16x32_bf16 v[34:37], v[170:173], v[194:197], v[34:37]
	v_mfma_f32_16x16x32_bf16 v[18:21], v[170:173], v[202:205], v[18:21]
	v_mfma_f32_16x16x32_bf16 v[10:13], v[178:181], v[202:205], v[10:13]
	v_mfma_f32_16x16x32_bf16 v[2:5], v[178:181], v[210:213], v[2:5]
	v_mfma_f32_16x16x32_bf16 v[6:9], v[170:173], v[210:213], v[6:9]
	v_mfma_f32_16x16x32_bf16 v[50:53], v[174:177], v[190:193], v[50:53]
	v_mfma_f32_16x16x32_bf16 v[42:45], v[182:185], v[190:193], v[42:45]
	v_mfma_f32_16x16x32_bf16 v[26:29], v[182:185], v[198:201], v[26:29]
	v_mfma_f32_16x16x32_bf16 v[34:37], v[174:177], v[198:201], v[34:37]
	v_mfma_f32_16x16x32_bf16 v[18:21], v[174:177], v[206:209], v[18:21]
	v_mfma_f32_16x16x32_bf16 v[10:13], v[182:185], v[206:209], v[10:13]
	v_mfma_f32_16x16x32_bf16 v[2:5], v[182:185], v[214:217], v[2:5]
	v_mfma_f32_16x16x32_bf16 v[6:9], v[174:177], v[214:217], v[6:9]
	s_setprio 0
	s_barrier
	s_add_i32 s58, s58, 2
	s_add_u32 s56, s56, 0x100
	s_addc_u32 s57, s57, 0
	s_cmpk_gt_u32 s58, 0x55
	s_mov_b64 s[24:25], s[26:27]
	s_cbranch_scc0 .LBB0_1656
	s_and_b64 vcc, exec, s[12:13]
	s_cbranch_vccz .LBB0_1659
	s_barrier

; #define PG8_STAGE(bufoff, gbase, voff) do { _Pragma("unroll") for (int _i = 0; _i < 2; ++_i) \
;         __builtin_amdgcn_global_load_lds((const unsigned*)((const char*)(gbase) + (voff)[_i]), (PG8_LAS unsigned*)(lds + (bufoff) + ldsw + _i * 8192), 16, 0, 0); } while (0)
; #define PG8_LDA(dst, b, h) do { _Pragma("unroll") for (int m = 0; m < 4; ++m) _Pragma("unroll") for (int k = 0; k < 2; ++k) dst[m][k] = *(const PG8_LAS bf16x8*)(lds + PG8_SA(b, h) + aoff + m * 2048 + k * 1024); } while (0)
; #define PG8_LDB(dst, b, h) do { _Pragma("unroll") for (int n = 0; n < 2; ++n) _Pragma("unroll") for (int k = 0; k < 2; ++k) dst[n][k] = *(const PG8_LAS bf16x8*)(lds + PG8_SB(b, h) + boff + n * 2048 + k * 1024); } while (0)
; #define PG8_MMA(ai, bj, At, Bt) do { __builtin_amdgcn_s_setprio(1); _Pragma("unroll") for (int m = 0; m < 4; ++m) _Pragma("unroll") for (int n = 0; n < 2; ++n) _Pragma("unroll") for (int k = 0; k < 2; ++k) \
;         acc[ai][bj][m][n] = __builtin_amdgcn_mfma_f32_16x16x32_bf16(Bt[n][k], At[m][k], acc[ai][bj][m][n], 0, 0, 0); __builtin_amdgcn_s_setprio(0); } while (0)
; #define PG8_WAIT_V(n) asm volatile("s_waitcnt vmcnt(" #n ")" ::: "memory")
; #define PG8_WAIT_L(n) asm volatile("s_waitcnt lgkmcnt(" #n ")" ::: "memory")
; template <class Epi, class Sched, bool ALIGN_EPI = false, bool SP2 = false>
; __device__ __forceinline__ void gemm_phase(PG8_LAS unsigned char* lds, const Gemm g, const Sched& S, const Epi& E) {
;     ...
;         for (int t = 0; t < nt; t += 2) {
;             if constexpr (Epi::MIDHOOK) { if (t == (nt >> 1)) E.mid(acc, cur, wr, wc, fr, fq); }
;             const bool last = (t == nt - 2);
;             const char* a1 = cA + (size_t)(t + 1) * kstep;
;             const char* a2 = last ? nA : cA + (size_t)(t + 2) * kstep; const char* b2 = last ? nB : cB + (size_t)(t + 2) * kstep;
;             const char* a3 = a2 + kstep; const char* b3 = b2 + kstep;
;             if (last && has_next) S.a_ready(nxt);
;             if constexpr (SP2) {
;             PG8_LDB(B0, 0, 0); PG8_LDB(B1, 0, 1); PG8_SCHED; PG8_LDA(At, 0, 0); PG8_STAGE(PG8_SA(1, 1), a1 + hstep, voffA);
;             PG8_WAIT_V(8); PG8_WAIT_L(0); PG8_BAR; PG8_MMA(0, 0, At, B0); PG8_MMA(0, 1, At, B1); PG8_BAR; PG8_SCHED;
;             PG8_LDA(At, 0, 1); PG8_STAGE(PG8_SB(0, 0), b2, voffB); PG8_STAGE(PG8_SB(0, 1), b2 + hstep, voffB); PG8_STAGE(PG8_SA(0, 0), a2, voffA);
.LBB0_1676:
	ds_read_b128 v[144:147], v141
	ds_read_b128 v[148:151], v141 offset:1024
	ds_read_b128 v[152:155], v141 offset:2048
	ds_read_b128 v[156:159], v141 offset:3072
	ds_read_b128 v[160:163], v142
	ds_read_b128 v[164:167], v142 offset:1024
	ds_read_b128 v[168:171], v142 offset:2048
	ds_read_b128 v[172:175], v142 offset:3072
	s_add_u32 s28, s26, 0x100
	s_addc_u32 s29, s27, 0
	s_cmp_eq_u32 s60, 18
	s_cselect_b32 s37, s23, s29
	s_cselect_b32 s36, s22, s28
	s_cselect_b32 s31, s25, s59
	s_cselect_b32 s30, s24, s7
	v_lshl_add_u64 v[208:209], s[26:27], 0, v[134:135]
	s_add_i32 m0, s41, 0xc000
	ds_read_b128 v[176:179], v143
	ds_read_b128 v[180:183], v143 offset:1024
	ds_read_b128 v[184:187], v143 offset:2048
	ds_read_b128 v[188:191], v143 offset:3072
	ds_read_b128 v[192:195], v143 offset:4096
	ds_read_b128 v[196:199], v143 offset:5120
	ds_read_b128 v[200:203], v143 offset:6144
	ds_read_b128 v[204:207], v143 offset:7168
	global_load_lds_dwordx4 v[208:209], off
	v_lshl_add_u64 v[208:209], s[26:27], 0, v[136:137]
	s_add_i32 m0, s41, 0xe000
	s_nop 0
	global_load_lds_dwordx4 v[208:209], off
	s_waitcnt vmcnt(8)
	s_waitcnt lgkmcnt(0)
	s_barrier
	s_setprio 1
	s_waitcnt lgkmcnt(0)
	v_mfma_f32_16x16x32_bf16 v[126:129], v[144:147], v[176:179], v[126:129]
	v_mfma_f32_16x16x32_bf16 v[122:125], v[152:155], v[176:179], v[122:125]
	v_mfma_f32_16x16x32_bf16 v[114:117], v[152:155], v[184:187], v[114:117]
	v_mfma_f32_16x16x32_bf16 v[118:121], v[144:147], v[184:187], v[118:121]
	v_mfma_f32_16x16x32_bf16 v[106:109], v[144:147], v[192:195], v[106:109]
	v_mfma_f32_16x16x32_bf16 v[98:101], v[152:155], v[192:195], v[98:101]
	v_mfma_f32_16x16x32_bf16 v[82:85], v[152:155], v[200:203], v[82:85]
	v_mfma_f32_16x16x32_bf16 v[90:93], v[144:147], v[200:203], v[90:93]
	v_mfma_f32_16x16x32_bf16 v[126:129], v[148:151], v[180:183], v[126:129]
	v_mfma_f32_16x16x32_bf16 v[122:125], v[156:159], v[180:183], v[122:125]
	v_mfma_f32_16x16x32_bf16 v[114:117], v[156:159], v[188:191], v[114:117]
	v_mfma_f32_16x16x32_bf16 v[118:121], v[148:151], v[188:191], v[118:121]
	v_mfma_f32_16x16x32_bf16 v[106:109], v[148:151], v[196:199], v[106:109]
	v_mfma_f32_16x16x32_bf16 v[98:101], v[156:159], v[196:199], v[98:101]
	v_mfma_f32_16x16x32_bf16 v[82:85], v[156:159], v[204:207], v[82:85]
	v_mfma_f32_16x16x32_bf16 v[90:93], v[148:151], v[204:207], v[90:93]
	s_setprio 0
	s_setprio 1
	v_mfma_f32_16x16x32_bf16 v[110:113], v[160:163], v[176:179], v[110:113]
	v_mfma_f32_16x16x32_bf16 v[102:105], v[168:171], v[176:179], v[102:105]
	v_mfma_f32_16x16x32_bf16 v[86:89], v[168:171], v[184:187], v[86:89]
	v_mfma_f32_16x16x32_bf16 v[94:97], v[160:163], v[184:187], v[94:97]
	v_mfma_f32_16x16x32_bf16 v[78:81], v[160:163], v[192:195], v[78:81]
	v_mfma_f32_16x16x32_bf16 v[74:77], v[168:171], v[192:195], v[74:77]
	v_mfma_f32_16x16x32_bf16 v[66:69], v[168:171], v[200:203], v[66:69]
	v_mfma_f32_16x16x32_bf16 v[70:73], v[160:163], v[200:203], v[70:73]
	v_mfma_f32_16x16x32_bf16 v[110:113], v[164:167], v[180:183], v[110:113]
	v_mfma_f32_16x16x32_bf16 v[102:105], v[172:175], v[180:183], v[102:105]
	v_mfma_f32_16x16x32_bf16 v[86:89], v[172:175], v[188:191], v[86:89]
	v_mfma_f32_16x16x32_bf16 v[94:97], v[164:167], v[188:191], v[94:97]
	v_mfma_f32_16x16x32_bf16 v[78:81], v[164:167], v[196:199], v[78:81]
	v_mfma_f32_16x16x32_bf16 v[74:77], v[172:175], v[196:199], v[74:77]
	v_mfma_f32_16x16x32_bf16 v[66:69], v[172:175], v[204:207], v[66:69]
	v_mfma_f32_16x16x32_bf16 v[70:73], v[164:167], v[204:207], v[70:73]
	s_setprio 0
	s_barrier
	s_add_i32 s26, s50, s39
	v_lshl_add_u64 v[208:209], s[30:31], 0, v[132:133]
	s_mov_b32 m0, s26
	ds_read_b128 v[176:179], v143 offset:16384
	ds_read_b128 v[180:183], v143 offset:17408
	ds_read_b128 v[184:187], v143 offset:18432
	ds_read_b128 v[188:191], v143 offset:19456
	ds_read_b128 v[192:195], v143 offset:20480
	ds_read_b128 v[196:199], v143 offset:21504
	ds_read_b128 v[200:203], v143 offset:22528
	ds_read_b128 v[204:207], v143 offset:23552
	global_load_lds_dwordx4 v[208:209], off
	s_add_i32 m0, s26, 0x2000
	s_add_u32 s26, s30, 0x160000
	v_lshl_add_u64 v[210:211], s[30:31], 0, v[130:131]
	s_addc_u32 s27, s31, 0
	s_add_i32 s61, s51, s39
	global_load_lds_dwordx4 v[210:211], off
	v_lshl_add_u64 v[212:213], s[26:27], 0, v[132:133]
	s_mov_b32 m0, s61
	v_lshl_add_u64 v[214:215], s[36:37], 0, v[130:131]
	global_load_lds_dwordx4 v[212:213], off
	v_lshl_add_u64 v[212:213], s[26:27], 0, v[130:131]
	s_add_i32 m0, s61, 0x2000
	s_nop 0
	global_load_lds_dwordx4 v[212:213], off
	v_lshl_add_u64 v[212:213], s[36:37], 0, v[132:133]
	s_mov_b32 m0, s41
	s_nop 0
	global_load_lds_dwordx4 v[212:213], off
	s_mov_b32 m0, s42
	s_nop 0
	global_load_lds_dwordx4 v[214:215], off
	s_waitcnt vmcnt(8)
	s_waitcnt lgkmcnt(0)
	s_barrier
; #define PG8_STAGE(bufoff, gbase, voff) do { _Pragma("unroll") for (int _i = 0; _i < 2; ++_i) \
;         __builtin_amdgcn_global_load_lds((const unsigned*)((const char*)(gbase) + (voff)[_i]), (PG8_LAS unsigned*)(lds + (bufoff) + ldsw + _i * 8192), 16, 0, 0); } while (0)
; #define PG8_LDA(dst, b, h) do { _Pragma("unroll") for (int m = 0; m < 4; ++m) _Pragma("unroll") for (int k = 0; k < 2; ++k) dst[m][k] = *(const PG8_LAS bf16x8*)(lds + PG8_SA(b, h) + aoff + m * 2048 + k * 1024); } while (0)
; #define PG8_LDB(dst, b, h) do { _Pragma("unroll") for (int n = 0; n < 2; ++n) _Pragma("unroll") for (int k = 0; k < 2; ++k) dst[n][k] = *(const PG8_LAS bf16x8*)(lds + PG8_SB(b, h) + boff + n * 2048 + k * 1024); } while (0)
; #define PG8_MMA(ai, bj, At, Bt) do { __builtin_amdgcn_s_setprio(1); _Pragma("unroll") for (int m = 0; m < 4; ++m) _Pragma("unroll") for (int n = 0; n < 2; ++n) _Pragma("unroll") for (int k = 0; k < 2; ++k) \
;         acc[ai][bj][m][n] = __builtin_amdgcn_mfma_f32_16x16x32_bf16(Bt[n][k], At[m][k], acc[ai][bj][m][n], 0, 0, 0); __builtin_amdgcn_s_setprio(0); } while (0)
; #define PG8_WAIT_V(n) asm volatile("s_waitcnt vmcnt(" #n ")" ::: "memory")
; #define PG8_WAIT_L(n) asm volatile("s_waitcnt lgkmcnt(" #n ")" ::: "memory")
; #define PG8_BAR __builtin_amdgcn_s_barrier()
; #define PG8_SCHED __builtin_amdgcn_sched_barrier(0)
; template <class Epi, class Sched, bool ALIGN_EPI = false, bool SP2 = false>
; __device__ __forceinline__ void gemm_phase(PG8_LAS unsigned char* lds, const Gemm g, const Sched& S, const Epi& E) {
;     ...
;             PG8_WAIT_V(8); PG8_WAIT_L(0); PG8_BAR; PG8_MMA(1, 0, At, B0); PG8_MMA(1, 1, At, B1); PG8_BAR; PG8_SCHED;
;             PG8_LDB(B0, 1, 0); PG8_LDB(B1, 1, 1); PG8_SCHED; PG8_LDA(At, 1, 0); PG8_STAGE(PG8_SA(0, 1), a2 + hstep, voffA);
;             PG8_WAIT_V(8); PG8_WAIT_L(0); PG8_BAR; PG8_MMA(0, 0, At, B0); PG8_MMA(0, 1, At, B1); PG8_BAR; PG8_SCHED;
	s_setprio 1
	s_waitcnt lgkmcnt(0)
	v_mfma_f32_16x16x32_bf16 v[62:65], v[144:147], v[176:179], v[62:65]
	v_mfma_f32_16x16x32_bf16 v[58:61], v[152:155], v[176:179], v[58:61]
	v_mfma_f32_16x16x32_bf16 v[50:53], v[152:155], v[184:187], v[50:53]
	v_mfma_f32_16x16x32_bf16 v[54:57], v[144:147], v[184:187], v[54:57]
	v_mfma_f32_16x16x32_bf16 v[42:45], v[144:147], v[192:195], v[42:45]
	v_mfma_f32_16x16x32_bf16 v[34:37], v[152:155], v[192:195], v[34:37]
	v_mfma_f32_16x16x32_bf16 v[18:21], v[152:155], v[200:203], v[18:21]
	v_mfma_f32_16x16x32_bf16 v[26:29], v[144:147], v[200:203], v[26:29]
	v_mfma_f32_16x16x32_bf16 v[62:65], v[148:151], v[180:183], v[62:65]
	v_mfma_f32_16x16x32_bf16 v[58:61], v[156:159], v[180:183], v[58:61]
	v_mfma_f32_16x16x32_bf16 v[50:53], v[156:159], v[188:191], v[50:53]
	v_mfma_f32_16x16x32_bf16 v[54:57], v[148:151], v[188:191], v[54:57]
	v_mfma_f32_16x16x32_bf16 v[42:45], v[148:151], v[196:199], v[42:45]
	v_mfma_f32_16x16x32_bf16 v[34:37], v[156:159], v[196:199], v[34:37]
	v_mfma_f32_16x16x32_bf16 v[18:21], v[156:159], v[204:207], v[18:21]
	v_mfma_f32_16x16x32_bf16 v[26:29], v[148:151], v[204:207], v[26:29]
	s_setprio 0
	s_setprio 1
	v_mfma_f32_16x16x32_bf16 v[46:49], v[160:163], v[176:179], v[46:49]
	v_mfma_f32_16x16x32_bf16 v[38:41], v[168:171], v[176:179], v[38:41]
	v_mfma_f32_16x16x32_bf16 v[22:25], v[168:171], v[184:187], v[22:25]
	v_mfma_f32_16x16x32_bf16 v[30:33], v[160:163], v[184:187], v[30:33]
	v_mfma_f32_16x16x32_bf16 v[14:17], v[160:163], v[192:195], v[14:17]
	v_mfma_f32_16x16x32_bf16 v[10:13], v[168:171], v[192:195], v[10:13]
	v_mfma_f32_16x16x32_bf16 v[2:5], v[168:171], v[200:203], v[2:5]
	v_mfma_f32_16x16x32_bf16 v[6:9], v[160:163], v[200:203], v[6:9]
	v_mfma_f32_16x16x32_bf16 v[46:49], v[164:167], v[180:183], v[46:49]
	v_mfma_f32_16x16x32_bf16 v[38:41], v[172:175], v[180:183], v[38:41]
	v_mfma_f32_16x16x32_bf16 v[22:25], v[172:175], v[188:191], v[22:25]
	v_mfma_f32_16x16x32_bf16 v[30:33], v[164:167], v[188:191], v[30:33]
	v_mfma_f32_16x16x32_bf16 v[14:17], v[164:167], v[196:199], v[14:17]
	v_mfma_f32_16x16x32_bf16 v[10:13], v[172:175], v[196:199], v[10:13]
	v_mfma_f32_16x16x32_bf16 v[2:5], v[172:175], v[204:207], v[2:5]
	v_mfma_f32_16x16x32_bf16 v[6:9], v[164:167], v[204:207], v[6:9]
	s_setprio 0
	s_barrier
	s_add_i32 s61, 0, 0x18000
	s_add_i32 s62, 0, 0x1c000
	v_add_u32_e32 v156, s61, v138
	v_add_u32_e32 v172, s62, v138
	ds_read_b128 v[144:147], v156
	ds_read_b128 v[148:151], v156 offset:1024
	ds_read_b128 v[152:155], v156 offset:2048
	ds_read_b128 v[156:159], v156 offset:3072
	ds_read_b128 v[160:163], v172
	ds_read_b128 v[164:167], v172 offset:1024
	ds_read_b128 v[168:171], v172 offset:2048
	ds_read_b128 v[172:175], v172 offset:3072
	s_add_u32 s26, s36, 0x160000
	s_addc_u32 s27, s37, 0
	s_mov_b32 m0, s43
	v_lshl_add_u64 v[216:217], s[26:27], 0, v[132:133]
	ds_read_b128 v[176:179], v143 offset:32768
	ds_read_b128 v[180:183], v143 offset:33792
	ds_read_b128 v[184:187], v143 offset:34816
	ds_read_b128 v[188:191], v143 offset:35840
	ds_read_b128 v[192:195], v143 offset:36864
	ds_read_b128 v[196:199], v143 offset:37888
	ds_read_b128 v[200:203], v143 offset:38912
	ds_read_b128 v[204:207], v143 offset:39936
	global_load_lds_dwordx4 v[216:217], off
	v_lshl_add_u64 v[216:217], s[26:27], 0, v[130:131]
	s_mov_b32 m0, s44
	s_nop 0
	global_load_lds_dwordx4 v[216:217], off
	s_waitcnt vmcnt(8)
	s_waitcnt lgkmcnt(0)
	s_barrier
	s_setprio 1
	s_waitcnt lgkmcnt(0)
	v_mfma_f32_16x16x32_bf16 v[126:129], v[144:147], v[176:179], v[126:129]
	v_mfma_f32_16x16x32_bf16 v[122:125], v[152:155], v[176:179], v[122:125]
	v_mfma_f32_16x16x32_bf16 v[114:117], v[152:155], v[184:187], v[114:117]
	v_mfma_f32_16x16x32_bf16 v[118:121], v[144:147], v[184:187], v[118:121]
	v_mfma_f32_16x16x32_bf16 v[106:109], v[144:147], v[192:195], v[106:109]
	v_mfma_f32_16x16x32_bf16 v[98:101], v[152:155], v[192:195], v[98:101]
	v_mfma_f32_16x16x32_bf16 v[82:85], v[152:155], v[200:203], v[82:85]
	v_mfma_f32_16x16x32_bf16 v[90:93], v[144:147], v[200:203], v[90:93]
	v_mfma_f32_16x16x32_bf16 v[126:129], v[148:151], v[180:183], v[126:129]
	v_mfma_f32_16x16x32_bf16 v[122:125], v[156:159], v[180:183], v[122:125]
	v_mfma_f32_16x16x32_bf16 v[114:117], v[156:159], v[188:191], v[114:117]
	v_mfma_f32_16x16x32_bf16 v[118:121], v[148:151], v[188:191], v[118:121]
	v_mfma_f32_16x16x32_bf16 v[106:109], v[148:151], v[196:199], v[106:109]
	v_mfma_f32_16x16x32_bf16 v[98:101], v[156:159], v[196:199], v[98:101]
	v_mfma_f32_16x16x32_bf16 v[82:85], v[156:159], v[204:207], v[82:85]
	v_mfma_f32_16x16x32_bf16 v[90:93], v[148:151], v[204:207], v[90:93]
	s_setprio 0
	s_setprio 1
	v_mfma_f32_16x16x32_bf16 v[110:113], v[160:163], v[176:179], v[110:113]
	v_mfma_f32_16x16x32_bf16 v[102:105], v[168:171], v[176:179], v[102:105]
	v_mfma_f32_16x16x32_bf16 v[86:89], v[168:171], v[184:187], v[86:89]
	v_mfma_f32_16x16x32_bf16 v[94:97], v[160:163], v[184:187], v[94:97]
	v_mfma_f32_16x16x32_bf16 v[78:81], v[160:163], v[192:195], v[78:81]
	v_mfma_f32_16x16x32_bf16 v[74:77], v[168:171], v[192:195], v[74:77]
	v_mfma_f32_16x16x32_bf16 v[66:69], v[168:171], v[200:203], v[66:69]
	v_mfma_f32_16x16x32_bf16 v[70:73], v[160:163], v[200:203], v[70:73]
	v_mfma_f32_16x16x32_bf16 v[110:113], v[164:167], v[180:183], v[110:113]
	v_mfma_f32_16x16x32_bf16 v[102:105], v[172:175], v[180:183], v[102:105]
	v_mfma_f32_16x16x32_bf16 v[86:89], v[172:175], v[188:191], v[86:89]
	v_mfma_f32_16x16x32_bf16 v[94:97], v[164:167], v[188:191], v[94:97]
	v_mfma_f32_16x16x32_bf16 v[78:81], v[164:167], v[196:199], v[78:81]
	v_mfma_f32_16x16x32_bf16 v[74:77], v[172:175], v[196:199], v[74:77]
	v_mfma_f32_16x16x32_bf16 v[66:69], v[172:175], v[204:207], v[66:69]
	v_mfma_f32_16x16x32_bf16 v[70:73], v[164:167], v[204:207], v[70:73]
	s_setprio 0
	s_barrier
; #define PG8_STAGE(bufoff, gbase, voff) do { _Pragma("unroll") for (int _i = 0; _i < 2; ++_i) \
;         __builtin_amdgcn_global_load_lds((const unsigned*)((const char*)(gbase) + (voff)[_i]), (PG8_LAS unsigned*)(lds + (bufoff) + ldsw + _i * 8192), 16, 0, 0); } while (0)
; #define PG8_LDA(dst, b, h) do { _Pragma("unroll") for (int m = 0; m < 4; ++m) _Pragma("unroll") for (int k = 0; k < 2; ++k) dst[m][k] = *(const PG8_LAS bf16x8*)(lds + PG8_SA(b, h) + aoff + m * 2048 + k * 1024); } while (0)
; #define PG8_MMA(ai, bj, At, Bt) do { __builtin_amdgcn_s_setprio(1); _Pragma("unroll") for (int m = 0; m < 4; ++m) _Pragma("unroll") for (int n = 0; n < 2; ++n) _Pragma("unroll") for (int k = 0; k < 2; ++k) \
;         acc[ai][bj][m][n] = __builtin_amdgcn_mfma_f32_16x16x32_bf16(Bt[n][k], At[m][k], acc[ai][bj][m][n], 0, 0, 0); __builtin_amdgcn_s_setprio(0); } while (0)
; #define PG8_WAIT_V(n) asm volatile("s_waitcnt vmcnt(" #n ")" ::: "memory")
; #define PG8_WAIT_L(n) asm volatile("s_waitcnt lgkmcnt(" #n ")" ::: "memory")
; #define PG8_BAR __builtin_amdgcn_s_barrier()
; #define PG8_SCHED __builtin_amdgcn_sched_barrier(0)
; template <class Epi, class Sched, bool ALIGN_EPI = false, bool SP2 = false>
; __device__ __forceinline__ void gemm_phase(PG8_LAS unsigned char* lds, const Gemm g, const Sched& S, const Epi& E) {
;     ...
;             PG8_LDA(At, 1, 1); PG8_STAGE(PG8_SB(1, 0), b3, voffB); PG8_STAGE(PG8_SB(1, 1), b3 + hstep, voffB); PG8_STAGE(PG8_SA(1, 0), a3, voffA);
;             PG8_WAIT_V(8); PG8_WAIT_L(0); PG8_BAR; PG8_MMA(1, 0, At, B0); PG8_MMA(1, 1, At, B1); PG8_BAR; PG8_SCHED;
;     ...
;         if constexpr (ALIGN_EPI) { if (wr == 0) PG8_BAR; }
	s_add_i32 s26, s61, s39
	v_lshl_add_u64 v[208:209], v[208:209], 0, s[12:13]
	s_mov_b32 m0, s26
	ds_read_b128 v[176:179], v143 offset:49152
	ds_read_b128 v[180:183], v143 offset:50176
	ds_read_b128 v[184:187], v143 offset:51200
	ds_read_b128 v[188:191], v143 offset:52224
	ds_read_b128 v[192:195], v143 offset:53248
	ds_read_b128 v[196:199], v143 offset:54272
	ds_read_b128 v[200:203], v143 offset:55296
	ds_read_b128 v[204:207], v143 offset:56320
	global_load_lds_dwordx4 v[208:209], off
	s_add_i32 m0, s26, 0x2000
	s_add_u32 s26, s30, 0x160080
	v_lshl_add_u64 v[208:209], v[210:211], 0, s[12:13]
	s_addc_u32 s27, s31, 0
	s_add_i32 s30, s62, s39
	global_load_lds_dwordx4 v[208:209], off
	v_lshl_add_u64 v[208:209], s[26:27], 0, v[132:133]
	s_mov_b32 m0, s30
	s_nop 0
	global_load_lds_dwordx4 v[208:209], off
	v_lshl_add_u64 v[208:209], s[26:27], 0, v[130:131]
	s_add_i32 m0, s30, 0x2000
	s_nop 0
	global_load_lds_dwordx4 v[208:209], off
	v_lshl_add_u64 v[208:209], v[212:213], 0, s[12:13]
	s_mov_b32 m0, s47
	s_nop 0
	global_load_lds_dwordx4 v[208:209], off
	v_lshl_add_u64 v[208:209], v[214:215], 0, s[12:13]
	s_mov_b32 m0, s48
	s_nop 0
	global_load_lds_dwordx4 v[208:209], off
	s_waitcnt vmcnt(8)
	s_waitcnt lgkmcnt(0)
	s_barrier
	s_setprio 1
	s_waitcnt lgkmcnt(0)
	v_mfma_f32_16x16x32_bf16 v[62:65], v[144:147], v[176:179], v[62:65]
	v_mfma_f32_16x16x32_bf16 v[58:61], v[152:155], v[176:179], v[58:61]
	v_mfma_f32_16x16x32_bf16 v[50:53], v[152:155], v[184:187], v[50:53]
	v_mfma_f32_16x16x32_bf16 v[54:57], v[144:147], v[184:187], v[54:57]
	v_mfma_f32_16x16x32_bf16 v[42:45], v[144:147], v[192:195], v[42:45]
	v_mfma_f32_16x16x32_bf16 v[34:37], v[152:155], v[192:195], v[34:37]
	v_mfma_f32_16x16x32_bf16 v[18:21], v[152:155], v[200:203], v[18:21]
	v_mfma_f32_16x16x32_bf16 v[26:29], v[144:147], v[200:203], v[26:29]
	v_mfma_f32_16x16x32_bf16 v[62:65], v[148:151], v[180:183], v[62:65]
	v_mfma_f32_16x16x32_bf16 v[58:61], v[156:159], v[180:183], v[58:61]
	v_mfma_f32_16x16x32_bf16 v[50:53], v[156:159], v[188:191], v[50:53]
	v_mfma_f32_16x16x32_bf16 v[54:57], v[148:151], v[188:191], v[54:57]
	v_mfma_f32_16x16x32_bf16 v[42:45], v[148:151], v[196:199], v[42:45]
	v_mfma_f32_16x16x32_bf16 v[34:37], v[156:159], v[196:199], v[34:37]
	v_mfma_f32_16x16x32_bf16 v[18:21], v[156:159], v[204:207], v[18:21]
	v_mfma_f32_16x16x32_bf16 v[26:29], v[148:151], v[204:207], v[26:29]
	s_setprio 0
	s_setprio 1
	v_mfma_f32_16x16x32_bf16 v[46:49], v[160:163], v[176:179], v[46:49]
	v_mfma_f32_16x16x32_bf16 v[38:41], v[168:171], v[176:179], v[38:41]
	v_mfma_f32_16x16x32_bf16 v[22:25], v[168:171], v[184:187], v[22:25]
	v_mfma_f32_16x16x32_bf16 v[30:33], v[160:163], v[184:187], v[30:33]
	v_mfma_f32_16x16x32_bf16 v[14:17], v[160:163], v[192:195], v[14:17]
	v_mfma_f32_16x16x32_bf16 v[10:13], v[168:171], v[192:195], v[10:13]
	v_mfma_f32_16x16x32_bf16 v[2:5], v[168:171], v[200:203], v[2:5]
	v_mfma_f32_16x16x32_bf16 v[6:9], v[160:163], v[200:203], v[6:9]
	v_mfma_f32_16x16x32_bf16 v[46:49], v[164:167], v[180:183], v[46:49]
	v_mfma_f32_16x16x32_bf16 v[38:41], v[172:175], v[180:183], v[38:41]
	v_mfma_f32_16x16x32_bf16 v[22:25], v[172:175], v[188:191], v[22:25]
	v_mfma_f32_16x16x32_bf16 v[30:33], v[164:167], v[188:191], v[30:33]
	v_mfma_f32_16x16x32_bf16 v[14:17], v[164:167], v[196:199], v[14:17]
	v_mfma_f32_16x16x32_bf16 v[10:13], v[172:175], v[196:199], v[10:13]
	v_mfma_f32_16x16x32_bf16 v[2:5], v[172:175], v[204:207], v[2:5]
	v_mfma_f32_16x16x32_bf16 v[6:9], v[164:167], v[204:207], v[6:9]
	s_setprio 0
	s_barrier
	s_add_i32 s60, s60, 2
	s_add_u32 s7, s7, 0x100
	s_addc_u32 s59, s59, 0
	s_cmp_gt_u32 s60, 19
	s_mov_b64 s[26:27], s[28:29]
	s_cbranch_scc0 .LBB0_1676
	s_and_b64 vcc, exec, s[14:15]
	s_cbranch_vccz .LBB0_1679
	s_barrier

;     __device__ bool next(int i, Unit& u) const { if (!s.next(i, u)) return false; const int p = u.pn; u.pn = p < 56 ? (p % 7) * 8 + p / 7 : p; return true; }
;     __device__ bool next(int i, Unit& u) const { Unit t; if (!s.next(i >> 1, t)) return false; const int pass = i & 1; u.pm = t.pm + pass * (M / BM); u.pn = t.pn + pass * (D / BM); u.kt0 = 0; return true; }
; #define PG8_STAGE(bufoff, gbase, voff) do { _Pragma("unroll") for (int _i = 0; _i < 2; ++_i) \
;         __builtin_amdgcn_global_load_lds((const unsigned*)((const char*)(gbase) + (voff)[_i]), (PG8_LAS unsigned*)(lds + (bufoff) + ldsw + _i * 8192), 16, 0, 0); } while (0)
; #define PG8_LDA(dst, b, h) do { _Pragma("unroll") for (int m = 0; m < 4; ++m) _Pragma("unroll") for (int k = 0; k < 2; ++k) dst[m][k] = *(const PG8_LAS bf16x8*)(lds + PG8_SA(b, h) + aoff + m * 2048 + k * 1024); } while (0)
; #define PG8_WAIT_V(n) asm volatile("s_waitcnt vmcnt(" #n ")" ::: "memory")
; #define PG8_BAR __builtin_amdgcn_s_barrier()
; template <class Epi, class Sched, bool ALIGN_EPI = false, bool SP2 = false>
; __device__ __forceinline__ void gemm_phase(PG8_LAS unsigned char* lds, const Gemm g, const Sched& S, const Epi& E) {
;     ...
;         const bool has_next = S.next(ui + 1, nxt);
;         const char* nA = has_next ? (const char*)g.A + (size_t)nxt.pm * tstep + (size_t)nxt.kt0 * kstep : cA; const char* nB = has_next ? (const char*)g.Bt + (size_t)nxt.pn * tstep + (size_t)nxt.kt0 * kstep : cB;
;         for (int t = 0; t < nt; t += 2) {
;             if constexpr (Epi::MIDHOOK) { if (t == (nt >> 1)) E.mid(acc, cur, wr, wc, fr, fq); }
;             const bool last = (t == nt - 2);
;             const char* a1 = cA + (size_t)(t + 1) * kstep;
;             const char* a2 = last ? nA : cA + (size_t)(t + 2) * kstep; const char* b2 = last ? nB : cB + (size_t)(t + 2) * kstep;
;             const char* a3 = a2 + kstep; const char* b3 = b2 + kstep;
;             if (last && has_next) S.a_ready(nxt);
;             if constexpr (SP2) {
;             PG8_LDB(B0, 0, 0); PG8_LDB(B1, 0, 1); PG8_SCHED; PG8_LDA(At, 0, 0); PG8_STAGE(PG8_SA(1, 1), a1 + hstep, voffA);
;             PG8_WAIT_V(8); PG8_WAIT_L(0); PG8_BAR; PG8_MMA(0, 0, At, B0); PG8_MMA(0, 1, At, B1); PG8_BAR; PG8_SCHED;
;             PG8_LDA(At, 0, 1); PG8_STAGE(PG8_SB(0, 0), b2, voffB); PG8_STAGE(PG8_SB(0, 1), b2 + hstep, voffB); PG8_STAGE(PG8_SA(0, 0), a2, voffA);
.LBB0_1693:
	s_add_u32 s37, s26, s36
	s_addc_u32 s42, s27, 0
	s_add_u32 s40, s37, 0x100
	s_addc_u32 s41, s42, 0
	s_and_b64 s[38:39], s[30:31], exec
	s_cselect_b32 s39, s19, s41
	s_cselect_b32 s38, s63, s40
	s_add_u32 s36, s24, s36
	s_addc_u32 s40, s25, 0
	s_add_u32 s36, s36, 0x100
	s_addc_u32 s40, s40, 0
	s_and_b64 s[30:31], s[30:31], exec
	s_cselect_b32 s41, s17, s40
	s_cselect_b32 s40, s64, s36
	s_add_u32 s44, s37, 0x10080
	ds_read_b128 v[150:153], v147
	ds_read_b128 v[154:157], v147 offset:1024
	ds_read_b128 v[158:161], v147 offset:2048
	ds_read_b128 v[162:165], v147 offset:3072
	ds_read_b128 v[166:169], v148
	ds_read_b128 v[170:173], v148 offset:1024
	ds_read_b128 v[174:177], v148 offset:2048
	ds_read_b128 v[178:181], v148 offset:3072
	s_addc_u32 s45, s42, 0
	s_add_i32 s74, s57, s33
	s_add_i32 m0, s50, 0xc000
	s_add_i32 s75, s50, 0xe000
	s_add_i32 s71, s74, 0x2000
	s_add_u32 s42, s40, 0x10000
	s_addc_u32 s43, s41, 0
	s_add_i32 s73, s58, s33
	s_add_i32 s72, s73, 0x2000
	s_add_i32 s70, 0, 0x18000
	s_add_i32 s69, 0, 0x1c000
	s_add_u32 s36, s38, 0x10000
	s_addc_u32 s37, s39, 0
	s_add_i32 s68, s70, s33
	s_add_i32 s66, s68, 0x2000
	s_add_u32 s30, s40, 0x10080
	s_addc_u32 s31, s41, 0
	s_add_i32 s67, s69, s33
	s_add_i32 s65, s67, 0x2000
	v_lshl_add_u64 v[142:143], s[44:45], 0, v[136:137]
	ds_read_b128 v[182:185], v149
	ds_read_b128 v[186:189], v149 offset:1024
	ds_read_b128 v[190:193], v149 offset:2048
	ds_read_b128 v[194:197], v149 offset:3072
	ds_read_b128 v[198:201], v149 offset:4096
	ds_read_b128 v[202:205], v149 offset:5120
	ds_read_b128 v[206:209], v149 offset:6144
	ds_read_b128 v[210:213], v149 offset:7168
	global_load_lds_dwordx4 v[142:143], off
	v_lshl_add_u64 v[142:143], s[44:45], 0, v[132:133]
	s_mov_b32 m0, s75
	s_nop 0
	global_load_lds_dwordx4 v[142:143], off
	s_waitcnt vmcnt(8)
	s_waitcnt lgkmcnt(0)
	s_barrier
	s_setprio 1
	s_waitcnt lgkmcnt(0)
	v_mfma_f32_16x16x32_bf16 v[126:129], v[150:153], v[182:185], v[126:129]
	v_mfma_f32_16x16x32_bf16 v[122:125], v[158:161], v[182:185], v[122:125]
	v_mfma_f32_16x16x32_bf16 v[110:113], v[158:161], v[190:193], v[110:113]
	v_mfma_f32_16x16x32_bf16 v[118:121], v[150:153], v[190:193], v[118:121]
	v_mfma_f32_16x16x32_bf16 v[102:105], v[150:153], v[198:201], v[102:105]
	v_mfma_f32_16x16x32_bf16 v[94:97], v[158:161], v[198:201], v[94:97]
	v_mfma_f32_16x16x32_bf16 v[78:81], v[158:161], v[206:209], v[78:81]
	v_mfma_f32_16x16x32_bf16 v[86:89], v[150:153], v[206:209], v[86:89]
	v_mfma_f32_16x16x32_bf16 v[126:129], v[154:157], v[186:189], v[126:129]
	v_mfma_f32_16x16x32_bf16 v[122:125], v[162:165], v[186:189], v[122:125]
	v_mfma_f32_16x16x32_bf16 v[110:113], v[162:165], v[194:197], v[110:113]
	v_mfma_f32_16x16x32_bf16 v[118:121], v[154:157], v[194:197], v[118:121]
	v_mfma_f32_16x16x32_bf16 v[102:105], v[154:157], v[202:205], v[102:105]
	v_mfma_f32_16x16x32_bf16 v[94:97], v[162:165], v[202:205], v[94:97]
	v_mfma_f32_16x16x32_bf16 v[78:81], v[162:165], v[210:213], v[78:81]
	v_mfma_f32_16x16x32_bf16 v[86:89], v[154:157], v[210:213], v[86:89]
	s_setprio 0
	s_setprio 1
	v_mfma_f32_16x16x32_bf16 v[114:117], v[166:169], v[182:185], v[114:117]
	v_mfma_f32_16x16x32_bf16 v[106:109], v[174:177], v[182:185], v[106:109]
	v_mfma_f32_16x16x32_bf16 v[90:93], v[174:177], v[190:193], v[90:93]
	v_mfma_f32_16x16x32_bf16 v[98:101], v[166:169], v[190:193], v[98:101]
	v_mfma_f32_16x16x32_bf16 v[82:85], v[166:169], v[198:201], v[82:85]
	v_mfma_f32_16x16x32_bf16 v[74:77], v[174:177], v[198:201], v[74:77]
	v_mfma_f32_16x16x32_bf16 v[66:69], v[174:177], v[206:209], v[66:69]
	v_mfma_f32_16x16x32_bf16 v[70:73], v[166:169], v[206:209], v[70:73]
	v_mfma_f32_16x16x32_bf16 v[114:117], v[170:173], v[186:189], v[114:117]
	v_mfma_f32_16x16x32_bf16 v[106:109], v[178:181], v[186:189], v[106:109]
	v_mfma_f32_16x16x32_bf16 v[90:93], v[178:181], v[194:197], v[90:93]
	v_mfma_f32_16x16x32_bf16 v[98:101], v[170:173], v[194:197], v[98:101]
	v_mfma_f32_16x16x32_bf16 v[82:85], v[170:173], v[202:205], v[82:85]
	v_mfma_f32_16x16x32_bf16 v[74:77], v[178:181], v[202:205], v[74:77]
	v_mfma_f32_16x16x32_bf16 v[66:69], v[178:181], v[210:213], v[66:69]
	v_mfma_f32_16x16x32_bf16 v[70:73], v[170:173], v[210:213], v[70:73]
	s_setprio 0
	s_barrier
	s_mov_b32 m0, s74
	v_lshl_add_u64 v[142:143], s[40:41], 0, v[134:135]
	ds_read_b128 v[182:185], v149 offset:16384
	ds_read_b128 v[186:189], v149 offset:17408
	ds_read_b128 v[190:193], v149 offset:18432
	ds_read_b128 v[194:197], v149 offset:19456
	ds_read_b128 v[198:201], v149 offset:20480
	ds_read_b128 v[202:205], v149 offset:21504
	ds_read_b128 v[206:209], v149 offset:22528
	ds_read_b128 v[210:213], v149 offset:23552
	global_load_lds_dwordx4 v[142:143], off
	v_lshl_add_u64 v[214:215], s[40:41], 0, v[130:131]
	s_mov_b32 m0, s71
	v_lshl_add_u64 v[216:217], s[42:43], 0, v[134:135]
	global_load_lds_dwordx4 v[214:215], off
	s_mov_b32 m0, s73
	v_lshl_add_u64 v[218:219], s[38:39], 0, v[132:133]
	global_load_lds_dwordx4 v[216:217], off
	v_lshl_add_u64 v[216:217], s[42:43], 0, v[130:131]
	s_mov_b32 m0, s72
	s_nop 0
	global_load_lds_dwordx4 v[216:217], off
	v_lshl_add_u64 v[216:217], s[38:39], 0, v[136:137]
	s_mov_b32 m0, s50
	s_nop 0
	global_load_lds_dwordx4 v[216:217], off
	s_mov_b32 m0, s51
	s_nop 0
	global_load_lds_dwordx4 v[218:219], off
	s_waitcnt vmcnt(8)
	s_waitcnt lgkmcnt(0)
	s_barrier
; #define PG8_STAGE(bufoff, gbase, voff) do { _Pragma("unroll") for (int _i = 0; _i < 2; ++_i) \
;         __builtin_amdgcn_global_load_lds((const unsigned*)((const char*)(gbase) + (voff)[_i]), (PG8_LAS unsigned*)(lds + (bufoff) + ldsw + _i * 8192), 16, 0, 0); } while (0)
; #define PG8_LDA(dst, b, h) do { _Pragma("unroll") for (int m = 0; m < 4; ++m) _Pragma("unroll") for (int k = 0; k < 2; ++k) dst[m][k] = *(const PG8_LAS bf16x8*)(lds + PG8_SA(b, h) + aoff + m * 2048 + k * 1024); } while (0)
; #define PG8_LDB(dst, b, h) do { _Pragma("unroll") for (int n = 0; n < 2; ++n) _Pragma("unroll") for (int k = 0; k < 2; ++k) dst[n][k] = *(const PG8_LAS bf16x8*)(lds + PG8_SB(b, h) + boff + n * 2048 + k * 1024); } while (0)
; #define PG8_MMA(ai, bj, At, Bt) do { __builtin_amdgcn_s_setprio(1); _Pragma("unroll") for (int m = 0; m < 4; ++m) _Pragma("unroll") for (int n = 0; n < 2; ++n) _Pragma("unroll") for (int k = 0; k < 2; ++k) \
;         acc[ai][bj][m][n] = __builtin_amdgcn_mfma_f32_16x16x32_bf16(Bt[n][k], At[m][k], acc[ai][bj][m][n], 0, 0, 0); __builtin_amdgcn_s_setprio(0); } while (0)
; #define PG8_WAIT_V(n) asm volatile("s_waitcnt vmcnt(" #n ")" ::: "memory")
; #define PG8_WAIT_L(n) asm volatile("s_waitcnt lgkmcnt(" #n ")" ::: "memory")
; #define PG8_BAR __builtin_amdgcn_s_barrier()
; #define PG8_SCHED __builtin_amdgcn_sched_barrier(0)
; template <class Epi, class Sched, bool ALIGN_EPI = false, bool SP2 = false>
; __device__ __forceinline__ void gemm_phase(PG8_LAS unsigned char* lds, const Gemm g, const Sched& S, const Epi& E) {
;     ...
;             PG8_WAIT_V(8); PG8_WAIT_L(0); PG8_BAR; PG8_MMA(1, 0, At, B0); PG8_MMA(1, 1, At, B1); PG8_BAR; PG8_SCHED;
;             PG8_LDB(B0, 1, 0); PG8_LDB(B1, 1, 1); PG8_SCHED; PG8_LDA(At, 1, 0); PG8_STAGE(PG8_SA(0, 1), a2 + hstep, voffA);
;             PG8_WAIT_V(8); PG8_WAIT_L(0); PG8_BAR; PG8_MMA(0, 0, At, B0); PG8_MMA(0, 1, At, B1); PG8_BAR; PG8_SCHED;
	s_setprio 1
	s_waitcnt lgkmcnt(0)
	v_mfma_f32_16x16x32_bf16 v[62:65], v[150:153], v[182:185], v[62:65]
	v_mfma_f32_16x16x32_bf16 v[58:61], v[158:161], v[182:185], v[58:61]
	v_mfma_f32_16x16x32_bf16 v[46:49], v[158:161], v[190:193], v[46:49]
	v_mfma_f32_16x16x32_bf16 v[54:57], v[150:153], v[190:193], v[54:57]
	v_mfma_f32_16x16x32_bf16 v[38:41], v[150:153], v[198:201], v[38:41]
	v_mfma_f32_16x16x32_bf16 v[30:33], v[158:161], v[198:201], v[30:33]
	v_mfma_f32_16x16x32_bf16 v[14:17], v[158:161], v[206:209], v[14:17]
	v_mfma_f32_16x16x32_bf16 v[22:25], v[150:153], v[206:209], v[22:25]
	v_mfma_f32_16x16x32_bf16 v[62:65], v[154:157], v[186:189], v[62:65]
	v_mfma_f32_16x16x32_bf16 v[58:61], v[162:165], v[186:189], v[58:61]
	v_mfma_f32_16x16x32_bf16 v[46:49], v[162:165], v[194:197], v[46:49]
	v_mfma_f32_16x16x32_bf16 v[54:57], v[154:157], v[194:197], v[54:57]
	v_mfma_f32_16x16x32_bf16 v[38:41], v[154:157], v[202:205], v[38:41]
	v_mfma_f32_16x16x32_bf16 v[30:33], v[162:165], v[202:205], v[30:33]
	v_mfma_f32_16x16x32_bf16 v[14:17], v[162:165], v[210:213], v[14:17]
	v_mfma_f32_16x16x32_bf16 v[22:25], v[154:157], v[210:213], v[22:25]
	s_setprio 0
	s_setprio 1
	v_mfma_f32_16x16x32_bf16 v[50:53], v[166:169], v[182:185], v[50:53]
	v_mfma_f32_16x16x32_bf16 v[42:45], v[174:177], v[182:185], v[42:45]
	v_mfma_f32_16x16x32_bf16 v[26:29], v[174:177], v[190:193], v[26:29]
	v_mfma_f32_16x16x32_bf16 v[34:37], v[166:169], v[190:193], v[34:37]
	v_mfma_f32_16x16x32_bf16 v[18:21], v[166:169], v[198:201], v[18:21]
	v_mfma_f32_16x16x32_bf16 v[10:13], v[174:177], v[198:201], v[10:13]
	v_mfma_f32_16x16x32_bf16 v[2:5], v[174:177], v[206:209], v[2:5]
	v_mfma_f32_16x16x32_bf16 v[6:9], v[166:169], v[206:209], v[6:9]
	v_mfma_f32_16x16x32_bf16 v[50:53], v[170:173], v[186:189], v[50:53]
	v_mfma_f32_16x16x32_bf16 v[42:45], v[178:181], v[186:189], v[42:45]
	v_mfma_f32_16x16x32_bf16 v[26:29], v[178:181], v[194:197], v[26:29]
	v_mfma_f32_16x16x32_bf16 v[34:37], v[170:173], v[194:197], v[34:37]
	v_mfma_f32_16x16x32_bf16 v[18:21], v[170:173], v[202:205], v[18:21]
	v_mfma_f32_16x16x32_bf16 v[10:13], v[178:181], v[202:205], v[10:13]
	v_mfma_f32_16x16x32_bf16 v[2:5], v[178:181], v[210:213], v[2:5]
	v_mfma_f32_16x16x32_bf16 v[6:9], v[170:173], v[210:213], v[6:9]
	s_setprio 0
	s_barrier
	v_add_u32_e32 v162, s70, v145
	v_add_u32_e32 v178, s69, v145
	ds_read_b128 v[150:153], v162
	ds_read_b128 v[154:157], v162 offset:1024
	ds_read_b128 v[158:161], v162 offset:2048
	ds_read_b128 v[162:165], v162 offset:3072
	ds_read_b128 v[166:169], v178
	ds_read_b128 v[170:173], v178 offset:1024
	ds_read_b128 v[174:177], v178 offset:2048
	ds_read_b128 v[178:181], v178 offset:3072
	s_mov_b32 m0, s52
	v_lshl_add_u64 v[220:221], s[36:37], 0, v[136:137]
	ds_read_b128 v[182:185], v149 offset:32768
	ds_read_b128 v[186:189], v149 offset:33792
	ds_read_b128 v[190:193], v149 offset:34816
	ds_read_b128 v[194:197], v149 offset:35840
	ds_read_b128 v[198:201], v149 offset:36864
	ds_read_b128 v[202:205], v149 offset:37888
	ds_read_b128 v[206:209], v149 offset:38912
	ds_read_b128 v[210:213], v149 offset:39936
	global_load_lds_dwordx4 v[220:221], off
	v_lshl_add_u64 v[220:221], s[36:37], 0, v[132:133]
	s_mov_b32 m0, s53
	s_nop 0
	global_load_lds_dwordx4 v[220:221], off
	s_waitcnt vmcnt(8)
	s_waitcnt lgkmcnt(0)
	s_barrier
	s_setprio 1
	s_waitcnt lgkmcnt(0)
	v_mfma_f32_16x16x32_bf16 v[126:129], v[150:153], v[182:185], v[126:129]
	v_mfma_f32_16x16x32_bf16 v[122:125], v[158:161], v[182:185], v[122:125]
	v_mfma_f32_16x16x32_bf16 v[110:113], v[158:161], v[190:193], v[110:113]
	v_mfma_f32_16x16x32_bf16 v[118:121], v[150:153], v[190:193], v[118:121]
	v_mfma_f32_16x16x32_bf16 v[102:105], v[150:153], v[198:201], v[102:105]
	v_mfma_f32_16x16x32_bf16 v[94:97], v[158:161], v[198:201], v[94:97]
	v_mfma_f32_16x16x32_bf16 v[78:81], v[158:161], v[206:209], v[78:81]
	v_mfma_f32_16x16x32_bf16 v[86:89], v[150:153], v[206:209], v[86:89]
	v_mfma_f32_16x16x32_bf16 v[126:129], v[154:157], v[186:189], v[126:129]
	v_mfma_f32_16x16x32_bf16 v[122:125], v[162:165], v[186:189], v[122:125]
	v_mfma_f32_16x16x32_bf16 v[110:113], v[162:165], v[194:197], v[110:113]
	v_mfma_f32_16x16x32_bf16 v[118:121], v[154:157], v[194:197], v[118:121]
	v_mfma_f32_16x16x32_bf16 v[102:105], v[154:157], v[202:205], v[102:105]
	v_mfma_f32_16x16x32_bf16 v[94:97], v[162:165], v[202:205], v[94:97]
	v_mfma_f32_16x16x32_bf16 v[78:81], v[162:165], v[210:213], v[78:81]
	v_mfma_f32_16x16x32_bf16 v[86:89], v[154:157], v[210:213], v[86:89]
	s_setprio 0
	s_setprio 1
	v_mfma_f32_16x16x32_bf16 v[114:117], v[166:169], v[182:185], v[114:117]
	v_mfma_f32_16x16x32_bf16 v[106:109], v[174:177], v[182:185], v[106:109]
	v_mfma_f32_16x16x32_bf16 v[90:93], v[174:177], v[190:193], v[90:93]
	v_mfma_f32_16x16x32_bf16 v[98:101], v[166:169], v[190:193], v[98:101]
	v_mfma_f32_16x16x32_bf16 v[82:85], v[166:169], v[198:201], v[82:85]
	v_mfma_f32_16x16x32_bf16 v[74:77], v[174:177], v[198:201], v[74:77]
	v_mfma_f32_16x16x32_bf16 v[66:69], v[174:177], v[206:209], v[66:69]
	v_mfma_f32_16x16x32_bf16 v[70:73], v[166:169], v[206:209], v[70:73]
	v_mfma_f32_16x16x32_bf16 v[114:117], v[170:173], v[186:189], v[114:117]
	v_mfma_f32_16x16x32_bf16 v[106:109], v[178:181], v[186:189], v[106:109]
	v_mfma_f32_16x16x32_bf16 v[90:93], v[178:181], v[194:197], v[90:93]
	v_mfma_f32_16x16x32_bf16 v[98:101], v[170:173], v[194:197], v[98:101]
	v_mfma_f32_16x16x32_bf16 v[82:85], v[170:173], v[202:205], v[82:85]
	v_mfma_f32_16x16x32_bf16 v[74:77], v[178:181], v[202:205], v[74:77]
	v_mfma_f32_16x16x32_bf16 v[66:69], v[178:181], v[210:213], v[66:69]
	v_mfma_f32_16x16x32_bf16 v[70:73], v[170:173], v[210:213], v[70:73]
	s_setprio 0
	s_barrier
; #define PG8_STAGE(bufoff, gbase, voff) do { _Pragma("unroll") for (int _i = 0; _i < 2; ++_i) \
;         __builtin_amdgcn_global_load_lds((const unsigned*)((const char*)(gbase) + (voff)[_i]), (PG8_LAS unsigned*)(lds + (bufoff) + ldsw + _i * 8192), 16, 0, 0); } while (0)
; #define PG8_LDA(dst, b, h) do { _Pragma("unroll") for (int m = 0; m < 4; ++m) _Pragma("unroll") for (int k = 0; k < 2; ++k) dst[m][k] = *(const PG8_LAS bf16x8*)(lds + PG8_SA(b, h) + aoff + m * 2048 + k * 1024); } while (0)
; #define PG8_MMA(ai, bj, At, Bt) do { __builtin_amdgcn_s_setprio(1); _Pragma("unroll") for (int m = 0; m < 4; ++m) _Pragma("unroll") for (int n = 0; n < 2; ++n) _Pragma("unroll") for (int k = 0; k < 2; ++k) \
;         acc[ai][bj][m][n] = __builtin_amdgcn_mfma_f32_16x16x32_bf16(Bt[n][k], At[m][k], acc[ai][bj][m][n], 0, 0, 0); __builtin_amdgcn_s_setprio(0); } while (0)
; #define PG8_WAIT_V(n) asm volatile("s_waitcnt vmcnt(" #n ")" ::: "memory")
; #define PG8_WAIT_L(n) asm volatile("s_waitcnt lgkmcnt(" #n ")" ::: "memory")
; #define PG8_BAR __builtin_amdgcn_s_barrier()
; #define PG8_SCHED __builtin_amdgcn_sched_barrier(0)
; template <class Epi, class Sched, bool ALIGN_EPI = false, bool SP2 = false>
; __device__ __forceinline__ void gemm_phase(PG8_LAS unsigned char* lds, const Gemm g, const Sched& S, const Epi& E) {
;     ...
;             PG8_LDA(At, 1, 1); PG8_STAGE(PG8_SB(1, 0), b3, voffB); PG8_STAGE(PG8_SB(1, 1), b3 + hstep, voffB); PG8_STAGE(PG8_SA(1, 0), a3, voffA);
;             PG8_WAIT_V(8); PG8_WAIT_L(0); PG8_BAR; PG8_MMA(1, 0, At, B0); PG8_MMA(1, 1, At, B1); PG8_BAR; PG8_SCHED;
;     ...
;         if constexpr (ALIGN_EPI) { if (wr == 0) PG8_BAR; }
	s_mov_b32 m0, s68
	v_lshl_add_u64 v[142:143], v[142:143], 0, s[10:11]
	ds_read_b128 v[182:185], v149 offset:49152
	ds_read_b128 v[186:189], v149 offset:50176
	ds_read_b128 v[190:193], v149 offset:51200
	ds_read_b128 v[194:197], v149 offset:52224
	ds_read_b128 v[198:201], v149 offset:53248
	ds_read_b128 v[202:205], v149 offset:54272
	ds_read_b128 v[206:209], v149 offset:55296
	ds_read_b128 v[210:213], v149 offset:56320
	global_load_lds_dwordx4 v[142:143], off
	v_lshl_add_u64 v[142:143], v[214:215], 0, s[10:11]
	s_mov_b32 m0, s66
	s_nop 0
	global_load_lds_dwordx4 v[142:143], off
	v_lshl_add_u64 v[142:143], s[30:31], 0, v[134:135]
	s_mov_b32 m0, s67
	s_nop 0
	global_load_lds_dwordx4 v[142:143], off
	v_lshl_add_u64 v[142:143], s[30:31], 0, v[130:131]
	s_mov_b32 m0, s65
	s_nop 0
	global_load_lds_dwordx4 v[142:143], off
	v_lshl_add_u64 v[142:143], v[216:217], 0, s[10:11]
	s_mov_b32 m0, s55
	s_nop 0
	global_load_lds_dwordx4 v[142:143], off
	v_lshl_add_u64 v[142:143], v[218:219], 0, s[10:11]
	s_mov_b32 m0, s56
	s_nop 0
	global_load_lds_dwordx4 v[142:143], off
	s_waitcnt vmcnt(8)
	s_waitcnt lgkmcnt(0)
	s_barrier
	s_setprio 1
	s_waitcnt lgkmcnt(0)
	v_mfma_f32_16x16x32_bf16 v[62:65], v[150:153], v[182:185], v[62:65]
	v_mfma_f32_16x16x32_bf16 v[58:61], v[158:161], v[182:185], v[58:61]
	v_mfma_f32_16x16x32_bf16 v[46:49], v[158:161], v[190:193], v[46:49]
	v_mfma_f32_16x16x32_bf16 v[54:57], v[150:153], v[190:193], v[54:57]
	v_mfma_f32_16x16x32_bf16 v[38:41], v[150:153], v[198:201], v[38:41]
	v_mfma_f32_16x16x32_bf16 v[30:33], v[158:161], v[198:201], v[30:33]
	v_mfma_f32_16x16x32_bf16 v[14:17], v[158:161], v[206:209], v[14:17]
	v_mfma_f32_16x16x32_bf16 v[22:25], v[150:153], v[206:209], v[22:25]
	v_mfma_f32_16x16x32_bf16 v[62:65], v[154:157], v[186:189], v[62:65]
	v_mfma_f32_16x16x32_bf16 v[58:61], v[162:165], v[186:189], v[58:61]
	v_mfma_f32_16x16x32_bf16 v[46:49], v[162:165], v[194:197], v[46:49]
	v_mfma_f32_16x16x32_bf16 v[54:57], v[154:157], v[194:197], v[54:57]
	v_mfma_f32_16x16x32_bf16 v[38:41], v[154:157], v[202:205], v[38:41]
	v_mfma_f32_16x16x32_bf16 v[30:33], v[162:165], v[202:205], v[30:33]
	v_mfma_f32_16x16x32_bf16 v[14:17], v[162:165], v[210:213], v[14:17]
	v_mfma_f32_16x16x32_bf16 v[22:25], v[154:157], v[210:213], v[22:25]
	s_setprio 0
	s_setprio 1
	v_mfma_f32_16x16x32_bf16 v[50:53], v[166:169], v[182:185], v[50:53]
	v_mfma_f32_16x16x32_bf16 v[42:45], v[174:177], v[182:185], v[42:45]
	v_mfma_f32_16x16x32_bf16 v[26:29], v[174:177], v[190:193], v[26:29]
	v_mfma_f32_16x16x32_bf16 v[34:37], v[166:169], v[190:193], v[34:37]
	v_mfma_f32_16x16x32_bf16 v[18:21], v[166:169], v[198:201], v[18:21]
	v_mfma_f32_16x16x32_bf16 v[10:13], v[174:177], v[198:201], v[10:13]
	v_mfma_f32_16x16x32_bf16 v[2:5], v[174:177], v[206:209], v[2:5]
	v_mfma_f32_16x16x32_bf16 v[6:9], v[166:169], v[206:209], v[6:9]
	v_mfma_f32_16x16x32_bf16 v[50:53], v[170:173], v[186:189], v[50:53]
	v_mfma_f32_16x16x32_bf16 v[42:45], v[178:181], v[186:189], v[42:45]
	v_mfma_f32_16x16x32_bf16 v[26:29], v[178:181], v[194:197], v[26:29]
	v_mfma_f32_16x16x32_bf16 v[34:37], v[170:173], v[194:197], v[34:37]
	v_mfma_f32_16x16x32_bf16 v[18:21], v[170:173], v[202:205], v[18:21]
	v_mfma_f32_16x16x32_bf16 v[10:13], v[178:181], v[202:205], v[10:13]
	v_mfma_f32_16x16x32_bf16 v[2:5], v[178:181], v[210:213], v[2:5]
	v_mfma_f32_16x16x32_bf16 v[6:9], v[170:173], v[210:213], v[6:9]
	s_setprio 0
	s_barrier
	s_movk_i32 s36, 0x100
	s_andn2_b64 vcc, exec, s[28:29]
	s_mov_b64 s[30:31], -1
	s_mov_b64 s[28:29], 0
	s_cbranch_vccz .LBB0_1693
	s_and_b64 vcc, exec, s[12:13]
	s_cbranch_vccz .LBB0_1696
	s_barrier

; #define PG8_STAGE(bufoff, gbase, voff) do { _Pragma("unroll") for (int _i = 0; _i < 2; ++_i) \
;         __builtin_amdgcn_global_load_lds((const unsigned*)((const char*)(gbase) + (voff)[_i]), (PG8_LAS unsigned*)(lds + (bufoff) + ldsw + _i * 8192), 16, 0, 0); } while (0)
; #define PG8_LDA(dst, b, h) do { _Pragma("unroll") for (int m = 0; m < 4; ++m) _Pragma("unroll") for (int k = 0; k < 2; ++k) dst[m][k] = *(const PG8_LAS bf16x8*)(lds + PG8_SA(b, h) + aoff + m * 2048 + k * 1024); } while (0)
; #define PG8_LDB(dst, b, h) do { _Pragma("unroll") for (int n = 0; n < 2; ++n) _Pragma("unroll") for (int k = 0; k < 2; ++k) dst[n][k] = *(const PG8_LAS bf16x8*)(lds + PG8_SB(b, h) + boff + n * 2048 + k * 1024); } while (0)
; #define PG8_MMA(ai, bj, At, Bt) do { __builtin_amdgcn_s_setprio(1); _Pragma("unroll") for (int m = 0; m < 4; ++m) _Pragma("unroll") for (int n = 0; n < 2; ++n) _Pragma("unroll") for (int k = 0; k < 2; ++k) \
;         acc[ai][bj][m][n] = __builtin_amdgcn_mfma_f32_16x16x32_bf16(Bt[n][k], At[m][k], acc[ai][bj][m][n], 0, 0, 0); __builtin_amdgcn_s_setprio(0); } while (0)
; #define PG8_WAIT_V(n) asm volatile("s_waitcnt vmcnt(" #n ")" ::: "memory")
; #define PG8_WAIT_L(n) asm volatile("s_waitcnt lgkmcnt(" #n ")" ::: "memory")
; template <class Epi, class Sched, bool ALIGN_EPI = false, bool SP2 = false>
; __device__ __forceinline__ void gemm_phase(PG8_LAS unsigned char* lds, const Gemm g, const Sched& S, const Epi& E) {
;     ...
;         for (int t = 0; t < nt; t += 2) {
;             if constexpr (Epi::MIDHOOK) { if (t == (nt >> 1)) E.mid(acc, cur, wr, wc, fr, fq); }
;             const bool last = (t == nt - 2);
;             const char* a1 = cA + (size_t)(t + 1) * kstep;
;             const char* a2 = last ? nA : cA + (size_t)(t + 2) * kstep; const char* b2 = last ? nB : cB + (size_t)(t + 2) * kstep;
;             const char* a3 = a2 + kstep; const char* b3 = b2 + kstep;
;             if (last && has_next) S.a_ready(nxt);
;             if constexpr (SP2) {
;             PG8_LDB(B0, 0, 0); PG8_LDB(B1, 0, 1); PG8_SCHED; PG8_LDA(At, 0, 0); PG8_STAGE(PG8_SA(1, 1), a1 + hstep, voffA);
;             PG8_WAIT_V(8); PG8_WAIT_L(0); PG8_BAR; PG8_MMA(0, 0, At, B0); PG8_MMA(0, 1, At, B1); PG8_BAR; PG8_SCHED;
;             PG8_LDA(At, 0, 1); PG8_STAGE(PG8_SB(0, 0), b2, voffB); PG8_STAGE(PG8_SB(0, 1), b2 + hstep, voffB); PG8_STAGE(PG8_SA(0, 0), a2, voffA);
.LBB0_1820:
	ds_read_b128 v[146:149], v155
	ds_read_b128 v[158:161], v155 offset:1024
	ds_read_b128 v[162:165], v155 offset:2048
	ds_read_b128 v[166:169], v155 offset:3072
	ds_read_b128 v[170:173], v156
	ds_read_b128 v[174:177], v156 offset:1024
	ds_read_b128 v[178:181], v156 offset:2048
	ds_read_b128 v[182:185], v156 offset:3072
	s_add_u32 s38, s36, 0xfff80080
	s_addc_u32 s39, s37, -1
	s_cmp_eq_u32 s58, 28
	s_cselect_b32 s41, s25, s39
	s_cselect_b32 s40, s54, s38
	s_cselect_b32 s39, s23, s57
	s_cselect_b32 s38, s55, s56
	v_lshl_add_u64 v[150:151], s[36:37], 0, v[138:139]
	s_add_i32 m0, s31, 0xc000
	ds_read_b128 v[186:189], v157
	ds_read_b128 v[190:193], v157 offset:1024
	ds_read_b128 v[194:197], v157 offset:2048
	ds_read_b128 v[198:201], v157 offset:3072
	ds_read_b128 v[202:205], v157 offset:4096
	ds_read_b128 v[206:209], v157 offset:5120
	ds_read_b128 v[210:213], v157 offset:6144
	ds_read_b128 v[214:217], v157 offset:7168
	global_load_lds_dwordx4 v[150:151], off
	v_lshl_add_u64 v[150:151], s[36:37], 0, v[140:141]
	s_add_i32 m0, s31, 0xe000
	s_nop 0
	global_load_lds_dwordx4 v[150:151], off
	s_waitcnt vmcnt(8)
	s_waitcnt lgkmcnt(0)
	s_barrier
	s_setprio 1
	s_waitcnt lgkmcnt(0)
	v_mfma_f32_16x16x32_bf16 v[126:129], v[146:149], v[186:189], v[126:129]
	v_mfma_f32_16x16x32_bf16 v[122:125], v[162:165], v[186:189], v[122:125]
	v_mfma_f32_16x16x32_bf16 v[106:109], v[162:165], v[194:197], v[106:109]
	v_mfma_f32_16x16x32_bf16 v[110:113], v[146:149], v[194:197], v[110:113]
	v_mfma_f32_16x16x32_bf16 v[94:97], v[146:149], v[202:205], v[94:97]
	v_mfma_f32_16x16x32_bf16 v[90:93], v[162:165], v[202:205], v[90:93]
	v_mfma_f32_16x16x32_bf16 v[74:77], v[162:165], v[210:213], v[74:77]
	v_mfma_f32_16x16x32_bf16 v[78:81], v[146:149], v[210:213], v[78:81]
	v_mfma_f32_16x16x32_bf16 v[126:129], v[158:161], v[190:193], v[126:129]
	v_mfma_f32_16x16x32_bf16 v[122:125], v[166:169], v[190:193], v[122:125]
	v_mfma_f32_16x16x32_bf16 v[106:109], v[166:169], v[198:201], v[106:109]
	v_mfma_f32_16x16x32_bf16 v[110:113], v[158:161], v[198:201], v[110:113]
	v_mfma_f32_16x16x32_bf16 v[94:97], v[158:161], v[206:209], v[94:97]
	v_mfma_f32_16x16x32_bf16 v[90:93], v[166:169], v[206:209], v[90:93]
	v_mfma_f32_16x16x32_bf16 v[74:77], v[166:169], v[214:217], v[74:77]
	v_mfma_f32_16x16x32_bf16 v[78:81], v[158:161], v[214:217], v[78:81]
	s_setprio 0
	s_setprio 1
	v_mfma_f32_16x16x32_bf16 v[118:121], v[170:173], v[186:189], v[118:121]
	v_mfma_f32_16x16x32_bf16 v[114:117], v[178:181], v[186:189], v[114:117]
	v_mfma_f32_16x16x32_bf16 v[98:101], v[178:181], v[194:197], v[98:101]
	v_mfma_f32_16x16x32_bf16 v[102:105], v[170:173], v[194:197], v[102:105]
	v_mfma_f32_16x16x32_bf16 v[86:89], v[170:173], v[202:205], v[86:89]
	v_mfma_f32_16x16x32_bf16 v[82:85], v[178:181], v[202:205], v[82:85]
	v_mfma_f32_16x16x32_bf16 v[66:69], v[178:181], v[210:213], v[66:69]
	v_mfma_f32_16x16x32_bf16 v[70:73], v[170:173], v[210:213], v[70:73]
	v_mfma_f32_16x16x32_bf16 v[118:121], v[174:177], v[190:193], v[118:121]
	v_mfma_f32_16x16x32_bf16 v[114:117], v[182:185], v[190:193], v[114:117]
	v_mfma_f32_16x16x32_bf16 v[98:101], v[182:185], v[198:201], v[98:101]
	v_mfma_f32_16x16x32_bf16 v[102:105], v[174:177], v[198:201], v[102:105]
	v_mfma_f32_16x16x32_bf16 v[86:89], v[174:177], v[206:209], v[86:89]
	v_mfma_f32_16x16x32_bf16 v[82:85], v[182:185], v[206:209], v[82:85]
	v_mfma_f32_16x16x32_bf16 v[66:69], v[182:185], v[214:217], v[66:69]
	v_mfma_f32_16x16x32_bf16 v[70:73], v[174:177], v[214:217], v[70:73]
	s_setprio 0
	s_barrier
	s_add_i32 s59, s51, s3
	v_lshl_add_u64 v[150:151], s[38:39], 0, v[134:135]
	s_mov_b32 m0, s59
	ds_read_b128 v[186:189], v157 offset:16384
	ds_read_b128 v[190:193], v157 offset:17408
	ds_read_b128 v[194:197], v157 offset:18432
	ds_read_b128 v[198:201], v157 offset:19456
	ds_read_b128 v[202:205], v157 offset:20480
	ds_read_b128 v[206:209], v157 offset:21504
	ds_read_b128 v[210:213], v157 offset:22528
	ds_read_b128 v[214:217], v157 offset:23552
	global_load_lds_dwordx4 v[150:151], off
	s_add_i32 m0, s59, 0x2000
	s_add_u32 s60, s38, 0x80000
	v_lshl_add_u64 v[218:219], s[38:39], 0, v[130:131]
	s_addc_u32 s61, s39, 0
	s_add_i32 s59, s52, s3
	global_load_lds_dwordx4 v[218:219], off
	v_lshl_add_u64 v[220:221], s[60:61], 0, v[134:135]
	s_mov_b32 m0, s59
	v_lshl_add_u64 v[222:223], s[40:41], 0, v[132:133]
	global_load_lds_dwordx4 v[220:221], off
	v_lshl_add_u64 v[220:221], s[60:61], 0, v[130:131]
	s_add_i32 m0, s59, 0x2000
	s_nop 0
	global_load_lds_dwordx4 v[220:221], off
	v_lshl_add_u64 v[220:221], s[40:41], 0, v[136:137]
	s_mov_b32 m0, s31
	s_nop 0
	global_load_lds_dwordx4 v[220:221], off
	s_mov_b32 m0, s43
	s_nop 0
	global_load_lds_dwordx4 v[222:223], off
	s_waitcnt vmcnt(8)
	s_waitcnt lgkmcnt(0)
	s_barrier
; #define PG8_STAGE(bufoff, gbase, voff) do { _Pragma("unroll") for (int _i = 0; _i < 2; ++_i) \
;         __builtin_amdgcn_global_load_lds((const unsigned*)((const char*)(gbase) + (voff)[_i]), (PG8_LAS unsigned*)(lds + (bufoff) + ldsw + _i * 8192), 16, 0, 0); } while (0)
; #define PG8_LDA(dst, b, h) do { _Pragma("unroll") for (int m = 0; m < 4; ++m) _Pragma("unroll") for (int k = 0; k < 2; ++k) dst[m][k] = *(const PG8_LAS bf16x8*)(lds + PG8_SA(b, h) + aoff + m * 2048 + k * 1024); } while (0)
; #define PG8_LDB(dst, b, h) do { _Pragma("unroll") for (int n = 0; n < 2; ++n) _Pragma("unroll") for (int k = 0; k < 2; ++k) dst[n][k] = *(const PG8_LAS bf16x8*)(lds + PG8_SB(b, h) + boff + n * 2048 + k * 1024); } while (0)
; #define PG8_MMA(ai, bj, At, Bt) do { __builtin_amdgcn_s_setprio(1); _Pragma("unroll") for (int m = 0; m < 4; ++m) _Pragma("unroll") for (int n = 0; n < 2; ++n) _Pragma("unroll") for (int k = 0; k < 2; ++k) \
;         acc[ai][bj][m][n] = __builtin_amdgcn_mfma_f32_16x16x32_bf16(Bt[n][k], At[m][k], acc[ai][bj][m][n], 0, 0, 0); __builtin_amdgcn_s_setprio(0); } while (0)
; #define PG8_WAIT_V(n) asm volatile("s_waitcnt vmcnt(" #n ")" ::: "memory")
; #define PG8_WAIT_L(n) asm volatile("s_waitcnt lgkmcnt(" #n ")" ::: "memory")
; #define PG8_BAR __builtin_amdgcn_s_barrier()
; #define PG8_SCHED __builtin_amdgcn_sched_barrier(0)
; template <class Epi, class Sched, bool ALIGN_EPI = false, bool SP2 = false>
; __device__ __forceinline__ void gemm_phase(PG8_LAS unsigned char* lds, const Gemm g, const Sched& S, const Epi& E) {
;     ...
;             PG8_WAIT_V(8); PG8_WAIT_L(0); PG8_BAR; PG8_MMA(1, 0, At, B0); PG8_MMA(1, 1, At, B1); PG8_BAR; PG8_SCHED;
;             PG8_LDB(B0, 1, 0); PG8_LDB(B1, 1, 1); PG8_SCHED; PG8_LDA(At, 1, 0); PG8_STAGE(PG8_SA(0, 1), a2 + hstep, voffA);
;             PG8_WAIT_V(8); PG8_WAIT_L(0); PG8_BAR; PG8_MMA(0, 0, At, B0); PG8_MMA(0, 1, At, B1); PG8_BAR; PG8_SCHED;
	s_setprio 1
	s_waitcnt lgkmcnt(0)
	v_mfma_f32_16x16x32_bf16 v[62:65], v[146:149], v[186:189], v[62:65]
	v_mfma_f32_16x16x32_bf16 v[58:61], v[162:165], v[186:189], v[58:61]
	v_mfma_f32_16x16x32_bf16 v[42:45], v[162:165], v[194:197], v[42:45]
	v_mfma_f32_16x16x32_bf16 v[46:49], v[146:149], v[194:197], v[46:49]
	v_mfma_f32_16x16x32_bf16 v[30:33], v[146:149], v[202:205], v[30:33]
	v_mfma_f32_16x16x32_bf16 v[26:29], v[162:165], v[202:205], v[26:29]
	v_mfma_f32_16x16x32_bf16 v[10:13], v[162:165], v[210:213], v[10:13]
	v_mfma_f32_16x16x32_bf16 v[14:17], v[146:149], v[210:213], v[14:17]
	v_mfma_f32_16x16x32_bf16 v[62:65], v[158:161], v[190:193], v[62:65]
	v_mfma_f32_16x16x32_bf16 v[58:61], v[166:169], v[190:193], v[58:61]
	v_mfma_f32_16x16x32_bf16 v[42:45], v[166:169], v[198:201], v[42:45]
	v_mfma_f32_16x16x32_bf16 v[46:49], v[158:161], v[198:201], v[46:49]
	v_mfma_f32_16x16x32_bf16 v[30:33], v[158:161], v[206:209], v[30:33]
	v_mfma_f32_16x16x32_bf16 v[26:29], v[166:169], v[206:209], v[26:29]
	v_mfma_f32_16x16x32_bf16 v[10:13], v[166:169], v[214:217], v[10:13]
	v_mfma_f32_16x16x32_bf16 v[14:17], v[158:161], v[214:217], v[14:17]
	s_setprio 0
	s_setprio 1
	v_mfma_f32_16x16x32_bf16 v[54:57], v[170:173], v[186:189], v[54:57]
	v_mfma_f32_16x16x32_bf16 v[50:53], v[178:181], v[186:189], v[50:53]
	v_mfma_f32_16x16x32_bf16 v[34:37], v[178:181], v[194:197], v[34:37]
	v_mfma_f32_16x16x32_bf16 v[38:41], v[170:173], v[194:197], v[38:41]
	v_mfma_f32_16x16x32_bf16 v[22:25], v[170:173], v[202:205], v[22:25]
	v_mfma_f32_16x16x32_bf16 v[18:21], v[178:181], v[202:205], v[18:21]
	v_mfma_f32_16x16x32_bf16 v[2:5], v[178:181], v[210:213], v[2:5]
	v_mfma_f32_16x16x32_bf16 v[6:9], v[170:173], v[210:213], v[6:9]
	v_mfma_f32_16x16x32_bf16 v[54:57], v[174:177], v[190:193], v[54:57]
	v_mfma_f32_16x16x32_bf16 v[50:53], v[182:185], v[190:193], v[50:53]
	v_mfma_f32_16x16x32_bf16 v[34:37], v[182:185], v[198:201], v[34:37]
	v_mfma_f32_16x16x32_bf16 v[38:41], v[174:177], v[198:201], v[38:41]
	v_mfma_f32_16x16x32_bf16 v[22:25], v[174:177], v[206:209], v[22:25]
	v_mfma_f32_16x16x32_bf16 v[18:21], v[182:185], v[206:209], v[18:21]
	v_mfma_f32_16x16x32_bf16 v[2:5], v[182:185], v[214:217], v[2:5]
	v_mfma_f32_16x16x32_bf16 v[6:9], v[174:177], v[214:217], v[6:9]
	s_setprio 0
	s_barrier
	s_add_i32 s59, 0, 0x18000
	s_add_i32 s60, 0, 0x1c000
	v_add_u32_e32 v166, s59, v153
	v_add_u32_e32 v182, s60, v153
	ds_read_b128 v[146:149], v166
	ds_read_b128 v[158:161], v166 offset:1024
	ds_read_b128 v[162:165], v166 offset:2048
	ds_read_b128 v[166:169], v166 offset:3072
	ds_read_b128 v[170:173], v182
	ds_read_b128 v[174:177], v182 offset:1024
	ds_read_b128 v[178:181], v182 offset:2048
	ds_read_b128 v[182:185], v182 offset:3072
	s_add_u32 s40, s40, 0x80000
	s_addc_u32 s41, s41, 0
	s_mov_b32 m0, s44
	v_lshl_add_u64 v[224:225], s[40:41], 0, v[136:137]
	ds_read_b128 v[186:189], v157 offset:32768
	ds_read_b128 v[190:193], v157 offset:33792
	ds_read_b128 v[194:197], v157 offset:34816
	ds_read_b128 v[198:201], v157 offset:35840
	ds_read_b128 v[202:205], v157 offset:36864
	ds_read_b128 v[206:209], v157 offset:37888
	ds_read_b128 v[210:213], v157 offset:38912
	ds_read_b128 v[214:217], v157 offset:39936
	global_load_lds_dwordx4 v[224:225], off
	v_lshl_add_u64 v[224:225], s[40:41], 0, v[132:133]
	s_mov_b32 m0, s45
	s_nop 0
	global_load_lds_dwordx4 v[224:225], off
	s_waitcnt vmcnt(8)
	s_waitcnt lgkmcnt(0)
	s_barrier
	s_setprio 1
	s_waitcnt lgkmcnt(0)
	v_mfma_f32_16x16x32_bf16 v[126:129], v[146:149], v[186:189], v[126:129]
	v_mfma_f32_16x16x32_bf16 v[122:125], v[162:165], v[186:189], v[122:125]
	v_mfma_f32_16x16x32_bf16 v[106:109], v[162:165], v[194:197], v[106:109]
	v_mfma_f32_16x16x32_bf16 v[110:113], v[146:149], v[194:197], v[110:113]
	v_mfma_f32_16x16x32_bf16 v[94:97], v[146:149], v[202:205], v[94:97]
	v_mfma_f32_16x16x32_bf16 v[90:93], v[162:165], v[202:205], v[90:93]
	v_mfma_f32_16x16x32_bf16 v[74:77], v[162:165], v[210:213], v[74:77]
	v_mfma_f32_16x16x32_bf16 v[78:81], v[146:149], v[210:213], v[78:81]
	v_mfma_f32_16x16x32_bf16 v[126:129], v[158:161], v[190:193], v[126:129]
	v_mfma_f32_16x16x32_bf16 v[122:125], v[166:169], v[190:193], v[122:125]
	v_mfma_f32_16x16x32_bf16 v[106:109], v[166:169], v[198:201], v[106:109]
	v_mfma_f32_16x16x32_bf16 v[110:113], v[158:161], v[198:201], v[110:113]
	v_mfma_f32_16x16x32_bf16 v[94:97], v[158:161], v[206:209], v[94:97]
	v_mfma_f32_16x16x32_bf16 v[90:93], v[166:169], v[206:209], v[90:93]
	v_mfma_f32_16x16x32_bf16 v[74:77], v[166:169], v[214:217], v[74:77]
	v_mfma_f32_16x16x32_bf16 v[78:81], v[158:161], v[214:217], v[78:81]
	s_setprio 0
	s_setprio 1
	v_mfma_f32_16x16x32_bf16 v[118:121], v[170:173], v[186:189], v[118:121]
	v_mfma_f32_16x16x32_bf16 v[114:117], v[178:181], v[186:189], v[114:117]
	v_mfma_f32_16x16x32_bf16 v[98:101], v[178:181], v[194:197], v[98:101]
	v_mfma_f32_16x16x32_bf16 v[102:105], v[170:173], v[194:197], v[102:105]
	v_mfma_f32_16x16x32_bf16 v[86:89], v[170:173], v[202:205], v[86:89]
	v_mfma_f32_16x16x32_bf16 v[82:85], v[178:181], v[202:205], v[82:85]
	v_mfma_f32_16x16x32_bf16 v[66:69], v[178:181], v[210:213], v[66:69]
	v_mfma_f32_16x16x32_bf16 v[70:73], v[170:173], v[210:213], v[70:73]
	v_mfma_f32_16x16x32_bf16 v[118:121], v[174:177], v[190:193], v[118:121]
	v_mfma_f32_16x16x32_bf16 v[114:117], v[182:185], v[190:193], v[114:117]
	v_mfma_f32_16x16x32_bf16 v[98:101], v[182:185], v[198:201], v[98:101]
	v_mfma_f32_16x16x32_bf16 v[102:105], v[174:177], v[198:201], v[102:105]
	v_mfma_f32_16x16x32_bf16 v[86:89], v[174:177], v[206:209], v[86:89]
	v_mfma_f32_16x16x32_bf16 v[82:85], v[182:185], v[206:209], v[82:85]
	v_mfma_f32_16x16x32_bf16 v[66:69], v[182:185], v[214:217], v[66:69]
	v_mfma_f32_16x16x32_bf16 v[70:73], v[174:177], v[214:217], v[70:73]
	s_setprio 0
	s_barrier
; #define PG8_STAGE(bufoff, gbase, voff) do { _Pragma("unroll") for (int _i = 0; _i < 2; ++_i) \
;         __builtin_amdgcn_global_load_lds((const unsigned*)((const char*)(gbase) + (voff)[_i]), (PG8_LAS unsigned*)(lds + (bufoff) + ldsw + _i * 8192), 16, 0, 0); } while (0)
; #define PG8_LDA(dst, b, h) do { _Pragma("unroll") for (int m = 0; m < 4; ++m) _Pragma("unroll") for (int k = 0; k < 2; ++k) dst[m][k] = *(const PG8_LAS bf16x8*)(lds + PG8_SA(b, h) + aoff + m * 2048 + k * 1024); } while (0)
; #define PG8_MMA(ai, bj, At, Bt) do { __builtin_amdgcn_s_setprio(1); _Pragma("unroll") for (int m = 0; m < 4; ++m) _Pragma("unroll") for (int n = 0; n < 2; ++n) _Pragma("unroll") for (int k = 0; k < 2; ++k) \
;         acc[ai][bj][m][n] = __builtin_amdgcn_mfma_f32_16x16x32_bf16(Bt[n][k], At[m][k], acc[ai][bj][m][n], 0, 0, 0); __builtin_amdgcn_s_setprio(0); } while (0)
; #define PG8_WAIT_V(n) asm volatile("s_waitcnt vmcnt(" #n ")" ::: "memory")
; #define PG8_WAIT_L(n) asm volatile("s_waitcnt lgkmcnt(" #n ")" ::: "memory")
; #define PG8_BAR __builtin_amdgcn_s_barrier()
; #define PG8_SCHED __builtin_amdgcn_sched_barrier(0)
; template <class Epi, class Sched, bool ALIGN_EPI = false, bool SP2 = false>
; __device__ __forceinline__ void gemm_phase(PG8_LAS unsigned char* lds, const Gemm g, const Sched& S, const Epi& E) {
;     ...
;             PG8_LDA(At, 1, 1); PG8_STAGE(PG8_SB(1, 0), b3, voffB); PG8_STAGE(PG8_SB(1, 1), b3 + hstep, voffB); PG8_STAGE(PG8_SA(1, 0), a3, voffA);
;             PG8_WAIT_V(8); PG8_WAIT_L(0); PG8_BAR; PG8_MMA(1, 0, At, B0); PG8_MMA(1, 1, At, B1); PG8_BAR; PG8_SCHED;
;     ...
;         if constexpr (ALIGN_EPI) { if (wr == 0) PG8_BAR; }
	s_add_i32 s40, s59, s3
	v_lshl_add_u64 v[150:151], v[150:151], 0, s[12:13]
	s_mov_b32 m0, s40
	ds_read_b128 v[186:189], v157 offset:49152
	ds_read_b128 v[190:193], v157 offset:50176
	ds_read_b128 v[194:197], v157 offset:51200
	ds_read_b128 v[198:201], v157 offset:52224
	ds_read_b128 v[202:205], v157 offset:53248
	ds_read_b128 v[206:209], v157 offset:54272
	ds_read_b128 v[210:213], v157 offset:55296
	ds_read_b128 v[214:217], v157 offset:56320
	global_load_lds_dwordx4 v[150:151], off
	s_add_i32 m0, s40, 0x2000
	s_add_u32 s38, s38, 0x80080
	v_lshl_add_u64 v[150:151], v[218:219], 0, s[12:13]
	s_addc_u32 s39, s39, 0
	s_add_i32 s40, s60, s3
	global_load_lds_dwordx4 v[150:151], off
	v_lshl_add_u64 v[150:151], s[38:39], 0, v[134:135]
	s_mov_b32 m0, s40
	s_nop 0
	global_load_lds_dwordx4 v[150:151], off
	v_lshl_add_u64 v[150:151], s[38:39], 0, v[130:131]
	s_add_i32 m0, s40, 0x2000
	s_nop 0
	global_load_lds_dwordx4 v[150:151], off
	v_lshl_add_u64 v[150:151], v[220:221], 0, s[12:13]
	s_mov_b32 m0, s48
	s_nop 0
	global_load_lds_dwordx4 v[150:151], off
	v_lshl_add_u64 v[150:151], v[222:223], 0, s[12:13]
	s_mov_b32 m0, s49
	s_nop 0
	global_load_lds_dwordx4 v[150:151], off
	s_waitcnt vmcnt(8)
	s_waitcnt lgkmcnt(0)
	s_barrier
	s_setprio 1
	s_waitcnt lgkmcnt(0)
	v_mfma_f32_16x16x32_bf16 v[62:65], v[146:149], v[186:189], v[62:65]
	v_mfma_f32_16x16x32_bf16 v[58:61], v[162:165], v[186:189], v[58:61]
	v_mfma_f32_16x16x32_bf16 v[42:45], v[162:165], v[194:197], v[42:45]
	v_mfma_f32_16x16x32_bf16 v[46:49], v[146:149], v[194:197], v[46:49]
	v_mfma_f32_16x16x32_bf16 v[30:33], v[146:149], v[202:205], v[30:33]
	v_mfma_f32_16x16x32_bf16 v[26:29], v[162:165], v[202:205], v[26:29]
	v_mfma_f32_16x16x32_bf16 v[10:13], v[162:165], v[210:213], v[10:13]
	v_mfma_f32_16x16x32_bf16 v[14:17], v[146:149], v[210:213], v[14:17]
	v_mfma_f32_16x16x32_bf16 v[62:65], v[158:161], v[190:193], v[62:65]
	v_mfma_f32_16x16x32_bf16 v[58:61], v[166:169], v[190:193], v[58:61]
	v_mfma_f32_16x16x32_bf16 v[42:45], v[166:169], v[198:201], v[42:45]
	v_mfma_f32_16x16x32_bf16 v[46:49], v[158:161], v[198:201], v[46:49]
	v_mfma_f32_16x16x32_bf16 v[30:33], v[158:161], v[206:209], v[30:33]
	v_mfma_f32_16x16x32_bf16 v[26:29], v[166:169], v[206:209], v[26:29]
	v_mfma_f32_16x16x32_bf16 v[10:13], v[166:169], v[214:217], v[10:13]
	v_mfma_f32_16x16x32_bf16 v[14:17], v[158:161], v[214:217], v[14:17]
	s_setprio 0
	s_setprio 1
	v_mfma_f32_16x16x32_bf16 v[54:57], v[170:173], v[186:189], v[54:57]
	v_mfma_f32_16x16x32_bf16 v[50:53], v[178:181], v[186:189], v[50:53]
	v_mfma_f32_16x16x32_bf16 v[34:37], v[178:181], v[194:197], v[34:37]
	v_mfma_f32_16x16x32_bf16 v[38:41], v[170:173], v[194:197], v[38:41]
	v_mfma_f32_16x16x32_bf16 v[22:25], v[170:173], v[202:205], v[22:25]
	v_mfma_f32_16x16x32_bf16 v[18:21], v[178:181], v[202:205], v[18:21]
	v_mfma_f32_16x16x32_bf16 v[2:5], v[178:181], v[210:213], v[2:5]
	v_mfma_f32_16x16x32_bf16 v[6:9], v[170:173], v[210:213], v[6:9]
	v_mfma_f32_16x16x32_bf16 v[54:57], v[174:177], v[190:193], v[54:57]
	v_mfma_f32_16x16x32_bf16 v[50:53], v[182:185], v[190:193], v[50:53]
	v_mfma_f32_16x16x32_bf16 v[34:37], v[182:185], v[198:201], v[34:37]
	v_mfma_f32_16x16x32_bf16 v[38:41], v[174:177], v[198:201], v[38:41]
	v_mfma_f32_16x16x32_bf16 v[22:25], v[174:177], v[206:209], v[22:25]
	v_mfma_f32_16x16x32_bf16 v[18:21], v[182:185], v[206:209], v[18:21]
	v_mfma_f32_16x16x32_bf16 v[2:5], v[182:185], v[214:217], v[2:5]
	v_mfma_f32_16x16x32_bf16 v[6:9], v[174:177], v[214:217], v[6:9]
	s_setprio 0
	s_barrier
	s_add_i32 s58, s58, 2
	s_add_u32 s36, s36, 0x100
	s_addc_u32 s37, s37, 0
	s_add_u32 s56, s56, 0x100
	s_addc_u32 s57, s57, 0
	s_cmp_gt_u32 s58, 29
	s_cbranch_scc0 .LBB0_1820
	s_and_b64 vcc, exec, s[14:15]
	s_cbranch_vccz .LBB0_1823
	s_barrier

;     __device__ bool next(int i, Unit& u) const { if (!s.next(i, u)) return false; const int p = u.pn; u.pn = p < 56 ? (p % 7) * 8 + p / 7 : p; return true; }
;     __device__ bool next(int i, Unit& u) const { Unit t; if (!s.next(i >> 1, t)) return false; const int pass = i & 1; u.pm = t.pm + pass * (M / BM); u.pn = t.pn + pass * (D / BM); u.kt0 = 0; return true; }
; #define PG8_STAGE(bufoff, gbase, voff) do { _Pragma("unroll") for (int _i = 0; _i < 2; ++_i) \
;         __builtin_amdgcn_global_load_lds((const unsigned*)((const char*)(gbase) + (voff)[_i]), (PG8_LAS unsigned*)(lds + (bufoff) + ldsw + _i * 8192), 16, 0, 0); } while (0)
; #define PG8_LDA(dst, b, h) do { _Pragma("unroll") for (int m = 0; m < 4; ++m) _Pragma("unroll") for (int k = 0; k < 2; ++k) dst[m][k] = *(const PG8_LAS bf16x8*)(lds + PG8_SA(b, h) + aoff + m * 2048 + k * 1024); } while (0)
; #define PG8_WAIT_V(n) asm volatile("s_waitcnt vmcnt(" #n ")" ::: "memory")
; #define PG8_BAR __builtin_amdgcn_s_barrier()
; template <class Epi, class Sched, bool ALIGN_EPI = false, bool SP2 = false>
; __device__ __forceinline__ void gemm_phase(PG8_LAS unsigned char* lds, const Gemm g, const Sched& S, const Epi& E) {
;     ...
;         const bool has_next = S.next(ui + 1, nxt);
;         const char* nA = has_next ? (const char*)g.A + (size_t)nxt.pm * tstep + (size_t)nxt.kt0 * kstep : cA; const char* nB = has_next ? (const char*)g.Bt + (size_t)nxt.pn * tstep + (size_t)nxt.kt0 * kstep : cB;
;         for (int t = 0; t < nt; t += 2) {
;             if constexpr (Epi::MIDHOOK) { if (t == (nt >> 1)) E.mid(acc, cur, wr, wc, fr, fq); }
;             const bool last = (t == nt - 2);
;             const char* a1 = cA + (size_t)(t + 1) * kstep;
;             const char* a2 = last ? nA : cA + (size_t)(t + 2) * kstep; const char* b2 = last ? nB : cB + (size_t)(t + 2) * kstep;
;             const char* a3 = a2 + kstep; const char* b3 = b2 + kstep;
;             if (last && has_next) S.a_ready(nxt);
;             if constexpr (SP2) {
;             PG8_LDB(B0, 0, 0); PG8_LDB(B1, 0, 1); PG8_SCHED; PG8_LDA(At, 0, 0); PG8_STAGE(PG8_SA(1, 1), a1 + hstep, voffA);
;             PG8_WAIT_V(8); PG8_WAIT_L(0); PG8_BAR; PG8_MMA(0, 0, At, B0); PG8_MMA(0, 1, At, B1); PG8_BAR; PG8_SCHED;
;             PG8_LDA(At, 0, 1); PG8_STAGE(PG8_SB(0, 0), b2, voffB); PG8_STAGE(PG8_SB(0, 1), b2 + hstep, voffB); PG8_STAGE(PG8_SA(0, 0), a2, voffA);
.LBB0_1840:
	s_add_u32 s25, s12, s3
	s_addc_u32 s27, s13, 0
	s_add_u32 s42, s25, 0x100
	s_addc_u32 s43, s27, 0
	s_and_b64 s[40:41], s[38:39], exec
	s_cselect_b32 s43, s29, s43
	s_cselect_b32 s42, s28, s42
	s_add_u32 s3, s8, s3
	s_addc_u32 s40, s9, 0
	s_add_u32 s3, s3, 0x100
	s_addc_u32 s40, s40, 0
	s_and_b64 s[38:39], s[38:39], exec
	s_cselect_b32 s45, s31, s40
	s_cselect_b32 s44, s30, s3
	s_add_u32 s48, s25, 0x80080
	ds_read_b128 v[140:143], v137
	ds_read_b128 v[144:147], v137 offset:1024
	ds_read_b128 v[148:151], v137 offset:2048
	ds_read_b128 v[152:155], v137 offset:3072
	ds_read_b128 v[156:159], v138
	ds_read_b128 v[160:163], v138 offset:1024
	ds_read_b128 v[164:167], v138 offset:2048
	ds_read_b128 v[168:171], v138 offset:3072
	s_addc_u32 s49, s27, 0
	s_add_i32 s74, s63, s51
	s_add_i32 m0, s54, 0xc000
	s_add_i32 s77, s54, 0xe000
	s_add_i32 s71, s74, 0x2000
	s_add_u32 s46, s44, 0x80000
	s_addc_u32 s47, s45, 0
	s_add_i32 s73, s64, s51
	s_add_i32 s72, s73, 0x2000
	s_add_i32 s70, 0, 0x18000
	s_add_i32 s27, 0, 0x1c000
	s_add_u32 s40, s42, 0x80000
	s_addc_u32 s41, s43, 0
	s_add_i32 s25, s70, s51
	s_add_i32 s3, s25, 0x2000
	s_add_u32 s38, s44, 0x80080
	s_addc_u32 s39, s45, 0
	s_add_i32 s76, s27, s51
	s_add_i32 s75, s76, 0x2000
	v_lshl_add_u64 v[204:205], s[48:49], 0, v[132:133]
	ds_read_b128 v[172:175], v139
	ds_read_b128 v[176:179], v139 offset:1024
	ds_read_b128 v[180:183], v139 offset:2048
	ds_read_b128 v[184:187], v139 offset:3072
	ds_read_b128 v[188:191], v139 offset:4096
	ds_read_b128 v[192:195], v139 offset:5120
	ds_read_b128 v[196:199], v139 offset:6144
	ds_read_b128 v[200:203], v139 offset:7168
	global_load_lds_dwordx4 v[204:205], off
	v_lshl_add_u64 v[204:205], s[48:49], 0, v[130:131]
	s_mov_b32 m0, s77
	s_nop 0
	global_load_lds_dwordx4 v[204:205], off
	s_waitcnt vmcnt(8)
	s_waitcnt lgkmcnt(0)
	s_barrier
	s_setprio 1
	s_waitcnt lgkmcnt(0)
	v_mfma_f32_16x16x32_bf16 v[126:129], v[140:143], v[172:175], v[126:129]
	v_mfma_f32_16x16x32_bf16 v[122:125], v[148:151], v[172:175], v[122:125]
	v_mfma_f32_16x16x32_bf16 v[114:117], v[148:151], v[180:183], v[114:117]
	v_mfma_f32_16x16x32_bf16 v[118:121], v[140:143], v[180:183], v[118:121]
	v_mfma_f32_16x16x32_bf16 v[106:109], v[140:143], v[188:191], v[106:109]
	v_mfma_f32_16x16x32_bf16 v[98:101], v[148:151], v[188:191], v[98:101]
	v_mfma_f32_16x16x32_bf16 v[82:85], v[148:151], v[196:199], v[82:85]
	v_mfma_f32_16x16x32_bf16 v[90:93], v[140:143], v[196:199], v[90:93]
	v_mfma_f32_16x16x32_bf16 v[126:129], v[144:147], v[176:179], v[126:129]
	v_mfma_f32_16x16x32_bf16 v[122:125], v[152:155], v[176:179], v[122:125]
	v_mfma_f32_16x16x32_bf16 v[114:117], v[152:155], v[184:187], v[114:117]
	v_mfma_f32_16x16x32_bf16 v[118:121], v[144:147], v[184:187], v[118:121]
	v_mfma_f32_16x16x32_bf16 v[106:109], v[144:147], v[192:195], v[106:109]
	v_mfma_f32_16x16x32_bf16 v[98:101], v[152:155], v[192:195], v[98:101]
	v_mfma_f32_16x16x32_bf16 v[82:85], v[152:155], v[200:203], v[82:85]
	v_mfma_f32_16x16x32_bf16 v[90:93], v[144:147], v[200:203], v[90:93]
	s_setprio 0
	s_setprio 1
	v_mfma_f32_16x16x32_bf16 v[110:113], v[156:159], v[172:175], v[110:113]
	v_mfma_f32_16x16x32_bf16 v[102:105], v[164:167], v[172:175], v[102:105]
	v_mfma_f32_16x16x32_bf16 v[86:89], v[164:167], v[180:183], v[86:89]
	v_mfma_f32_16x16x32_bf16 v[94:97], v[156:159], v[180:183], v[94:97]
	v_mfma_f32_16x16x32_bf16 v[78:81], v[156:159], v[188:191], v[78:81]
	v_mfma_f32_16x16x32_bf16 v[74:77], v[164:167], v[188:191], v[74:77]
	v_mfma_f32_16x16x32_bf16 v[66:69], v[164:167], v[196:199], v[66:69]
	v_mfma_f32_16x16x32_bf16 v[70:73], v[156:159], v[196:199], v[70:73]
	v_mfma_f32_16x16x32_bf16 v[110:113], v[160:163], v[176:179], v[110:113]
	v_mfma_f32_16x16x32_bf16 v[102:105], v[168:171], v[176:179], v[102:105]
	v_mfma_f32_16x16x32_bf16 v[86:89], v[168:171], v[184:187], v[86:89]
	v_mfma_f32_16x16x32_bf16 v[94:97], v[160:163], v[184:187], v[94:97]
	v_mfma_f32_16x16x32_bf16 v[78:81], v[160:163], v[192:195], v[78:81]
	v_mfma_f32_16x16x32_bf16 v[74:77], v[168:171], v[192:195], v[74:77]
	v_mfma_f32_16x16x32_bf16 v[66:69], v[168:171], v[200:203], v[66:69]
	v_mfma_f32_16x16x32_bf16 v[70:73], v[160:163], v[200:203], v[70:73]
	s_setprio 0
	s_barrier
	s_mov_b32 m0, s74
	v_lshl_add_u64 v[204:205], s[44:45], 0, v[132:133]
	ds_read_b128 v[172:175], v139 offset:16384
	ds_read_b128 v[176:179], v139 offset:17408
	ds_read_b128 v[180:183], v139 offset:18432
	ds_read_b128 v[184:187], v139 offset:19456
	ds_read_b128 v[188:191], v139 offset:20480
	ds_read_b128 v[192:195], v139 offset:21504
	ds_read_b128 v[196:199], v139 offset:22528
	ds_read_b128 v[200:203], v139 offset:23552
	global_load_lds_dwordx4 v[204:205], off
	v_lshl_add_u64 v[206:207], s[44:45], 0, v[130:131]
	s_mov_b32 m0, s71
	v_lshl_add_u64 v[208:209], s[46:47], 0, v[132:133]
	global_load_lds_dwordx4 v[206:207], off
	s_mov_b32 m0, s73
	v_lshl_add_u64 v[210:211], s[42:43], 0, v[130:131]
	global_load_lds_dwordx4 v[208:209], off
	v_lshl_add_u64 v[208:209], s[46:47], 0, v[130:131]
	s_mov_b32 m0, s72
	s_nop 0
	global_load_lds_dwordx4 v[208:209], off
	v_lshl_add_u64 v[208:209], s[42:43], 0, v[132:133]
	s_mov_b32 m0, s54
	s_nop 0
	global_load_lds_dwordx4 v[208:209], off
	s_mov_b32 m0, s55
	s_nop 0
	global_load_lds_dwordx4 v[210:211], off
	s_waitcnt vmcnt(8)
	s_waitcnt lgkmcnt(0)
	s_barrier
; #define PG8_STAGE(bufoff, gbase, voff) do { _Pragma("unroll") for (int _i = 0; _i < 2; ++_i) \
;         __builtin_amdgcn_global_load_lds((const unsigned*)((const char*)(gbase) + (voff)[_i]), (PG8_LAS unsigned*)(lds + (bufoff) + ldsw + _i * 8192), 16, 0, 0); } while (0)
; #define PG8_LDA(dst, b, h) do { _Pragma("unroll") for (int m = 0; m < 4; ++m) _Pragma("unroll") for (int k = 0; k < 2; ++k) dst[m][k] = *(const PG8_LAS bf16x8*)(lds + PG8_SA(b, h) + aoff + m * 2048 + k * 1024); } while (0)
; #define PG8_LDB(dst, b, h) do { _Pragma("unroll") for (int n = 0; n < 2; ++n) _Pragma("unroll") for (int k = 0; k < 2; ++k) dst[n][k] = *(const PG8_LAS bf16x8*)(lds + PG8_SB(b, h) + boff + n * 2048 + k * 1024); } while (0)
; #define PG8_MMA(ai, bj, At, Bt) do { __builtin_amdgcn_s_setprio(1); _Pragma("unroll") for (int m = 0; m < 4; ++m) _Pragma("unroll") for (int n = 0; n < 2; ++n) _Pragma("unroll") for (int k = 0; k < 2; ++k) \
;         acc[ai][bj][m][n] = __builtin_amdgcn_mfma_f32_16x16x32_bf16(Bt[n][k], At[m][k], acc[ai][bj][m][n], 0, 0, 0); __builtin_amdgcn_s_setprio(0); } while (0)
; #define PG8_WAIT_V(n) asm volatile("s_waitcnt vmcnt(" #n ")" ::: "memory")
; #define PG8_WAIT_L(n) asm volatile("s_waitcnt lgkmcnt(" #n ")" ::: "memory")
; #define PG8_BAR __builtin_amdgcn_s_barrier()
; #define PG8_SCHED __builtin_amdgcn_sched_barrier(0)
; template <class Epi, class Sched, bool ALIGN_EPI = false, bool SP2 = false>
; __device__ __forceinline__ void gemm_phase(PG8_LAS unsigned char* lds, const Gemm g, const Sched& S, const Epi& E) {
;     ...
;             PG8_WAIT_V(8); PG8_WAIT_L(0); PG8_BAR; PG8_MMA(1, 0, At, B0); PG8_MMA(1, 1, At, B1); PG8_BAR; PG8_SCHED;
;             PG8_LDB(B0, 1, 0); PG8_LDB(B1, 1, 1); PG8_SCHED; PG8_LDA(At, 1, 0); PG8_STAGE(PG8_SA(0, 1), a2 + hstep, voffA);
;             PG8_WAIT_V(8); PG8_WAIT_L(0); PG8_BAR; PG8_MMA(0, 0, At, B0); PG8_MMA(0, 1, At, B1); PG8_BAR; PG8_SCHED;
	s_setprio 1
	s_waitcnt lgkmcnt(0)
	v_mfma_f32_16x16x32_bf16 v[62:65], v[140:143], v[172:175], v[62:65]
	v_mfma_f32_16x16x32_bf16 v[58:61], v[148:151], v[172:175], v[58:61]
	v_mfma_f32_16x16x32_bf16 v[50:53], v[148:151], v[180:183], v[50:53]
	v_mfma_f32_16x16x32_bf16 v[54:57], v[140:143], v[180:183], v[54:57]
	v_mfma_f32_16x16x32_bf16 v[42:45], v[140:143], v[188:191], v[42:45]
	v_mfma_f32_16x16x32_bf16 v[34:37], v[148:151], v[188:191], v[34:37]
	v_mfma_f32_16x16x32_bf16 v[18:21], v[148:151], v[196:199], v[18:21]
	v_mfma_f32_16x16x32_bf16 v[26:29], v[140:143], v[196:199], v[26:29]
	v_mfma_f32_16x16x32_bf16 v[62:65], v[144:147], v[176:179], v[62:65]
	v_mfma_f32_16x16x32_bf16 v[58:61], v[152:155], v[176:179], v[58:61]
	v_mfma_f32_16x16x32_bf16 v[50:53], v[152:155], v[184:187], v[50:53]
	v_mfma_f32_16x16x32_bf16 v[54:57], v[144:147], v[184:187], v[54:57]
	v_mfma_f32_16x16x32_bf16 v[42:45], v[144:147], v[192:195], v[42:45]
	v_mfma_f32_16x16x32_bf16 v[34:37], v[152:155], v[192:195], v[34:37]
	v_mfma_f32_16x16x32_bf16 v[18:21], v[152:155], v[200:203], v[18:21]
	v_mfma_f32_16x16x32_bf16 v[26:29], v[144:147], v[200:203], v[26:29]
	s_setprio 0
	s_setprio 1
	v_mfma_f32_16x16x32_bf16 v[46:49], v[156:159], v[172:175], v[46:49]
	v_mfma_f32_16x16x32_bf16 v[38:41], v[164:167], v[172:175], v[38:41]
	v_mfma_f32_16x16x32_bf16 v[22:25], v[164:167], v[180:183], v[22:25]
	v_mfma_f32_16x16x32_bf16 v[30:33], v[156:159], v[180:183], v[30:33]
	v_mfma_f32_16x16x32_bf16 v[14:17], v[156:159], v[188:191], v[14:17]
	v_mfma_f32_16x16x32_bf16 v[10:13], v[164:167], v[188:191], v[10:13]
	v_mfma_f32_16x16x32_bf16 v[2:5], v[164:167], v[196:199], v[2:5]
	v_mfma_f32_16x16x32_bf16 v[6:9], v[156:159], v[196:199], v[6:9]
	v_mfma_f32_16x16x32_bf16 v[46:49], v[160:163], v[176:179], v[46:49]
	v_mfma_f32_16x16x32_bf16 v[38:41], v[168:171], v[176:179], v[38:41]
	v_mfma_f32_16x16x32_bf16 v[22:25], v[168:171], v[184:187], v[22:25]
	v_mfma_f32_16x16x32_bf16 v[30:33], v[160:163], v[184:187], v[30:33]
	v_mfma_f32_16x16x32_bf16 v[14:17], v[160:163], v[192:195], v[14:17]
	v_mfma_f32_16x16x32_bf16 v[10:13], v[168:171], v[192:195], v[10:13]
	v_mfma_f32_16x16x32_bf16 v[2:5], v[168:171], v[200:203], v[2:5]
	v_mfma_f32_16x16x32_bf16 v[6:9], v[160:163], v[200:203], v[6:9]
	s_setprio 0
	s_barrier
	v_add_u32_e32 v152, s70, v134
	v_add_u32_e32 v168, s27, v134
	ds_read_b128 v[140:143], v152
	ds_read_b128 v[144:147], v152 offset:1024
	ds_read_b128 v[148:151], v152 offset:2048
	ds_read_b128 v[152:155], v152 offset:3072
	ds_read_b128 v[156:159], v168
	ds_read_b128 v[160:163], v168 offset:1024
	ds_read_b128 v[164:167], v168 offset:2048
	ds_read_b128 v[168:171], v168 offset:3072
	s_mov_b32 m0, s56
	v_lshl_add_u64 v[212:213], s[40:41], 0, v[132:133]
	ds_read_b128 v[172:175], v139 offset:32768
	ds_read_b128 v[176:179], v139 offset:33792
	ds_read_b128 v[180:183], v139 offset:34816
	ds_read_b128 v[184:187], v139 offset:35840
	ds_read_b128 v[188:191], v139 offset:36864
	ds_read_b128 v[192:195], v139 offset:37888
	ds_read_b128 v[196:199], v139 offset:38912
	ds_read_b128 v[200:203], v139 offset:39936
	global_load_lds_dwordx4 v[212:213], off
	v_lshl_add_u64 v[212:213], s[40:41], 0, v[130:131]
	s_mov_b32 m0, s57
	s_nop 0
	global_load_lds_dwordx4 v[212:213], off
	s_waitcnt vmcnt(8)
	s_waitcnt lgkmcnt(0)
	s_barrier
	s_setprio 1
	s_waitcnt lgkmcnt(0)
	v_mfma_f32_16x16x32_bf16 v[126:129], v[140:143], v[172:175], v[126:129]
	v_mfma_f32_16x16x32_bf16 v[122:125], v[148:151], v[172:175], v[122:125]
	v_mfma_f32_16x16x32_bf16 v[114:117], v[148:151], v[180:183], v[114:117]
	v_mfma_f32_16x16x32_bf16 v[118:121], v[140:143], v[180:183], v[118:121]
	v_mfma_f32_16x16x32_bf16 v[106:109], v[140:143], v[188:191], v[106:109]
	v_mfma_f32_16x16x32_bf16 v[98:101], v[148:151], v[188:191], v[98:101]
	v_mfma_f32_16x16x32_bf16 v[82:85], v[148:151], v[196:199], v[82:85]
	v_mfma_f32_16x16x32_bf16 v[90:93], v[140:143], v[196:199], v[90:93]
	v_mfma_f32_16x16x32_bf16 v[126:129], v[144:147], v[176:179], v[126:129]
	v_mfma_f32_16x16x32_bf16 v[122:125], v[152:155], v[176:179], v[122:125]
	v_mfma_f32_16x16x32_bf16 v[114:117], v[152:155], v[184:187], v[114:117]
	v_mfma_f32_16x16x32_bf16 v[118:121], v[144:147], v[184:187], v[118:121]
	v_mfma_f32_16x16x32_bf16 v[106:109], v[144:147], v[192:195], v[106:109]
	v_mfma_f32_16x16x32_bf16 v[98:101], v[152:155], v[192:195], v[98:101]
	v_mfma_f32_16x16x32_bf16 v[82:85], v[152:155], v[200:203], v[82:85]
	v_mfma_f32_16x16x32_bf16 v[90:93], v[144:147], v[200:203], v[90:93]
	s_setprio 0
	s_setprio 1
	v_mfma_f32_16x16x32_bf16 v[110:113], v[156:159], v[172:175], v[110:113]
	v_mfma_f32_16x16x32_bf16 v[102:105], v[164:167], v[172:175], v[102:105]
	v_mfma_f32_16x16x32_bf16 v[86:89], v[164:167], v[180:183], v[86:89]
	v_mfma_f32_16x16x32_bf16 v[94:97], v[156:159], v[180:183], v[94:97]
	v_mfma_f32_16x16x32_bf16 v[78:81], v[156:159], v[188:191], v[78:81]
	v_mfma_f32_16x16x32_bf16 v[74:77], v[164:167], v[188:191], v[74:77]
	v_mfma_f32_16x16x32_bf16 v[66:69], v[164:167], v[196:199], v[66:69]
	v_mfma_f32_16x16x32_bf16 v[70:73], v[156:159], v[196:199], v[70:73]
	v_mfma_f32_16x16x32_bf16 v[110:113], v[160:163], v[176:179], v[110:113]
	v_mfma_f32_16x16x32_bf16 v[102:105], v[168:171], v[176:179], v[102:105]
	v_mfma_f32_16x16x32_bf16 v[86:89], v[168:171], v[184:187], v[86:89]
	v_mfma_f32_16x16x32_bf16 v[94:97], v[160:163], v[184:187], v[94:97]
	v_mfma_f32_16x16x32_bf16 v[78:81], v[160:163], v[192:195], v[78:81]
	v_mfma_f32_16x16x32_bf16 v[74:77], v[168:171], v[192:195], v[74:77]
	v_mfma_f32_16x16x32_bf16 v[66:69], v[168:171], v[200:203], v[66:69]
	v_mfma_f32_16x16x32_bf16 v[70:73], v[160:163], v[200:203], v[70:73]
	s_setprio 0
	s_barrier
; #define PG8_STAGE(bufoff, gbase, voff) do { _Pragma("unroll") for (int _i = 0; _i < 2; ++_i) \
;         __builtin_amdgcn_global_load_lds((const unsigned*)((const char*)(gbase) + (voff)[_i]), (PG8_LAS unsigned*)(lds + (bufoff) + ldsw + _i * 8192), 16, 0, 0); } while (0)
; #define PG8_LDA(dst, b, h) do { _Pragma("unroll") for (int m = 0; m < 4; ++m) _Pragma("unroll") for (int k = 0; k < 2; ++k) dst[m][k] = *(const PG8_LAS bf16x8*)(lds + PG8_SA(b, h) + aoff + m * 2048 + k * 1024); } while (0)
; #define PG8_MMA(ai, bj, At, Bt) do { __builtin_amdgcn_s_setprio(1); _Pragma("unroll") for (int m = 0; m < 4; ++m) _Pragma("unroll") for (int n = 0; n < 2; ++n) _Pragma("unroll") for (int k = 0; k < 2; ++k) \
;         acc[ai][bj][m][n] = __builtin_amdgcn_mfma_f32_16x16x32_bf16(Bt[n][k], At[m][k], acc[ai][bj][m][n], 0, 0, 0); __builtin_amdgcn_s_setprio(0); } while (0)
; #define PG8_WAIT_V(n) asm volatile("s_waitcnt vmcnt(" #n ")" ::: "memory")
; #define PG8_WAIT_L(n) asm volatile("s_waitcnt lgkmcnt(" #n ")" ::: "memory")
; #define PG8_BAR __builtin_amdgcn_s_barrier()
; #define PG8_SCHED __builtin_amdgcn_sched_barrier(0)
; template <class Epi, class Sched, bool ALIGN_EPI = false, bool SP2 = false>
; __device__ __forceinline__ void gemm_phase(PG8_LAS unsigned char* lds, const Gemm g, const Sched& S, const Epi& E) {
;     ...
;             PG8_LDA(At, 1, 1); PG8_STAGE(PG8_SB(1, 0), b3, voffB); PG8_STAGE(PG8_SB(1, 1), b3 + hstep, voffB); PG8_STAGE(PG8_SA(1, 0), a3, voffA);
;             PG8_WAIT_V(8); PG8_WAIT_L(0); PG8_BAR; PG8_MMA(1, 0, At, B0); PG8_MMA(1, 1, At, B1); PG8_BAR; PG8_SCHED;
;     ...
;         if constexpr (ALIGN_EPI) { if (wr == 0) PG8_BAR; }
	s_mov_b32 m0, s25
	v_lshl_add_u64 v[204:205], v[204:205], 0, s[10:11]
	ds_read_b128 v[172:175], v139 offset:49152
	ds_read_b128 v[176:179], v139 offset:50176
	ds_read_b128 v[180:183], v139 offset:51200
	ds_read_b128 v[184:187], v139 offset:52224
	ds_read_b128 v[188:191], v139 offset:53248
	ds_read_b128 v[192:195], v139 offset:54272
	ds_read_b128 v[196:199], v139 offset:55296
	ds_read_b128 v[200:203], v139 offset:56320
	global_load_lds_dwordx4 v[204:205], off
	v_lshl_add_u64 v[204:205], v[206:207], 0, s[10:11]
	s_mov_b32 m0, s3
	s_nop 0
	global_load_lds_dwordx4 v[204:205], off
	v_lshl_add_u64 v[204:205], s[38:39], 0, v[132:133]
	s_mov_b32 m0, s76
	s_nop 0
	global_load_lds_dwordx4 v[204:205], off
	v_lshl_add_u64 v[204:205], s[38:39], 0, v[130:131]
	s_mov_b32 m0, s75
	s_nop 0
	global_load_lds_dwordx4 v[204:205], off
	v_lshl_add_u64 v[204:205], v[208:209], 0, s[10:11]
	s_mov_b32 m0, s60
	s_nop 0
	global_load_lds_dwordx4 v[204:205], off
	v_lshl_add_u64 v[204:205], v[210:211], 0, s[10:11]
	s_mov_b32 m0, s61
	s_nop 0
	global_load_lds_dwordx4 v[204:205], off
	s_waitcnt vmcnt(8)
	s_waitcnt lgkmcnt(0)
	s_barrier
	s_setprio 1
	s_waitcnt lgkmcnt(0)
	v_mfma_f32_16x16x32_bf16 v[62:65], v[140:143], v[172:175], v[62:65]
	v_mfma_f32_16x16x32_bf16 v[58:61], v[148:151], v[172:175], v[58:61]
	v_mfma_f32_16x16x32_bf16 v[50:53], v[148:151], v[180:183], v[50:53]
	v_mfma_f32_16x16x32_bf16 v[54:57], v[140:143], v[180:183], v[54:57]
	v_mfma_f32_16x16x32_bf16 v[42:45], v[140:143], v[188:191], v[42:45]
	v_mfma_f32_16x16x32_bf16 v[34:37], v[148:151], v[188:191], v[34:37]
	v_mfma_f32_16x16x32_bf16 v[18:21], v[148:151], v[196:199], v[18:21]
	v_mfma_f32_16x16x32_bf16 v[26:29], v[140:143], v[196:199], v[26:29]
	v_mfma_f32_16x16x32_bf16 v[62:65], v[144:147], v[176:179], v[62:65]
	v_mfma_f32_16x16x32_bf16 v[58:61], v[152:155], v[176:179], v[58:61]
	v_mfma_f32_16x16x32_bf16 v[50:53], v[152:155], v[184:187], v[50:53]
	v_mfma_f32_16x16x32_bf16 v[54:57], v[144:147], v[184:187], v[54:57]
	v_mfma_f32_16x16x32_bf16 v[42:45], v[144:147], v[192:195], v[42:45]
	v_mfma_f32_16x16x32_bf16 v[34:37], v[152:155], v[192:195], v[34:37]
	v_mfma_f32_16x16x32_bf16 v[18:21], v[152:155], v[200:203], v[18:21]
	v_mfma_f32_16x16x32_bf16 v[26:29], v[144:147], v[200:203], v[26:29]
	s_setprio 0
	s_setprio 1
	v_mfma_f32_16x16x32_bf16 v[46:49], v[156:159], v[172:175], v[46:49]
	v_mfma_f32_16x16x32_bf16 v[38:41], v[164:167], v[172:175], v[38:41]
	v_mfma_f32_16x16x32_bf16 v[22:25], v[164:167], v[180:183], v[22:25]
	v_mfma_f32_16x16x32_bf16 v[30:33], v[156:159], v[180:183], v[30:33]
	v_mfma_f32_16x16x32_bf16 v[14:17], v[156:159], v[188:191], v[14:17]
	v_mfma_f32_16x16x32_bf16 v[10:13], v[164:167], v[188:191], v[10:13]
	v_mfma_f32_16x16x32_bf16 v[2:5], v[164:167], v[196:199], v[2:5]
	v_mfma_f32_16x16x32_bf16 v[6:9], v[156:159], v[196:199], v[6:9]
	v_mfma_f32_16x16x32_bf16 v[46:49], v[160:163], v[176:179], v[46:49]
	v_mfma_f32_16x16x32_bf16 v[38:41], v[168:171], v[176:179], v[38:41]
	v_mfma_f32_16x16x32_bf16 v[22:25], v[168:171], v[184:187], v[22:25]
	v_mfma_f32_16x16x32_bf16 v[30:33], v[160:163], v[184:187], v[30:33]
	v_mfma_f32_16x16x32_bf16 v[14:17], v[160:163], v[192:195], v[14:17]
	v_mfma_f32_16x16x32_bf16 v[10:13], v[168:171], v[192:195], v[10:13]
	v_mfma_f32_16x16x32_bf16 v[2:5], v[168:171], v[200:203], v[2:5]
	v_mfma_f32_16x16x32_bf16 v[6:9], v[160:163], v[200:203], v[6:9]
	s_setprio 0
	s_barrier
	s_movk_i32 s3, 0x100
	s_andn2_b64 vcc, exec, s[36:37]
	s_mov_b64 s[38:39], -1
	s_mov_b64 s[36:37], 0
	s_cbranch_vccz .LBB0_1840
	s_and_b64 vcc, exec, s[14:15]
	s_cbranch_vccz .LBB0_1843
	s_barrier
